# modulated-norm ladders software-pipelined one step ahead (regular steps only: 9-11 of 15 per ladder), counted vmcnt
# baseline (speedup 1.0000x reference)
.LBB0_842:
	v_lshl_add_u64 v[18:19], s[38:39], 0, v[94:95]
	v_lshl_add_u64 v[22:23], s[38:39], 0, v[92:93]
	v_add_co_u32_e32 v20, vcc, 0x7800000, v18
	v_add_co_u32_e64 v102, s[6:7], s31, v22
	s_nop 0
	v_addc_co_u32_e32 v21, vcc, 0, v19, vcc
	v_addc_co_u32_e64 v103, s[6:7], 0, v23, s[6:7]
	v_add_co_u32_e64 v104, s[6:7], s33, v22
	v_add_co_u32_e32 v22, vcc, 0x7801000, v18
	s_nop 0
	v_addc_co_u32_e64 v105, s[6:7], 0, v23, s[6:7]
	global_load_dwordx4 v[78:81], v[20:21], off
	global_load_dwordx4 v[74:77], v[20:21], off offset:1024
	global_load_dwordx4 v[70:73], v[20:21], off offset:2048
	global_load_dwordx4 v[66:69], v[20:21], off offset:3072
	v_addc_co_u32_e32 v23, vcc, 0, v19, vcc
	v_add_co_u32_e32 v20, vcc, 0x7802000, v18
	global_load_dwordx4 v[62:65], v[22:23], off
	global_load_dwordx4 v[58:61], v[22:23], off offset:1024
	global_load_dwordx4 v[54:57], v[22:23], off offset:2048
	global_load_dwordx4 v[50:53], v[22:23], off offset:3072
	v_addc_co_u32_e32 v21, vcc, 0, v19, vcc
	global_load_dwordx4 v[46:49], v[20:21], off
	global_load_dwordx4 v[42:45], v[20:21], off offset:1024
	global_load_dwordx4 v[38:41], v[20:21], off offset:2048
	global_load_dwordx4 v[34:37], v[20:21], off offset:3072
	v_add_co_u32_e32 v18, vcc, 0x7803000, v18
	s_ashr_i32 s8, s18, 13
	s_nop 0
	v_addc_co_u32_e32 v19, vcc, 0, v19, vcc
	global_load_dwordx4 v[30:33], v[18:19], off
	global_load_dwordx4 v[26:29], v[18:19], off offset:1024
	global_load_dwordx4 v[22:25], v[18:19], off offset:2048
	s_nop 0
	global_load_dwordx4 v[18:21], v[18:19], off offset:3072
	s_add_i32 s9, s18, 0xffffc002
	s_cmpk_lt_i32 s18, 0x4000
	s_cselect_b32 s6, s8, s9
	s_mul_hi_i32 s7, s6, 0x9000
	s_mul_i32 s6, s6, 0x9000
	s_add_u32 s6, s27, s6
	s_addc_u32 s7, s28, s7
	s_add_u32 s10, s6, 0x1000
	s_addc_u32 s11, s7, 0
	v_lshl_add_u64 v[122:123], s[6:7], 0, v[90:91]
	v_lshl_add_u64 v[86:87], s[10:11], 0, v[90:91]
	global_load_dwordx4 v[82:85], v[122:123], off
	s_add_i32 s6, s18, 0xffffc003
	global_load_dwordx4 v[86:89], v[86:87], off
	s_cmpk_lt_i32 s18, 0x3fff
	s_cselect_b32 s6, s8, s6
	s_mul_hi_i32 s7, s6, 0x9000
	s_mul_i32 s6, s6, 0x9000
	s_add_u32 s6, s27, s6
	s_addc_u32 s7, s28, s7
	v_lshl_add_u64 v[142:143], s[10:11], 0, v[96:97]
	v_lshl_add_u64 v[138:139], s[10:11], 0, v[98:99]
	v_lshl_add_u64 v[128:129], s[10:11], 0, v[100:101]
	s_add_u32 s10, s6, 0x1000
	v_lshl_add_u64 v[110:111], s[6:7], 0, v[90:91]
	s_addc_u32 s11, s7, 0
	s_add_i32 s6, s18, 0xffffc004
	s_cmpk_lt_i32 s18, 0x3ffe
	s_cselect_b32 s6, s8, s6
	s_mul_hi_i32 s7, s6, 0x9000
	s_mul_i32 s6, s6, 0x9000
	v_lshl_add_u64 v[124:125], s[10:11], 0, v[90:91]
	v_lshl_add_u64 v[118:119], s[10:11], 0, v[96:97]
	v_lshl_add_u64 v[114:115], s[10:11], 0, v[98:99]
	v_lshl_add_u64 v[112:113], s[10:11], 0, v[100:101]
	s_add_u32 s10, s27, s6
	s_addc_u32 s11, s28, s7
	s_add_u32 s6, s10, 0x1000
	s_addc_u32 s7, s11, 0
	s_add_i32 s9, s18, 0xffffc005
	s_cmpk_lt_i32 s18, 0x3ffd
	v_lshl_add_u64 v[146:147], s[6:7], 0, v[90:91]
	v_lshl_add_u64 v[144:145], s[6:7], 0, v[96:97]
	v_lshl_add_u64 v[140:141], s[6:7], 0, v[98:99]
	v_lshl_add_u64 v[126:127], s[6:7], 0, v[100:101]
	s_cselect_b32 s6, s8, s9
	s_mul_hi_i32 s7, s6, 0x9000
	s_mul_i32 s6, s6, 0x9000
	s_add_u32 s6, s27, s6
	s_addc_u32 s7, s28, s7
	s_add_u32 s24, s6, 0x1000
	v_lshl_add_u64 v[106:107], s[6:7], 0, v[90:91]
	s_addc_u32 s25, s7, 0
	v_lshl_add_u64 v[108:109], s[10:11], 0, v[90:91]
	v_lshl_add_u64 v[120:121], s[24:25], 0, v[90:91]
	v_lshl_add_u64 v[116:117], s[24:25], 0, v[96:97]
	s_add_i32 s18, s18, 32
	v_lshl_add_u64 v[92:93], v[92:93], 0, s[20:21]
	v_lshl_add_u64 v[94:95], v[94:95], 0, s[22:23]
	s_cmp_lt_i32 s18, s26
	s_waitcnt vmcnt(0) lgkmcnt(0)
	v_pk_mul_f32 v[148:149], v[80:81], v[80:81]
	v_pk_mul_f32 v[150:151], v[78:79], v[78:79]
	v_pk_mul_f32 v[152:153], v[76:77], v[76:77]
	v_pk_mul_f32 v[154:155], v[74:75], v[74:75]
	v_mul_f32_e32 v164, v71, v71
	v_mul_f32_e32 v166, v73, v73
	v_pk_mov_b32 v[168:169], v[150:151], v[148:149] op_sel:[1,0]
	v_mov_b32_e32 v151, v149
	v_pk_mov_b32 v[148:149], v[154:155], v[152:153] op_sel:[1,0]
	v_mov_b32_e32 v155, v153
	v_mul_f32_e32 v177, v68, v68
	v_mul_f32_e32 v179, v69, v69
	v_pk_fma_f32 v[152:153], v[70:71], v[70:71], v[164:165] op_sel_hi:[1,1,0]
	v_pk_fma_f32 v[164:165], v[72:73], v[72:73], v[166:167] op_sel_hi:[1,1,0]
	v_pk_mul_f32 v[166:167], v[64:65], v[64:65]
	v_pk_mul_f32 v[170:171], v[62:63], v[62:63]
	v_pk_mul_f32 v[172:173], v[60:61], v[60:61]
	v_pk_mul_f32 v[174:175], v[58:59], v[58:59]
	v_mul_f32_e32 v176, v55, v55
	v_mul_f32_e32 v178, v57, v57
	v_pk_add_f32 v[150:151], v[168:169], v[150:151]
	v_pk_add_f32 v[148:149], v[148:149], v[154:155]
	v_mul_f32_e32 v163, v66, v66
	v_mul_f32_e32 v187, v67, v67
	v_mov_b32_e32 v153, v177
	v_mov_b32_e32 v165, v179
	v_pk_mov_b32 v[154:155], v[170:171], v[166:167] op_sel:[1,0]
	v_mov_b32_e32 v171, v167
	v_pk_mov_b32 v[166:167], v[174:175], v[172:173] op_sel:[1,0]
	v_mov_b32_e32 v175, v173
	v_pk_fma_f32 v[168:169], v[54:55], v[54:55], v[176:177] op_sel_hi:[1,1,0]
	v_pk_fma_f32 v[172:173], v[56:57], v[56:57], v[178:179] op_sel_hi:[1,1,0]
	v_pk_mul_f32 v[176:177], v[48:49], v[48:49]
	v_pk_mul_f32 v[178:179], v[46:47], v[46:47]
	v_pk_add_f32 v[188:189], v[150:151], v[150:151] op_sel:[0,1] op_sel_hi:[1,0]
	v_pk_add_f32 v[190:191], v[148:149], v[148:149] op_sel:[0,1] op_sel_hi:[1,0]
	v_mul_f32_e32 v185, v52, v52
	v_pk_mul_f32 v[180:181], v[44:45], v[44:45]
	v_pk_mul_f32 v[182:183], v[42:43], v[42:43]
	v_mul_f32_e32 v184, v39, v39
	v_mul_f32_e32 v186, v41, v41
	v_pk_add_f32 v[164:165], v[152:153], v[164:165]
	v_pk_add_f32 v[148:149], v[154:155], v[170:171]
	v_pk_add_f32 v[150:151], v[166:167], v[174:175]
	v_pk_mov_b32 v[152:153], v[178:179], v[176:177] op_sel:[1,0]
	v_mov_b32_e32 v179, v177
	v_mov_b32_e32 v189, v163
	v_mov_b32_e32 v191, v187
	v_mul_f32_e32 v193, v50, v50
	v_mul_f32_e32 v198, v51, v51
	v_mul_f32_e32 v192, v53, v53
	v_mul_f32_e32 v201, v36, v36
	v_mul_f32_e32 v202, v37, v37
	v_pk_mov_b32 v[154:155], v[182:183], v[180:181] op_sel:[1,0]
	v_mov_b32_e32 v183, v181
	v_pk_fma_f32 v[166:167], v[38:39], v[38:39], v[184:185] op_sel_hi:[1,1,0]
	v_pk_fma_f32 v[170:171], v[40:41], v[40:41], v[186:187] op_sel_hi:[1,1,0]
	v_pk_add_f32 v[194:195], v[148:149], v[148:149] op_sel:[0,1] op_sel_hi:[1,0]
	v_pk_add_f32 v[196:197], v[150:151], v[150:151] op_sel:[0,1] op_sel_hi:[1,0]
	v_pk_add_f32 v[152:153], v[152:153], v[178:179]
	v_pk_add_f32 v[178:179], v[188:189], v[190:191]
	v_mov_b32_e32 v169, v185
	v_mov_b32_e32 v173, v192
	v_pk_mul_f32 v[174:175], v[32:33], v[32:33]
	v_pk_mul_f32 v[176:177], v[30:31], v[30:31]
	v_pk_mul_f32 v[180:181], v[28:29], v[28:29]
	v_pk_mul_f32 v[184:185], v[26:27], v[26:27]
	v_pk_add_f32 v[154:155], v[154:155], v[182:183]
	v_mov_b32_e32 v167, v201
	v_mov_b32_e32 v171, v202
	v_mov_b32_e32 v195, v193
	v_mov_b32_e32 v197, v198
	v_pk_add_f32 v[164:165], v[178:179], v[164:165]
	v_mul_f32_e32 v199, v34, v34
	v_mul_f32_e32 v200, v35, v35
	v_pk_add_f32 v[168:169], v[168:169], v[172:173]
	v_pk_mov_b32 v[172:173], v[176:177], v[174:175] op_sel:[1,0]
	v_mov_b32_e32 v177, v175
	v_pk_mov_b32 v[174:175], v[184:185], v[180:181] op_sel:[1,0]
	v_mov_b32_e32 v185, v181
	v_pk_add_f32 v[180:181], v[152:153], v[152:153] op_sel:[0,1] op_sel_hi:[1,0]
	v_pk_add_f32 v[182:183], v[154:155], v[154:155] op_sel:[0,1] op_sel_hi:[1,0]
	v_pk_add_f32 v[166:167], v[166:167], v[170:171]
	v_pk_add_f32 v[170:171], v[194:195], v[196:197]
	v_add_f32_e32 v163, v164, v165
	v_mov_b32_e32 v181, v199
	v_mov_b32_e32 v183, v200
	v_pk_add_f32 v[164:165], v[170:171], v[168:169]
	ds_bpermute_b32 v171, v133, v163
	v_pk_add_f32 v[168:169], v[180:181], v[182:183]
	v_add_f32_e32 v170, v164, v165
	v_pk_add_f32 v[164:165], v[168:169], v[166:167]
	ds_bpermute_b32 v166, v133, v170
	v_add_f32_e32 v164, v164, v165
	ds_bpermute_b32 v165, v133, v164
	s_waitcnt lgkmcnt(2)
	v_add_f32_e32 v163, v163, v171
	ds_bpermute_b32 v167, v156, v163
	s_waitcnt lgkmcnt(2)
	v_add_f32_e32 v166, v170, v166
	ds_bpermute_b32 v168, v156, v166
	s_waitcnt lgkmcnt(2)
	v_add_f32_e32 v164, v164, v165
	ds_bpermute_b32 v165, v156, v164
	s_waitcnt lgkmcnt(2)
	v_add_f32_e32 v163, v163, v167
	ds_bpermute_b32 v167, v157, v163
	s_waitcnt lgkmcnt(2)
	v_add_f32_e32 v166, v166, v168
	ds_bpermute_b32 v168, v157, v166
	s_waitcnt lgkmcnt(2)
	v_add_f32_e32 v164, v164, v165
	ds_bpermute_b32 v165, v157, v164
	s_waitcnt lgkmcnt(2)
	v_add_f32_e32 v163, v163, v167
	ds_bpermute_b32 v167, v158, v163
	s_waitcnt lgkmcnt(2)
	v_add_f32_e32 v166, v166, v168
	ds_bpermute_b32 v168, v158, v166
	s_waitcnt lgkmcnt(2)
	v_add_f32_e32 v164, v164, v165
	ds_bpermute_b32 v165, v158, v164
	s_waitcnt lgkmcnt(2)
	v_add_f32_e32 v163, v163, v167
	ds_bpermute_b32 v167, v159, v163
	s_waitcnt lgkmcnt(2)
	v_add_f32_e32 v166, v166, v168
	ds_bpermute_b32 v168, v159, v166
	s_waitcnt lgkmcnt(2)
	v_add_f32_e32 v164, v164, v165
	ds_bpermute_b32 v165, v159, v164
	s_waitcnt lgkmcnt(2)
	v_add_f32_e32 v163, v163, v167
	ds_bpermute_b32 v167, v160, v163
	s_waitcnt lgkmcnt(2)
	v_add_f32_e32 v166, v166, v168
	ds_bpermute_b32 v168, v160, v166
	s_waitcnt lgkmcnt(2)
	v_add_f32_e32 v164, v164, v165
	ds_bpermute_b32 v165, v160, v164
	s_waitcnt lgkmcnt(2)
	v_add_f32_e32 v163, v163, v167
	v_fmamk_f32 v163, v163, 0x3a800000, v161
	s_waitcnt lgkmcnt(1)
	v_add_f32_e32 v166, v166, v168
	v_mul_f32_e32 v167, 0x4f800000, v163
	v_cmp_gt_f32_e32 vcc, s19, v163
	v_fmamk_f32 v166, v166, 0x3a800000, v161
	s_waitcnt lgkmcnt(0)
	v_add_f32_e32 v164, v164, v165
	v_cndmask_b32_e32 v163, v163, v167, vcc
	v_mul_f32_e32 v165, 0x4f800000, v166
	v_cmp_gt_f32_e64 s[6:7], s19, v166
	v_sqrt_f32_e32 v167, v163
	v_fmamk_f32 v164, v164, 0x3a800000, v161
	v_cndmask_b32_e64 v165, v166, v165, s[6:7]
	v_mul_f32_e32 v166, 0x4f800000, v164
	v_cmp_gt_f32_e64 s[8:9], s19, v164
	v_sqrt_f32_e32 v168, v165
	v_add_u32_e32 v169, -1, v167
	v_cndmask_b32_e64 v164, v164, v166, s[8:9]
	v_sqrt_f32_e32 v166, v164
	v_add_u32_e32 v170, 1, v167
	v_fma_f32 v171, -v169, v167, v163
	v_pk_add_f32 v[152:153], v[172:173], v[176:177]
	v_fma_f32 v172, -v170, v167, v163
	v_add_u32_e32 v173, -1, v168
	v_cmp_ge_f32_e64 s[10:11], 0, v171
	v_pk_add_f32 v[154:155], v[174:175], v[184:185]
	v_add_u32_e32 v174, 1, v168
	v_cndmask_b32_e64 v167, v167, v169, s[10:11]
	v_fma_f32 v169, -v173, v168, v165
	v_cmp_lt_f32_e64 s[10:11], 0, v172
	v_fma_f32 v171, -v174, v168, v165
	v_add_u32_e32 v175, -1, v166
	v_cndmask_b32_e64 v167, v167, v170, s[10:11]
	v_cmp_ge_f32_e64 s[10:11], 0, v169
	v_add_u32_e32 v176, 1, v166
	v_fma_f32 v169, -v175, v166, v164
	v_cndmask_b32_e64 v168, v168, v173, s[10:11]
	v_cmp_lt_f32_e64 s[10:11], 0, v171
	v_fma_f32 v170, -v176, v166, v164
	v_mul_f32_e32 v171, 0x37800000, v167
	v_cndmask_b32_e64 v168, v168, v174, s[10:11]
	v_cmp_ge_f32_e64 s[10:11], 0, v169
	v_cndmask_b32_e32 v167, v167, v171, vcc
	v_cmp_class_f32_e32 vcc, v163, v162
	v_cndmask_b32_e64 v166, v166, v175, s[10:11]
	v_cmp_lt_f32_e64 s[10:11], 0, v170
	v_mul_f32_e32 v169, 0x37800000, v168
	v_cndmask_b32_e32 v163, v167, v163, vcc
	v_cndmask_b32_e64 v166, v166, v176, s[10:11]
	v_cndmask_b32_e64 v167, v168, v169, s[6:7]
	v_cmp_class_f32_e32 vcc, v165, v162
	v_mul_f32_e32 v168, 0x37800000, v166
	v_div_scale_f32 v169, s[6:7], v163, v163, 1.0
	v_cndmask_b32_e32 v165, v167, v165, vcc
	v_cndmask_b32_e64 v166, v166, v168, s[8:9]
	v_cmp_class_f32_e32 vcc, v164, v162
	v_rcp_f32_e32 v167, v169
	v_div_scale_f32 v168, s[8:9], v165, v165, 1.0
	v_cndmask_b32_e32 v166, v166, v164, vcc
	v_rcp_f32_e32 v172, v168
	v_div_scale_f32 v173, s[10:11], v166, v166, 1.0
	v_rcp_f32_e32 v175, v173
	v_fma_f32 v164, -v169, v167, 1.0
	v_div_scale_f32 v170, s[6:7], 1.0, v163, 1.0
	v_fmac_f32_e32 v167, v164, v167
	v_fma_f32 v164, -v168, v172, 1.0
	v_mul_f32_e32 v176, v170, v167
	v_div_scale_f32 v171, s[8:9], 1.0, v165, 1.0
	v_fmac_f32_e32 v172, v164, v172
	v_fma_f32 v164, -v173, v175, 1.0
	v_fma_f32 v177, -v169, v176, v170
	v_div_scale_f32 v174, s[10:11], 1.0, v166, 1.0
	v_mul_f32_e32 v178, v171, v172
	v_fmac_f32_e32 v175, v164, v175
	v_fmac_f32_e32 v176, v177, v167
	v_fma_f32 v164, -v168, v178, v171
	v_mul_f32_e32 v177, v174, v175
	v_fma_f32 v169, -v169, v176, v170
	s_mov_b64 vcc, s[6:7]
	v_fmac_f32_e32 v178, v164, v172
	v_fma_f32 v164, -v173, v177, v174
	v_div_fmas_f32 v167, v169, v167, v176
	v_fma_f32 v168, -v168, v178, v171
	v_fmac_f32_e32 v177, v164, v175
	v_div_fixup_f32 v164, v167, v163, 1.0
	s_mov_b64 vcc, s[8:9]
	v_div_fmas_f32 v163, v168, v172, v178
	v_fma_f32 v167, -v173, v177, v174
	v_pk_mul_f32 v[80:81], v[80:81], v[164:165] op_sel_hi:[1,0]
	v_pk_mul_f32 v[78:79], v[78:79], v[164:165] op_sel_hi:[1,0]
	s_mov_b64 vcc, s[10:11]
	v_pk_add_f32 v[88:89], v[88:89], 1.0 op_sel_hi:[1,0]
	v_pk_add_f32 v[86:87], v[86:87], 1.0 op_sel_hi:[1,0]
	v_pk_mul_f32 v[76:77], v[76:77], v[164:165] op_sel_hi:[1,0]
	v_pk_mul_f32 v[74:75], v[74:75], v[164:165] op_sel_hi:[1,0]
	v_pk_mul_f32 v[72:73], v[72:73], v[164:165] op_sel_hi:[1,0]
	v_pk_mul_f32 v[70:71], v[70:71], v[164:165] op_sel_hi:[1,0]
	v_pk_mul_f32 v[68:69], v[68:69], v[164:165] op_sel_hi:[1,0]
	v_pk_mul_f32 v[66:67], v[66:67], v[164:165] op_sel_hi:[1,0]
	v_div_fixup_f32 v164, v163, v165, 1.0
	v_div_fmas_f32 v163, v167, v175, v177
	v_pk_mul_f32 v[78:79], v[78:79], v[2:3]
	v_pk_mul_f32 v[80:81], v[80:81], v[4:5]
	v_pk_mul_f32 v[64:65], v[64:65], v[164:165] op_sel_hi:[1,0]
	v_pk_mul_f32 v[62:63], v[62:63], v[164:165] op_sel_hi:[1,0]
	v_pk_mul_f32 v[60:61], v[60:61], v[164:165] op_sel_hi:[1,0]
	v_pk_mul_f32 v[58:59], v[58:59], v[164:165] op_sel_hi:[1,0]
	v_pk_mul_f32 v[56:57], v[56:57], v[164:165] op_sel_hi:[1,0]
	v_pk_mul_f32 v[54:55], v[54:55], v[164:165] op_sel_hi:[1,0]
	v_pk_mul_f32 v[52:53], v[52:53], v[164:165] op_sel_hi:[1,0]
	v_pk_mul_f32 v[50:51], v[50:51], v[164:165] op_sel_hi:[1,0]
	v_div_fixup_f32 v164, v163, v166, 1.0
	v_pk_fma_f32 v[80:81], v[80:81], v[88:89], v[84:85]
	v_pk_fma_f32 v[78:79], v[78:79], v[86:87], v[82:83]
	v_pk_mul_f32 v[82:83], v[50:51], v[14:15]
	v_pk_mul_f32 v[84:85], v[52:53], v[16:17]
	v_pk_mul_f32 v[48:49], v[48:49], v[164:165] op_sel_hi:[1,0]
	v_pk_mul_f32 v[46:47], v[46:47], v[164:165] op_sel_hi:[1,0]
	v_pk_mul_f32 v[86:87], v[46:47], v[2:3]
	v_pk_mul_f32 v[88:89], v[48:49], v[4:5]
	v_cvt_pk_bf16_f32 v46, v78, v79
	v_cvt_pk_bf16_f32 v47, v80, v81
	global_store_dwordx2 v[102:103], v[46:47], off
	global_load_dwordx4 v[238:241], v[142:143], off
	s_nop 0
	global_load_dwordx4 v[242:245], v[122:123], off offset:1024
	v_pk_mul_f32 v[74:75], v[74:75], v[6:7]
	v_pk_mul_f32 v[76:77], v[76:77], v[8:9]
	v_pk_mul_f32 v[70:71], v[70:71], v[10:11]
	v_pk_mul_f32 v[72:73], v[72:73], v[12:13]
	v_pk_mul_f32 v[66:67], v[66:67], v[14:15]
	v_pk_mul_f32 v[68:69], v[68:69], v[16:17]
	v_pk_mul_f32 v[62:63], v[62:63], v[2:3]
	v_pk_mul_f32 v[64:65], v[64:65], v[4:5]
	v_pk_mul_f32 v[58:59], v[58:59], v[6:7]
	v_pk_mul_f32 v[60:61], v[60:61], v[8:9]
	v_pk_mul_f32 v[54:55], v[54:55], v[10:11]
	v_pk_mul_f32 v[56:57], v[56:57], v[12:13]
	v_pk_mul_f32 v[44:45], v[44:45], v[164:165] op_sel_hi:[1,0]
	v_pk_mul_f32 v[42:43], v[42:43], v[164:165] op_sel_hi:[1,0]
	v_pk_mul_f32 v[44:45], v[44:45], v[8:9]
	v_pk_mul_f32 v[42:43], v[42:43], v[6:7]
	v_pk_mul_f32 v[40:41], v[40:41], v[164:165] op_sel_hi:[1,0]
	v_pk_mul_f32 v[38:39], v[38:39], v[164:165] op_sel_hi:[1,0]
	v_pk_mul_f32 v[40:41], v[40:41], v[12:13]
	v_pk_mul_f32 v[38:39], v[38:39], v[10:11]
	v_pk_mul_f32 v[36:37], v[36:37], v[164:165] op_sel_hi:[1,0]
	v_pk_mul_f32 v[34:35], v[34:35], v[164:165] op_sel_hi:[1,0]
	v_pk_mul_f32 v[36:37], v[36:37], v[16:17]
	v_pk_mul_f32 v[34:35], v[34:35], v[14:15]
	v_mul_f32_e32 v186, v23, v23
	v_mul_f32_e32 v192, v25, v25
	v_mul_f32_e32 v203, v18, v18
	v_mul_f32_e32 v204, v19, v19
	v_mul_f32_e32 v205, v20, v20
	v_mul_f32_e32 v206, v21, v21
	v_pk_fma_f32 v[148:149], v[22:23], v[22:23], v[186:187] op_sel_hi:[1,1,0]
	v_pk_fma_f32 v[150:151], v[24:25], v[24:25], v[192:193] op_sel_hi:[1,1,0]
	v_mov_b32_e32 v149, v205
	v_mov_b32_e32 v151, v206
	global_load_dwordx4 v[230:233], v[138:139], off
	s_nop 0
	global_load_dwordx4 v[234:237], v[122:123], off offset:2048
	s_waitcnt vmcnt(2) lgkmcnt(0)
	v_pk_add_f32 v[240:241], v[240:241], 1.0 op_sel_hi:[1,0]
	v_pk_add_f32 v[238:239], v[238:239], 1.0 op_sel_hi:[1,0]
	v_pk_fma_f32 v[240:241], v[76:77], v[240:241], v[244:245]
	v_pk_fma_f32 v[238:239], v[74:75], v[238:239], v[242:243]
	v_cvt_pk_bf16_f32 v238, v238, v239
	v_cvt_pk_bf16_f32 v239, v240, v241
	global_store_dwordx2 v[102:103], v[238:239], off offset:512
	global_load_dwordx4 v[238:241], v[128:129], off
	s_nop 0
	global_load_dwordx4 v[242:245], v[122:123], off offset:3072
	s_waitcnt vmcnt(3) lgkmcnt(0)
	v_pk_add_f32 v[232:233], v[232:233], 1.0 op_sel_hi:[1,0]
	v_pk_add_f32 v[230:231], v[230:231], 1.0 op_sel_hi:[1,0]
	v_pk_fma_f32 v[232:233], v[72:73], v[232:233], v[236:237]
	v_pk_fma_f32 v[230:231], v[70:71], v[230:231], v[234:235]
	v_cvt_pk_bf16_f32 v230, v230, v231
	v_cvt_pk_bf16_f32 v231, v232, v233
	global_store_dwordx2 v[102:103], v[230:231], off offset:1024
	global_load_dwordx4 v[230:233], v[124:125], off
	s_nop 0
	global_load_dwordx4 v[234:237], v[110:111], off
	s_waitcnt vmcnt(3) lgkmcnt(0)
	v_pk_add_f32 v[240:241], v[240:241], 1.0 op_sel_hi:[1,0]
	v_pk_add_f32 v[238:239], v[238:239], 1.0 op_sel_hi:[1,0]
	v_pk_fma_f32 v[240:241], v[68:69], v[240:241], v[244:245]
	v_pk_fma_f32 v[238:239], v[66:67], v[238:239], v[242:243]
	v_cvt_pk_bf16_f32 v238, v238, v239
	v_cvt_pk_bf16_f32 v239, v240, v241
	global_store_dwordx2 v[102:103], v[238:239], off offset:1536
	global_load_dwordx4 v[238:241], v[118:119], off
	s_nop 0
	global_load_dwordx4 v[242:245], v[110:111], off offset:1024
	s_waitcnt vmcnt(3) lgkmcnt(0)
	v_pk_add_f32 v[232:233], v[232:233], 1.0 op_sel_hi:[1,0]
	v_pk_add_f32 v[230:231], v[230:231], 1.0 op_sel_hi:[1,0]
	v_pk_fma_f32 v[232:233], v[64:65], v[232:233], v[236:237]
	v_pk_fma_f32 v[230:231], v[62:63], v[230:231], v[234:235]
	v_cvt_pk_bf16_f32 v230, v230, v231
	v_cvt_pk_bf16_f32 v231, v232, v233
	global_store_dwordx2 v[102:103], v[230:231], off offset:2048
	global_load_dwordx4 v[230:233], v[114:115], off
	s_nop 0
	global_load_dwordx4 v[234:237], v[110:111], off offset:2048
	s_waitcnt vmcnt(3) lgkmcnt(0)
	v_pk_add_f32 v[240:241], v[240:241], 1.0 op_sel_hi:[1,0]
	v_pk_add_f32 v[238:239], v[238:239], 1.0 op_sel_hi:[1,0]
	v_pk_fma_f32 v[240:241], v[60:61], v[240:241], v[244:245]
	v_pk_fma_f32 v[238:239], v[58:59], v[238:239], v[242:243]
	v_cvt_pk_bf16_f32 v238, v238, v239
	v_cvt_pk_bf16_f32 v239, v240, v241
	global_store_dwordx2 v[102:103], v[238:239], off offset:2560
	v_pk_add_f32 v[58:59], v[148:149], v[150:151]
	global_load_dwordx4 v[238:241], v[112:113], off
	s_nop 0
	global_load_dwordx4 v[242:245], v[110:111], off offset:3072
	s_waitcnt vmcnt(3) lgkmcnt(0)
	v_pk_add_f32 v[232:233], v[232:233], 1.0 op_sel_hi:[1,0]
	v_pk_add_f32 v[230:231], v[230:231], 1.0 op_sel_hi:[1,0]
	v_pk_fma_f32 v[232:233], v[56:57], v[232:233], v[236:237]
	v_pk_fma_f32 v[230:231], v[54:55], v[230:231], v[234:235]
	v_cvt_pk_bf16_f32 v230, v230, v231
	v_cvt_pk_bf16_f32 v231, v232, v233
	global_store_dwordx2 v[102:103], v[230:231], off offset:3072
	v_pk_add_f32 v[54:55], v[152:153], v[152:153] op_sel:[0,1] op_sel_hi:[1,0]
	v_pk_add_f32 v[56:57], v[154:155], v[154:155] op_sel:[0,1] op_sel_hi:[1,0]
	v_mov_b32_e32 v55, v203
	v_mov_b32_e32 v57, v204
	global_load_dwordx4 v[230:233], v[146:147], off
	s_nop 0
	global_load_dwordx4 v[234:237], v[108:109], off
	s_waitcnt vmcnt(3) lgkmcnt(0)
	v_pk_add_f32 v[240:241], v[240:241], 1.0 op_sel_hi:[1,0]
	v_pk_add_f32 v[238:239], v[238:239], 1.0 op_sel_hi:[1,0]
	v_pk_fma_f32 v[240:241], v[84:85], v[240:241], v[244:245]
	v_pk_fma_f32 v[238:239], v[82:83], v[238:239], v[242:243]
	v_cvt_pk_bf16_f32 v238, v238, v239
	v_cvt_pk_bf16_f32 v239, v240, v241
	global_store_dwordx2 v[102:103], v[238:239], off offset:3584
	global_load_dwordx4 v[238:241], v[144:145], off
	s_nop 0
	global_load_dwordx4 v[242:245], v[108:109], off offset:1024
	s_waitcnt vmcnt(3) lgkmcnt(0)
	v_pk_add_f32 v[232:233], v[232:233], 1.0 op_sel_hi:[1,0]
	v_pk_add_f32 v[230:231], v[230:231], 1.0 op_sel_hi:[1,0]
	v_pk_fma_f32 v[232:233], v[88:89], v[232:233], v[236:237]
	v_pk_fma_f32 v[230:231], v[86:87], v[230:231], v[234:235]
	v_cvt_pk_bf16_f32 v230, v230, v231
	v_cvt_pk_bf16_f32 v231, v232, v233
	global_store_dwordx2 v[104:105], v[230:231], off
	global_load_dwordx4 v[230:233], v[140:141], off
	s_nop 0
	global_load_dwordx4 v[234:237], v[108:109], off offset:2048
	s_waitcnt vmcnt(3) lgkmcnt(0)
	v_pk_add_f32 v[240:241], v[240:241], 1.0 op_sel_hi:[1,0]
	v_pk_add_f32 v[238:239], v[238:239], 1.0 op_sel_hi:[1,0]
	v_pk_fma_f32 v[44:45], v[44:45], v[240:241], v[244:245]
	v_pk_fma_f32 v[42:43], v[42:43], v[238:239], v[242:243]
	v_cvt_pk_bf16_f32 v42, v42, v43
	v_cvt_pk_bf16_f32 v43, v44, v45
	global_store_dwordx2 v[104:105], v[42:43], off offset:512
	v_pk_add_f32 v[50:51], v[54:55], v[56:57]
	global_load_dwordx4 v[238:241], v[126:127], off
	s_nop 0
	global_load_dwordx4 v[242:245], v[108:109], off offset:3072
	s_waitcnt vmcnt(3) lgkmcnt(0)
	v_pk_add_f32 v[232:233], v[232:233], 1.0 op_sel_hi:[1,0]
	v_pk_add_f32 v[230:231], v[230:231], 1.0 op_sel_hi:[1,0]
	v_pk_fma_f32 v[40:41], v[40:41], v[232:233], v[236:237]
	v_pk_fma_f32 v[38:39], v[38:39], v[230:231], v[234:235]
	v_cvt_pk_bf16_f32 v38, v38, v39
	v_cvt_pk_bf16_f32 v39, v40, v41
	global_store_dwordx2 v[104:105], v[38:39], off offset:1024
	v_pk_add_f32 v[50:51], v[50:51], v[58:59]
	s_waitcnt vmcnt(1) lgkmcnt(0)
	v_pk_add_f32 v[240:241], v[240:241], 1.0 op_sel_hi:[1,0]
	v_pk_add_f32 v[238:239], v[238:239], 1.0 op_sel_hi:[1,0]
	v_pk_fma_f32 v[36:37], v[36:37], v[240:241], v[244:245]
	v_pk_fma_f32 v[34:35], v[34:35], v[238:239], v[242:243]
	v_cvt_pk_bf16_f32 v34, v34, v35
	v_cvt_pk_bf16_f32 v35, v36, v37
	global_store_dwordx2 v[104:105], v[34:35], off offset:1536
	global_load_dwordx4 v[34:37], v[120:121], off
	s_nop 0
	global_load_dwordx4 v[38:41], v[106:107], off
	v_add_f32_e32 v50, v50, v51
	ds_bpermute_b32 v51, v133, v50
	s_waitcnt lgkmcnt(0)
	v_add_f32_e32 v50, v50, v51
	ds_bpermute_b32 v51, v156, v50
	s_waitcnt lgkmcnt(0)
	v_add_f32_e32 v50, v50, v51
	ds_bpermute_b32 v46, v157, v50
	s_waitcnt lgkmcnt(0)
	v_add_f32_e32 v46, v50, v46
	ds_bpermute_b32 v47, v158, v46
	s_waitcnt lgkmcnt(0)
	v_add_f32_e32 v46, v46, v47
	ds_bpermute_b32 v47, v159, v46
	s_waitcnt lgkmcnt(0)
	v_add_f32_e32 v46, v46, v47
	ds_bpermute_b32 v47, v160, v46
	s_waitcnt lgkmcnt(0)
	v_add_f32_e32 v46, v46, v47
	v_fmamk_f32 v46, v46, 0x3a800000, v161
	v_mul_f32_e32 v47, 0x4f800000, v46
	v_cmp_gt_f32_e32 vcc, s19, v46
	s_waitcnt vmcnt(0)
	v_pk_add_f32 v[36:37], v[36:37], 1.0 op_sel_hi:[1,0]
	v_cndmask_b32_e32 v42, v46, v47, vcc
	v_sqrt_f32_e32 v43, v42
	v_pk_add_f32 v[34:35], v[34:35], 1.0 op_sel_hi:[1,0]
	v_add_u32_e32 v44, -1, v43
	v_add_u32_e32 v45, 1, v43
	v_fma_f32 v46, -v44, v43, v42
	v_fma_f32 v47, -v45, v43, v42
	v_cmp_ge_f32_e64 s[6:7], 0, v46
	s_nop 1
	v_cndmask_b32_e64 v43, v43, v44, s[6:7]
	v_cmp_lt_f32_e64 s[6:7], 0, v47
	s_nop 1
	v_cndmask_b32_e64 v43, v43, v45, s[6:7]
	v_mul_f32_e32 v44, 0x37800000, v43
	v_cndmask_b32_e32 v43, v43, v44, vcc
	v_cmp_class_f32_e32 vcc, v42, v162
	s_nop 1
	v_cndmask_b32_e32 v42, v43, v42, vcc
	v_div_scale_f32 v43, s[6:7], v42, v42, 1.0
	v_rcp_f32_e32 v45, v43
	v_div_scale_f32 v44, vcc, 1.0, v42, 1.0
	v_fma_f32 v46, -v43, v45, 1.0
	v_fmac_f32_e32 v45, v46, v45
	v_mul_f32_e32 v46, v44, v45
	v_fma_f32 v47, -v43, v46, v44
	v_fmac_f32_e32 v46, v47, v45
	v_fma_f32 v43, -v43, v46, v44
	v_div_fmas_f32 v43, v43, v45, v46
	v_div_fixup_f32 v42, v43, v42, 1.0
	v_pk_mul_f32 v[32:33], v[32:33], v[42:43] op_sel_hi:[1,0]
	v_pk_mul_f32 v[30:31], v[30:31], v[42:43] op_sel_hi:[1,0]
	v_pk_mul_f32 v[32:33], v[32:33], v[4:5]
	v_pk_mul_f32 v[30:31], v[30:31], v[2:3]
	v_pk_fma_f32 v[32:33], v[32:33], v[36:37], v[40:41]
	v_pk_fma_f32 v[30:31], v[30:31], v[34:35], v[38:39]
	v_cvt_pk_bf16_f32 v30, v30, v31
	v_cvt_pk_bf16_f32 v31, v32, v33
	global_store_dwordx2 v[104:105], v[30:31], off offset:2048
	global_load_dwordx4 v[30:33], v[116:117], off
	s_nop 0
	global_load_dwordx4 v[34:37], v[106:107], off offset:1024
	v_pk_mul_f32 v[28:29], v[28:29], v[42:43] op_sel_hi:[1,0]
	v_pk_mul_f32 v[26:27], v[26:27], v[42:43] op_sel_hi:[1,0]
	v_pk_mul_f32 v[28:29], v[28:29], v[8:9]
	v_pk_mul_f32 v[26:27], v[26:27], v[6:7]
	v_lshl_add_u64 v[38:39], s[24:25], 0, v[98:99]
	v_pk_mul_f32 v[24:25], v[24:25], v[42:43] op_sel_hi:[1,0]
	v_pk_mul_f32 v[22:23], v[22:23], v[42:43] op_sel_hi:[1,0]
	v_pk_mul_f32 v[24:25], v[24:25], v[12:13]
	v_pk_mul_f32 v[22:23], v[22:23], v[10:11]
	v_pk_mul_f32 v[20:21], v[20:21], v[42:43] op_sel_hi:[1,0]
	v_pk_mul_f32 v[18:19], v[18:19], v[42:43] op_sel_hi:[1,0]
	v_pk_mul_f32 v[20:21], v[20:21], v[16:17]
	v_pk_mul_f32 v[18:19], v[18:19], v[14:15]
	s_waitcnt vmcnt(0) lgkmcnt(0)
	v_pk_add_f32 v[32:33], v[32:33], 1.0 op_sel_hi:[1,0]
	v_pk_add_f32 v[30:31], v[30:31], 1.0 op_sel_hi:[1,0]
	v_pk_fma_f32 v[28:29], v[28:29], v[32:33], v[36:37]
	v_pk_fma_f32 v[26:27], v[26:27], v[30:31], v[34:35]
	v_cvt_pk_bf16_f32 v26, v26, v27
	v_cvt_pk_bf16_f32 v27, v28, v29
	global_store_dwordx2 v[104:105], v[26:27], off offset:2560
	global_load_dwordx4 v[26:29], v[38:39], off
	s_nop 0
	global_load_dwordx4 v[30:33], v[106:107], off offset:2048
	v_lshl_add_u64 v[34:35], s[24:25], 0, v[100:101]
	s_waitcnt vmcnt(0) lgkmcnt(0)
	v_pk_add_f32 v[28:29], v[28:29], 1.0 op_sel_hi:[1,0]
	v_pk_add_f32 v[26:27], v[26:27], 1.0 op_sel_hi:[1,0]
	v_pk_fma_f32 v[24:25], v[24:25], v[28:29], v[32:33]
	v_pk_fma_f32 v[22:23], v[22:23], v[26:27], v[30:31]
	v_cvt_pk_bf16_f32 v22, v22, v23
	v_cvt_pk_bf16_f32 v23, v24, v25
	global_store_dwordx2 v[104:105], v[22:23], off offset:3072
	global_load_dwordx4 v[22:25], v[34:35], off
	s_nop 0
	global_load_dwordx4 v[26:29], v[106:107], off offset:3072
	s_waitcnt vmcnt(0) lgkmcnt(0)
	v_pk_add_f32 v[24:25], v[24:25], 1.0 op_sel_hi:[1,0]
	v_pk_add_f32 v[22:23], v[22:23], 1.0 op_sel_hi:[1,0]
	v_pk_fma_f32 v[20:21], v[20:21], v[24:25], v[28:29]
	v_pk_fma_f32 v[18:19], v[18:19], v[22:23], v[26:27]
	v_cvt_pk_bf16_f32 v18, v18, v19
	v_cvt_pk_bf16_f32 v19, v20, v21
	global_store_dwordx2 v[104:105], v[18:19], off offset:3584
	s_cbranch_scc1 .LBB0_842

.LBB0_1004:
	v_lshl_add_u64 v[18:19], s[38:39], 0, v[94:95]
	v_lshl_add_u64 v[22:23], s[38:39], 0, v[92:93]
	v_add_co_u32_e32 v20, vcc, 0x7800000, v18
	v_add_co_u32_e64 v102, s[6:7], s24, v22
	s_nop 0
	v_addc_co_u32_e32 v21, vcc, 0, v19, vcc
	v_addc_co_u32_e64 v103, s[6:7], 0, v23, s[6:7]
	v_add_co_u32_e64 v104, s[6:7], s25, v22
	v_add_co_u32_e32 v22, vcc, 0x7801000, v18
	s_nop 0
	v_addc_co_u32_e64 v105, s[6:7], 0, v23, s[6:7]
	global_load_dwordx4 v[78:81], v[20:21], off
	global_load_dwordx4 v[74:77], v[20:21], off offset:1024
	global_load_dwordx4 v[70:73], v[20:21], off offset:2048
	global_load_dwordx4 v[66:69], v[20:21], off offset:3072
	v_addc_co_u32_e32 v23, vcc, 0, v19, vcc
	v_add_co_u32_e32 v20, vcc, 0x7802000, v18
	global_load_dwordx4 v[62:65], v[22:23], off
	global_load_dwordx4 v[58:61], v[22:23], off offset:1024
	global_load_dwordx4 v[54:57], v[22:23], off offset:2048
	global_load_dwordx4 v[50:53], v[22:23], off offset:3072
	v_addc_co_u32_e32 v21, vcc, 0, v19, vcc
	global_load_dwordx4 v[46:49], v[20:21], off
	global_load_dwordx4 v[42:45], v[20:21], off offset:1024
	global_load_dwordx4 v[38:41], v[20:21], off offset:2048
	global_load_dwordx4 v[34:37], v[20:21], off offset:3072
	v_add_co_u32_e32 v82, vcc, 0x7803000, v18
	s_add_i32 s26, s8, 32
	s_nop 0
	v_addc_co_u32_e32 v83, vcc, 0, v19, vcc
	global_load_dwordx4 v[30:33], v[82:83], off
	global_load_dwordx4 v[26:29], v[82:83], off offset:1024
	global_load_dwordx4 v[22:25], v[82:83], off offset:2048
	global_load_dwordx4 v[18:21], v[82:83], off offset:3072
	s_add_i32 s10, s8, 0xffffc022
	s_ashr_i32 s9, s26, 13
	s_cmpk_lt_i32 s26, 0x4000
	s_cselect_b32 s6, s9, s10
	s_mul_hi_i32 s7, s6, 0x9000
	s_mul_i32 s6, s6, 0x9000
	s_add_u32 s6, s2, s6
	s_addc_u32 s7, s13, s7
	s_add_u32 s10, s6, 0x1000
	s_addc_u32 s11, s7, 0
	v_lshl_add_u64 v[124:125], s[6:7], 0, v[90:91]
	v_lshl_add_u64 v[86:87], s[10:11], 0, v[90:91]
	global_load_dwordx4 v[82:85], v[124:125], off
	s_add_i32 s6, s8, 0xffffc023
	global_load_dwordx4 v[86:89], v[86:87], off
	s_cmpk_lt_i32 s26, 0x3fff
	s_cselect_b32 s6, s9, s6
	s_mul_hi_i32 s7, s6, 0x9000
	s_mul_i32 s6, s6, 0x9000
	s_add_u32 s6, s2, s6
	s_addc_u32 s7, s13, s7
	v_lshl_add_u64 v[138:139], s[10:11], 0, v[96:97]
	v_lshl_add_u64 v[134:135], s[10:11], 0, v[98:99]
	v_lshl_add_u64 v[128:129], s[10:11], 0, v[100:101]
	s_add_u32 s10, s6, 0x1000
	v_lshl_add_u64 v[110:111], s[6:7], 0, v[90:91]
	s_addc_u32 s11, s7, 0
	s_add_i32 s6, s8, 0xffffc024
	s_cmpk_lt_i32 s26, 0x3ffe
	s_cselect_b32 s6, s9, s6
	s_mul_hi_i32 s7, s6, 0x9000
	s_mul_i32 s6, s6, 0x9000
	v_lshl_add_u64 v[126:127], s[10:11], 0, v[90:91]
	v_lshl_add_u64 v[120:121], s[10:11], 0, v[96:97]
	v_lshl_add_u64 v[116:117], s[10:11], 0, v[98:99]
	v_lshl_add_u64 v[112:113], s[10:11], 0, v[100:101]
	s_add_u32 s10, s2, s6
	s_addc_u32 s11, s13, s7
	s_add_u32 s6, s10, 0x1000
	s_addc_u32 s7, s11, 0
	s_addk_i32 s8, 0xc025
	s_cmpk_lt_i32 s26, 0x3ffd
	v_lshl_add_u64 v[142:143], s[6:7], 0, v[90:91]
	v_lshl_add_u64 v[140:141], s[6:7], 0, v[96:97]
	v_lshl_add_u64 v[136:137], s[6:7], 0, v[98:99]
	v_lshl_add_u64 v[122:123], s[6:7], 0, v[100:101]
	s_cselect_b32 s6, s9, s8
	s_mul_hi_i32 s7, s6, 0x9000
	s_mul_i32 s6, s6, 0x9000
	s_add_u32 s6, s2, s6
	s_addc_u32 s7, s13, s7
	s_add_u32 s20, s6, 0x1000
	v_lshl_add_u64 v[106:107], s[6:7], 0, v[90:91]
	s_addc_u32 s21, s7, 0
	v_lshl_add_u64 v[108:109], s[10:11], 0, v[90:91]
	v_lshl_add_u64 v[118:119], s[20:21], 0, v[90:91]
	v_lshl_add_u64 v[114:115], s[20:21], 0, v[96:97]
	v_lshl_add_u64 v[92:93], v[92:93], 0, s[16:17]
	v_lshl_add_u64 v[94:95], v[94:95], 0, s[18:19]
	s_cmp_lt_i32 s26, s22
	s_waitcnt vmcnt(0) lgkmcnt(0)
	v_pk_mul_f32 v[144:145], v[80:81], v[80:81]
	v_pk_mul_f32 v[146:147], v[78:79], v[78:79]
	v_pk_mul_f32 v[148:149], v[76:77], v[76:77]
	v_pk_mul_f32 v[150:151], v[74:75], v[74:75]
	v_mul_f32_e32 v158, v71, v71
	v_mul_f32_e32 v160, v73, v73
	v_pk_mov_b32 v[162:163], v[146:147], v[144:145] op_sel:[1,0]
	v_mov_b32_e32 v147, v145
	v_pk_mov_b32 v[144:145], v[150:151], v[148:149] op_sel:[1,0]
	v_mov_b32_e32 v151, v149
	v_mul_f32_e32 v171, v68, v68
	v_mul_f32_e32 v173, v69, v69
	v_pk_fma_f32 v[148:149], v[70:71], v[70:71], v[158:159] op_sel_hi:[1,1,0]
	v_pk_fma_f32 v[158:159], v[72:73], v[72:73], v[160:161] op_sel_hi:[1,1,0]
	v_pk_mul_f32 v[160:161], v[64:65], v[64:65]
	v_pk_mul_f32 v[164:165], v[62:63], v[62:63]
	v_pk_mul_f32 v[166:167], v[60:61], v[60:61]
	v_pk_mul_f32 v[168:169], v[58:59], v[58:59]
	v_mul_f32_e32 v170, v55, v55
	v_mul_f32_e32 v172, v57, v57
	v_pk_add_f32 v[146:147], v[162:163], v[146:147]
	v_pk_add_f32 v[144:145], v[144:145], v[150:151]
	v_mul_f32_e32 v157, v66, v66
	v_mul_f32_e32 v181, v67, v67
	v_mov_b32_e32 v149, v171
	v_mov_b32_e32 v159, v173
	v_pk_mov_b32 v[150:151], v[164:165], v[160:161] op_sel:[1,0]
	v_mov_b32_e32 v165, v161
	v_pk_mov_b32 v[160:161], v[168:169], v[166:167] op_sel:[1,0]
	v_mov_b32_e32 v169, v167
	v_pk_fma_f32 v[162:163], v[54:55], v[54:55], v[170:171] op_sel_hi:[1,1,0]
	v_pk_fma_f32 v[166:167], v[56:57], v[56:57], v[172:173] op_sel_hi:[1,1,0]
	v_pk_mul_f32 v[170:171], v[48:49], v[48:49]
	v_pk_mul_f32 v[172:173], v[46:47], v[46:47]
	v_pk_add_f32 v[182:183], v[146:147], v[146:147] op_sel:[0,1] op_sel_hi:[1,0]
	v_pk_add_f32 v[184:185], v[144:145], v[144:145] op_sel:[0,1] op_sel_hi:[1,0]
	v_mul_f32_e32 v179, v52, v52
	v_pk_mul_f32 v[174:175], v[44:45], v[44:45]
	v_pk_mul_f32 v[176:177], v[42:43], v[42:43]
	v_mul_f32_e32 v178, v39, v39
	v_mul_f32_e32 v180, v41, v41
	v_pk_add_f32 v[158:159], v[148:149], v[158:159]
	v_pk_add_f32 v[144:145], v[150:151], v[164:165]
	v_pk_add_f32 v[146:147], v[160:161], v[168:169]
	v_pk_mov_b32 v[148:149], v[172:173], v[170:171] op_sel:[1,0]
	v_mov_b32_e32 v173, v171
	v_mov_b32_e32 v183, v157
	v_mov_b32_e32 v185, v181
	v_mul_f32_e32 v187, v50, v50
	v_mul_f32_e32 v192, v51, v51
	v_mul_f32_e32 v186, v53, v53
	v_mul_f32_e32 v195, v36, v36
	v_mul_f32_e32 v196, v37, v37
	v_pk_mov_b32 v[150:151], v[176:177], v[174:175] op_sel:[1,0]
	v_mov_b32_e32 v177, v175
	v_pk_fma_f32 v[160:161], v[38:39], v[38:39], v[178:179] op_sel_hi:[1,1,0]
	v_pk_fma_f32 v[164:165], v[40:41], v[40:41], v[180:181] op_sel_hi:[1,1,0]
	v_pk_add_f32 v[188:189], v[144:145], v[144:145] op_sel:[0,1] op_sel_hi:[1,0]
	v_pk_add_f32 v[190:191], v[146:147], v[146:147] op_sel:[0,1] op_sel_hi:[1,0]
	v_pk_add_f32 v[148:149], v[148:149], v[172:173]
	v_pk_add_f32 v[172:173], v[182:183], v[184:185]
	v_mov_b32_e32 v163, v179
	v_mov_b32_e32 v167, v186
	v_pk_mul_f32 v[168:169], v[32:33], v[32:33]
	v_pk_mul_f32 v[170:171], v[30:31], v[30:31]
	v_pk_mul_f32 v[174:175], v[28:29], v[28:29]
	v_pk_mul_f32 v[178:179], v[26:27], v[26:27]
	v_pk_add_f32 v[150:151], v[150:151], v[176:177]
	v_mov_b32_e32 v161, v195
	v_mov_b32_e32 v165, v196
	v_mov_b32_e32 v189, v187
	v_mov_b32_e32 v191, v192
	v_pk_add_f32 v[158:159], v[172:173], v[158:159]
	v_mul_f32_e32 v193, v34, v34
	v_mul_f32_e32 v194, v35, v35
	v_pk_add_f32 v[162:163], v[162:163], v[166:167]
	v_pk_mov_b32 v[166:167], v[170:171], v[168:169] op_sel:[1,0]
	v_mov_b32_e32 v171, v169
	v_pk_mov_b32 v[168:169], v[178:179], v[174:175] op_sel:[1,0]
	v_mov_b32_e32 v179, v175
	v_pk_add_f32 v[174:175], v[148:149], v[148:149] op_sel:[0,1] op_sel_hi:[1,0]
	v_pk_add_f32 v[176:177], v[150:151], v[150:151] op_sel:[0,1] op_sel_hi:[1,0]
	v_pk_add_f32 v[160:161], v[160:161], v[164:165]
	v_pk_add_f32 v[164:165], v[188:189], v[190:191]
	v_add_f32_e32 v157, v158, v159
	v_mov_b32_e32 v175, v193
	v_mov_b32_e32 v177, v194
	v_pk_add_f32 v[158:159], v[164:165], v[162:163]
	ds_bpermute_b32 v165, v1, v157
	v_pk_add_f32 v[162:163], v[174:175], v[176:177]
	v_add_f32_e32 v164, v158, v159
	v_pk_add_f32 v[158:159], v[162:163], v[160:161]
	ds_bpermute_b32 v160, v1, v164
	v_add_f32_e32 v158, v158, v159
	ds_bpermute_b32 v159, v1, v158
	s_waitcnt lgkmcnt(2)
	v_add_f32_e32 v157, v157, v165
	ds_bpermute_b32 v161, v131, v157
	s_waitcnt lgkmcnt(2)
	v_add_f32_e32 v160, v164, v160
	ds_bpermute_b32 v162, v131, v160
	s_waitcnt lgkmcnt(2)
	v_add_f32_e32 v158, v158, v159
	ds_bpermute_b32 v159, v131, v158
	s_waitcnt lgkmcnt(2)
	v_add_f32_e32 v157, v157, v161
	ds_bpermute_b32 v161, v133, v157
	s_waitcnt lgkmcnt(2)
	v_add_f32_e32 v160, v160, v162
	ds_bpermute_b32 v162, v133, v160
	s_waitcnt lgkmcnt(2)
	v_add_f32_e32 v158, v158, v159
	ds_bpermute_b32 v159, v133, v158
	s_waitcnt lgkmcnt(2)
	v_add_f32_e32 v157, v157, v161
	ds_bpermute_b32 v161, v152, v157
	s_waitcnt lgkmcnt(2)
	v_add_f32_e32 v160, v160, v162
	ds_bpermute_b32 v162, v152, v160
	s_waitcnt lgkmcnt(2)
	v_add_f32_e32 v158, v158, v159
	ds_bpermute_b32 v159, v152, v158
	s_waitcnt lgkmcnt(2)
	v_add_f32_e32 v157, v157, v161
	ds_bpermute_b32 v161, v153, v157
	s_waitcnt lgkmcnt(2)
	v_add_f32_e32 v160, v160, v162
	ds_bpermute_b32 v162, v153, v160
	s_waitcnt lgkmcnt(2)
	v_add_f32_e32 v158, v158, v159
	ds_bpermute_b32 v159, v153, v158
	s_waitcnt lgkmcnt(2)
	v_add_f32_e32 v157, v157, v161
	ds_bpermute_b32 v161, v154, v157
	s_waitcnt lgkmcnt(2)
	v_add_f32_e32 v160, v160, v162
	ds_bpermute_b32 v162, v154, v160
	s_waitcnt lgkmcnt(2)
	v_add_f32_e32 v158, v158, v159
	ds_bpermute_b32 v159, v154, v158
	s_waitcnt lgkmcnt(2)
	v_add_f32_e32 v157, v157, v161
	v_fmamk_f32 v157, v157, 0x3a800000, v155
	s_waitcnt lgkmcnt(1)
	v_add_f32_e32 v160, v160, v162
	v_mul_f32_e32 v161, 0x4f800000, v157
	v_cmp_gt_f32_e32 vcc, s4, v157
	v_fmamk_f32 v160, v160, 0x3a800000, v155
	s_waitcnt lgkmcnt(0)
	v_add_f32_e32 v158, v158, v159
	v_cndmask_b32_e32 v157, v157, v161, vcc
	v_mul_f32_e32 v159, 0x4f800000, v160
	v_cmp_gt_f32_e64 s[6:7], s4, v160
	v_sqrt_f32_e32 v161, v157
	v_fmamk_f32 v158, v158, 0x3a800000, v155
	v_cndmask_b32_e64 v159, v160, v159, s[6:7]
	v_mul_f32_e32 v160, 0x4f800000, v158
	v_cmp_gt_f32_e64 s[8:9], s4, v158
	v_sqrt_f32_e32 v162, v159
	v_add_u32_e32 v163, -1, v161
	v_cndmask_b32_e64 v158, v158, v160, s[8:9]
	v_sqrt_f32_e32 v160, v158
	v_add_u32_e32 v164, 1, v161
	v_fma_f32 v165, -v163, v161, v157
	v_pk_add_f32 v[148:149], v[166:167], v[170:171]
	v_fma_f32 v166, -v164, v161, v157
	v_add_u32_e32 v167, -1, v162
	v_cmp_ge_f32_e64 s[10:11], 0, v165
	v_pk_add_f32 v[150:151], v[168:169], v[178:179]
	v_add_u32_e32 v168, 1, v162
	v_cndmask_b32_e64 v161, v161, v163, s[10:11]
	v_fma_f32 v163, -v167, v162, v159
	v_cmp_lt_f32_e64 s[10:11], 0, v166
	v_fma_f32 v165, -v168, v162, v159
	v_add_u32_e32 v169, -1, v160
	v_cndmask_b32_e64 v161, v161, v164, s[10:11]
	v_cmp_ge_f32_e64 s[10:11], 0, v163
	v_add_u32_e32 v170, 1, v160
	v_fma_f32 v163, -v169, v160, v158
	v_cndmask_b32_e64 v162, v162, v167, s[10:11]
	v_cmp_lt_f32_e64 s[10:11], 0, v165
	v_fma_f32 v164, -v170, v160, v158
	v_mul_f32_e32 v165, 0x37800000, v161
	v_cndmask_b32_e64 v162, v162, v168, s[10:11]
	v_cmp_ge_f32_e64 s[10:11], 0, v163
	v_cndmask_b32_e32 v161, v161, v165, vcc
	v_cmp_class_f32_e32 vcc, v157, v156
	v_cndmask_b32_e64 v160, v160, v169, s[10:11]
	v_cmp_lt_f32_e64 s[10:11], 0, v164
	v_mul_f32_e32 v163, 0x37800000, v162
	v_cndmask_b32_e32 v157, v161, v157, vcc
	v_cndmask_b32_e64 v160, v160, v170, s[10:11]
	v_cndmask_b32_e64 v161, v162, v163, s[6:7]
	v_cmp_class_f32_e32 vcc, v159, v156
	v_mul_f32_e32 v162, 0x37800000, v160
	v_div_scale_f32 v163, s[6:7], v157, v157, 1.0
	v_cndmask_b32_e32 v159, v161, v159, vcc
	v_cndmask_b32_e64 v160, v160, v162, s[8:9]
	v_cmp_class_f32_e32 vcc, v158, v156
	v_rcp_f32_e32 v161, v163
	v_div_scale_f32 v162, s[8:9], v159, v159, 1.0
	v_cndmask_b32_e32 v160, v160, v158, vcc
	v_rcp_f32_e32 v166, v162
	v_div_scale_f32 v167, s[10:11], v160, v160, 1.0
	v_rcp_f32_e32 v169, v167
	v_fma_f32 v158, -v163, v161, 1.0
	v_div_scale_f32 v164, s[6:7], 1.0, v157, 1.0
	v_fmac_f32_e32 v161, v158, v161
	v_fma_f32 v158, -v162, v166, 1.0
	v_mul_f32_e32 v170, v164, v161
	v_div_scale_f32 v165, s[8:9], 1.0, v159, 1.0
	v_fmac_f32_e32 v166, v158, v166
	v_fma_f32 v158, -v167, v169, 1.0
	v_fma_f32 v171, -v163, v170, v164
	v_div_scale_f32 v168, s[10:11], 1.0, v160, 1.0
	v_mul_f32_e32 v172, v165, v166
	v_fmac_f32_e32 v169, v158, v169
	v_fmac_f32_e32 v170, v171, v161
	v_fma_f32 v158, -v162, v172, v165
	v_mul_f32_e32 v171, v168, v169
	v_fma_f32 v163, -v163, v170, v164
	s_mov_b64 vcc, s[6:7]
	v_fmac_f32_e32 v172, v158, v166
	v_fma_f32 v158, -v167, v171, v168
	v_div_fmas_f32 v161, v163, v161, v170
	v_fma_f32 v162, -v162, v172, v165
	v_fmac_f32_e32 v171, v158, v169
	v_div_fixup_f32 v158, v161, v157, 1.0
	s_mov_b64 vcc, s[8:9]
	v_div_fmas_f32 v157, v162, v166, v172
	v_fma_f32 v161, -v167, v171, v168
	v_pk_mul_f32 v[80:81], v[80:81], v[158:159] op_sel_hi:[1,0]
	v_pk_mul_f32 v[78:79], v[78:79], v[158:159] op_sel_hi:[1,0]
	s_mov_b64 vcc, s[10:11]
	v_pk_add_f32 v[88:89], v[88:89], 1.0 op_sel_hi:[1,0]
	v_pk_add_f32 v[86:87], v[86:87], 1.0 op_sel_hi:[1,0]
	v_pk_mul_f32 v[76:77], v[76:77], v[158:159] op_sel_hi:[1,0]
	v_pk_mul_f32 v[74:75], v[74:75], v[158:159] op_sel_hi:[1,0]
	v_pk_mul_f32 v[72:73], v[72:73], v[158:159] op_sel_hi:[1,0]
	v_pk_mul_f32 v[70:71], v[70:71], v[158:159] op_sel_hi:[1,0]
	v_pk_mul_f32 v[68:69], v[68:69], v[158:159] op_sel_hi:[1,0]
	v_pk_mul_f32 v[66:67], v[66:67], v[158:159] op_sel_hi:[1,0]
	v_div_fixup_f32 v158, v157, v159, 1.0
	v_div_fmas_f32 v157, v161, v169, v171
	v_pk_mul_f32 v[78:79], v[78:79], v[2:3]
	v_pk_mul_f32 v[80:81], v[80:81], v[4:5]
	v_pk_mul_f32 v[64:65], v[64:65], v[158:159] op_sel_hi:[1,0]
	v_pk_mul_f32 v[62:63], v[62:63], v[158:159] op_sel_hi:[1,0]
	v_pk_mul_f32 v[60:61], v[60:61], v[158:159] op_sel_hi:[1,0]
	v_pk_mul_f32 v[58:59], v[58:59], v[158:159] op_sel_hi:[1,0]
	v_pk_mul_f32 v[56:57], v[56:57], v[158:159] op_sel_hi:[1,0]
	v_pk_mul_f32 v[54:55], v[54:55], v[158:159] op_sel_hi:[1,0]
	v_pk_mul_f32 v[52:53], v[52:53], v[158:159] op_sel_hi:[1,0]
	v_pk_mul_f32 v[158:159], v[50:51], v[158:159] op_sel_hi:[1,0]
	v_div_fixup_f32 v50, v157, v160, 1.0
	v_pk_fma_f32 v[80:81], v[80:81], v[88:89], v[84:85]
	v_pk_fma_f32 v[78:79], v[78:79], v[86:87], v[82:83]
	v_pk_mul_f32 v[86:87], v[52:53], v[16:17]
	v_pk_mul_f32 v[48:49], v[48:49], v[50:51] op_sel_hi:[1,0]
	v_pk_mul_f32 v[46:47], v[46:47], v[50:51] op_sel_hi:[1,0]
	v_pk_mul_f32 v[82:83], v[54:55], v[10:11]
	v_pk_mul_f32 v[84:85], v[158:159], v[14:15]
	v_pk_mul_f32 v[88:89], v[46:47], v[2:3]
	v_pk_mul_f32 v[158:159], v[48:49], v[4:5]
	v_cvt_pk_bf16_f32 v46, v78, v79
	v_cvt_pk_bf16_f32 v47, v80, v81
	global_store_dwordx2 v[102:103], v[46:47], off
	global_load_dwordx4 v[238:241], v[138:139], off
	s_nop 0
	global_load_dwordx4 v[242:245], v[124:125], off offset:1024
	v_pk_mul_f32 v[74:75], v[74:75], v[6:7]
	v_pk_mul_f32 v[76:77], v[76:77], v[8:9]
	v_pk_mul_f32 v[70:71], v[70:71], v[10:11]
	v_pk_mul_f32 v[72:73], v[72:73], v[12:13]
	v_pk_mul_f32 v[66:67], v[66:67], v[14:15]
	v_pk_mul_f32 v[68:69], v[68:69], v[16:17]
	v_pk_mul_f32 v[62:63], v[62:63], v[2:3]
	v_pk_mul_f32 v[64:65], v[64:65], v[4:5]
	v_pk_mul_f32 v[58:59], v[58:59], v[6:7]
	v_pk_mul_f32 v[60:61], v[60:61], v[8:9]
	v_pk_mul_f32 v[56:57], v[56:57], v[12:13]
	v_mul_f32_e32 v180, v23, v23
	v_mul_f32_e32 v186, v25, v25
	v_mul_f32_e32 v197, v18, v18
	v_mul_f32_e32 v198, v19, v19
	v_mul_f32_e32 v199, v20, v20
	v_mul_f32_e32 v200, v21, v21
	v_pk_fma_f32 v[144:145], v[22:23], v[22:23], v[180:181] op_sel_hi:[1,1,0]
	v_pk_fma_f32 v[146:147], v[24:25], v[24:25], v[186:187] op_sel_hi:[1,1,0]
	v_mov_b32_e32 v145, v199
	v_mov_b32_e32 v147, v200
	s_mov_b32 s8, s26
	global_load_dwordx4 v[230:233], v[134:135], off
	s_nop 0
	global_load_dwordx4 v[234:237], v[124:125], off offset:2048
	s_waitcnt vmcnt(2) lgkmcnt(0)
	v_pk_add_f32 v[240:241], v[240:241], 1.0 op_sel_hi:[1,0]
	v_pk_add_f32 v[238:239], v[238:239], 1.0 op_sel_hi:[1,0]
	v_pk_fma_f32 v[240:241], v[76:77], v[240:241], v[244:245]
	v_pk_fma_f32 v[238:239], v[74:75], v[238:239], v[242:243]
	v_cvt_pk_bf16_f32 v238, v238, v239
	v_cvt_pk_bf16_f32 v239, v240, v241
	global_store_dwordx2 v[102:103], v[238:239], off offset:512
	global_load_dwordx4 v[238:241], v[128:129], off
	s_nop 0
	global_load_dwordx4 v[242:245], v[124:125], off offset:3072
	s_waitcnt vmcnt(3) lgkmcnt(0)
	v_pk_add_f32 v[232:233], v[232:233], 1.0 op_sel_hi:[1,0]
	v_pk_add_f32 v[230:231], v[230:231], 1.0 op_sel_hi:[1,0]
	v_pk_fma_f32 v[232:233], v[72:73], v[232:233], v[236:237]
	v_pk_fma_f32 v[230:231], v[70:71], v[230:231], v[234:235]
	v_cvt_pk_bf16_f32 v230, v230, v231
	v_cvt_pk_bf16_f32 v231, v232, v233
	global_store_dwordx2 v[102:103], v[230:231], off offset:1024
	global_load_dwordx4 v[230:233], v[126:127], off
	s_nop 0
	global_load_dwordx4 v[234:237], v[110:111], off
	s_waitcnt vmcnt(3) lgkmcnt(0)
	v_pk_add_f32 v[240:241], v[240:241], 1.0 op_sel_hi:[1,0]
	v_pk_add_f32 v[238:239], v[238:239], 1.0 op_sel_hi:[1,0]
	v_pk_fma_f32 v[240:241], v[68:69], v[240:241], v[244:245]
	v_pk_fma_f32 v[238:239], v[66:67], v[238:239], v[242:243]
	v_cvt_pk_bf16_f32 v238, v238, v239
	v_cvt_pk_bf16_f32 v239, v240, v241
	global_store_dwordx2 v[102:103], v[238:239], off offset:1536
	global_load_dwordx4 v[238:241], v[120:121], off
	s_nop 0
	global_load_dwordx4 v[242:245], v[110:111], off offset:1024
	s_waitcnt vmcnt(3) lgkmcnt(0)
	v_pk_add_f32 v[232:233], v[232:233], 1.0 op_sel_hi:[1,0]
	v_pk_add_f32 v[230:231], v[230:231], 1.0 op_sel_hi:[1,0]
	v_pk_fma_f32 v[232:233], v[64:65], v[232:233], v[236:237]
	v_pk_fma_f32 v[230:231], v[62:63], v[230:231], v[234:235]
	v_cvt_pk_bf16_f32 v230, v230, v231
	v_cvt_pk_bf16_f32 v231, v232, v233
	global_store_dwordx2 v[102:103], v[230:231], off offset:2048
	global_load_dwordx4 v[230:233], v[116:117], off
	s_nop 0
	global_load_dwordx4 v[234:237], v[110:111], off offset:2048
	s_waitcnt vmcnt(3) lgkmcnt(0)
	v_pk_add_f32 v[240:241], v[240:241], 1.0 op_sel_hi:[1,0]
	v_pk_add_f32 v[238:239], v[238:239], 1.0 op_sel_hi:[1,0]
	v_pk_fma_f32 v[240:241], v[60:61], v[240:241], v[244:245]
	v_pk_fma_f32 v[238:239], v[58:59], v[238:239], v[242:243]
	v_cvt_pk_bf16_f32 v238, v238, v239
	v_cvt_pk_bf16_f32 v239, v240, v241
	global_store_dwordx2 v[102:103], v[238:239], off offset:2560
	v_pk_add_f32 v[58:59], v[150:151], v[150:151] op_sel:[0,1] op_sel_hi:[1,0]
	v_pk_add_f32 v[60:61], v[144:145], v[146:147]
	v_mov_b32_e32 v59, v198
	global_load_dwordx4 v[238:241], v[112:113], off
	s_nop 0
	global_load_dwordx4 v[242:245], v[110:111], off offset:3072
	s_waitcnt vmcnt(3) lgkmcnt(0)
	v_pk_add_f32 v[232:233], v[232:233], 1.0 op_sel_hi:[1,0]
	v_pk_add_f32 v[230:231], v[230:231], 1.0 op_sel_hi:[1,0]
	v_pk_fma_f32 v[232:233], v[56:57], v[232:233], v[236:237]
	v_pk_fma_f32 v[230:231], v[82:83], v[230:231], v[234:235]
	v_cvt_pk_bf16_f32 v230, v230, v231
	v_cvt_pk_bf16_f32 v231, v232, v233
	global_store_dwordx2 v[102:103], v[230:231], off offset:3072
	v_pk_add_f32 v[56:57], v[148:149], v[148:149] op_sel:[0,1] op_sel_hi:[1,0]
	global_load_dwordx4 v[230:233], v[142:143], off
	s_nop 0
	global_load_dwordx4 v[234:237], v[108:109], off
	s_waitcnt vmcnt(3) lgkmcnt(0)
	v_pk_add_f32 v[240:241], v[240:241], 1.0 op_sel_hi:[1,0]
	v_pk_add_f32 v[238:239], v[238:239], 1.0 op_sel_hi:[1,0]
	v_pk_fma_f32 v[240:241], v[86:87], v[240:241], v[244:245]
	v_pk_fma_f32 v[238:239], v[84:85], v[238:239], v[242:243]
	v_cvt_pk_bf16_f32 v238, v238, v239
	v_cvt_pk_bf16_f32 v239, v240, v241
	global_store_dwordx2 v[102:103], v[238:239], off offset:3584
	v_mov_b32_e32 v57, v197
	global_load_dwordx4 v[238:241], v[140:141], off
	s_nop 0
	global_load_dwordx4 v[242:245], v[108:109], off offset:1024
	s_waitcnt vmcnt(3) lgkmcnt(0)
	v_pk_add_f32 v[232:233], v[232:233], 1.0 op_sel_hi:[1,0]
	v_pk_add_f32 v[230:231], v[230:231], 1.0 op_sel_hi:[1,0]
	v_pk_fma_f32 v[232:233], v[158:159], v[232:233], v[236:237]
	v_pk_fma_f32 v[230:231], v[88:89], v[230:231], v[234:235]
	v_bfe_u32 v51, v230, 16, 1
	v_bfe_u32 v234, v231, 16, 1
	v_add3_u32 v230, v230, v51, s5
	v_add3_u32 v231, v231, v234, s5
	v_lshrrev_b32_e32 v230, 16, v230
	v_and_or_b32 v230, v231, s23, v230
	v_cvt_pk_bf16_f32 v231, v232, v233
	global_store_dwordx2 v[104:105], v[230:231], off
	v_pk_mul_f32 v[44:45], v[44:45], v[50:51] op_sel_hi:[1,0]
	v_pk_mul_f32 v[42:43], v[42:43], v[50:51] op_sel_hi:[1,0]
	v_pk_mul_f32 v[44:45], v[44:45], v[8:9]
	v_pk_mul_f32 v[42:43], v[42:43], v[6:7]
	s_waitcnt vmcnt(1) lgkmcnt(0)
	v_pk_add_f32 v[240:241], v[240:241], 1.0 op_sel_hi:[1,0]
	v_pk_add_f32 v[238:239], v[238:239], 1.0 op_sel_hi:[1,0]
	v_pk_fma_f32 v[44:45], v[44:45], v[240:241], v[244:245]
	v_pk_fma_f32 v[42:43], v[42:43], v[238:239], v[242:243]
	v_cvt_pk_bf16_f32 v42, v42, v43
	v_cvt_pk_bf16_f32 v43, v44, v45
	global_store_dwordx2 v[104:105], v[42:43], off offset:512
	global_load_dwordx4 v[42:45], v[136:137], off
	s_nop 0
	global_load_dwordx4 v[46:49], v[108:109], off offset:2048
	v_pk_add_f32 v[52:53], v[56:57], v[58:59]
	s_waitcnt vmcnt(0) lgkmcnt(0)
	v_pk_add_f32 v[44:45], v[44:45], 1.0 op_sel_hi:[1,0]
	v_pk_add_f32 v[52:53], v[52:53], v[60:61]
	v_pk_add_f32 v[42:43], v[42:43], 1.0 op_sel_hi:[1,0]
	v_add_f32_e32 v51, v52, v53
	ds_bpermute_b32 v52, v1, v51
	s_waitcnt lgkmcnt(0)
	v_add_f32_e32 v51, v51, v52
	ds_bpermute_b32 v52, v131, v51
	s_waitcnt lgkmcnt(0)
	v_add_f32_e32 v51, v51, v52
	v_pk_mul_f32 v[40:41], v[40:41], v[50:51] op_sel_hi:[1,0]
	v_pk_mul_f32 v[38:39], v[38:39], v[50:51] op_sel_hi:[1,0]
	v_pk_mul_f32 v[40:41], v[40:41], v[12:13]
	v_pk_mul_f32 v[38:39], v[38:39], v[10:11]
	v_pk_fma_f32 v[40:41], v[40:41], v[44:45], v[48:49]
	v_pk_fma_f32 v[38:39], v[38:39], v[42:43], v[46:47]
	v_cvt_pk_bf16_f32 v38, v38, v39
	v_cvt_pk_bf16_f32 v39, v40, v41
	global_store_dwordx2 v[104:105], v[38:39], off offset:1024
	global_load_dwordx4 v[38:41], v[122:123], off
	s_nop 0
	global_load_dwordx4 v[42:45], v[108:109], off offset:3072
	v_pk_mul_f32 v[36:37], v[36:37], v[50:51] op_sel_hi:[1,0]
	v_pk_mul_f32 v[34:35], v[34:35], v[50:51] op_sel_hi:[1,0]
	v_pk_mul_f32 v[36:37], v[36:37], v[16:17]
	v_pk_mul_f32 v[34:35], v[34:35], v[14:15]
	ds_bpermute_b32 v46, v133, v51
	s_waitcnt lgkmcnt(0)
	v_add_f32_e32 v46, v51, v46
	ds_bpermute_b32 v47, v152, v46
	s_waitcnt lgkmcnt(0)
	v_add_f32_e32 v46, v46, v47
	ds_bpermute_b32 v47, v153, v46
	s_waitcnt lgkmcnt(0)
	v_add_f32_e32 v46, v46, v47
	ds_bpermute_b32 v47, v154, v46
	s_waitcnt lgkmcnt(0)
	v_add_f32_e32 v46, v46, v47
	v_fmamk_f32 v46, v46, 0x3a800000, v155
	v_mul_f32_e32 v47, 0x4f800000, v46
	v_cmp_gt_f32_e32 vcc, s4, v46
	s_waitcnt vmcnt(0)
	v_pk_add_f32 v[40:41], v[40:41], 1.0 op_sel_hi:[1,0]
	v_pk_add_f32 v[38:39], v[38:39], 1.0 op_sel_hi:[1,0]
	v_pk_fma_f32 v[36:37], v[36:37], v[40:41], v[44:45]
	v_pk_fma_f32 v[34:35], v[34:35], v[38:39], v[42:43]
	v_cvt_pk_bf16_f32 v34, v34, v35
	v_cvt_pk_bf16_f32 v35, v36, v37
	global_store_dwordx2 v[104:105], v[34:35], off offset:1536
	global_load_dwordx4 v[34:37], v[118:119], off
	s_nop 0
	global_load_dwordx4 v[38:41], v[106:107], off
	v_cndmask_b32_e32 v42, v46, v47, vcc
	v_sqrt_f32_e32 v43, v42
	s_waitcnt vmcnt(0) lgkmcnt(0)
	v_pk_add_f32 v[36:37], v[36:37], 1.0 op_sel_hi:[1,0]
	v_add_u32_e32 v44, -1, v43
	v_add_u32_e32 v45, 1, v43
	v_fma_f32 v46, -v44, v43, v42
	v_fma_f32 v47, -v45, v43, v42
	v_cmp_ge_f32_e64 s[6:7], 0, v46
	v_pk_add_f32 v[34:35], v[34:35], 1.0 op_sel_hi:[1,0]
	s_nop 0
	v_cndmask_b32_e64 v43, v43, v44, s[6:7]
	v_cmp_lt_f32_e64 s[6:7], 0, v47
	s_nop 1
	v_cndmask_b32_e64 v43, v43, v45, s[6:7]
	v_mul_f32_e32 v44, 0x37800000, v43
	v_cndmask_b32_e32 v43, v43, v44, vcc
	v_cmp_class_f32_e32 vcc, v42, v156
	s_nop 1
	v_cndmask_b32_e32 v42, v43, v42, vcc
	v_div_scale_f32 v43, s[6:7], v42, v42, 1.0
	v_rcp_f32_e32 v45, v43
	v_div_scale_f32 v44, vcc, 1.0, v42, 1.0
	v_fma_f32 v46, -v43, v45, 1.0
	v_fmac_f32_e32 v45, v46, v45
	v_mul_f32_e32 v46, v44, v45
	v_fma_f32 v47, -v43, v46, v44
	v_fmac_f32_e32 v46, v47, v45
	v_fma_f32 v43, -v43, v46, v44
	v_div_fmas_f32 v43, v43, v45, v46
	v_div_fixup_f32 v42, v43, v42, 1.0
	v_pk_mul_f32 v[32:33], v[32:33], v[42:43] op_sel_hi:[1,0]
	v_pk_mul_f32 v[30:31], v[30:31], v[42:43] op_sel_hi:[1,0]
	v_pk_mul_f32 v[32:33], v[32:33], v[4:5]
	v_pk_mul_f32 v[30:31], v[30:31], v[2:3]
	v_pk_fma_f32 v[32:33], v[32:33], v[36:37], v[40:41]
	v_pk_fma_f32 v[30:31], v[30:31], v[34:35], v[38:39]
	v_cvt_pk_bf16_f32 v30, v30, v31
	v_cvt_pk_bf16_f32 v31, v32, v33
	global_store_dwordx2 v[104:105], v[30:31], off offset:2048
	global_load_dwordx4 v[30:33], v[114:115], off
	s_nop 0
	global_load_dwordx4 v[34:37], v[106:107], off offset:1024
	v_pk_mul_f32 v[28:29], v[28:29], v[42:43] op_sel_hi:[1,0]
	v_pk_mul_f32 v[26:27], v[26:27], v[42:43] op_sel_hi:[1,0]
	v_pk_mul_f32 v[28:29], v[28:29], v[8:9]
	v_pk_mul_f32 v[26:27], v[26:27], v[6:7]
	v_lshl_add_u64 v[38:39], s[20:21], 0, v[98:99]
	v_pk_mul_f32 v[24:25], v[24:25], v[42:43] op_sel_hi:[1,0]
	v_pk_mul_f32 v[22:23], v[22:23], v[42:43] op_sel_hi:[1,0]
	v_pk_mul_f32 v[24:25], v[24:25], v[12:13]
	v_pk_mul_f32 v[22:23], v[22:23], v[10:11]
	v_pk_mul_f32 v[20:21], v[20:21], v[42:43] op_sel_hi:[1,0]
	v_pk_mul_f32 v[18:19], v[18:19], v[42:43] op_sel_hi:[1,0]
	v_pk_mul_f32 v[20:21], v[20:21], v[16:17]
	v_pk_mul_f32 v[18:19], v[18:19], v[14:15]
	s_waitcnt vmcnt(0) lgkmcnt(0)
	v_pk_add_f32 v[32:33], v[32:33], 1.0 op_sel_hi:[1,0]
	v_pk_add_f32 v[30:31], v[30:31], 1.0 op_sel_hi:[1,0]
	v_pk_fma_f32 v[28:29], v[28:29], v[32:33], v[36:37]
	v_pk_fma_f32 v[26:27], v[26:27], v[30:31], v[34:35]
	v_cvt_pk_bf16_f32 v26, v26, v27
	v_cvt_pk_bf16_f32 v27, v28, v29
	global_store_dwordx2 v[104:105], v[26:27], off offset:2560
	global_load_dwordx4 v[26:29], v[38:39], off
	s_nop 0
	global_load_dwordx4 v[30:33], v[106:107], off offset:2048
	v_lshl_add_u64 v[34:35], s[20:21], 0, v[100:101]
	s_waitcnt vmcnt(0) lgkmcnt(0)
	v_pk_add_f32 v[28:29], v[28:29], 1.0 op_sel_hi:[1,0]
	v_pk_add_f32 v[26:27], v[26:27], 1.0 op_sel_hi:[1,0]
	v_pk_fma_f32 v[24:25], v[24:25], v[28:29], v[32:33]
	v_pk_fma_f32 v[22:23], v[22:23], v[26:27], v[30:31]
	v_cvt_pk_bf16_f32 v22, v22, v23
	v_cvt_pk_bf16_f32 v23, v24, v25
	global_store_dwordx2 v[104:105], v[22:23], off offset:3072
	global_load_dwordx4 v[22:25], v[34:35], off
	s_nop 0
	global_load_dwordx4 v[26:29], v[106:107], off offset:3072
	s_waitcnt vmcnt(0) lgkmcnt(0)
	v_pk_add_f32 v[24:25], v[24:25], 1.0 op_sel_hi:[1,0]
	v_pk_add_f32 v[22:23], v[22:23], 1.0 op_sel_hi:[1,0]
	v_pk_fma_f32 v[20:21], v[20:21], v[24:25], v[28:29]
	v_pk_fma_f32 v[18:19], v[18:19], v[22:23], v[26:27]
	v_cvt_pk_bf16_f32 v18, v18, v19
	v_cvt_pk_bf16_f32 v19, v20, v21
	global_store_dwordx2 v[104:105], v[18:19], off offset:3584
	s_cbranch_scc1 .LBB0_1004

.LBB0_2937:
	v_lshl_add_u64 v[18:19], s[68:69], 0, v[94:95]
	v_lshl_add_u64 v[22:23], s[68:69], 0, v[92:93]
	v_add_co_u32_e32 v20, vcc, 0x7800000, v18
	v_add_co_u32_e64 v102, s[6:7], s24, v22
	s_nop 0
	v_addc_co_u32_e32 v21, vcc, 0, v19, vcc
	v_addc_co_u32_e64 v103, s[6:7], 0, v23, s[6:7]
	v_add_co_u32_e64 v104, s[6:7], s25, v22
	v_add_co_u32_e32 v22, vcc, 0x7801000, v18
	s_nop 0
	v_addc_co_u32_e64 v105, s[6:7], 0, v23, s[6:7]
	global_load_dwordx4 v[78:81], v[20:21], off
	global_load_dwordx4 v[74:77], v[20:21], off offset:1024
	global_load_dwordx4 v[70:73], v[20:21], off offset:2048
	global_load_dwordx4 v[66:69], v[20:21], off offset:3072
	v_addc_co_u32_e32 v23, vcc, 0, v19, vcc
	v_add_co_u32_e32 v20, vcc, 0x7802000, v18
	global_load_dwordx4 v[62:65], v[22:23], off
	global_load_dwordx4 v[58:61], v[22:23], off offset:1024
	global_load_dwordx4 v[54:57], v[22:23], off offset:2048
	global_load_dwordx4 v[50:53], v[22:23], off offset:3072
	v_addc_co_u32_e32 v21, vcc, 0, v19, vcc
	v_add_co_u32_e32 v82, vcc, 0x7803000, v18
	global_load_dwordx4 v[46:49], v[20:21], off
	global_load_dwordx4 v[42:45], v[20:21], off offset:1024
	global_load_dwordx4 v[38:41], v[20:21], off offset:2048
	global_load_dwordx4 v[34:37], v[20:21], off offset:3072
	v_addc_co_u32_e32 v83, vcc, 0, v19, vcc
	global_load_dwordx4 v[30:33], v[82:83], off
	global_load_dwordx4 v[26:29], v[82:83], off offset:1024
	global_load_dwordx4 v[22:25], v[82:83], off offset:2048
	global_load_dwordx4 v[18:21], v[82:83], off offset:3072
	s_ashr_i32 s8, s12, 13
	s_add_i32 s9, s12, 0xffffc002
	s_cmpk_lt_i32 s12, 0x4000
	s_cselect_b32 s6, s8, s9
	s_mul_hi_i32 s7, s6, 0x9000
	s_mul_i32 s6, s6, 0x9000
	s_add_u32 s9, s3, s6
	s_addc_u32 s11, s4, s7
	s_add_u32 s6, s9, 0x6000
	s_addc_u32 s7, s11, 0
	s_add_u32 s10, s9, 0x7000
	s_addc_u32 s11, s11, 0
	v_lshl_add_u64 v[82:83], s[6:7], 0, v[90:91]
	v_lshl_add_u64 v[86:87], s[10:11], 0, v[90:91]
	global_load_dwordx4 v[82:85], v[82:83], off
	v_lshl_add_u64 v[148:149], s[6:7], 0, v[96:97]
	global_load_dwordx4 v[86:89], v[86:87], off
	v_lshl_add_u64 v[142:143], s[6:7], 0, v[98:99]
	v_lshl_add_u64 v[134:135], s[6:7], 0, v[100:101]
	s_add_i32 s6, s12, 0xffffc003
	s_cmpk_lt_i32 s12, 0x3fff
	s_cselect_b32 s6, s8, s6
	s_mul_hi_i32 s7, s6, 0x9000
	s_mul_i32 s6, s6, 0x9000
	s_add_u32 s9, s3, s6
	v_lshl_add_u64 v[152:153], s[10:11], 0, v[96:97]
	v_lshl_add_u64 v[146:147], s[10:11], 0, v[98:99]
	v_lshl_add_u64 v[140:141], s[10:11], 0, v[100:101]
	s_addc_u32 s11, s4, s7
	s_add_u32 s6, s9, 0x6000
	s_addc_u32 s7, s11, 0
	s_add_u32 s10, s9, 0x7000
	v_lshl_add_u64 v[132:133], s[6:7], 0, v[90:91]
	v_lshl_add_u64 v[126:127], s[6:7], 0, v[96:97]
	v_lshl_add_u64 v[118:119], s[6:7], 0, v[98:99]
	v_lshl_add_u64 v[114:115], s[6:7], 0, v[100:101]
	s_addc_u32 s11, s11, 0
	s_add_i32 s6, s12, 0xffffc004
	s_cmpk_lt_i32 s12, 0x3ffe
	s_cselect_b32 s6, s8, s6
	s_mul_hi_i32 s7, s6, 0x9000
	s_mul_i32 s6, s6, 0x9000
	s_add_u32 s6, s3, s6
	s_addc_u32 s7, s4, s7
	v_lshl_add_u64 v[138:139], s[10:11], 0, v[90:91]
	v_lshl_add_u64 v[130:131], s[10:11], 0, v[96:97]
	v_lshl_add_u64 v[122:123], s[10:11], 0, v[98:99]
	v_lshl_add_u64 v[116:117], s[10:11], 0, v[100:101]
	s_add_u32 s10, s6, 0x6000
	s_addc_u32 s11, s7, 0
	s_add_u32 s6, s6, 0x7000
	s_addc_u32 s7, s7, 0
	s_add_i32 s9, s12, 0xffffc005
	s_cmpk_lt_i32 s12, 0x3ffd
	v_lshl_add_u64 v[156:157], s[6:7], 0, v[90:91]
	v_lshl_add_u64 v[154:155], s[6:7], 0, v[96:97]
	v_lshl_add_u64 v[150:151], s[6:7], 0, v[98:99]
	v_lshl_add_u64 v[136:137], s[6:7], 0, v[100:101]
	s_cselect_b32 s6, s8, s9
	s_mul_hi_i32 s7, s6, 0x9000
	s_mul_i32 s6, s6, 0x9000
	s_add_u32 s6, s3, s6
	s_addc_u32 s7, s4, s7
	s_waitcnt vmcnt(0) lgkmcnt(0)
	v_pk_mul_f32 v[158:159], v[80:81], v[80:81]
	v_pk_mul_f32 v[160:161], v[78:79], v[78:79]
	v_pk_mul_f32 v[162:163], v[76:77], v[76:77]
	v_pk_mul_f32 v[164:165], v[74:75], v[74:75]
	v_mul_f32_e32 v174, v71, v71
	v_mul_f32_e32 v176, v73, v73
	v_mul_f32_e32 v187, v68, v68
	v_mul_f32_e32 v189, v69, v69
	v_pk_mov_b32 v[178:179], v[160:161], v[158:159] op_sel:[1,0]
	v_mov_b32_e32 v161, v159
	v_pk_mov_b32 v[158:159], v[164:165], v[162:163] op_sel:[1,0]
	v_mov_b32_e32 v165, v163
	v_pk_fma_f32 v[162:163], v[70:71], v[70:71], v[174:175] op_sel_hi:[1,1,0]
	v_pk_fma_f32 v[174:175], v[72:73], v[72:73], v[176:177] op_sel_hi:[1,1,0]
	v_pk_mul_f32 v[176:177], v[64:65], v[64:65]
	v_pk_mul_f32 v[180:181], v[62:63], v[62:63]
	v_pk_mul_f32 v[182:183], v[60:61], v[60:61]
	v_pk_mul_f32 v[184:185], v[58:59], v[58:59]
	v_mul_f32_e32 v186, v55, v55
	v_mul_f32_e32 v188, v57, v57
	v_pk_add_f32 v[160:161], v[178:179], v[160:161]
	v_pk_add_f32 v[158:159], v[158:159], v[164:165]
	v_mov_b32_e32 v163, v187
	v_mov_b32_e32 v175, v189
	v_pk_mov_b32 v[164:165], v[180:181], v[176:177] op_sel:[1,0]
	v_mov_b32_e32 v181, v177
	v_pk_mov_b32 v[176:177], v[184:185], v[182:183] op_sel:[1,0]
	v_mov_b32_e32 v185, v183
	v_pk_fma_f32 v[178:179], v[54:55], v[54:55], v[186:187] op_sel_hi:[1,1,0]
	v_pk_fma_f32 v[182:183], v[56:57], v[56:57], v[188:189] op_sel_hi:[1,1,0]
	v_pk_mul_f32 v[186:187], v[48:49], v[48:49]
	v_pk_mul_f32 v[188:189], v[46:47], v[46:47]
	v_pk_mul_f32 v[190:191], v[44:45], v[44:45]
	v_pk_mul_f32 v[192:193], v[42:43], v[42:43]
	v_mul_f32_e32 v197, v66, v66
	v_mul_f32_e32 v203, v67, v67
	v_mul_f32_e32 v195, v52, v52
	v_mul_f32_e32 v202, v53, v53
	v_mul_f32_e32 v194, v39, v39
	v_mul_f32_e32 v196, v41, v41
	v_pk_add_f32 v[198:199], v[160:161], v[160:161] op_sel:[0,1] op_sel_hi:[1,0]
	v_pk_add_f32 v[200:201], v[158:159], v[158:159] op_sel:[0,1] op_sel_hi:[1,0]
	v_pk_add_f32 v[174:175], v[162:163], v[174:175]
	v_pk_add_f32 v[158:159], v[164:165], v[180:181]
	v_pk_add_f32 v[160:161], v[176:177], v[184:185]
	v_pk_mov_b32 v[162:163], v[188:189], v[186:187] op_sel:[1,0]
	v_mov_b32_e32 v189, v187
	v_pk_mov_b32 v[164:165], v[192:193], v[190:191] op_sel:[1,0]
	v_mov_b32_e32 v193, v191
	v_mul_f32_e32 v208, v50, v50
	v_mul_f32_e32 v209, v51, v51
	v_mul_f32_e32 v212, v36, v36
	v_mul_f32_e32 v213, v37, v37
	v_mov_b32_e32 v179, v195
	v_mov_b32_e32 v183, v202
	v_pk_fma_f32 v[176:177], v[38:39], v[38:39], v[194:195] op_sel_hi:[1,1,0]
	v_pk_fma_f32 v[180:181], v[40:41], v[40:41], v[196:197] op_sel_hi:[1,1,0]
	v_pk_mul_f32 v[184:185], v[32:33], v[32:33]
	v_pk_mul_f32 v[186:187], v[30:31], v[30:31]
	v_pk_mul_f32 v[190:191], v[28:29], v[28:29]
	v_pk_mul_f32 v[194:195], v[26:27], v[26:27]
	v_mov_b32_e32 v199, v197
	v_mov_b32_e32 v201, v203
	v_pk_add_f32 v[204:205], v[158:159], v[158:159] op_sel:[0,1] op_sel_hi:[1,0]
	v_pk_add_f32 v[206:207], v[160:161], v[160:161] op_sel:[0,1] op_sel_hi:[1,0]
	v_pk_add_f32 v[162:163], v[162:163], v[188:189]
	v_pk_add_f32 v[164:165], v[164:165], v[192:193]
	v_mul_f32_e32 v210, v34, v34
	v_mul_f32_e32 v211, v35, v35
	v_pk_add_f32 v[178:179], v[178:179], v[182:183]
	v_mov_b32_e32 v177, v212
	v_mov_b32_e32 v181, v213
	v_pk_mov_b32 v[182:183], v[186:187], v[184:185] op_sel:[1,0]
	v_mov_b32_e32 v187, v185
	v_pk_mov_b32 v[184:185], v[194:195], v[190:191] op_sel:[1,0]
	v_mov_b32_e32 v195, v191
	v_pk_add_f32 v[188:189], v[198:199], v[200:201]
	v_mov_b32_e32 v205, v208
	v_mov_b32_e32 v207, v209
	v_pk_add_f32 v[190:191], v[162:163], v[162:163] op_sel:[0,1] op_sel_hi:[1,0]
	v_pk_add_f32 v[192:193], v[164:165], v[164:165] op_sel:[0,1] op_sel_hi:[1,0]
	v_pk_add_f32 v[176:177], v[176:177], v[180:181]
	v_pk_add_f32 v[174:175], v[188:189], v[174:175]
	v_pk_add_f32 v[180:181], v[204:205], v[206:207]
	v_mov_b32_e32 v191, v210
	v_mov_b32_e32 v193, v211
	v_pk_add_f32 v[162:163], v[182:183], v[186:187]
	v_add_f32_e32 v182, v174, v175
	v_pk_add_f32 v[174:175], v[180:181], v[178:179]
	v_pk_add_f32 v[178:179], v[190:191], v[192:193]
	v_add_f32_e32 v180, v174, v175
	v_pk_add_f32 v[174:175], v[178:179], v[176:177]
	ds_bpermute_b32 v176, v1, v182
	ds_bpermute_b32 v177, v1, v180
	v_add_f32_e32 v174, v174, v175
	ds_bpermute_b32 v175, v1, v174
	s_add_u32 s18, s6, 0x6000
	s_waitcnt lgkmcnt(2)
	v_add_f32_e32 v176, v182, v176
	ds_bpermute_b32 v178, v167, v176
	s_waitcnt lgkmcnt(2)
	v_add_f32_e32 v177, v180, v177
	ds_bpermute_b32 v179, v167, v177
	s_waitcnt lgkmcnt(2)
	v_add_f32_e32 v174, v174, v175
	ds_bpermute_b32 v175, v167, v174
	s_waitcnt lgkmcnt(2)
	v_add_f32_e32 v176, v176, v178
	ds_bpermute_b32 v178, v168, v176
	s_waitcnt lgkmcnt(2)
	v_add_f32_e32 v177, v177, v179
	ds_bpermute_b32 v179, v168, v177
	s_waitcnt lgkmcnt(2)
	v_add_f32_e32 v174, v174, v175
	ds_bpermute_b32 v175, v168, v174
	s_waitcnt lgkmcnt(2)
	v_add_f32_e32 v176, v176, v178
	ds_bpermute_b32 v178, v169, v176
	s_waitcnt lgkmcnt(2)
	v_add_f32_e32 v177, v177, v179
	ds_bpermute_b32 v179, v169, v177
	s_waitcnt lgkmcnt(2)
	v_add_f32_e32 v174, v174, v175
	ds_bpermute_b32 v175, v169, v174
	s_waitcnt lgkmcnt(2)
	v_add_f32_e32 v176, v176, v178
	ds_bpermute_b32 v178, v170, v176
	s_waitcnt lgkmcnt(2)
	v_add_f32_e32 v177, v177, v179
	ds_bpermute_b32 v179, v170, v177
	s_waitcnt lgkmcnt(2)
	v_add_f32_e32 v174, v174, v175
	ds_bpermute_b32 v175, v170, v174
	s_waitcnt lgkmcnt(2)
	v_add_f32_e32 v176, v176, v178
	ds_bpermute_b32 v178, v171, v176
	s_waitcnt lgkmcnt(2)
	v_add_f32_e32 v177, v177, v179
	ds_bpermute_b32 v179, v171, v177
	s_waitcnt lgkmcnt(2)
	v_add_f32_e32 v174, v174, v175
	ds_bpermute_b32 v175, v171, v174
	s_waitcnt lgkmcnt(2)
	v_add_f32_e32 v176, v176, v178
	v_fmamk_f32 v176, v176, 0x3a800000, v172
	s_addc_u32 s19, s7, 0
	s_waitcnt lgkmcnt(1)
	v_add_f32_e32 v177, v177, v179
	v_mul_f32_e32 v178, 0x4f800000, v176
	v_cmp_gt_f32_e32 vcc, s13, v176
	s_add_u32 s20, s6, 0x7000
	v_fmamk_f32 v177, v177, 0x3a800000, v172
	s_waitcnt lgkmcnt(0)
	v_add_f32_e32 v174, v174, v175
	v_cndmask_b32_e32 v175, v176, v178, vcc
	s_addc_u32 s21, s7, 0
	v_mul_f32_e32 v176, 0x4f800000, v177
	v_cmp_gt_f32_e64 s[6:7], s13, v177
	v_sqrt_f32_e32 v178, v175
	v_fmamk_f32 v174, v174, 0x3a800000, v172
	v_cndmask_b32_e64 v176, v177, v176, s[6:7]
	v_mul_f32_e32 v177, 0x4f800000, v174
	v_cmp_gt_f32_e64 s[8:9], s13, v174
	v_sqrt_f32_e32 v179, v176
	v_add_u32_e32 v180, -1, v178
	v_cndmask_b32_e64 v174, v174, v177, s[8:9]
	v_sqrt_f32_e32 v177, v174
	v_add_u32_e32 v181, 1, v178
	v_fma_f32 v182, -v180, v178, v175
	v_lshl_add_u64 v[112:113], s[10:11], 0, v[90:91]
	v_lshl_add_u64 v[106:107], s[10:11], 0, v[96:97]
	v_lshl_add_u64 v[110:111], s[10:11], 0, v[98:99]
	v_lshl_add_u64 v[108:109], s[10:11], 0, v[100:101]
	v_pk_add_f32 v[164:165], v[184:185], v[194:195]
	v_fma_f32 v183, -v181, v178, v175
	v_add_u32_e32 v184, -1, v179
	v_cmp_ge_f32_e64 s[10:11], 0, v182
	v_add_u32_e32 v185, 1, v179
	v_fma_f32 v182, -v185, v179, v176
	v_cndmask_b32_e64 v178, v178, v180, s[10:11]
	v_fma_f32 v180, -v184, v179, v176
	v_cmp_lt_f32_e64 s[10:11], 0, v183
	v_add_u32_e32 v186, -1, v177
	v_add_u32_e32 v187, 1, v177
	v_cndmask_b32_e64 v178, v178, v181, s[10:11]
	v_cmp_ge_f32_e64 s[10:11], 0, v180
	v_fma_f32 v180, -v186, v177, v174
	v_fma_f32 v181, -v187, v177, v174
	v_cndmask_b32_e64 v179, v179, v184, s[10:11]
	v_cmp_lt_f32_e64 s[10:11], 0, v182
	v_mul_f32_e32 v182, 0x37800000, v178
	v_cndmask_b32_e32 v178, v178, v182, vcc
	v_cndmask_b32_e64 v179, v179, v185, s[10:11]
	v_cmp_ge_f32_e64 s[10:11], 0, v180
	v_mul_f32_e32 v180, 0x37800000, v179
	v_cmp_class_f32_e32 vcc, v175, v173
	v_cndmask_b32_e64 v177, v177, v186, s[10:11]
	v_cmp_lt_f32_e64 s[10:11], 0, v181
	v_cndmask_b32_e32 v175, v178, v175, vcc
	v_cndmask_b32_e64 v178, v179, v180, s[6:7]
	v_cndmask_b32_e64 v177, v177, v187, s[10:11]
	v_cmp_class_f32_e32 vcc, v176, v173
	v_mul_f32_e32 v179, 0x37800000, v177
	v_div_scale_f32 v180, s[6:7], v175, v175, 1.0
	v_cndmask_b32_e32 v176, v178, v176, vcc
	v_cndmask_b32_e64 v177, v177, v179, s[8:9]
	v_cmp_class_f32_e32 vcc, v174, v173
	v_rcp_f32_e32 v178, v180
	v_div_scale_f32 v179, s[8:9], v176, v176, 1.0
	v_cndmask_b32_e32 v177, v177, v174, vcc
	v_rcp_f32_e32 v183, v179
	v_div_scale_f32 v184, s[10:11], v177, v177, 1.0
	v_rcp_f32_e32 v186, v184
	v_fma_f32 v174, -v180, v178, 1.0
	v_div_scale_f32 v181, s[6:7], 1.0, v175, 1.0
	v_fmac_f32_e32 v178, v174, v178
	v_fma_f32 v174, -v179, v183, 1.0
	v_div_scale_f32 v182, s[8:9], 1.0, v176, 1.0
	v_mul_f32_e32 v187, v181, v178
	v_fmac_f32_e32 v183, v174, v183
	v_fma_f32 v174, -v184, v186, 1.0
	v_fma_f32 v188, -v180, v187, v181
	v_mul_f32_e32 v189, v182, v183
	v_div_scale_f32 v185, s[10:11], 1.0, v177, 1.0
	v_fmac_f32_e32 v186, v174, v186
	v_fmac_f32_e32 v187, v188, v178
	v_fma_f32 v174, -v179, v189, v182
	v_mul_f32_e32 v188, v185, v186
	v_fma_f32 v180, -v180, v187, v181
	v_fmac_f32_e32 v189, v174, v183
	s_mov_b64 vcc, s[6:7]
	v_fma_f32 v174, -v184, v188, v185
	v_div_fmas_f32 v178, v180, v178, v187
	v_fma_f32 v179, -v179, v189, v182
	s_mov_b64 vcc, s[8:9]
	v_fmac_f32_e32 v188, v174, v186
	v_div_fixup_f32 v174, v178, v175, 1.0
	v_div_fmas_f32 v175, v179, v183, v189
	v_fma_f32 v178, -v184, v188, v185
	v_pk_mul_f32 v[80:81], v[80:81], v[174:175] op_sel_hi:[1,0]
	v_pk_mul_f32 v[78:79], v[78:79], v[174:175] op_sel_hi:[1,0]
	s_mov_b64 vcc, s[10:11]
	v_pk_add_f32 v[88:89], v[88:89], 1.0 op_sel_hi:[1,0]
	v_pk_add_f32 v[86:87], v[86:87], 1.0 op_sel_hi:[1,0]
	v_pk_mul_f32 v[76:77], v[76:77], v[174:175] op_sel_hi:[1,0]
	v_pk_mul_f32 v[74:75], v[74:75], v[174:175] op_sel_hi:[1,0]
	v_pk_mul_f32 v[72:73], v[72:73], v[174:175] op_sel_hi:[1,0]
	v_pk_mul_f32 v[70:71], v[70:71], v[174:175] op_sel_hi:[1,0]
	v_pk_mul_f32 v[68:69], v[68:69], v[174:175] op_sel_hi:[1,0]
	v_pk_mul_f32 v[66:67], v[66:67], v[174:175] op_sel_hi:[1,0]
	v_div_fixup_f32 v174, v175, v176, 1.0
	v_div_fmas_f32 v176, v178, v186, v188
	v_pk_mul_f32 v[78:79], v[2:3], v[78:79]
	v_pk_mul_f32 v[80:81], v[4:5], v[80:81]
	v_pk_mul_f32 v[64:65], v[64:65], v[174:175] op_sel_hi:[1,0]
	v_pk_mul_f32 v[62:63], v[62:63], v[174:175] op_sel_hi:[1,0]
	v_pk_mul_f32 v[60:61], v[60:61], v[174:175] op_sel_hi:[1,0]
	v_pk_mul_f32 v[58:59], v[58:59], v[174:175] op_sel_hi:[1,0]
	v_pk_mul_f32 v[56:57], v[56:57], v[174:175] op_sel_hi:[1,0]
	v_pk_mul_f32 v[54:55], v[54:55], v[174:175] op_sel_hi:[1,0]
	v_pk_mul_f32 v[52:53], v[52:53], v[174:175] op_sel_hi:[1,0]
	v_pk_mul_f32 v[174:175], v[50:51], v[174:175] op_sel_hi:[1,0]
	v_div_fixup_f32 v50, v176, v177, 1.0
	v_pk_fma_f32 v[80:81], v[88:89], v[80:81], v[84:85]
	v_pk_fma_f32 v[78:79], v[86:87], v[78:79], v[82:83]
	v_pk_mul_f32 v[86:87], v[16:17], v[52:53]
	v_pk_mul_f32 v[48:49], v[48:49], v[50:51] op_sel_hi:[1,0]
	v_pk_mul_f32 v[46:47], v[46:47], v[50:51] op_sel_hi:[1,0]
	v_pk_mul_f32 v[82:83], v[10:11], v[54:55]
	v_pk_mul_f32 v[84:85], v[14:15], v[174:175]
	v_pk_mul_f32 v[88:89], v[2:3], v[46:47]
	v_pk_mul_f32 v[174:175], v[4:5], v[48:49]
	v_cvt_pk_bf16_f32 v46, v78, v79
	v_cvt_pk_bf16_f32 v47, v80, v81
	global_store_dwordx2 v[102:103], v[46:47], off
	global_load_dwordx4 v[238:241], v[152:153], off
	s_nop 0
	global_load_dwordx4 v[242:245], v[148:149], off
	v_pk_mul_f32 v[74:75], v[6:7], v[74:75]
	v_pk_mul_f32 v[76:77], v[8:9], v[76:77]
	v_pk_mul_f32 v[70:71], v[10:11], v[70:71]
	v_pk_mul_f32 v[72:73], v[12:13], v[72:73]
	v_pk_mul_f32 v[66:67], v[66:67], v[14:15]
	v_pk_mul_f32 v[68:69], v[68:69], v[16:17]
	v_pk_mul_f32 v[62:63], v[2:3], v[62:63]
	v_pk_mul_f32 v[64:65], v[4:5], v[64:65]
	v_pk_mul_f32 v[58:59], v[6:7], v[58:59]
	v_pk_mul_f32 v[60:61], v[8:9], v[60:61]
	v_pk_mul_f32 v[56:57], v[12:13], v[56:57]
	v_mul_f32_e32 v196, v23, v23
	v_mul_f32_e32 v202, v25, v25
	v_mul_f32_e32 v214, v18, v18
	v_mul_f32_e32 v215, v19, v19
	v_mul_f32_e32 v216, v20, v20
	v_mul_f32_e32 v217, v21, v21
	v_pk_fma_f32 v[158:159], v[22:23], v[22:23], v[196:197] op_sel_hi:[1,1,0]
	v_pk_fma_f32 v[160:161], v[24:25], v[24:25], v[202:203] op_sel_hi:[1,1,0]
	v_mov_b32_e32 v159, v216
	v_mov_b32_e32 v161, v217
	v_lshl_add_u64 v[144:145], s[20:21], 0, v[90:91]
	v_lshl_add_u64 v[128:129], s[18:19], 0, v[90:91]
	v_lshl_add_u64 v[124:125], s[20:21], 0, v[96:97]
	v_lshl_add_u64 v[120:121], s[18:19], 0, v[96:97]
	s_add_i32 s12, s12, 32
	v_lshl_add_u64 v[92:93], v[92:93], 0, s[14:15]
	v_lshl_add_u64 v[94:95], v[94:95], 0, s[16:17]
	s_cmp_lt_i32 s12, s2
	global_load_dwordx4 v[230:233], v[146:147], off
	s_nop 0
	global_load_dwordx4 v[234:237], v[142:143], off
	s_waitcnt vmcnt(2) lgkmcnt(0)
	v_pk_add_f32 v[240:241], v[240:241], 1.0 op_sel_hi:[1,0]
	v_pk_add_f32 v[238:239], v[238:239], 1.0 op_sel_hi:[1,0]
	v_pk_fma_f32 v[240:241], v[240:241], v[76:77], v[244:245]
	v_pk_fma_f32 v[238:239], v[238:239], v[74:75], v[242:243]
	v_cvt_pk_bf16_f32 v238, v238, v239
	v_cvt_pk_bf16_f32 v239, v240, v241
	global_store_dwordx2 v[102:103], v[238:239], off offset:512
	global_load_dwordx4 v[238:241], v[140:141], off
	s_nop 0
	global_load_dwordx4 v[242:245], v[134:135], off
	s_waitcnt vmcnt(3) lgkmcnt(0)
	v_pk_add_f32 v[232:233], v[232:233], 1.0 op_sel_hi:[1,0]
	v_pk_add_f32 v[230:231], v[230:231], 1.0 op_sel_hi:[1,0]
	v_pk_fma_f32 v[232:233], v[72:73], v[232:233], v[236:237]
	v_pk_fma_f32 v[230:231], v[70:71], v[230:231], v[234:235]
	v_cvt_pk_bf16_f32 v230, v230, v231
	v_cvt_pk_bf16_f32 v231, v232, v233
	global_store_dwordx2 v[102:103], v[230:231], off offset:1024
	global_load_dwordx4 v[230:233], v[138:139], off
	s_nop 0
	global_load_dwordx4 v[234:237], v[132:133], off
	s_waitcnt vmcnt(3) lgkmcnt(0)
	v_pk_add_f32 v[240:241], v[240:241], 1.0 op_sel_hi:[1,0]
	v_pk_add_f32 v[238:239], v[238:239], 1.0 op_sel_hi:[1,0]
	v_pk_fma_f32 v[240:241], v[68:69], v[240:241], v[244:245]
	v_pk_fma_f32 v[238:239], v[66:67], v[238:239], v[242:243]
	v_cvt_pk_bf16_f32 v238, v238, v239
	v_cvt_pk_bf16_f32 v239, v240, v241
	global_store_dwordx2 v[102:103], v[238:239], off offset:1536
	global_load_dwordx4 v[238:241], v[130:131], off
	s_nop 0
	global_load_dwordx4 v[242:245], v[126:127], off
	s_waitcnt vmcnt(3) lgkmcnt(0)
	v_pk_add_f32 v[232:233], v[232:233], 1.0 op_sel_hi:[1,0]
	v_pk_add_f32 v[230:231], v[230:231], 1.0 op_sel_hi:[1,0]
	v_pk_fma_f32 v[232:233], v[232:233], v[64:65], v[236:237]
	v_pk_fma_f32 v[230:231], v[230:231], v[62:63], v[234:235]
	v_cvt_pk_bf16_f32 v230, v230, v231
	v_cvt_pk_bf16_f32 v231, v232, v233
	global_store_dwordx2 v[102:103], v[230:231], off offset:2048
	global_load_dwordx4 v[230:233], v[122:123], off
	s_nop 0
	global_load_dwordx4 v[234:237], v[118:119], off
	s_waitcnt vmcnt(3) lgkmcnt(0)
	v_pk_add_f32 v[240:241], v[240:241], 1.0 op_sel_hi:[1,0]
	v_pk_add_f32 v[238:239], v[238:239], 1.0 op_sel_hi:[1,0]
	v_pk_fma_f32 v[240:241], v[240:241], v[60:61], v[244:245]
	v_pk_fma_f32 v[238:239], v[238:239], v[58:59], v[242:243]
	v_cvt_pk_bf16_f32 v238, v238, v239
	v_cvt_pk_bf16_f32 v239, v240, v241
	global_store_dwordx2 v[102:103], v[238:239], off offset:2560
	v_pk_add_f32 v[58:59], v[164:165], v[164:165] op_sel:[0,1] op_sel_hi:[1,0]
	v_pk_add_f32 v[60:61], v[158:159], v[160:161]
	v_mov_b32_e32 v59, v215
	global_load_dwordx4 v[238:241], v[116:117], off
	s_nop 0
	global_load_dwordx4 v[242:245], v[114:115], off
	s_waitcnt vmcnt(3) lgkmcnt(0)
	v_pk_add_f32 v[232:233], v[232:233], 1.0 op_sel_hi:[1,0]
	v_pk_add_f32 v[230:231], v[230:231], 1.0 op_sel_hi:[1,0]
	v_pk_fma_f32 v[232:233], v[232:233], v[56:57], v[236:237]
	v_pk_fma_f32 v[230:231], v[230:231], v[82:83], v[234:235]
	v_cvt_pk_bf16_f32 v230, v230, v231
	v_cvt_pk_bf16_f32 v231, v232, v233
	global_store_dwordx2 v[102:103], v[230:231], off offset:3072
	v_pk_add_f32 v[56:57], v[162:163], v[162:163] op_sel:[0,1] op_sel_hi:[1,0]
	global_load_dwordx4 v[230:233], v[156:157], off
	s_nop 0
	global_load_dwordx4 v[234:237], v[112:113], off
	s_waitcnt vmcnt(3) lgkmcnt(0)
	v_pk_add_f32 v[240:241], v[240:241], 1.0 op_sel_hi:[1,0]
	v_pk_add_f32 v[238:239], v[238:239], 1.0 op_sel_hi:[1,0]
	v_pk_fma_f32 v[240:241], v[86:87], v[240:241], v[244:245]
	v_pk_fma_f32 v[238:239], v[84:85], v[238:239], v[242:243]
	v_cvt_pk_bf16_f32 v238, v238, v239
	v_cvt_pk_bf16_f32 v239, v240, v241
	global_store_dwordx2 v[102:103], v[238:239], off offset:3584
	v_mov_b32_e32 v57, v214
	global_load_dwordx4 v[238:241], v[154:155], off
	s_nop 0
	global_load_dwordx4 v[242:245], v[106:107], off
	s_waitcnt vmcnt(3) lgkmcnt(0)
	v_pk_add_f32 v[232:233], v[232:233], 1.0 op_sel_hi:[1,0]
	v_pk_add_f32 v[230:231], v[230:231], 1.0 op_sel_hi:[1,0]
	v_pk_fma_f32 v[232:233], v[232:233], v[174:175], v[236:237]
	v_pk_fma_f32 v[230:231], v[230:231], v[88:89], v[234:235]
	v_bfe_u32 v51, v230, 16, 1
	v_bfe_u32 v234, v231, 16, 1
	v_add3_u32 v230, v230, v51, s22
	v_add3_u32 v231, v231, v234, s22
	v_lshrrev_b32_e32 v230, 16, v230
	v_and_or_b32 v230, v231, s23, v230
	v_cvt_pk_bf16_f32 v231, v232, v233
	global_store_dwordx2 v[104:105], v[230:231], off
	v_pk_mul_f32 v[44:45], v[44:45], v[50:51] op_sel_hi:[1,0]
	v_pk_mul_f32 v[42:43], v[42:43], v[50:51] op_sel_hi:[1,0]
	v_pk_mul_f32 v[44:45], v[8:9], v[44:45]
	v_pk_mul_f32 v[42:43], v[6:7], v[42:43]
	s_waitcnt vmcnt(1) lgkmcnt(0)
	v_pk_add_f32 v[240:241], v[240:241], 1.0 op_sel_hi:[1,0]
	v_pk_add_f32 v[238:239], v[238:239], 1.0 op_sel_hi:[1,0]
	v_pk_fma_f32 v[44:45], v[240:241], v[44:45], v[244:245]
	v_pk_fma_f32 v[42:43], v[238:239], v[42:43], v[242:243]
	v_cvt_pk_bf16_f32 v42, v42, v43
	v_cvt_pk_bf16_f32 v43, v44, v45
	global_store_dwordx2 v[104:105], v[42:43], off offset:512
	global_load_dwordx4 v[42:45], v[150:151], off
	s_nop 0
	global_load_dwordx4 v[46:49], v[110:111], off
	v_pk_add_f32 v[52:53], v[56:57], v[58:59]
	s_waitcnt vmcnt(0) lgkmcnt(0)
	v_pk_add_f32 v[44:45], v[44:45], 1.0 op_sel_hi:[1,0]
	v_pk_add_f32 v[52:53], v[52:53], v[60:61]
	v_pk_add_f32 v[42:43], v[42:43], 1.0 op_sel_hi:[1,0]
	v_add_f32_e32 v51, v52, v53
	ds_bpermute_b32 v52, v1, v51
	s_waitcnt lgkmcnt(0)
	v_add_f32_e32 v51, v51, v52
	ds_bpermute_b32 v52, v167, v51
	s_waitcnt lgkmcnt(0)
	v_add_f32_e32 v51, v51, v52
	v_pk_mul_f32 v[40:41], v[40:41], v[50:51] op_sel_hi:[1,0]
	v_pk_mul_f32 v[38:39], v[38:39], v[50:51] op_sel_hi:[1,0]
	v_pk_mul_f32 v[40:41], v[12:13], v[40:41]
	v_pk_mul_f32 v[38:39], v[10:11], v[38:39]
	v_pk_fma_f32 v[40:41], v[44:45], v[40:41], v[48:49]
	v_pk_fma_f32 v[38:39], v[42:43], v[38:39], v[46:47]
	v_cvt_pk_bf16_f32 v38, v38, v39
	v_cvt_pk_bf16_f32 v39, v40, v41
	global_store_dwordx2 v[104:105], v[38:39], off offset:1024
	global_load_dwordx4 v[38:41], v[136:137], off
	s_nop 0
	global_load_dwordx4 v[42:45], v[108:109], off
	v_pk_mul_f32 v[36:37], v[36:37], v[50:51] op_sel_hi:[1,0]
	v_pk_mul_f32 v[34:35], v[34:35], v[50:51] op_sel_hi:[1,0]
	v_pk_mul_f32 v[36:37], v[16:17], v[36:37]
	v_pk_mul_f32 v[34:35], v[14:15], v[34:35]
	ds_bpermute_b32 v46, v168, v51
	s_waitcnt lgkmcnt(0)
	v_add_f32_e32 v46, v51, v46
	ds_bpermute_b32 v47, v169, v46
	s_waitcnt lgkmcnt(0)
	v_add_f32_e32 v46, v46, v47
	ds_bpermute_b32 v47, v170, v46
	s_waitcnt lgkmcnt(0)
	v_add_f32_e32 v46, v46, v47
	ds_bpermute_b32 v47, v171, v46
	s_waitcnt lgkmcnt(0)
	v_add_f32_e32 v46, v46, v47
	v_fmamk_f32 v46, v46, 0x3a800000, v172
	v_mul_f32_e32 v47, 0x4f800000, v46
	v_cmp_gt_f32_e32 vcc, s13, v46
	s_waitcnt vmcnt(0)
	v_pk_add_f32 v[40:41], v[40:41], 1.0 op_sel_hi:[1,0]
	v_pk_add_f32 v[38:39], v[38:39], 1.0 op_sel_hi:[1,0]
	v_pk_fma_f32 v[36:37], v[36:37], v[40:41], v[44:45]
	v_pk_fma_f32 v[34:35], v[34:35], v[38:39], v[42:43]
	v_cvt_pk_bf16_f32 v34, v34, v35
	v_cvt_pk_bf16_f32 v35, v36, v37
	global_store_dwordx2 v[104:105], v[34:35], off offset:1536
	global_load_dwordx4 v[34:37], v[144:145], off
	s_nop 0
	global_load_dwordx4 v[38:41], v[128:129], off
	v_cndmask_b32_e32 v42, v46, v47, vcc
	v_sqrt_f32_e32 v43, v42
	s_waitcnt vmcnt(0) lgkmcnt(0)
	v_pk_add_f32 v[36:37], v[36:37], 1.0 op_sel_hi:[1,0]
	v_add_u32_e32 v44, -1, v43
	v_add_u32_e32 v45, 1, v43
	v_fma_f32 v46, -v44, v43, v42
	v_fma_f32 v47, -v45, v43, v42
	v_cmp_ge_f32_e64 s[6:7], 0, v46
	v_pk_add_f32 v[34:35], v[34:35], 1.0 op_sel_hi:[1,0]
	s_nop 0
	v_cndmask_b32_e64 v43, v43, v44, s[6:7]
	v_cmp_lt_f32_e64 s[6:7], 0, v47
	s_nop 1
	v_cndmask_b32_e64 v43, v43, v45, s[6:7]
	v_mul_f32_e32 v44, 0x37800000, v43
	v_cndmask_b32_e32 v43, v43, v44, vcc
	v_cmp_class_f32_e32 vcc, v42, v173
	s_nop 1
	v_cndmask_b32_e32 v42, v43, v42, vcc
	v_div_scale_f32 v43, s[6:7], v42, v42, 1.0
	v_rcp_f32_e32 v45, v43
	v_div_scale_f32 v44, vcc, 1.0, v42, 1.0
	v_fma_f32 v46, -v43, v45, 1.0
	v_fmac_f32_e32 v45, v46, v45
	v_mul_f32_e32 v46, v44, v45
	v_fma_f32 v47, -v43, v46, v44
	v_fmac_f32_e32 v46, v47, v45
	v_fma_f32 v43, -v43, v46, v44
	v_div_fmas_f32 v43, v43, v45, v46
	v_div_fixup_f32 v42, v43, v42, 1.0
	v_pk_mul_f32 v[32:33], v[32:33], v[42:43] op_sel_hi:[1,0]
	v_pk_mul_f32 v[30:31], v[30:31], v[42:43] op_sel_hi:[1,0]
	v_pk_mul_f32 v[32:33], v[4:5], v[32:33]
	v_pk_mul_f32 v[30:31], v[2:3], v[30:31]
	v_pk_fma_f32 v[32:33], v[36:37], v[32:33], v[40:41]
	v_pk_fma_f32 v[30:31], v[34:35], v[30:31], v[38:39]
	v_cvt_pk_bf16_f32 v30, v30, v31
	v_cvt_pk_bf16_f32 v31, v32, v33
	global_store_dwordx2 v[104:105], v[30:31], off offset:2048
	global_load_dwordx4 v[30:33], v[124:125], off
	s_nop 0
	global_load_dwordx4 v[34:37], v[120:121], off
	v_pk_mul_f32 v[28:29], v[28:29], v[42:43] op_sel_hi:[1,0]
	v_pk_mul_f32 v[26:27], v[26:27], v[42:43] op_sel_hi:[1,0]
	v_pk_mul_f32 v[28:29], v[8:9], v[28:29]
	v_pk_mul_f32 v[26:27], v[6:7], v[26:27]
	v_lshl_add_u64 v[40:41], s[20:21], 0, v[98:99]
	v_lshl_add_u64 v[38:39], s[18:19], 0, v[98:99]
	v_pk_mul_f32 v[24:25], v[24:25], v[42:43] op_sel_hi:[1,0]
	v_pk_mul_f32 v[22:23], v[22:23], v[42:43] op_sel_hi:[1,0]
	v_pk_mul_f32 v[24:25], v[12:13], v[24:25]
	v_pk_mul_f32 v[22:23], v[10:11], v[22:23]
	v_pk_mul_f32 v[20:21], v[20:21], v[42:43] op_sel_hi:[1,0]
	v_pk_mul_f32 v[18:19], v[18:19], v[42:43] op_sel_hi:[1,0]
	v_pk_mul_f32 v[20:21], v[16:17], v[20:21]
	v_pk_mul_f32 v[18:19], v[14:15], v[18:19]
	s_waitcnt vmcnt(0) lgkmcnt(0)
	v_pk_add_f32 v[32:33], v[32:33], 1.0 op_sel_hi:[1,0]
	v_pk_add_f32 v[30:31], v[30:31], 1.0 op_sel_hi:[1,0]
	v_pk_fma_f32 v[28:29], v[32:33], v[28:29], v[36:37]
	v_pk_fma_f32 v[26:27], v[30:31], v[26:27], v[34:35]
	v_cvt_pk_bf16_f32 v26, v26, v27
	v_cvt_pk_bf16_f32 v27, v28, v29
	global_store_dwordx2 v[104:105], v[26:27], off offset:2560
	global_load_dwordx4 v[26:29], v[40:41], off
	s_nop 0
	global_load_dwordx4 v[30:33], v[38:39], off
	v_lshl_add_u64 v[36:37], s[20:21], 0, v[100:101]
	v_lshl_add_u64 v[34:35], s[18:19], 0, v[100:101]
	s_waitcnt vmcnt(0) lgkmcnt(0)
	v_pk_add_f32 v[28:29], v[28:29], 1.0 op_sel_hi:[1,0]
	v_pk_add_f32 v[26:27], v[26:27], 1.0 op_sel_hi:[1,0]
	v_pk_fma_f32 v[24:25], v[28:29], v[24:25], v[32:33]
	v_pk_fma_f32 v[22:23], v[26:27], v[22:23], v[30:31]
	v_cvt_pk_bf16_f32 v22, v22, v23
	v_cvt_pk_bf16_f32 v23, v24, v25
	global_store_dwordx2 v[104:105], v[22:23], off offset:3072
	global_load_dwordx4 v[22:25], v[36:37], off
	s_nop 0
	global_load_dwordx4 v[26:29], v[34:35], off
	s_waitcnt vmcnt(0) lgkmcnt(0)
	v_pk_add_f32 v[24:25], v[24:25], 1.0 op_sel_hi:[1,0]
	v_pk_add_f32 v[22:23], v[22:23], 1.0 op_sel_hi:[1,0]
	v_pk_fma_f32 v[20:21], v[20:21], v[24:25], v[28:29]
	v_pk_fma_f32 v[18:19], v[18:19], v[22:23], v[26:27]
	v_cvt_pk_bf16_f32 v18, v18, v19
	v_cvt_pk_bf16_f32 v19, v20, v21
	global_store_dwordx2 v[104:105], v[18:19], off offset:3584
	s_cbranch_scc1 .LBB0_2937

.LBB0_3086:
	v_lshl_add_u64 v[18:19], s[68:69], 0, v[94:95]
	v_lshl_add_u64 v[22:23], s[68:69], 0, v[92:93]
	v_add_co_u32_e32 v20, vcc, 0x7800000, v18
	v_add_co_u32_e64 v102, s[6:7], s22, v22
	s_nop 0
	v_addc_co_u32_e32 v21, vcc, 0, v19, vcc
	v_addc_co_u32_e64 v103, s[6:7], 0, v23, s[6:7]
	v_add_co_u32_e64 v104, s[6:7], s23, v22
	v_add_co_u32_e32 v22, vcc, 0x7801000, v18
	s_nop 0
	v_addc_co_u32_e64 v105, s[6:7], 0, v23, s[6:7]
	global_load_dwordx4 v[78:81], v[20:21], off
	global_load_dwordx4 v[74:77], v[20:21], off offset:1024
	global_load_dwordx4 v[70:73], v[20:21], off offset:2048
	global_load_dwordx4 v[66:69], v[20:21], off offset:3072
	v_addc_co_u32_e32 v23, vcc, 0, v19, vcc
	v_add_co_u32_e32 v20, vcc, 0x7802000, v18
	global_load_dwordx4 v[62:65], v[22:23], off
	global_load_dwordx4 v[58:61], v[22:23], off offset:1024
	global_load_dwordx4 v[54:57], v[22:23], off offset:2048
	global_load_dwordx4 v[50:53], v[22:23], off offset:3072
	v_addc_co_u32_e32 v21, vcc, 0, v19, vcc
	v_add_co_u32_e32 v82, vcc, 0x7803000, v18
	global_load_dwordx4 v[46:49], v[20:21], off
	global_load_dwordx4 v[42:45], v[20:21], off offset:1024
	global_load_dwordx4 v[38:41], v[20:21], off offset:2048
	global_load_dwordx4 v[34:37], v[20:21], off offset:3072
	v_addc_co_u32_e32 v83, vcc, 0, v19, vcc
	global_load_dwordx4 v[30:33], v[82:83], off
	global_load_dwordx4 v[26:29], v[82:83], off offset:1024
	global_load_dwordx4 v[22:25], v[82:83], off offset:2048
	global_load_dwordx4 v[18:21], v[82:83], off offset:3072
	s_add_i32 s24, s8, 32
	s_add_i32 s10, s8, 0xffffc022
	s_ashr_i32 s9, s24, 13
	s_cmpk_lt_i32 s24, 0x4000
	s_cselect_b32 s6, s9, s10
	s_mul_hi_i32 s7, s6, 0x9000
	s_mul_i32 s6, s6, 0x9000
	s_add_u32 s10, s4, s6
	s_addc_u32 s11, s5, s7
	s_add_u32 s6, s10, 0x6000
	s_addc_u32 s7, s11, 0
	s_add_u32 s10, s10, 0x7000
	s_addc_u32 s11, s11, 0
	v_lshl_add_u64 v[82:83], s[6:7], 0, v[90:91]
	v_lshl_add_u64 v[86:87], s[10:11], 0, v[90:91]
	global_load_dwordx4 v[82:85], v[82:83], off
	v_lshl_add_u64 v[148:149], s[6:7], 0, v[96:97]
	global_load_dwordx4 v[86:89], v[86:87], off
	v_lshl_add_u64 v[142:143], s[6:7], 0, v[98:99]
	v_lshl_add_u64 v[134:135], s[6:7], 0, v[100:101]
	s_add_i32 s6, s8, 0xffffc023
	s_cmpk_lt_i32 s24, 0x3fff
	s_cselect_b32 s6, s9, s6
	s_mul_hi_i32 s7, s6, 0x9000
	s_mul_i32 s6, s6, 0x9000
	v_lshl_add_u64 v[152:153], s[10:11], 0, v[96:97]
	v_lshl_add_u64 v[146:147], s[10:11], 0, v[98:99]
	v_lshl_add_u64 v[140:141], s[10:11], 0, v[100:101]
	s_add_u32 s10, s4, s6
	s_addc_u32 s11, s5, s7
	s_add_u32 s6, s10, 0x6000
	s_addc_u32 s7, s11, 0
	s_add_u32 s10, s10, 0x7000
	v_lshl_add_u64 v[132:133], s[6:7], 0, v[90:91]
	v_lshl_add_u64 v[126:127], s[6:7], 0, v[96:97]
	v_lshl_add_u64 v[118:119], s[6:7], 0, v[98:99]
	v_lshl_add_u64 v[114:115], s[6:7], 0, v[100:101]
	s_addc_u32 s11, s11, 0
	s_add_i32 s6, s8, 0xffffc024
	s_cmpk_lt_i32 s24, 0x3ffe
	s_cselect_b32 s6, s9, s6
	s_mul_hi_i32 s7, s6, 0x9000
	s_mul_i32 s6, s6, 0x9000
	s_add_u32 s6, s4, s6
	s_addc_u32 s7, s5, s7
	v_lshl_add_u64 v[138:139], s[10:11], 0, v[90:91]
	v_lshl_add_u64 v[130:131], s[10:11], 0, v[96:97]
	v_lshl_add_u64 v[124:125], s[10:11], 0, v[98:99]
	v_lshl_add_u64 v[116:117], s[10:11], 0, v[100:101]
	s_add_u32 s10, s6, 0x6000
	s_addc_u32 s11, s7, 0
	s_add_u32 s6, s6, 0x7000
	s_addc_u32 s7, s7, 0
	s_addk_i32 s8, 0xc025
	s_cmpk_lt_i32 s24, 0x3ffd
	v_lshl_add_u64 v[156:157], s[6:7], 0, v[90:91]
	v_lshl_add_u64 v[154:155], s[6:7], 0, v[96:97]
	v_lshl_add_u64 v[150:151], s[6:7], 0, v[98:99]
	v_lshl_add_u64 v[136:137], s[6:7], 0, v[100:101]
	s_cselect_b32 s6, s9, s8
	s_mul_hi_i32 s7, s6, 0x9000
	s_mul_i32 s6, s6, 0x9000
	s_add_u32 s6, s4, s6
	s_waitcnt vmcnt(0) lgkmcnt(0)
	v_pk_mul_f32 v[158:159], v[80:81], v[80:81]
	v_pk_mul_f32 v[160:161], v[78:79], v[78:79]
	v_pk_mul_f32 v[162:163], v[76:77], v[76:77]
	v_pk_mul_f32 v[164:165], v[74:75], v[74:75]
	v_mul_f32_e32 v174, v71, v71
	v_mul_f32_e32 v176, v73, v73
	v_mul_f32_e32 v187, v68, v68
	v_mul_f32_e32 v189, v69, v69
	v_pk_mov_b32 v[178:179], v[160:161], v[158:159] op_sel:[1,0]
	v_mov_b32_e32 v161, v159
	v_pk_mov_b32 v[158:159], v[164:165], v[162:163] op_sel:[1,0]
	v_mov_b32_e32 v165, v163
	v_pk_fma_f32 v[162:163], v[70:71], v[70:71], v[174:175] op_sel_hi:[1,1,0]
	v_pk_fma_f32 v[174:175], v[72:73], v[72:73], v[176:177] op_sel_hi:[1,1,0]
	v_pk_mul_f32 v[176:177], v[64:65], v[64:65]
	v_pk_mul_f32 v[180:181], v[62:63], v[62:63]
	v_pk_mul_f32 v[182:183], v[60:61], v[60:61]
	v_pk_mul_f32 v[184:185], v[58:59], v[58:59]
	v_mul_f32_e32 v186, v55, v55
	v_mul_f32_e32 v188, v57, v57
	v_pk_add_f32 v[160:161], v[178:179], v[160:161]
	v_pk_add_f32 v[158:159], v[158:159], v[164:165]
	v_mov_b32_e32 v163, v187
	v_mov_b32_e32 v175, v189
	v_pk_mov_b32 v[164:165], v[180:181], v[176:177] op_sel:[1,0]
	v_mov_b32_e32 v181, v177
	v_pk_mov_b32 v[176:177], v[184:185], v[182:183] op_sel:[1,0]
	v_mov_b32_e32 v185, v183
	v_pk_fma_f32 v[178:179], v[54:55], v[54:55], v[186:187] op_sel_hi:[1,1,0]
	v_pk_fma_f32 v[182:183], v[56:57], v[56:57], v[188:189] op_sel_hi:[1,1,0]
	v_pk_mul_f32 v[186:187], v[48:49], v[48:49]
	v_pk_mul_f32 v[188:189], v[46:47], v[46:47]
	v_pk_mul_f32 v[190:191], v[44:45], v[44:45]
	v_pk_mul_f32 v[192:193], v[42:43], v[42:43]
	v_mul_f32_e32 v173, v66, v66
	v_mul_f32_e32 v197, v67, v67
	v_mul_f32_e32 v195, v52, v52
	v_mul_f32_e32 v202, v53, v53
	v_mul_f32_e32 v194, v39, v39
	v_mul_f32_e32 v196, v41, v41
	v_pk_add_f32 v[198:199], v[160:161], v[160:161] op_sel:[0,1] op_sel_hi:[1,0]
	v_pk_add_f32 v[200:201], v[158:159], v[158:159] op_sel:[0,1] op_sel_hi:[1,0]
	v_pk_add_f32 v[174:175], v[162:163], v[174:175]
	v_pk_add_f32 v[158:159], v[164:165], v[180:181]
	v_pk_add_f32 v[160:161], v[176:177], v[184:185]
	v_pk_mov_b32 v[162:163], v[188:189], v[186:187] op_sel:[1,0]
	v_mov_b32_e32 v189, v187
	v_pk_mov_b32 v[164:165], v[192:193], v[190:191] op_sel:[1,0]
	v_mov_b32_e32 v193, v191
	v_mul_f32_e32 v203, v50, v50
	v_mul_f32_e32 v208, v51, v51
	v_mul_f32_e32 v211, v36, v36
	v_mul_f32_e32 v212, v37, v37
	v_mov_b32_e32 v179, v195
	v_mov_b32_e32 v183, v202
	v_pk_fma_f32 v[176:177], v[38:39], v[38:39], v[194:195] op_sel_hi:[1,1,0]
	v_pk_fma_f32 v[180:181], v[40:41], v[40:41], v[196:197] op_sel_hi:[1,1,0]
	v_pk_mul_f32 v[184:185], v[32:33], v[32:33]
	v_pk_mul_f32 v[186:187], v[30:31], v[30:31]
	v_pk_mul_f32 v[190:191], v[28:29], v[28:29]
	v_pk_mul_f32 v[194:195], v[26:27], v[26:27]
	v_mov_b32_e32 v199, v173
	v_mov_b32_e32 v201, v197
	v_pk_add_f32 v[204:205], v[158:159], v[158:159] op_sel:[0,1] op_sel_hi:[1,0]
	v_pk_add_f32 v[206:207], v[160:161], v[160:161] op_sel:[0,1] op_sel_hi:[1,0]
	v_pk_add_f32 v[162:163], v[162:163], v[188:189]
	v_pk_add_f32 v[164:165], v[164:165], v[192:193]
	v_mul_f32_e32 v209, v34, v34
	v_mul_f32_e32 v210, v35, v35
	v_pk_add_f32 v[178:179], v[178:179], v[182:183]
	v_mov_b32_e32 v177, v211
	v_mov_b32_e32 v181, v212
	v_pk_mov_b32 v[182:183], v[186:187], v[184:185] op_sel:[1,0]
	v_mov_b32_e32 v187, v185
	v_pk_mov_b32 v[184:185], v[194:195], v[190:191] op_sel:[1,0]
	v_mov_b32_e32 v195, v191
	v_pk_add_f32 v[188:189], v[198:199], v[200:201]
	v_mov_b32_e32 v205, v203
	v_mov_b32_e32 v207, v208
	v_pk_add_f32 v[190:191], v[162:163], v[162:163] op_sel:[0,1] op_sel_hi:[1,0]
	v_pk_add_f32 v[192:193], v[164:165], v[164:165] op_sel:[0,1] op_sel_hi:[1,0]
	v_pk_add_f32 v[176:177], v[176:177], v[180:181]
	v_pk_add_f32 v[174:175], v[188:189], v[174:175]
	v_pk_add_f32 v[180:181], v[204:205], v[206:207]
	v_mov_b32_e32 v191, v209
	v_mov_b32_e32 v193, v210
	v_add_f32_e32 v173, v174, v175
	v_pk_add_f32 v[174:175], v[180:181], v[178:179]
	v_pk_add_f32 v[178:179], v[190:191], v[192:193]
	v_add_f32_e32 v180, v174, v175
	v_pk_add_f32 v[174:175], v[178:179], v[176:177]
	ds_bpermute_b32 v176, v1, v173
	v_add_f32_e32 v174, v174, v175
	ds_bpermute_b32 v175, v1, v180
	ds_bpermute_b32 v177, v1, v174
	s_addc_u32 s7, s5, s7
	s_waitcnt lgkmcnt(2)
	v_add_f32_e32 v173, v173, v176
	ds_bpermute_b32 v176, v166, v173
	s_waitcnt lgkmcnt(2)
	v_add_f32_e32 v175, v180, v175
	ds_bpermute_b32 v178, v166, v175
	s_waitcnt lgkmcnt(2)
	v_add_f32_e32 v174, v174, v177
	ds_bpermute_b32 v177, v166, v174
	s_waitcnt lgkmcnt(2)
	v_add_f32_e32 v173, v173, v176
	ds_bpermute_b32 v176, v167, v173
	s_waitcnt lgkmcnt(2)
	v_add_f32_e32 v175, v175, v178
	ds_bpermute_b32 v178, v167, v175
	s_waitcnt lgkmcnt(2)
	v_add_f32_e32 v174, v174, v177
	ds_bpermute_b32 v177, v167, v174
	s_waitcnt lgkmcnt(2)
	v_add_f32_e32 v173, v173, v176
	ds_bpermute_b32 v176, v168, v173
	s_waitcnt lgkmcnt(2)
	v_add_f32_e32 v175, v175, v178
	ds_bpermute_b32 v178, v168, v175
	s_waitcnt lgkmcnt(2)
	v_add_f32_e32 v174, v174, v177
	ds_bpermute_b32 v177, v168, v174
	s_waitcnt lgkmcnt(2)
	v_add_f32_e32 v173, v173, v176
	ds_bpermute_b32 v176, v169, v173
	s_waitcnt lgkmcnt(2)
	v_add_f32_e32 v175, v175, v178
	ds_bpermute_b32 v178, v169, v175
	s_waitcnt lgkmcnt(2)
	v_add_f32_e32 v174, v174, v177
	ds_bpermute_b32 v177, v169, v174
	s_waitcnt lgkmcnt(2)
	v_add_f32_e32 v173, v173, v176
	ds_bpermute_b32 v176, v170, v173
	s_waitcnt lgkmcnt(2)
	v_add_f32_e32 v175, v175, v178
	ds_bpermute_b32 v178, v170, v175
	s_waitcnt lgkmcnt(2)
	v_add_f32_e32 v174, v174, v177
	ds_bpermute_b32 v177, v170, v174
	s_waitcnt lgkmcnt(2)
	v_add_f32_e32 v173, v173, v176
	s_add_u32 s16, s6, 0x6000
	v_fmamk_f32 v173, v173, 0x3a800000, v171
	s_addc_u32 s17, s7, 0
	s_waitcnt lgkmcnt(1)
	v_add_f32_e32 v175, v175, v178
	v_mul_f32_e32 v176, 0x4f800000, v173
	v_cmp_gt_f32_e32 vcc, s2, v173
	s_add_u32 s18, s6, 0x7000
	v_fmamk_f32 v175, v175, 0x3a800000, v171
	v_cndmask_b32_e32 v173, v173, v176, vcc
	s_addc_u32 s19, s7, 0
	s_waitcnt lgkmcnt(0)
	v_add_f32_e32 v174, v174, v177
	v_mul_f32_e32 v176, 0x4f800000, v175
	v_cmp_gt_f32_e64 s[6:7], s2, v175
	v_sqrt_f32_e32 v177, v173
	v_fmamk_f32 v174, v174, 0x3a800000, v171
	v_cndmask_b32_e64 v175, v175, v176, s[6:7]
	v_mul_f32_e32 v176, 0x4f800000, v174
	v_cmp_gt_f32_e64 s[8:9], s2, v174
	v_sqrt_f32_e32 v178, v175
	v_add_u32_e32 v179, -1, v177
	v_cndmask_b32_e64 v174, v174, v176, s[8:9]
	v_sqrt_f32_e32 v176, v174
	v_add_u32_e32 v180, 1, v177
	v_fma_f32 v181, -v179, v177, v173
	v_lshl_add_u64 v[112:113], s[10:11], 0, v[90:91]
	v_lshl_add_u64 v[106:107], s[10:11], 0, v[96:97]
	v_lshl_add_u64 v[108:109], s[10:11], 0, v[98:99]
	v_lshl_add_u64 v[110:111], s[10:11], 0, v[100:101]
	v_pk_add_f32 v[162:163], v[182:183], v[186:187]
	v_fma_f32 v182, -v180, v177, v173
	v_add_u32_e32 v183, -1, v178
	v_cmp_ge_f32_e64 s[10:11], 0, v181
	v_pk_add_f32 v[164:165], v[184:185], v[194:195]
	v_add_u32_e32 v184, 1, v178
	v_cndmask_b32_e64 v177, v177, v179, s[10:11]
	v_fma_f32 v179, -v183, v178, v175
	v_cmp_lt_f32_e64 s[10:11], 0, v182
	v_fma_f32 v181, -v184, v178, v175
	v_add_u32_e32 v185, -1, v176
	v_cndmask_b32_e64 v177, v177, v180, s[10:11]
	v_cmp_ge_f32_e64 s[10:11], 0, v179
	v_add_u32_e32 v186, 1, v176
	v_fma_f32 v179, -v185, v176, v174
	v_cndmask_b32_e64 v178, v178, v183, s[10:11]
	v_cmp_lt_f32_e64 s[10:11], 0, v181
	v_fma_f32 v180, -v186, v176, v174
	v_mul_f32_e32 v181, 0x37800000, v177
	v_cndmask_b32_e64 v178, v178, v184, s[10:11]
	v_cmp_ge_f32_e64 s[10:11], 0, v179
	v_cndmask_b32_e32 v177, v177, v181, vcc
	v_cmp_class_f32_e32 vcc, v173, v172
	v_cndmask_b32_e64 v176, v176, v185, s[10:11]
	v_cmp_lt_f32_e64 s[10:11], 0, v180
	v_mul_f32_e32 v179, 0x37800000, v178
	v_cndmask_b32_e32 v173, v177, v173, vcc
	v_cndmask_b32_e64 v176, v176, v186, s[10:11]
	v_cndmask_b32_e64 v177, v178, v179, s[6:7]
	v_cmp_class_f32_e32 vcc, v175, v172
	v_mul_f32_e32 v178, 0x37800000, v176
	v_div_scale_f32 v179, s[6:7], v173, v173, 1.0
	v_cndmask_b32_e32 v175, v177, v175, vcc
	v_cndmask_b32_e64 v176, v176, v178, s[8:9]
	v_cmp_class_f32_e32 vcc, v174, v172
	v_rcp_f32_e32 v177, v179
	v_div_scale_f32 v178, s[8:9], v175, v175, 1.0
	v_cndmask_b32_e32 v176, v176, v174, vcc
	v_rcp_f32_e32 v182, v178
	v_div_scale_f32 v183, s[10:11], v176, v176, 1.0
	v_rcp_f32_e32 v185, v183
	v_fma_f32 v174, -v179, v177, 1.0
	v_div_scale_f32 v180, s[6:7], 1.0, v173, 1.0
	v_fmac_f32_e32 v177, v174, v177
	v_fma_f32 v174, -v178, v182, 1.0
	v_mul_f32_e32 v186, v180, v177
	v_div_scale_f32 v181, s[8:9], 1.0, v175, 1.0
	v_fmac_f32_e32 v182, v174, v182
	v_fma_f32 v174, -v183, v185, 1.0
	v_fma_f32 v187, -v179, v186, v180
	v_div_scale_f32 v184, s[10:11], 1.0, v176, 1.0
	v_mul_f32_e32 v188, v181, v182
	v_fmac_f32_e32 v185, v174, v185
	v_fmac_f32_e32 v186, v187, v177
	v_fma_f32 v174, -v178, v188, v181
	v_mul_f32_e32 v187, v184, v185
	v_fma_f32 v179, -v179, v186, v180
	s_mov_b64 vcc, s[6:7]
	v_fmac_f32_e32 v188, v174, v182
	v_fma_f32 v174, -v183, v187, v184
	v_div_fmas_f32 v177, v179, v177, v186
	v_fma_f32 v178, -v178, v188, v181
	v_fmac_f32_e32 v187, v174, v185
	v_div_fixup_f32 v174, v177, v173, 1.0
	s_mov_b64 vcc, s[8:9]
	v_div_fmas_f32 v173, v178, v182, v188
	v_fma_f32 v177, -v183, v187, v184
	v_pk_mul_f32 v[80:81], v[80:81], v[174:175] op_sel_hi:[1,0]
	v_pk_mul_f32 v[78:79], v[78:79], v[174:175] op_sel_hi:[1,0]
	s_mov_b64 vcc, s[10:11]
	v_pk_add_f32 v[88:89], v[88:89], 1.0 op_sel_hi:[1,0]
	v_pk_add_f32 v[86:87], v[86:87], 1.0 op_sel_hi:[1,0]
	v_pk_mul_f32 v[76:77], v[76:77], v[174:175] op_sel_hi:[1,0]
	v_pk_mul_f32 v[74:75], v[74:75], v[174:175] op_sel_hi:[1,0]
	v_pk_mul_f32 v[72:73], v[72:73], v[174:175] op_sel_hi:[1,0]
	v_pk_mul_f32 v[70:71], v[70:71], v[174:175] op_sel_hi:[1,0]
	v_pk_mul_f32 v[68:69], v[68:69], v[174:175] op_sel_hi:[1,0]
	v_pk_mul_f32 v[66:67], v[66:67], v[174:175] op_sel_hi:[1,0]
	v_div_fixup_f32 v174, v173, v175, 1.0
	v_div_fmas_f32 v173, v177, v185, v187
	v_pk_mul_f32 v[78:79], v[2:3], v[78:79]
	v_pk_mul_f32 v[80:81], v[4:5], v[80:81]
	v_pk_mul_f32 v[64:65], v[64:65], v[174:175] op_sel_hi:[1,0]
	v_pk_mul_f32 v[62:63], v[62:63], v[174:175] op_sel_hi:[1,0]
	v_pk_mul_f32 v[60:61], v[60:61], v[174:175] op_sel_hi:[1,0]
	v_pk_mul_f32 v[58:59], v[58:59], v[174:175] op_sel_hi:[1,0]
	v_pk_mul_f32 v[56:57], v[56:57], v[174:175] op_sel_hi:[1,0]
	v_pk_mul_f32 v[54:55], v[54:55], v[174:175] op_sel_hi:[1,0]
	v_pk_mul_f32 v[52:53], v[52:53], v[174:175] op_sel_hi:[1,0]
	v_pk_mul_f32 v[174:175], v[50:51], v[174:175] op_sel_hi:[1,0]
	v_div_fixup_f32 v50, v173, v176, 1.0
	v_pk_fma_f32 v[80:81], v[88:89], v[80:81], v[84:85]
	v_pk_fma_f32 v[78:79], v[86:87], v[78:79], v[82:83]
	v_pk_mul_f32 v[86:87], v[16:17], v[52:53]
	v_pk_mul_f32 v[48:49], v[48:49], v[50:51] op_sel_hi:[1,0]
	v_pk_mul_f32 v[46:47], v[46:47], v[50:51] op_sel_hi:[1,0]
	v_pk_mul_f32 v[82:83], v[10:11], v[54:55]
	v_pk_mul_f32 v[84:85], v[14:15], v[174:175]
	v_pk_mul_f32 v[88:89], v[2:3], v[46:47]
	v_pk_mul_f32 v[174:175], v[4:5], v[48:49]
	v_cvt_pk_bf16_f32 v46, v78, v79
	v_cvt_pk_bf16_f32 v47, v80, v81
	global_store_dwordx2 v[102:103], v[46:47], off
	global_load_dwordx4 v[238:241], v[152:153], off
	s_nop 0
	global_load_dwordx4 v[242:245], v[148:149], off
	v_pk_mul_f32 v[74:75], v[6:7], v[74:75]
	v_pk_mul_f32 v[76:77], v[8:9], v[76:77]
	v_pk_mul_f32 v[70:71], v[10:11], v[70:71]
	v_pk_mul_f32 v[72:73], v[12:13], v[72:73]
	v_pk_mul_f32 v[66:67], v[66:67], v[14:15]
	v_pk_mul_f32 v[68:69], v[68:69], v[16:17]
	v_pk_mul_f32 v[62:63], v[2:3], v[62:63]
	v_pk_mul_f32 v[64:65], v[4:5], v[64:65]
	v_pk_mul_f32 v[58:59], v[6:7], v[58:59]
	v_pk_mul_f32 v[60:61], v[8:9], v[60:61]
	v_pk_mul_f32 v[56:57], v[12:13], v[56:57]
	v_mul_f32_e32 v196, v23, v23
	v_mul_f32_e32 v202, v25, v25
	v_mul_f32_e32 v213, v18, v18
	v_mul_f32_e32 v214, v19, v19
	v_mul_f32_e32 v215, v20, v20
	v_mul_f32_e32 v216, v21, v21
	v_pk_fma_f32 v[158:159], v[22:23], v[22:23], v[196:197] op_sel_hi:[1,1,0]
	v_pk_fma_f32 v[160:161], v[24:25], v[24:25], v[202:203] op_sel_hi:[1,1,0]
	v_mov_b32_e32 v159, v215
	v_mov_b32_e32 v161, v216
	v_lshl_add_u64 v[144:145], s[18:19], 0, v[90:91]
	v_lshl_add_u64 v[128:129], s[16:17], 0, v[90:91]
	v_lshl_add_u64 v[122:123], s[18:19], 0, v[96:97]
	v_lshl_add_u64 v[120:121], s[16:17], 0, v[96:97]
	v_lshl_add_u64 v[92:93], v[92:93], 0, s[12:13]
	v_lshl_add_u64 v[94:95], v[94:95], 0, s[14:15]
	s_mov_b32 s8, s24
	s_cmp_lt_i32 s24, s20
	global_load_dwordx4 v[230:233], v[146:147], off
	s_nop 0
	global_load_dwordx4 v[234:237], v[142:143], off
	s_waitcnt vmcnt(2) lgkmcnt(0)
	v_pk_add_f32 v[240:241], v[240:241], 1.0 op_sel_hi:[1,0]
	v_pk_add_f32 v[238:239], v[238:239], 1.0 op_sel_hi:[1,0]
	v_pk_fma_f32 v[240:241], v[240:241], v[76:77], v[244:245]
	v_pk_fma_f32 v[238:239], v[238:239], v[74:75], v[242:243]
	v_cvt_pk_bf16_f32 v238, v238, v239
	v_cvt_pk_bf16_f32 v239, v240, v241
	global_store_dwordx2 v[102:103], v[238:239], off offset:512
	global_load_dwordx4 v[238:241], v[140:141], off
	s_nop 0
	global_load_dwordx4 v[242:245], v[134:135], off
	s_waitcnt vmcnt(3) lgkmcnt(0)
	v_pk_add_f32 v[232:233], v[232:233], 1.0 op_sel_hi:[1,0]
	v_pk_add_f32 v[230:231], v[230:231], 1.0 op_sel_hi:[1,0]
	v_pk_fma_f32 v[232:233], v[72:73], v[232:233], v[236:237]
	v_pk_fma_f32 v[230:231], v[70:71], v[230:231], v[234:235]
	v_cvt_pk_bf16_f32 v230, v230, v231
	v_cvt_pk_bf16_f32 v231, v232, v233
	global_store_dwordx2 v[102:103], v[230:231], off offset:1024
	global_load_dwordx4 v[230:233], v[138:139], off
	s_nop 0
	global_load_dwordx4 v[234:237], v[132:133], off
	s_waitcnt vmcnt(3) lgkmcnt(0)
	v_pk_add_f32 v[240:241], v[240:241], 1.0 op_sel_hi:[1,0]
	v_pk_add_f32 v[238:239], v[238:239], 1.0 op_sel_hi:[1,0]
	v_pk_fma_f32 v[240:241], v[68:69], v[240:241], v[244:245]
	v_pk_fma_f32 v[238:239], v[66:67], v[238:239], v[242:243]
	v_cvt_pk_bf16_f32 v238, v238, v239
	v_cvt_pk_bf16_f32 v239, v240, v241
	global_store_dwordx2 v[102:103], v[238:239], off offset:1536
	global_load_dwordx4 v[238:241], v[130:131], off
	s_nop 0
	global_load_dwordx4 v[242:245], v[126:127], off
	s_waitcnt vmcnt(3) lgkmcnt(0)
	v_pk_add_f32 v[232:233], v[232:233], 1.0 op_sel_hi:[1,0]
	v_pk_add_f32 v[230:231], v[230:231], 1.0 op_sel_hi:[1,0]
	v_pk_fma_f32 v[232:233], v[232:233], v[64:65], v[236:237]
	v_pk_fma_f32 v[230:231], v[230:231], v[62:63], v[234:235]
	v_cvt_pk_bf16_f32 v230, v230, v231
	v_cvt_pk_bf16_f32 v231, v232, v233
	global_store_dwordx2 v[102:103], v[230:231], off offset:2048
	global_load_dwordx4 v[230:233], v[124:125], off
	s_nop 0
	global_load_dwordx4 v[234:237], v[118:119], off
	s_waitcnt vmcnt(3) lgkmcnt(0)
	v_pk_add_f32 v[240:241], v[240:241], 1.0 op_sel_hi:[1,0]
	v_pk_add_f32 v[238:239], v[238:239], 1.0 op_sel_hi:[1,0]
	v_pk_fma_f32 v[240:241], v[240:241], v[60:61], v[244:245]
	v_pk_fma_f32 v[238:239], v[238:239], v[58:59], v[242:243]
	v_cvt_pk_bf16_f32 v238, v238, v239
	v_cvt_pk_bf16_f32 v239, v240, v241
	global_store_dwordx2 v[102:103], v[238:239], off offset:2560
	v_pk_add_f32 v[58:59], v[164:165], v[164:165] op_sel:[0,1] op_sel_hi:[1,0]
	v_pk_add_f32 v[60:61], v[158:159], v[160:161]
	v_mov_b32_e32 v59, v214
	global_load_dwordx4 v[238:241], v[116:117], off
	s_nop 0
	global_load_dwordx4 v[242:245], v[114:115], off
	s_waitcnt vmcnt(3) lgkmcnt(0)
	v_pk_add_f32 v[232:233], v[232:233], 1.0 op_sel_hi:[1,0]
	v_pk_add_f32 v[230:231], v[230:231], 1.0 op_sel_hi:[1,0]
	v_pk_fma_f32 v[232:233], v[232:233], v[56:57], v[236:237]
	v_pk_fma_f32 v[230:231], v[230:231], v[82:83], v[234:235]
	v_cvt_pk_bf16_f32 v230, v230, v231
	v_cvt_pk_bf16_f32 v231, v232, v233
	global_store_dwordx2 v[102:103], v[230:231], off offset:3072
	v_pk_add_f32 v[56:57], v[162:163], v[162:163] op_sel:[0,1] op_sel_hi:[1,0]
	global_load_dwordx4 v[230:233], v[156:157], off
	s_nop 0
	global_load_dwordx4 v[234:237], v[112:113], off
	s_waitcnt vmcnt(3) lgkmcnt(0)
	v_pk_add_f32 v[240:241], v[240:241], 1.0 op_sel_hi:[1,0]
	v_pk_add_f32 v[238:239], v[238:239], 1.0 op_sel_hi:[1,0]
	v_pk_fma_f32 v[240:241], v[86:87], v[240:241], v[244:245]
	v_pk_fma_f32 v[238:239], v[84:85], v[238:239], v[242:243]
	v_cvt_pk_bf16_f32 v238, v238, v239
	v_cvt_pk_bf16_f32 v239, v240, v241
	global_store_dwordx2 v[102:103], v[238:239], off offset:3584
	v_mov_b32_e32 v57, v213
	global_load_dwordx4 v[238:241], v[154:155], off
	s_nop 0
	global_load_dwordx4 v[242:245], v[106:107], off
	s_waitcnt vmcnt(3) lgkmcnt(0)
	v_pk_add_f32 v[232:233], v[232:233], 1.0 op_sel_hi:[1,0]
	v_pk_add_f32 v[230:231], v[230:231], 1.0 op_sel_hi:[1,0]
	v_pk_fma_f32 v[232:233], v[232:233], v[174:175], v[236:237]
	v_pk_fma_f32 v[230:231], v[230:231], v[88:89], v[234:235]
	v_bfe_u32 v51, v230, 16, 1
	v_bfe_u32 v234, v231, 16, 1
	v_add3_u32 v230, v230, v51, s3
	v_add3_u32 v231, v231, v234, s3
	v_lshrrev_b32_e32 v230, 16, v230
	v_and_or_b32 v230, v231, s21, v230
	v_cvt_pk_bf16_f32 v231, v232, v233
	global_store_dwordx2 v[104:105], v[230:231], off
	v_pk_mul_f32 v[44:45], v[44:45], v[50:51] op_sel_hi:[1,0]
	v_pk_mul_f32 v[42:43], v[42:43], v[50:51] op_sel_hi:[1,0]
	v_pk_mul_f32 v[44:45], v[8:9], v[44:45]
	v_pk_mul_f32 v[42:43], v[6:7], v[42:43]
	s_waitcnt vmcnt(1) lgkmcnt(0)
	v_pk_add_f32 v[240:241], v[240:241], 1.0 op_sel_hi:[1,0]
	v_pk_add_f32 v[238:239], v[238:239], 1.0 op_sel_hi:[1,0]
	v_pk_fma_f32 v[44:45], v[240:241], v[44:45], v[244:245]
	v_pk_fma_f32 v[42:43], v[238:239], v[42:43], v[242:243]
	v_cvt_pk_bf16_f32 v42, v42, v43
	v_cvt_pk_bf16_f32 v43, v44, v45
	global_store_dwordx2 v[104:105], v[42:43], off offset:512
	global_load_dwordx4 v[42:45], v[150:151], off
	s_nop 0
	global_load_dwordx4 v[46:49], v[108:109], off
	v_pk_add_f32 v[52:53], v[56:57], v[58:59]
	s_waitcnt vmcnt(0) lgkmcnt(0)
	v_pk_add_f32 v[44:45], v[44:45], 1.0 op_sel_hi:[1,0]
	v_pk_add_f32 v[52:53], v[52:53], v[60:61]
	v_pk_add_f32 v[42:43], v[42:43], 1.0 op_sel_hi:[1,0]
	v_add_f32_e32 v51, v52, v53
	ds_bpermute_b32 v52, v1, v51
	s_waitcnt lgkmcnt(0)
	v_add_f32_e32 v51, v51, v52
	ds_bpermute_b32 v52, v166, v51
	s_waitcnt lgkmcnt(0)
	v_add_f32_e32 v51, v51, v52
	v_pk_mul_f32 v[40:41], v[40:41], v[50:51] op_sel_hi:[1,0]
	v_pk_mul_f32 v[38:39], v[38:39], v[50:51] op_sel_hi:[1,0]
	v_pk_mul_f32 v[40:41], v[12:13], v[40:41]
	v_pk_mul_f32 v[38:39], v[10:11], v[38:39]
	v_pk_fma_f32 v[40:41], v[44:45], v[40:41], v[48:49]
	v_pk_fma_f32 v[38:39], v[42:43], v[38:39], v[46:47]
	v_cvt_pk_bf16_f32 v38, v38, v39
	v_cvt_pk_bf16_f32 v39, v40, v41
	global_store_dwordx2 v[104:105], v[38:39], off offset:1024
	global_load_dwordx4 v[38:41], v[136:137], off
	s_nop 0
	global_load_dwordx4 v[42:45], v[110:111], off
	v_pk_mul_f32 v[36:37], v[36:37], v[50:51] op_sel_hi:[1,0]
	v_pk_mul_f32 v[34:35], v[34:35], v[50:51] op_sel_hi:[1,0]
	v_pk_mul_f32 v[36:37], v[16:17], v[36:37]
	v_pk_mul_f32 v[34:35], v[14:15], v[34:35]
	ds_bpermute_b32 v46, v167, v51
	s_waitcnt lgkmcnt(0)
	v_add_f32_e32 v46, v51, v46
	ds_bpermute_b32 v47, v168, v46
	s_waitcnt lgkmcnt(0)
	v_add_f32_e32 v46, v46, v47
	ds_bpermute_b32 v47, v169, v46
	s_waitcnt lgkmcnt(0)
	v_add_f32_e32 v46, v46, v47
	ds_bpermute_b32 v47, v170, v46
	s_waitcnt lgkmcnt(0)
	v_add_f32_e32 v46, v46, v47
	v_fmamk_f32 v46, v46, 0x3a800000, v171
	v_mul_f32_e32 v47, 0x4f800000, v46
	v_cmp_gt_f32_e32 vcc, s2, v46
	s_waitcnt vmcnt(0)
	v_pk_add_f32 v[40:41], v[40:41], 1.0 op_sel_hi:[1,0]
	v_pk_add_f32 v[38:39], v[38:39], 1.0 op_sel_hi:[1,0]
	v_pk_fma_f32 v[36:37], v[36:37], v[40:41], v[44:45]
	v_pk_fma_f32 v[34:35], v[34:35], v[38:39], v[42:43]
	v_cvt_pk_bf16_f32 v34, v34, v35
	v_cvt_pk_bf16_f32 v35, v36, v37
	global_store_dwordx2 v[104:105], v[34:35], off offset:1536
	global_load_dwordx4 v[34:37], v[144:145], off
	s_nop 0
	global_load_dwordx4 v[38:41], v[128:129], off
	v_cndmask_b32_e32 v42, v46, v47, vcc
	v_sqrt_f32_e32 v43, v42
	s_waitcnt vmcnt(0) lgkmcnt(0)
	v_pk_add_f32 v[36:37], v[36:37], 1.0 op_sel_hi:[1,0]
	v_add_u32_e32 v44, -1, v43
	v_add_u32_e32 v45, 1, v43
	v_fma_f32 v46, -v44, v43, v42
	v_fma_f32 v47, -v45, v43, v42
	v_cmp_ge_f32_e64 s[6:7], 0, v46
	v_pk_add_f32 v[34:35], v[34:35], 1.0 op_sel_hi:[1,0]
	s_nop 0
	v_cndmask_b32_e64 v43, v43, v44, s[6:7]
	v_cmp_lt_f32_e64 s[6:7], 0, v47
	s_nop 1
	v_cndmask_b32_e64 v43, v43, v45, s[6:7]
	v_mul_f32_e32 v44, 0x37800000, v43
	v_cndmask_b32_e32 v43, v43, v44, vcc
	v_cmp_class_f32_e32 vcc, v42, v172
	s_nop 1
	v_cndmask_b32_e32 v42, v43, v42, vcc
	v_div_scale_f32 v43, s[6:7], v42, v42, 1.0
	v_rcp_f32_e32 v45, v43
	v_div_scale_f32 v44, vcc, 1.0, v42, 1.0
	v_fma_f32 v46, -v43, v45, 1.0
	v_fmac_f32_e32 v45, v46, v45
	v_mul_f32_e32 v46, v44, v45
	v_fma_f32 v47, -v43, v46, v44
	v_fmac_f32_e32 v46, v47, v45
	v_fma_f32 v43, -v43, v46, v44
	v_div_fmas_f32 v43, v43, v45, v46
	v_div_fixup_f32 v42, v43, v42, 1.0
	v_pk_mul_f32 v[32:33], v[32:33], v[42:43] op_sel_hi:[1,0]
	v_pk_mul_f32 v[30:31], v[30:31], v[42:43] op_sel_hi:[1,0]
	v_pk_mul_f32 v[32:33], v[4:5], v[32:33]
	v_pk_mul_f32 v[30:31], v[2:3], v[30:31]
	v_pk_fma_f32 v[32:33], v[36:37], v[32:33], v[40:41]
	v_pk_fma_f32 v[30:31], v[34:35], v[30:31], v[38:39]
	v_cvt_pk_bf16_f32 v30, v30, v31
	v_cvt_pk_bf16_f32 v31, v32, v33
	global_store_dwordx2 v[104:105], v[30:31], off offset:2048
	global_load_dwordx4 v[30:33], v[122:123], off
	s_nop 0
	global_load_dwordx4 v[34:37], v[120:121], off
	v_pk_mul_f32 v[28:29], v[28:29], v[42:43] op_sel_hi:[1,0]
	v_pk_mul_f32 v[26:27], v[26:27], v[42:43] op_sel_hi:[1,0]
	v_pk_mul_f32 v[28:29], v[8:9], v[28:29]
	v_pk_mul_f32 v[26:27], v[6:7], v[26:27]
	v_lshl_add_u64 v[40:41], s[18:19], 0, v[98:99]
	v_lshl_add_u64 v[38:39], s[16:17], 0, v[98:99]
	v_pk_mul_f32 v[24:25], v[24:25], v[42:43] op_sel_hi:[1,0]
	v_pk_mul_f32 v[22:23], v[22:23], v[42:43] op_sel_hi:[1,0]
	v_pk_mul_f32 v[24:25], v[12:13], v[24:25]
	v_pk_mul_f32 v[22:23], v[10:11], v[22:23]
	v_pk_mul_f32 v[20:21], v[20:21], v[42:43] op_sel_hi:[1,0]
	v_pk_mul_f32 v[18:19], v[18:19], v[42:43] op_sel_hi:[1,0]
	v_pk_mul_f32 v[20:21], v[16:17], v[20:21]
	v_pk_mul_f32 v[18:19], v[14:15], v[18:19]
	s_waitcnt vmcnt(0) lgkmcnt(0)
	v_pk_add_f32 v[32:33], v[32:33], 1.0 op_sel_hi:[1,0]
	v_pk_add_f32 v[30:31], v[30:31], 1.0 op_sel_hi:[1,0]
	v_pk_fma_f32 v[28:29], v[32:33], v[28:29], v[36:37]
	v_pk_fma_f32 v[26:27], v[30:31], v[26:27], v[34:35]
	v_cvt_pk_bf16_f32 v26, v26, v27
	v_cvt_pk_bf16_f32 v27, v28, v29
	global_store_dwordx2 v[104:105], v[26:27], off offset:2560
	global_load_dwordx4 v[26:29], v[40:41], off
	s_nop 0
	global_load_dwordx4 v[30:33], v[38:39], off
	v_lshl_add_u64 v[36:37], s[18:19], 0, v[100:101]
	v_lshl_add_u64 v[34:35], s[16:17], 0, v[100:101]
	s_waitcnt vmcnt(0) lgkmcnt(0)
	v_pk_add_f32 v[28:29], v[28:29], 1.0 op_sel_hi:[1,0]
	v_pk_add_f32 v[26:27], v[26:27], 1.0 op_sel_hi:[1,0]
	v_pk_fma_f32 v[24:25], v[28:29], v[24:25], v[32:33]
	v_pk_fma_f32 v[22:23], v[26:27], v[22:23], v[30:31]
	v_cvt_pk_bf16_f32 v22, v22, v23
	v_cvt_pk_bf16_f32 v23, v24, v25
	global_store_dwordx2 v[104:105], v[22:23], off offset:3072
	global_load_dwordx4 v[22:25], v[36:37], off
	s_nop 0
	global_load_dwordx4 v[26:29], v[34:35], off
	s_waitcnt vmcnt(0) lgkmcnt(0)
	v_pk_add_f32 v[24:25], v[24:25], 1.0 op_sel_hi:[1,0]
	v_pk_add_f32 v[22:23], v[22:23], 1.0 op_sel_hi:[1,0]
	v_pk_fma_f32 v[20:21], v[20:21], v[24:25], v[28:29]
	v_pk_fma_f32 v[18:19], v[18:19], v[22:23], v[26:27]
	v_cvt_pk_bf16_f32 v18, v18, v19
	v_cvt_pk_bf16_f32 v19, v20, v21
	global_store_dwordx2 v[104:105], v[18:19], off offset:3584
	s_cbranch_scc1 .LBB0_3086

.LBB0_3194:
	v_lshl_add_u64 v[18:19], s[12:13], 0, v[94:95]
	v_lshl_add_u64 v[22:23], s[12:13], 0, v[92:93]
	v_add_co_u32_e32 v20, vcc, 0x7800000, v18
	v_add_co_u32_e64 v102, s[6:7], s29, v22
	s_nop 0
	v_addc_co_u32_e32 v21, vcc, 0, v19, vcc
	v_addc_co_u32_e64 v103, s[6:7], 0, v23, s[6:7]
	v_add_co_u32_e64 v104, s[6:7], s30, v22
	v_add_co_u32_e32 v22, vcc, 0x7801000, v18
	s_nop 0
	v_addc_co_u32_e64 v105, s[6:7], 0, v23, s[6:7]
	global_load_dwordx4 v[78:81], v[20:21], off
	global_load_dwordx4 v[74:77], v[20:21], off offset:1024
	global_load_dwordx4 v[70:73], v[20:21], off offset:2048
	global_load_dwordx4 v[66:69], v[20:21], off offset:3072
	v_addc_co_u32_e32 v23, vcc, 0, v19, vcc
	v_add_co_u32_e32 v20, vcc, 0x7802000, v18
	global_load_dwordx4 v[62:65], v[22:23], off
	global_load_dwordx4 v[58:61], v[22:23], off offset:1024
	global_load_dwordx4 v[54:57], v[22:23], off offset:2048
	global_load_dwordx4 v[50:53], v[22:23], off offset:3072
	v_addc_co_u32_e32 v21, vcc, 0, v19, vcc
	global_load_dwordx4 v[46:49], v[20:21], off
	global_load_dwordx4 v[42:45], v[20:21], off offset:1024
	global_load_dwordx4 v[38:41], v[20:21], off offset:2048
	global_load_dwordx4 v[34:37], v[20:21], off offset:3072
	v_add_co_u32_e32 v82, vcc, 0x7803000, v18
	s_ashr_i32 s8, s24, 13
	s_nop 0
	v_addc_co_u32_e32 v83, vcc, 0, v19, vcc
	global_load_dwordx4 v[30:33], v[82:83], off
	global_load_dwordx4 v[26:29], v[82:83], off offset:1024
	global_load_dwordx4 v[22:25], v[82:83], off offset:2048
	global_load_dwordx4 v[18:21], v[82:83], off offset:3072
	s_add_i32 s9, s24, 0xffffc002
	s_cmpk_lt_i32 s24, 0x4000
	s_cselect_b32 s6, s8, s9
	s_addk_i32 s6, 0x82
	s_mul_hi_i32 s7, s6, 0x9000
	s_mul_i32 s6, s6, 0x9000
	s_add_u32 s6, s14, s6
	s_addc_u32 s7, s15, s7
	s_add_u32 s10, s6, 0x1000
	s_addc_u32 s11, s7, 0
	v_lshl_add_u64 v[124:125], s[6:7], 0, v[90:91]
	v_lshl_add_u64 v[86:87], s[10:11], 0, v[90:91]
	global_load_dwordx4 v[82:85], v[124:125], off
	s_add_i32 s6, s24, 0xffffc003
	global_load_dwordx4 v[86:89], v[86:87], off
	s_cmpk_lt_i32 s24, 0x3fff
	s_cselect_b32 s6, s8, s6
	s_addk_i32 s6, 0x82
	s_mul_hi_i32 s7, s6, 0x9000
	s_mul_i32 s6, s6, 0x9000
	s_add_u32 s6, s14, s6
	s_addc_u32 s7, s15, s7
	v_lshl_add_u64 v[134:135], s[10:11], 0, v[96:97]
	v_lshl_add_u64 v[130:131], s[10:11], 0, v[98:99]
	v_lshl_add_u64 v[128:129], s[10:11], 0, v[100:101]
	s_add_u32 s10, s6, 0x1000
	v_lshl_add_u64 v[110:111], s[6:7], 0, v[90:91]
	s_addc_u32 s11, s7, 0
	s_add_i32 s6, s24, 0xffffc004
	s_cmpk_lt_i32 s24, 0x3ffe
	s_cselect_b32 s6, s8, s6
	s_addk_i32 s6, 0x82
	s_mul_hi_i32 s7, s6, 0x9000
	s_mul_i32 s6, s6, 0x9000
	v_lshl_add_u64 v[126:127], s[10:11], 0, v[90:91]
	v_lshl_add_u64 v[120:121], s[10:11], 0, v[96:97]
	v_lshl_add_u64 v[116:117], s[10:11], 0, v[98:99]
	v_lshl_add_u64 v[112:113], s[10:11], 0, v[100:101]
	s_add_u32 s10, s14, s6
	s_addc_u32 s11, s15, s7
	s_add_u32 s6, s10, 0x1000
	s_addc_u32 s7, s11, 0
	s_add_i32 s9, s24, 0xffffc005
	s_cmpk_lt_i32 s24, 0x3ffd
	v_lshl_add_u64 v[138:139], s[6:7], 0, v[90:91]
	v_lshl_add_u64 v[136:137], s[6:7], 0, v[96:97]
	v_lshl_add_u64 v[132:133], s[6:7], 0, v[98:99]
	v_lshl_add_u64 v[122:123], s[6:7], 0, v[100:101]
	s_cselect_b32 s6, s8, s9
	s_addk_i32 s6, 0x82
	s_mul_hi_i32 s7, s6, 0x9000
	s_mul_i32 s6, s6, 0x9000
	s_add_u32 s6, s14, s6
	s_addc_u32 s7, s15, s7
	s_add_u32 s40, s6, 0x1000
	v_lshl_add_u64 v[106:107], s[6:7], 0, v[90:91]
	s_addc_u32 s41, s7, 0
	v_lshl_add_u64 v[108:109], s[10:11], 0, v[90:91]
	v_lshl_add_u64 v[118:119], s[40:41], 0, v[90:91]
	v_lshl_add_u64 v[114:115], s[40:41], 0, v[96:97]
	s_add_i32 s24, s24, 32
	v_lshl_add_u64 v[92:93], v[92:93], 0, s[26:27]
	s_waitcnt vmcnt(0) lgkmcnt(0)
	v_pk_mul_f32 v[140:141], v[80:81], v[80:81]
	v_pk_mul_f32 v[142:143], v[78:79], v[78:79]
	v_pk_mul_f32 v[144:145], v[76:77], v[76:77]
	v_pk_mul_f32 v[146:147], v[74:75], v[74:75]
	v_mul_f32_e32 v156, v71, v71
	v_mul_f32_e32 v158, v73, v73
	v_pk_mov_b32 v[160:161], v[142:143], v[140:141] op_sel:[1,0]
	v_mov_b32_e32 v143, v141
	v_pk_mov_b32 v[140:141], v[146:147], v[144:145] op_sel:[1,0]
	v_mov_b32_e32 v147, v145
	v_mul_f32_e32 v169, v68, v68
	v_mul_f32_e32 v171, v69, v69
	v_pk_fma_f32 v[144:145], v[70:71], v[70:71], v[156:157] op_sel_hi:[1,1,0]
	v_pk_fma_f32 v[156:157], v[72:73], v[72:73], v[158:159] op_sel_hi:[1,1,0]
	v_pk_mul_f32 v[158:159], v[64:65], v[64:65]
	v_pk_mul_f32 v[162:163], v[62:63], v[62:63]
	v_pk_mul_f32 v[164:165], v[60:61], v[60:61]
	v_pk_mul_f32 v[166:167], v[58:59], v[58:59]
	v_mul_f32_e32 v168, v55, v55
	v_mul_f32_e32 v170, v57, v57
	v_pk_add_f32 v[142:143], v[160:161], v[142:143]
	v_pk_add_f32 v[140:141], v[140:141], v[146:147]
	v_mul_f32_e32 v155, v66, v66
	v_mul_f32_e32 v179, v67, v67
	v_mov_b32_e32 v145, v169
	v_mov_b32_e32 v157, v171
	v_pk_mov_b32 v[146:147], v[162:163], v[158:159] op_sel:[1,0]
	v_mov_b32_e32 v163, v159
	v_pk_mov_b32 v[158:159], v[166:167], v[164:165] op_sel:[1,0]
	v_mov_b32_e32 v167, v165
	v_pk_fma_f32 v[160:161], v[54:55], v[54:55], v[168:169] op_sel_hi:[1,1,0]
	v_pk_fma_f32 v[164:165], v[56:57], v[56:57], v[170:171] op_sel_hi:[1,1,0]
	v_pk_mul_f32 v[168:169], v[48:49], v[48:49]
	v_pk_mul_f32 v[170:171], v[46:47], v[46:47]
	v_pk_add_f32 v[180:181], v[142:143], v[142:143] op_sel:[0,1] op_sel_hi:[1,0]
	v_pk_add_f32 v[182:183], v[140:141], v[140:141] op_sel:[0,1] op_sel_hi:[1,0]
	v_mul_f32_e32 v177, v52, v52
	v_pk_mul_f32 v[172:173], v[44:45], v[44:45]
	v_pk_mul_f32 v[174:175], v[42:43], v[42:43]
	v_mul_f32_e32 v176, v39, v39
	v_mul_f32_e32 v178, v41, v41
	v_pk_add_f32 v[156:157], v[144:145], v[156:157]
	v_pk_add_f32 v[140:141], v[146:147], v[162:163]
	v_pk_add_f32 v[142:143], v[158:159], v[166:167]
	v_pk_mov_b32 v[144:145], v[170:171], v[168:169] op_sel:[1,0]
	v_mov_b32_e32 v171, v169
	v_mov_b32_e32 v181, v155
	v_mov_b32_e32 v183, v179
	v_mul_f32_e32 v185, v50, v50
	v_mul_f32_e32 v190, v51, v51
	v_mul_f32_e32 v184, v53, v53
	v_mul_f32_e32 v193, v36, v36
	v_mul_f32_e32 v194, v37, v37
	v_pk_mov_b32 v[146:147], v[174:175], v[172:173] op_sel:[1,0]
	v_mov_b32_e32 v175, v173
	v_pk_fma_f32 v[158:159], v[38:39], v[38:39], v[176:177] op_sel_hi:[1,1,0]
	v_pk_fma_f32 v[162:163], v[40:41], v[40:41], v[178:179] op_sel_hi:[1,1,0]
	v_pk_add_f32 v[186:187], v[140:141], v[140:141] op_sel:[0,1] op_sel_hi:[1,0]
	v_pk_add_f32 v[188:189], v[142:143], v[142:143] op_sel:[0,1] op_sel_hi:[1,0]
	v_pk_add_f32 v[144:145], v[144:145], v[170:171]
	v_pk_add_f32 v[170:171], v[180:181], v[182:183]
	v_mov_b32_e32 v161, v177
	v_mov_b32_e32 v165, v184
	v_pk_mul_f32 v[166:167], v[32:33], v[32:33]
	v_pk_mul_f32 v[168:169], v[30:31], v[30:31]
	v_pk_mul_f32 v[172:173], v[28:29], v[28:29]
	v_pk_mul_f32 v[176:177], v[26:27], v[26:27]
	v_pk_add_f32 v[146:147], v[146:147], v[174:175]
	v_mov_b32_e32 v159, v193
	v_mov_b32_e32 v163, v194
	v_mov_b32_e32 v187, v185
	v_mov_b32_e32 v189, v190
	v_pk_add_f32 v[156:157], v[170:171], v[156:157]
	v_mul_f32_e32 v191, v34, v34
	v_mul_f32_e32 v192, v35, v35
	v_pk_add_f32 v[160:161], v[160:161], v[164:165]
	v_pk_mov_b32 v[164:165], v[168:169], v[166:167] op_sel:[1,0]
	v_mov_b32_e32 v169, v167
	v_pk_mov_b32 v[166:167], v[176:177], v[172:173] op_sel:[1,0]
	v_mov_b32_e32 v177, v173
	v_pk_add_f32 v[172:173], v[144:145], v[144:145] op_sel:[0,1] op_sel_hi:[1,0]
	v_pk_add_f32 v[174:175], v[146:147], v[146:147] op_sel:[0,1] op_sel_hi:[1,0]
	v_pk_add_f32 v[158:159], v[158:159], v[162:163]
	v_pk_add_f32 v[162:163], v[186:187], v[188:189]
	v_add_f32_e32 v155, v156, v157
	v_mov_b32_e32 v173, v191
	v_mov_b32_e32 v175, v192
	v_pk_add_f32 v[156:157], v[162:163], v[160:161]
	ds_bpermute_b32 v163, v1, v155
	v_pk_add_f32 v[160:161], v[172:173], v[174:175]
	v_add_f32_e32 v162, v156, v157
	v_pk_add_f32 v[156:157], v[160:161], v[158:159]
	ds_bpermute_b32 v158, v1, v162
	v_add_f32_e32 v156, v156, v157
	ds_bpermute_b32 v157, v1, v156
	s_waitcnt lgkmcnt(2)
	v_add_f32_e32 v155, v155, v163
	ds_bpermute_b32 v159, v148, v155
	s_waitcnt lgkmcnt(2)
	v_add_f32_e32 v158, v162, v158
	ds_bpermute_b32 v160, v148, v158
	s_waitcnt lgkmcnt(2)
	v_add_f32_e32 v156, v156, v157
	ds_bpermute_b32 v157, v148, v156
	s_waitcnt lgkmcnt(2)
	v_add_f32_e32 v155, v155, v159
	ds_bpermute_b32 v159, v149, v155
	s_waitcnt lgkmcnt(2)
	v_add_f32_e32 v158, v158, v160
	ds_bpermute_b32 v160, v149, v158
	s_waitcnt lgkmcnt(2)
	v_add_f32_e32 v156, v156, v157
	ds_bpermute_b32 v157, v149, v156
	s_waitcnt lgkmcnt(2)
	v_add_f32_e32 v155, v155, v159
	ds_bpermute_b32 v159, v150, v155
	s_waitcnt lgkmcnt(2)
	v_add_f32_e32 v158, v158, v160
	ds_bpermute_b32 v160, v150, v158
	s_waitcnt lgkmcnt(2)
	v_add_f32_e32 v156, v156, v157
	ds_bpermute_b32 v157, v150, v156
	s_waitcnt lgkmcnt(2)
	v_add_f32_e32 v155, v155, v159
	ds_bpermute_b32 v159, v151, v155
	s_waitcnt lgkmcnt(2)
	v_add_f32_e32 v158, v158, v160
	ds_bpermute_b32 v160, v151, v158
	s_waitcnt lgkmcnt(2)
	v_add_f32_e32 v156, v156, v157
	ds_bpermute_b32 v157, v151, v156
	s_waitcnt lgkmcnt(2)
	v_add_f32_e32 v155, v155, v159
	ds_bpermute_b32 v159, v152, v155
	s_waitcnt lgkmcnt(2)
	v_add_f32_e32 v158, v158, v160
	ds_bpermute_b32 v160, v152, v158
	s_waitcnt lgkmcnt(2)
	v_add_f32_e32 v156, v156, v157
	ds_bpermute_b32 v157, v152, v156
	s_waitcnt lgkmcnt(2)
	v_add_f32_e32 v155, v155, v159
	v_fmamk_f32 v155, v155, 0x3a800000, v153
	s_waitcnt lgkmcnt(1)
	v_add_f32_e32 v158, v158, v160
	v_mul_f32_e32 v159, 0x4f800000, v155
	v_cmp_gt_f32_e32 vcc, s17, v155
	v_fmamk_f32 v158, v158, 0x3a800000, v153
	s_waitcnt lgkmcnt(0)
	v_add_f32_e32 v156, v156, v157
	v_cndmask_b32_e32 v155, v155, v159, vcc
	v_mul_f32_e32 v157, 0x4f800000, v158
	v_cmp_gt_f32_e64 s[6:7], s17, v158
	v_sqrt_f32_e32 v159, v155
	v_fmamk_f32 v156, v156, 0x3a800000, v153
	v_cndmask_b32_e64 v157, v158, v157, s[6:7]
	v_mul_f32_e32 v158, 0x4f800000, v156
	v_cmp_gt_f32_e64 s[8:9], s17, v156
	v_sqrt_f32_e32 v160, v157
	v_add_u32_e32 v161, -1, v159
	v_cndmask_b32_e64 v156, v156, v158, s[8:9]
	v_sqrt_f32_e32 v158, v156
	v_add_u32_e32 v162, 1, v159
	v_fma_f32 v163, -v161, v159, v155
	v_pk_add_f32 v[144:145], v[164:165], v[168:169]
	v_fma_f32 v164, -v162, v159, v155
	v_add_u32_e32 v165, -1, v160
	v_cmp_ge_f32_e64 s[10:11], 0, v163
	v_pk_add_f32 v[146:147], v[166:167], v[176:177]
	v_add_u32_e32 v166, 1, v160
	v_cndmask_b32_e64 v159, v159, v161, s[10:11]
	v_fma_f32 v161, -v165, v160, v157
	v_cmp_lt_f32_e64 s[10:11], 0, v164
	v_fma_f32 v163, -v166, v160, v157
	v_add_u32_e32 v167, -1, v158
	v_cndmask_b32_e64 v159, v159, v162, s[10:11]
	v_cmp_ge_f32_e64 s[10:11], 0, v161
	v_add_u32_e32 v168, 1, v158
	v_fma_f32 v161, -v167, v158, v156
	v_cndmask_b32_e64 v160, v160, v165, s[10:11]
	v_cmp_lt_f32_e64 s[10:11], 0, v163
	v_fma_f32 v162, -v168, v158, v156
	v_mul_f32_e32 v163, 0x37800000, v159
	v_cndmask_b32_e64 v160, v160, v166, s[10:11]
	v_cmp_ge_f32_e64 s[10:11], 0, v161
	v_cndmask_b32_e32 v159, v159, v163, vcc
	v_cmp_class_f32_e32 vcc, v155, v154
	v_cndmask_b32_e64 v158, v158, v167, s[10:11]
	v_cmp_lt_f32_e64 s[10:11], 0, v162
	v_mul_f32_e32 v161, 0x37800000, v160
	v_cndmask_b32_e32 v155, v159, v155, vcc
	v_cndmask_b32_e64 v158, v158, v168, s[10:11]
	v_cndmask_b32_e64 v159, v160, v161, s[6:7]
	v_cmp_class_f32_e32 vcc, v157, v154
	v_mul_f32_e32 v160, 0x37800000, v158
	v_div_scale_f32 v161, s[6:7], v155, v155, 1.0
	v_cndmask_b32_e32 v157, v159, v157, vcc
	v_cndmask_b32_e64 v158, v158, v160, s[8:9]
	v_cmp_class_f32_e32 vcc, v156, v154
	v_rcp_f32_e32 v159, v161
	v_div_scale_f32 v160, s[8:9], v157, v157, 1.0
	v_cndmask_b32_e32 v158, v158, v156, vcc
	v_rcp_f32_e32 v164, v160
	v_div_scale_f32 v165, s[10:11], v158, v158, 1.0
	v_rcp_f32_e32 v167, v165
	v_fma_f32 v156, -v161, v159, 1.0
	v_div_scale_f32 v162, s[6:7], 1.0, v155, 1.0
	v_fmac_f32_e32 v159, v156, v159
	v_fma_f32 v156, -v160, v164, 1.0
	v_mul_f32_e32 v168, v162, v159
	v_div_scale_f32 v163, s[8:9], 1.0, v157, 1.0
	v_fmac_f32_e32 v164, v156, v164
	v_fma_f32 v156, -v165, v167, 1.0
	v_fma_f32 v169, -v161, v168, v162
	v_div_scale_f32 v166, s[10:11], 1.0, v158, 1.0
	v_mul_f32_e32 v170, v163, v164
	v_fmac_f32_e32 v167, v156, v167
	v_fmac_f32_e32 v168, v169, v159
	v_fma_f32 v156, -v160, v170, v163
	v_mul_f32_e32 v169, v166, v167
	v_fma_f32 v161, -v161, v168, v162
	s_mov_b64 vcc, s[6:7]
	v_fmac_f32_e32 v170, v156, v164
	v_fma_f32 v156, -v165, v169, v166
	v_div_fmas_f32 v159, v161, v159, v168
	v_fma_f32 v160, -v160, v170, v163
	v_fmac_f32_e32 v169, v156, v167
	v_div_fixup_f32 v156, v159, v155, 1.0
	s_mov_b64 vcc, s[8:9]
	v_div_fmas_f32 v155, v160, v164, v170
	v_fma_f32 v159, -v165, v169, v166
	v_pk_mul_f32 v[80:81], v[80:81], v[156:157] op_sel_hi:[1,0]
	v_pk_mul_f32 v[78:79], v[78:79], v[156:157] op_sel_hi:[1,0]
	s_mov_b64 vcc, s[10:11]
	v_pk_add_f32 v[88:89], v[88:89], 1.0 op_sel_hi:[1,0]
	v_pk_add_f32 v[86:87], v[86:87], 1.0 op_sel_hi:[1,0]
	v_pk_mul_f32 v[76:77], v[76:77], v[156:157] op_sel_hi:[1,0]
	v_pk_mul_f32 v[74:75], v[74:75], v[156:157] op_sel_hi:[1,0]
	v_pk_mul_f32 v[72:73], v[72:73], v[156:157] op_sel_hi:[1,0]
	v_pk_mul_f32 v[70:71], v[70:71], v[156:157] op_sel_hi:[1,0]
	v_pk_mul_f32 v[68:69], v[68:69], v[156:157] op_sel_hi:[1,0]
	v_pk_mul_f32 v[66:67], v[66:67], v[156:157] op_sel_hi:[1,0]
	v_div_fixup_f32 v156, v155, v157, 1.0
	v_div_fmas_f32 v155, v159, v167, v169
	v_pk_mul_f32 v[78:79], v[78:79], v[2:3]
	v_pk_mul_f32 v[80:81], v[80:81], v[4:5]
	v_pk_mul_f32 v[64:65], v[64:65], v[156:157] op_sel_hi:[1,0]
	v_pk_mul_f32 v[62:63], v[62:63], v[156:157] op_sel_hi:[1,0]
	v_pk_mul_f32 v[60:61], v[60:61], v[156:157] op_sel_hi:[1,0]
	v_pk_mul_f32 v[58:59], v[58:59], v[156:157] op_sel_hi:[1,0]
	v_pk_mul_f32 v[56:57], v[56:57], v[156:157] op_sel_hi:[1,0]
	v_pk_mul_f32 v[54:55], v[54:55], v[156:157] op_sel_hi:[1,0]
	v_pk_mul_f32 v[52:53], v[52:53], v[156:157] op_sel_hi:[1,0]
	v_pk_mul_f32 v[156:157], v[50:51], v[156:157] op_sel_hi:[1,0]
	v_div_fixup_f32 v50, v155, v158, 1.0
	v_pk_fma_f32 v[80:81], v[80:81], v[88:89], v[84:85]
	v_pk_fma_f32 v[78:79], v[78:79], v[86:87], v[82:83]
	v_pk_mul_f32 v[86:87], v[52:53], v[16:17]
	v_pk_mul_f32 v[48:49], v[48:49], v[50:51] op_sel_hi:[1,0]
	v_pk_mul_f32 v[46:47], v[46:47], v[50:51] op_sel_hi:[1,0]
	v_pk_mul_f32 v[82:83], v[54:55], v[10:11]
	v_pk_mul_f32 v[84:85], v[156:157], v[14:15]
	v_pk_mul_f32 v[88:89], v[46:47], v[2:3]
	v_pk_mul_f32 v[156:157], v[48:49], v[4:5]
	v_cvt_pk_bf16_f32 v46, v78, v79
	v_cvt_pk_bf16_f32 v47, v80, v81
	global_store_dwordx2 v[102:103], v[46:47], off
	global_load_dwordx4 v[238:241], v[134:135], off
	s_nop 0
	global_load_dwordx4 v[242:245], v[124:125], off offset:1024
	v_pk_mul_f32 v[74:75], v[74:75], v[6:7]
	v_pk_mul_f32 v[76:77], v[76:77], v[8:9]
	v_pk_mul_f32 v[70:71], v[70:71], v[10:11]
	v_pk_mul_f32 v[72:73], v[72:73], v[12:13]
	v_pk_mul_f32 v[66:67], v[66:67], v[14:15]
	v_pk_mul_f32 v[68:69], v[68:69], v[16:17]
	v_pk_mul_f32 v[62:63], v[62:63], v[2:3]
	v_pk_mul_f32 v[64:65], v[64:65], v[4:5]
	v_pk_mul_f32 v[58:59], v[58:59], v[6:7]
	v_pk_mul_f32 v[60:61], v[60:61], v[8:9]
	v_pk_mul_f32 v[56:57], v[56:57], v[12:13]
	v_mul_f32_e32 v178, v23, v23
	v_mul_f32_e32 v184, v25, v25
	v_mul_f32_e32 v195, v18, v18
	v_mul_f32_e32 v196, v19, v19
	v_mul_f32_e32 v197, v20, v20
	v_mul_f32_e32 v198, v21, v21
	v_pk_fma_f32 v[140:141], v[22:23], v[22:23], v[178:179] op_sel_hi:[1,1,0]
	v_pk_fma_f32 v[142:143], v[24:25], v[24:25], v[184:185] op_sel_hi:[1,1,0]
	v_mov_b32_e32 v141, v197
	v_mov_b32_e32 v143, v198
	v_lshl_add_u64 v[94:95], v[94:95], 0, s[38:39]
	s_cmp_lt_i32 s24, s5
	global_load_dwordx4 v[230:233], v[130:131], off
	s_nop 0
	global_load_dwordx4 v[234:237], v[124:125], off offset:2048
	s_waitcnt vmcnt(2) lgkmcnt(0)
	v_pk_add_f32 v[240:241], v[240:241], 1.0 op_sel_hi:[1,0]
	v_pk_add_f32 v[238:239], v[238:239], 1.0 op_sel_hi:[1,0]
	v_pk_fma_f32 v[240:241], v[76:77], v[240:241], v[244:245]
	v_pk_fma_f32 v[238:239], v[74:75], v[238:239], v[242:243]
	v_cvt_pk_bf16_f32 v238, v238, v239
	v_cvt_pk_bf16_f32 v239, v240, v241
	global_store_dwordx2 v[102:103], v[238:239], off offset:512
	global_load_dwordx4 v[238:241], v[128:129], off
	s_nop 0
	global_load_dwordx4 v[242:245], v[124:125], off offset:3072
	s_waitcnt vmcnt(3) lgkmcnt(0)
	v_pk_add_f32 v[232:233], v[232:233], 1.0 op_sel_hi:[1,0]
	v_pk_add_f32 v[230:231], v[230:231], 1.0 op_sel_hi:[1,0]
	v_pk_fma_f32 v[232:233], v[72:73], v[232:233], v[236:237]
	v_pk_fma_f32 v[230:231], v[70:71], v[230:231], v[234:235]
	v_cvt_pk_bf16_f32 v230, v230, v231
	v_cvt_pk_bf16_f32 v231, v232, v233
	global_store_dwordx2 v[102:103], v[230:231], off offset:1024
	global_load_dwordx4 v[230:233], v[126:127], off
	s_nop 0
	global_load_dwordx4 v[234:237], v[110:111], off
	s_waitcnt vmcnt(3) lgkmcnt(0)
	v_pk_add_f32 v[240:241], v[240:241], 1.0 op_sel_hi:[1,0]
	v_pk_add_f32 v[238:239], v[238:239], 1.0 op_sel_hi:[1,0]
	v_pk_fma_f32 v[240:241], v[68:69], v[240:241], v[244:245]
	v_pk_fma_f32 v[238:239], v[66:67], v[238:239], v[242:243]
	v_cvt_pk_bf16_f32 v238, v238, v239
	v_cvt_pk_bf16_f32 v239, v240, v241
	global_store_dwordx2 v[102:103], v[238:239], off offset:1536
	global_load_dwordx4 v[238:241], v[120:121], off
	s_nop 0
	global_load_dwordx4 v[242:245], v[110:111], off offset:1024
	s_waitcnt vmcnt(3) lgkmcnt(0)
	v_pk_add_f32 v[232:233], v[232:233], 1.0 op_sel_hi:[1,0]
	v_pk_add_f32 v[230:231], v[230:231], 1.0 op_sel_hi:[1,0]
	v_pk_fma_f32 v[232:233], v[64:65], v[232:233], v[236:237]
	v_pk_fma_f32 v[230:231], v[62:63], v[230:231], v[234:235]
	v_cvt_pk_bf16_f32 v230, v230, v231
	v_cvt_pk_bf16_f32 v231, v232, v233
	global_store_dwordx2 v[102:103], v[230:231], off offset:2048
	global_load_dwordx4 v[230:233], v[116:117], off
	s_nop 0
	global_load_dwordx4 v[234:237], v[110:111], off offset:2048
	s_waitcnt vmcnt(3) lgkmcnt(0)
	v_pk_add_f32 v[240:241], v[240:241], 1.0 op_sel_hi:[1,0]
	v_pk_add_f32 v[238:239], v[238:239], 1.0 op_sel_hi:[1,0]
	v_pk_fma_f32 v[240:241], v[60:61], v[240:241], v[244:245]
	v_pk_fma_f32 v[238:239], v[58:59], v[238:239], v[242:243]
	v_cvt_pk_bf16_f32 v238, v238, v239
	v_cvt_pk_bf16_f32 v239, v240, v241
	global_store_dwordx2 v[102:103], v[238:239], off offset:2560
	v_pk_add_f32 v[58:59], v[146:147], v[146:147] op_sel:[0,1] op_sel_hi:[1,0]
	v_pk_add_f32 v[60:61], v[140:141], v[142:143]
	v_mov_b32_e32 v59, v196
	global_load_dwordx4 v[238:241], v[112:113], off
	s_nop 0
	global_load_dwordx4 v[242:245], v[110:111], off offset:3072
	s_waitcnt vmcnt(3) lgkmcnt(0)
	v_pk_add_f32 v[232:233], v[232:233], 1.0 op_sel_hi:[1,0]
	v_pk_add_f32 v[230:231], v[230:231], 1.0 op_sel_hi:[1,0]
	v_pk_fma_f32 v[232:233], v[56:57], v[232:233], v[236:237]
	v_pk_fma_f32 v[230:231], v[82:83], v[230:231], v[234:235]
	v_cvt_pk_bf16_f32 v230, v230, v231
	v_cvt_pk_bf16_f32 v231, v232, v233
	global_store_dwordx2 v[102:103], v[230:231], off offset:3072
	v_pk_add_f32 v[56:57], v[144:145], v[144:145] op_sel:[0,1] op_sel_hi:[1,0]
	global_load_dwordx4 v[230:233], v[138:139], off
	s_nop 0
	global_load_dwordx4 v[234:237], v[108:109], off
	s_waitcnt vmcnt(3) lgkmcnt(0)
	v_pk_add_f32 v[240:241], v[240:241], 1.0 op_sel_hi:[1,0]
	v_pk_add_f32 v[238:239], v[238:239], 1.0 op_sel_hi:[1,0]
	v_pk_fma_f32 v[240:241], v[86:87], v[240:241], v[244:245]
	v_pk_fma_f32 v[238:239], v[84:85], v[238:239], v[242:243]
	v_cvt_pk_bf16_f32 v238, v238, v239
	v_cvt_pk_bf16_f32 v239, v240, v241
	global_store_dwordx2 v[102:103], v[238:239], off offset:3584
	v_mov_b32_e32 v57, v195
	global_load_dwordx4 v[238:241], v[136:137], off
	s_nop 0
	global_load_dwordx4 v[242:245], v[108:109], off offset:1024
	s_waitcnt vmcnt(3) lgkmcnt(0)
	v_pk_add_f32 v[232:233], v[232:233], 1.0 op_sel_hi:[1,0]
	v_pk_add_f32 v[230:231], v[230:231], 1.0 op_sel_hi:[1,0]
	v_pk_fma_f32 v[232:233], v[156:157], v[232:233], v[236:237]
	v_pk_fma_f32 v[230:231], v[88:89], v[230:231], v[234:235]
	v_bfe_u32 v51, v230, 16, 1
	v_bfe_u32 v234, v231, 16, 1
	v_add3_u32 v230, v230, v51, s25
	v_add3_u32 v231, v231, v234, s25
	v_lshrrev_b32_e32 v230, 16, v230
	v_and_or_b32 v230, v231, s28, v230
	v_cvt_pk_bf16_f32 v231, v232, v233
	global_store_dwordx2 v[104:105], v[230:231], off
	v_pk_mul_f32 v[44:45], v[44:45], v[50:51] op_sel_hi:[1,0]
	v_pk_mul_f32 v[42:43], v[42:43], v[50:51] op_sel_hi:[1,0]
	v_pk_mul_f32 v[44:45], v[44:45], v[8:9]
	v_pk_mul_f32 v[42:43], v[42:43], v[6:7]
	s_waitcnt vmcnt(1) lgkmcnt(0)
	v_pk_add_f32 v[240:241], v[240:241], 1.0 op_sel_hi:[1,0]
	v_pk_add_f32 v[238:239], v[238:239], 1.0 op_sel_hi:[1,0]
	v_pk_fma_f32 v[44:45], v[44:45], v[240:241], v[244:245]
	v_pk_fma_f32 v[42:43], v[42:43], v[238:239], v[242:243]
	v_cvt_pk_bf16_f32 v42, v42, v43
	v_cvt_pk_bf16_f32 v43, v44, v45
	global_store_dwordx2 v[104:105], v[42:43], off offset:512
	global_load_dwordx4 v[42:45], v[132:133], off
	s_nop 0
	global_load_dwordx4 v[46:49], v[108:109], off offset:2048
	v_pk_add_f32 v[52:53], v[56:57], v[58:59]
	s_waitcnt vmcnt(0) lgkmcnt(0)
	v_pk_add_f32 v[44:45], v[44:45], 1.0 op_sel_hi:[1,0]
	v_pk_add_f32 v[52:53], v[52:53], v[60:61]
	v_pk_add_f32 v[42:43], v[42:43], 1.0 op_sel_hi:[1,0]
	v_add_f32_e32 v51, v52, v53
	ds_bpermute_b32 v52, v1, v51
	s_waitcnt lgkmcnt(0)
	v_add_f32_e32 v51, v51, v52
	ds_bpermute_b32 v52, v148, v51
	s_waitcnt lgkmcnt(0)
	v_add_f32_e32 v51, v51, v52
	v_pk_mul_f32 v[40:41], v[40:41], v[50:51] op_sel_hi:[1,0]
	v_pk_mul_f32 v[38:39], v[38:39], v[50:51] op_sel_hi:[1,0]
	v_pk_mul_f32 v[40:41], v[40:41], v[12:13]
	v_pk_mul_f32 v[38:39], v[38:39], v[10:11]
	v_pk_fma_f32 v[40:41], v[40:41], v[44:45], v[48:49]
	v_pk_fma_f32 v[38:39], v[38:39], v[42:43], v[46:47]
	v_cvt_pk_bf16_f32 v38, v38, v39
	v_cvt_pk_bf16_f32 v39, v40, v41
	global_store_dwordx2 v[104:105], v[38:39], off offset:1024
	global_load_dwordx4 v[38:41], v[122:123], off
	s_nop 0
	global_load_dwordx4 v[42:45], v[108:109], off offset:3072
	v_pk_mul_f32 v[36:37], v[36:37], v[50:51] op_sel_hi:[1,0]
	v_pk_mul_f32 v[34:35], v[34:35], v[50:51] op_sel_hi:[1,0]
	v_pk_mul_f32 v[36:37], v[36:37], v[16:17]
	v_pk_mul_f32 v[34:35], v[34:35], v[14:15]
	ds_bpermute_b32 v46, v149, v51
	s_waitcnt lgkmcnt(0)
	v_add_f32_e32 v46, v51, v46
	ds_bpermute_b32 v47, v150, v46
	s_waitcnt lgkmcnt(0)
	v_add_f32_e32 v46, v46, v47
	ds_bpermute_b32 v47, v151, v46
	s_waitcnt lgkmcnt(0)
	v_add_f32_e32 v46, v46, v47
	ds_bpermute_b32 v47, v152, v46
	s_waitcnt lgkmcnt(0)
	v_add_f32_e32 v46, v46, v47
	v_fmamk_f32 v46, v46, 0x3a800000, v153
	v_mul_f32_e32 v47, 0x4f800000, v46
	v_cmp_gt_f32_e32 vcc, s17, v46
	s_waitcnt vmcnt(0)
	v_pk_add_f32 v[40:41], v[40:41], 1.0 op_sel_hi:[1,0]
	v_pk_add_f32 v[38:39], v[38:39], 1.0 op_sel_hi:[1,0]
	v_pk_fma_f32 v[36:37], v[36:37], v[40:41], v[44:45]
	v_pk_fma_f32 v[34:35], v[34:35], v[38:39], v[42:43]
	v_cvt_pk_bf16_f32 v34, v34, v35
	v_cvt_pk_bf16_f32 v35, v36, v37
	global_store_dwordx2 v[104:105], v[34:35], off offset:1536
	global_load_dwordx4 v[34:37], v[118:119], off
	s_nop 0
	global_load_dwordx4 v[38:41], v[106:107], off
	v_cndmask_b32_e32 v42, v46, v47, vcc
	v_sqrt_f32_e32 v43, v42
	s_waitcnt vmcnt(0) lgkmcnt(0)
	v_pk_add_f32 v[36:37], v[36:37], 1.0 op_sel_hi:[1,0]
	v_add_u32_e32 v44, -1, v43
	v_add_u32_e32 v45, 1, v43
	v_fma_f32 v46, -v44, v43, v42
	v_fma_f32 v47, -v45, v43, v42
	v_cmp_ge_f32_e64 s[6:7], 0, v46
	v_pk_add_f32 v[34:35], v[34:35], 1.0 op_sel_hi:[1,0]
	s_nop 0
	v_cndmask_b32_e64 v43, v43, v44, s[6:7]
	v_cmp_lt_f32_e64 s[6:7], 0, v47
	s_nop 1
	v_cndmask_b32_e64 v43, v43, v45, s[6:7]
	v_mul_f32_e32 v44, 0x37800000, v43
	v_cndmask_b32_e32 v43, v43, v44, vcc
	v_cmp_class_f32_e32 vcc, v42, v154
	s_nop 1
	v_cndmask_b32_e32 v42, v43, v42, vcc
	v_div_scale_f32 v43, s[6:7], v42, v42, 1.0
	v_rcp_f32_e32 v45, v43
	v_div_scale_f32 v44, vcc, 1.0, v42, 1.0
	v_fma_f32 v46, -v43, v45, 1.0
	v_fmac_f32_e32 v45, v46, v45
	v_mul_f32_e32 v46, v44, v45
	v_fma_f32 v47, -v43, v46, v44
	v_fmac_f32_e32 v46, v47, v45
	v_fma_f32 v43, -v43, v46, v44
	v_div_fmas_f32 v43, v43, v45, v46
	v_div_fixup_f32 v42, v43, v42, 1.0
	v_pk_mul_f32 v[32:33], v[32:33], v[42:43] op_sel_hi:[1,0]
	v_pk_mul_f32 v[30:31], v[30:31], v[42:43] op_sel_hi:[1,0]
	v_pk_mul_f32 v[32:33], v[32:33], v[4:5]
	v_pk_mul_f32 v[30:31], v[30:31], v[2:3]
	v_pk_fma_f32 v[32:33], v[32:33], v[36:37], v[40:41]
	v_pk_fma_f32 v[30:31], v[30:31], v[34:35], v[38:39]
	v_cvt_pk_bf16_f32 v30, v30, v31
	v_cvt_pk_bf16_f32 v31, v32, v33
	global_store_dwordx2 v[104:105], v[30:31], off offset:2048
	global_load_dwordx4 v[30:33], v[114:115], off
	s_nop 0
	global_load_dwordx4 v[34:37], v[106:107], off offset:1024
	v_pk_mul_f32 v[28:29], v[28:29], v[42:43] op_sel_hi:[1,0]
	v_pk_mul_f32 v[26:27], v[26:27], v[42:43] op_sel_hi:[1,0]
	v_pk_mul_f32 v[28:29], v[28:29], v[8:9]
	v_pk_mul_f32 v[26:27], v[26:27], v[6:7]
	v_lshl_add_u64 v[38:39], s[40:41], 0, v[98:99]
	v_pk_mul_f32 v[24:25], v[24:25], v[42:43] op_sel_hi:[1,0]
	v_pk_mul_f32 v[22:23], v[22:23], v[42:43] op_sel_hi:[1,0]
	v_pk_mul_f32 v[24:25], v[24:25], v[12:13]
	v_pk_mul_f32 v[22:23], v[22:23], v[10:11]
	v_pk_mul_f32 v[20:21], v[20:21], v[42:43] op_sel_hi:[1,0]
	v_pk_mul_f32 v[18:19], v[18:19], v[42:43] op_sel_hi:[1,0]
	v_pk_mul_f32 v[20:21], v[20:21], v[16:17]
	v_pk_mul_f32 v[18:19], v[18:19], v[14:15]
	s_waitcnt vmcnt(0) lgkmcnt(0)
	v_pk_add_f32 v[32:33], v[32:33], 1.0 op_sel_hi:[1,0]
	v_pk_add_f32 v[30:31], v[30:31], 1.0 op_sel_hi:[1,0]
	v_pk_fma_f32 v[28:29], v[28:29], v[32:33], v[36:37]
	v_pk_fma_f32 v[26:27], v[26:27], v[30:31], v[34:35]
	v_cvt_pk_bf16_f32 v26, v26, v27
	v_cvt_pk_bf16_f32 v27, v28, v29
	global_store_dwordx2 v[104:105], v[26:27], off offset:2560
	global_load_dwordx4 v[26:29], v[38:39], off
	s_nop 0
	global_load_dwordx4 v[30:33], v[106:107], off offset:2048
	v_lshl_add_u64 v[34:35], s[40:41], 0, v[100:101]
	s_waitcnt vmcnt(0) lgkmcnt(0)
	v_pk_add_f32 v[28:29], v[28:29], 1.0 op_sel_hi:[1,0]
	v_pk_add_f32 v[26:27], v[26:27], 1.0 op_sel_hi:[1,0]
	v_pk_fma_f32 v[24:25], v[24:25], v[28:29], v[32:33]
	v_pk_fma_f32 v[22:23], v[22:23], v[26:27], v[30:31]
	v_cvt_pk_bf16_f32 v22, v22, v23
	v_cvt_pk_bf16_f32 v23, v24, v25
	global_store_dwordx2 v[104:105], v[22:23], off offset:3072
	global_load_dwordx4 v[22:25], v[34:35], off
	s_nop 0
	global_load_dwordx4 v[26:29], v[106:107], off offset:3072
	s_waitcnt vmcnt(0) lgkmcnt(0)
	v_pk_add_f32 v[24:25], v[24:25], 1.0 op_sel_hi:[1,0]
	v_pk_add_f32 v[22:23], v[22:23], 1.0 op_sel_hi:[1,0]
	v_pk_fma_f32 v[20:21], v[20:21], v[24:25], v[28:29]
	v_pk_fma_f32 v[18:19], v[18:19], v[22:23], v[26:27]
	v_cvt_pk_bf16_f32 v18, v18, v19
	v_cvt_pk_bf16_f32 v19, v20, v21
	global_store_dwordx2 v[104:105], v[18:19], off offset:3584
	s_cbranch_scc1 .LBB0_3194

.LBB0_3341:
	v_lshl_add_u64 v[18:19], s[12:13], 0, v[94:95]
	v_lshl_add_u64 v[22:23], s[12:13], 0, v[92:93]
	v_add_co_u32_e32 v20, vcc, 0x7800000, v18
	v_add_co_u32_e64 v102, s[6:7], s28, v22
	s_nop 0
	v_addc_co_u32_e32 v21, vcc, 0, v19, vcc
	v_addc_co_u32_e64 v103, s[6:7], 0, v23, s[6:7]
	v_add_co_u32_e64 v104, s[6:7], s29, v22
	v_add_co_u32_e32 v22, vcc, 0x7801000, v18
	s_nop 0
	v_addc_co_u32_e64 v105, s[6:7], 0, v23, s[6:7]
	global_load_dwordx4 v[78:81], v[20:21], off
	global_load_dwordx4 v[74:77], v[20:21], off offset:1024
	global_load_dwordx4 v[70:73], v[20:21], off offset:2048
	global_load_dwordx4 v[66:69], v[20:21], off offset:3072
	v_addc_co_u32_e32 v23, vcc, 0, v19, vcc
	v_add_co_u32_e32 v20, vcc, 0x7802000, v18
	global_load_dwordx4 v[62:65], v[22:23], off
	global_load_dwordx4 v[58:61], v[22:23], off offset:1024
	global_load_dwordx4 v[54:57], v[22:23], off offset:2048
	global_load_dwordx4 v[50:53], v[22:23], off offset:3072
	v_addc_co_u32_e32 v21, vcc, 0, v19, vcc
	v_add_co_u32_e32 v82, vcc, 0x7803000, v18
	global_load_dwordx4 v[46:49], v[20:21], off
	global_load_dwordx4 v[42:45], v[20:21], off offset:1024
	global_load_dwordx4 v[38:41], v[20:21], off offset:2048
	global_load_dwordx4 v[34:37], v[20:21], off offset:3072
	v_addc_co_u32_e32 v83, vcc, 0, v19, vcc
	global_load_dwordx4 v[30:33], v[82:83], off
	global_load_dwordx4 v[26:29], v[82:83], off offset:1024
	global_load_dwordx4 v[22:25], v[82:83], off offset:2048
	global_load_dwordx4 v[18:21], v[82:83], off offset:3072
	s_add_i32 s30, s8, 32
	s_add_i32 s10, s8, 0xffffc022
	s_ashr_i32 s9, s30, 13
	s_cmpk_lt_i32 s30, 0x4000
	s_cselect_b32 s6, s9, s10
	s_addk_i32 s6, 0x82
	s_mul_hi_i32 s7, s6, 0x9000
	s_mul_i32 s6, s6, 0x9000
	s_add_u32 s6, s14, s6
	s_addc_u32 s7, s15, s7
	s_add_u32 s10, s6, 0x1000
	s_addc_u32 s11, s7, 0
	v_lshl_add_u64 v[124:125], s[6:7], 0, v[90:91]
	v_lshl_add_u64 v[86:87], s[10:11], 0, v[90:91]
	global_load_dwordx4 v[82:85], v[124:125], off
	s_add_i32 s6, s8, 0xffffc023
	global_load_dwordx4 v[86:89], v[86:87], off
	s_cmpk_lt_i32 s30, 0x3fff
	s_cselect_b32 s6, s9, s6
	s_addk_i32 s6, 0x82
	s_mul_hi_i32 s7, s6, 0x9000
	s_mul_i32 s6, s6, 0x9000
	s_add_u32 s6, s14, s6
	s_addc_u32 s7, s15, s7
	v_lshl_add_u64 v[134:135], s[10:11], 0, v[96:97]
	v_lshl_add_u64 v[130:131], s[10:11], 0, v[98:99]
	v_lshl_add_u64 v[128:129], s[10:11], 0, v[100:101]
	s_add_u32 s10, s6, 0x1000
	v_lshl_add_u64 v[110:111], s[6:7], 0, v[90:91]
	s_addc_u32 s11, s7, 0
	s_add_i32 s6, s8, 0xffffc024
	s_cmpk_lt_i32 s30, 0x3ffe
	s_cselect_b32 s6, s9, s6
	s_addk_i32 s6, 0x82
	s_mul_hi_i32 s7, s6, 0x9000
	s_mul_i32 s6, s6, 0x9000
	v_lshl_add_u64 v[126:127], s[10:11], 0, v[90:91]
	v_lshl_add_u64 v[120:121], s[10:11], 0, v[96:97]
	v_lshl_add_u64 v[116:117], s[10:11], 0, v[98:99]
	v_lshl_add_u64 v[112:113], s[10:11], 0, v[100:101]
	s_add_u32 s10, s14, s6
	s_addc_u32 s11, s15, s7
	s_add_u32 s6, s10, 0x1000
	s_addc_u32 s7, s11, 0
	s_addk_i32 s8, 0xc025
	s_cmpk_lt_i32 s30, 0x3ffd
	v_lshl_add_u64 v[138:139], s[6:7], 0, v[90:91]
	v_lshl_add_u64 v[136:137], s[6:7], 0, v[96:97]
	v_lshl_add_u64 v[132:133], s[6:7], 0, v[98:99]
	v_lshl_add_u64 v[122:123], s[6:7], 0, v[100:101]
	s_cselect_b32 s6, s9, s8
	s_addk_i32 s6, 0x82
	s_mul_hi_i32 s7, s6, 0x9000
	s_mul_i32 s6, s6, 0x9000
	s_add_u32 s6, s14, s6
	s_addc_u32 s7, s15, s7
	s_add_u32 s22, s6, 0x1000
	v_lshl_add_u64 v[106:107], s[6:7], 0, v[90:91]
	s_addc_u32 s23, s7, 0
	v_lshl_add_u64 v[108:109], s[10:11], 0, v[90:91]
	v_lshl_add_u64 v[118:119], s[22:23], 0, v[90:91]
	v_lshl_add_u64 v[114:115], s[22:23], 0, v[96:97]
	v_lshl_add_u64 v[92:93], v[92:93], 0, s[16:17]
	s_waitcnt vmcnt(0) lgkmcnt(0)
	v_pk_mul_f32 v[140:141], v[80:81], v[80:81]
	v_pk_mul_f32 v[142:143], v[78:79], v[78:79]
	v_pk_mul_f32 v[144:145], v[76:77], v[76:77]
	v_pk_mul_f32 v[146:147], v[74:75], v[74:75]
	v_mul_f32_e32 v156, v71, v71
	v_mul_f32_e32 v158, v73, v73
	v_mul_f32_e32 v169, v68, v68
	v_mul_f32_e32 v171, v69, v69
	v_pk_mov_b32 v[160:161], v[142:143], v[140:141] op_sel:[1,0]
	v_mov_b32_e32 v143, v141
	v_pk_mov_b32 v[140:141], v[146:147], v[144:145] op_sel:[1,0]
	v_mov_b32_e32 v147, v145
	v_pk_fma_f32 v[144:145], v[70:71], v[70:71], v[156:157] op_sel_hi:[1,1,0]
	v_pk_fma_f32 v[156:157], v[72:73], v[72:73], v[158:159] op_sel_hi:[1,1,0]
	v_pk_mul_f32 v[158:159], v[64:65], v[64:65]
	v_pk_mul_f32 v[162:163], v[62:63], v[62:63]
	v_pk_mul_f32 v[164:165], v[60:61], v[60:61]
	v_pk_mul_f32 v[166:167], v[58:59], v[58:59]
	v_mul_f32_e32 v168, v55, v55
	v_mul_f32_e32 v170, v57, v57
	v_pk_add_f32 v[142:143], v[160:161], v[142:143]
	v_pk_add_f32 v[140:141], v[140:141], v[146:147]
	v_mov_b32_e32 v145, v169
	v_mov_b32_e32 v157, v171
	v_pk_mov_b32 v[146:147], v[162:163], v[158:159] op_sel:[1,0]
	v_mov_b32_e32 v163, v159
	v_pk_mov_b32 v[158:159], v[166:167], v[164:165] op_sel:[1,0]
	v_mov_b32_e32 v167, v165
	v_pk_fma_f32 v[160:161], v[54:55], v[54:55], v[168:169] op_sel_hi:[1,1,0]
	v_pk_fma_f32 v[164:165], v[56:57], v[56:57], v[170:171] op_sel_hi:[1,1,0]
	v_pk_mul_f32 v[168:169], v[48:49], v[48:49]
	v_pk_mul_f32 v[170:171], v[46:47], v[46:47]
	v_pk_mul_f32 v[172:173], v[44:45], v[44:45]
	v_pk_mul_f32 v[174:175], v[42:43], v[42:43]
	v_mul_f32_e32 v155, v66, v66
	v_mul_f32_e32 v179, v67, v67
	v_mul_f32_e32 v177, v52, v52
	v_mul_f32_e32 v184, v53, v53
	v_mul_f32_e32 v176, v39, v39
	v_mul_f32_e32 v178, v41, v41
	v_pk_add_f32 v[180:181], v[142:143], v[142:143] op_sel:[0,1] op_sel_hi:[1,0]
	v_pk_add_f32 v[182:183], v[140:141], v[140:141] op_sel:[0,1] op_sel_hi:[1,0]
	v_pk_add_f32 v[156:157], v[144:145], v[156:157]
	v_pk_add_f32 v[140:141], v[146:147], v[162:163]
	v_pk_add_f32 v[142:143], v[158:159], v[166:167]
	v_pk_mov_b32 v[144:145], v[170:171], v[168:169] op_sel:[1,0]
	v_mov_b32_e32 v171, v169
	v_pk_mov_b32 v[146:147], v[174:175], v[172:173] op_sel:[1,0]
	v_mov_b32_e32 v175, v173
	v_mul_f32_e32 v185, v50, v50
	v_mul_f32_e32 v190, v51, v51
	v_mul_f32_e32 v193, v36, v36
	v_mul_f32_e32 v194, v37, v37
	v_mov_b32_e32 v161, v177
	v_mov_b32_e32 v165, v184
	v_pk_fma_f32 v[158:159], v[38:39], v[38:39], v[176:177] op_sel_hi:[1,1,0]
	v_pk_fma_f32 v[162:163], v[40:41], v[40:41], v[178:179] op_sel_hi:[1,1,0]
	v_pk_mul_f32 v[166:167], v[32:33], v[32:33]
	v_pk_mul_f32 v[168:169], v[30:31], v[30:31]
	v_pk_mul_f32 v[172:173], v[28:29], v[28:29]
	v_pk_mul_f32 v[176:177], v[26:27], v[26:27]
	v_mov_b32_e32 v181, v155
	v_mov_b32_e32 v183, v179
	v_pk_add_f32 v[186:187], v[140:141], v[140:141] op_sel:[0,1] op_sel_hi:[1,0]
	v_pk_add_f32 v[188:189], v[142:143], v[142:143] op_sel:[0,1] op_sel_hi:[1,0]
	v_pk_add_f32 v[144:145], v[144:145], v[170:171]
	v_pk_add_f32 v[146:147], v[146:147], v[174:175]
	v_mul_f32_e32 v191, v34, v34
	v_mul_f32_e32 v192, v35, v35
	v_pk_add_f32 v[160:161], v[160:161], v[164:165]
	v_mov_b32_e32 v159, v193
	v_mov_b32_e32 v163, v194
	v_pk_mov_b32 v[164:165], v[168:169], v[166:167] op_sel:[1,0]
	v_mov_b32_e32 v169, v167
	v_pk_mov_b32 v[166:167], v[176:177], v[172:173] op_sel:[1,0]
	v_mov_b32_e32 v177, v173
	v_pk_add_f32 v[170:171], v[180:181], v[182:183]
	v_mov_b32_e32 v187, v185
	v_mov_b32_e32 v189, v190
	v_pk_add_f32 v[172:173], v[144:145], v[144:145] op_sel:[0,1] op_sel_hi:[1,0]
	v_pk_add_f32 v[174:175], v[146:147], v[146:147] op_sel:[0,1] op_sel_hi:[1,0]
	v_pk_add_f32 v[158:159], v[158:159], v[162:163]
	v_pk_add_f32 v[156:157], v[170:171], v[156:157]
	v_pk_add_f32 v[162:163], v[186:187], v[188:189]
	v_mov_b32_e32 v173, v191
	v_mov_b32_e32 v175, v192
	v_add_f32_e32 v155, v156, v157
	v_pk_add_f32 v[156:157], v[162:163], v[160:161]
	v_pk_add_f32 v[160:161], v[172:173], v[174:175]
	v_add_f32_e32 v162, v156, v157
	v_pk_add_f32 v[156:157], v[160:161], v[158:159]
	ds_bpermute_b32 v158, v1, v155
	ds_bpermute_b32 v159, v1, v162
	v_add_f32_e32 v156, v156, v157
	ds_bpermute_b32 v157, v1, v156
	v_pk_add_f32 v[144:145], v[164:165], v[168:169]
	s_waitcnt lgkmcnt(2)
	v_add_f32_e32 v155, v155, v158
	ds_bpermute_b32 v158, v148, v155
	s_waitcnt lgkmcnt(2)
	v_add_f32_e32 v159, v162, v159
	ds_bpermute_b32 v160, v148, v159
	s_waitcnt lgkmcnt(2)
	v_add_f32_e32 v156, v156, v157
	ds_bpermute_b32 v157, v148, v156
	s_waitcnt lgkmcnt(2)
	v_add_f32_e32 v155, v155, v158
	ds_bpermute_b32 v158, v149, v155
	s_waitcnt lgkmcnt(2)
	v_add_f32_e32 v159, v159, v160
	ds_bpermute_b32 v160, v149, v159
	s_waitcnt lgkmcnt(2)
	v_add_f32_e32 v156, v156, v157
	ds_bpermute_b32 v157, v149, v156
	s_waitcnt lgkmcnt(2)
	v_add_f32_e32 v155, v155, v158
	ds_bpermute_b32 v158, v150, v155
	s_waitcnt lgkmcnt(2)
	v_add_f32_e32 v159, v159, v160
	ds_bpermute_b32 v160, v150, v159
	s_waitcnt lgkmcnt(2)
	v_add_f32_e32 v156, v156, v157
	ds_bpermute_b32 v157, v150, v156
	s_waitcnt lgkmcnt(2)
	v_add_f32_e32 v155, v155, v158
	ds_bpermute_b32 v158, v151, v155
	s_waitcnt lgkmcnt(2)
	v_add_f32_e32 v159, v159, v160
	ds_bpermute_b32 v160, v151, v159
	s_waitcnt lgkmcnt(2)
	v_add_f32_e32 v156, v156, v157
	ds_bpermute_b32 v157, v151, v156
	s_waitcnt lgkmcnt(2)
	v_add_f32_e32 v155, v155, v158
	ds_bpermute_b32 v158, v152, v155
	s_waitcnt lgkmcnt(2)
	v_add_f32_e32 v159, v159, v160
	ds_bpermute_b32 v160, v152, v159
	s_waitcnt lgkmcnt(2)
	v_add_f32_e32 v156, v156, v157
	ds_bpermute_b32 v157, v152, v156
	s_waitcnt lgkmcnt(2)
	v_add_f32_e32 v155, v155, v158
	v_fmamk_f32 v155, v155, 0x3a800000, v153
	s_waitcnt lgkmcnt(1)
	v_add_f32_e32 v158, v159, v160
	v_mul_f32_e32 v159, 0x4f800000, v155
	v_cmp_gt_f32_e32 vcc, s25, v155
	v_fmamk_f32 v158, v158, 0x3a800000, v153
	s_waitcnt lgkmcnt(0)
	v_add_f32_e32 v156, v156, v157
	v_cndmask_b32_e32 v155, v155, v159, vcc
	v_mul_f32_e32 v157, 0x4f800000, v158
	v_cmp_gt_f32_e64 s[6:7], s25, v158
	v_sqrt_f32_e32 v159, v155
	v_fmamk_f32 v156, v156, 0x3a800000, v153
	v_cndmask_b32_e64 v157, v158, v157, s[6:7]
	v_mul_f32_e32 v158, 0x4f800000, v156
	v_cmp_gt_f32_e64 s[8:9], s25, v156
	v_sqrt_f32_e32 v160, v157
	v_add_u32_e32 v161, -1, v159
	v_cndmask_b32_e64 v156, v156, v158, s[8:9]
	v_sqrt_f32_e32 v158, v156
	v_add_u32_e32 v162, 1, v159
	v_fma_f32 v163, -v161, v159, v155
	v_fma_f32 v164, -v162, v159, v155
	v_add_u32_e32 v165, -1, v160
	v_cmp_ge_f32_e64 s[10:11], 0, v163
	v_pk_add_f32 v[146:147], v[166:167], v[176:177]
	v_add_u32_e32 v166, 1, v160
	v_cndmask_b32_e64 v159, v159, v161, s[10:11]
	v_fma_f32 v161, -v165, v160, v157
	v_cmp_lt_f32_e64 s[10:11], 0, v164
	v_fma_f32 v163, -v166, v160, v157
	v_add_u32_e32 v167, -1, v158
	v_cndmask_b32_e64 v159, v159, v162, s[10:11]
	v_cmp_ge_f32_e64 s[10:11], 0, v161
	v_add_u32_e32 v168, 1, v158
	v_fma_f32 v161, -v167, v158, v156
	v_cndmask_b32_e64 v160, v160, v165, s[10:11]
	v_cmp_lt_f32_e64 s[10:11], 0, v163
	v_fma_f32 v162, -v168, v158, v156
	v_mul_f32_e32 v163, 0x37800000, v159
	v_cndmask_b32_e64 v160, v160, v166, s[10:11]
	v_cmp_ge_f32_e64 s[10:11], 0, v161
	v_cndmask_b32_e32 v159, v159, v163, vcc
	v_cmp_class_f32_e32 vcc, v155, v154
	v_cndmask_b32_e64 v158, v158, v167, s[10:11]
	v_cmp_lt_f32_e64 s[10:11], 0, v162
	v_mul_f32_e32 v161, 0x37800000, v160
	v_cndmask_b32_e32 v155, v159, v155, vcc
	v_cndmask_b32_e64 v158, v158, v168, s[10:11]
	v_cndmask_b32_e64 v159, v160, v161, s[6:7]
	v_cmp_class_f32_e32 vcc, v157, v154
	v_mul_f32_e32 v160, 0x37800000, v158
	v_div_scale_f32 v161, s[6:7], v155, v155, 1.0
	v_cndmask_b32_e32 v157, v159, v157, vcc
	v_cndmask_b32_e64 v158, v158, v160, s[8:9]
	v_cmp_class_f32_e32 vcc, v156, v154
	v_rcp_f32_e32 v159, v161
	v_div_scale_f32 v160, s[8:9], v157, v157, 1.0
	v_cndmask_b32_e32 v158, v158, v156, vcc
	v_rcp_f32_e32 v164, v160
	v_div_scale_f32 v165, s[10:11], v158, v158, 1.0
	v_rcp_f32_e32 v167, v165
	v_fma_f32 v156, -v161, v159, 1.0
	v_div_scale_f32 v162, s[6:7], 1.0, v155, 1.0
	v_fmac_f32_e32 v159, v156, v159
	v_fma_f32 v156, -v160, v164, 1.0
	v_mul_f32_e32 v168, v162, v159
	v_div_scale_f32 v163, s[8:9], 1.0, v157, 1.0
	v_fmac_f32_e32 v164, v156, v164
	v_fma_f32 v156, -v165, v167, 1.0
	v_fma_f32 v169, -v161, v168, v162
	v_div_scale_f32 v166, s[10:11], 1.0, v158, 1.0
	v_mul_f32_e32 v170, v163, v164
	v_fmac_f32_e32 v167, v156, v167
	v_fmac_f32_e32 v168, v169, v159
	v_fma_f32 v156, -v160, v170, v163
	v_mul_f32_e32 v169, v166, v167
	v_fma_f32 v161, -v161, v168, v162
	s_mov_b64 vcc, s[6:7]
	v_fmac_f32_e32 v170, v156, v164
	v_fma_f32 v156, -v165, v169, v166
	v_div_fmas_f32 v159, v161, v159, v168
	v_fma_f32 v160, -v160, v170, v163
	v_fmac_f32_e32 v169, v156, v167
	v_div_fixup_f32 v156, v159, v155, 1.0
	s_mov_b64 vcc, s[8:9]
	v_div_fmas_f32 v155, v160, v164, v170
	v_fma_f32 v159, -v165, v169, v166
	v_pk_mul_f32 v[80:81], v[80:81], v[156:157] op_sel_hi:[1,0]
	v_pk_mul_f32 v[78:79], v[78:79], v[156:157] op_sel_hi:[1,0]
	s_mov_b64 vcc, s[10:11]
	v_pk_add_f32 v[88:89], v[88:89], 1.0 op_sel_hi:[1,0]
	v_pk_add_f32 v[86:87], v[86:87], 1.0 op_sel_hi:[1,0]
	v_pk_mul_f32 v[76:77], v[76:77], v[156:157] op_sel_hi:[1,0]
	v_pk_mul_f32 v[74:75], v[74:75], v[156:157] op_sel_hi:[1,0]
	v_pk_mul_f32 v[72:73], v[72:73], v[156:157] op_sel_hi:[1,0]
	v_pk_mul_f32 v[70:71], v[70:71], v[156:157] op_sel_hi:[1,0]
	v_pk_mul_f32 v[68:69], v[68:69], v[156:157] op_sel_hi:[1,0]
	v_pk_mul_f32 v[66:67], v[66:67], v[156:157] op_sel_hi:[1,0]
	v_div_fixup_f32 v156, v155, v157, 1.0
	v_div_fmas_f32 v155, v159, v167, v169
	v_pk_mul_f32 v[78:79], v[78:79], v[2:3]
	v_pk_mul_f32 v[80:81], v[80:81], v[4:5]
	v_pk_mul_f32 v[64:65], v[64:65], v[156:157] op_sel_hi:[1,0]
	v_pk_mul_f32 v[62:63], v[62:63], v[156:157] op_sel_hi:[1,0]
	v_pk_mul_f32 v[60:61], v[60:61], v[156:157] op_sel_hi:[1,0]
	v_pk_mul_f32 v[58:59], v[58:59], v[156:157] op_sel_hi:[1,0]
	v_pk_mul_f32 v[56:57], v[56:57], v[156:157] op_sel_hi:[1,0]
	v_pk_mul_f32 v[54:55], v[54:55], v[156:157] op_sel_hi:[1,0]
	v_pk_mul_f32 v[52:53], v[52:53], v[156:157] op_sel_hi:[1,0]
	v_pk_mul_f32 v[156:157], v[50:51], v[156:157] op_sel_hi:[1,0]
	v_div_fixup_f32 v50, v155, v158, 1.0
	v_pk_fma_f32 v[80:81], v[80:81], v[88:89], v[84:85]
	v_pk_fma_f32 v[78:79], v[78:79], v[86:87], v[82:83]
	v_pk_mul_f32 v[86:87], v[52:53], v[16:17]
	v_pk_mul_f32 v[48:49], v[48:49], v[50:51] op_sel_hi:[1,0]
	v_pk_mul_f32 v[46:47], v[46:47], v[50:51] op_sel_hi:[1,0]
	v_pk_mul_f32 v[82:83], v[54:55], v[10:11]
	v_pk_mul_f32 v[84:85], v[156:157], v[14:15]
	v_pk_mul_f32 v[88:89], v[46:47], v[2:3]
	v_pk_mul_f32 v[156:157], v[48:49], v[4:5]
	v_cvt_pk_bf16_f32 v46, v78, v79
	v_cvt_pk_bf16_f32 v47, v80, v81
	global_store_dwordx2 v[102:103], v[46:47], off
	global_load_dwordx4 v[238:241], v[134:135], off
	s_nop 0
	global_load_dwordx4 v[242:245], v[124:125], off offset:1024
	v_pk_mul_f32 v[74:75], v[74:75], v[6:7]
	v_pk_mul_f32 v[76:77], v[76:77], v[8:9]
	v_pk_mul_f32 v[70:71], v[70:71], v[10:11]
	v_pk_mul_f32 v[72:73], v[72:73], v[12:13]
	v_pk_mul_f32 v[66:67], v[66:67], v[14:15]
	v_pk_mul_f32 v[68:69], v[68:69], v[16:17]
	v_pk_mul_f32 v[62:63], v[62:63], v[2:3]
	v_pk_mul_f32 v[64:65], v[64:65], v[4:5]
	v_pk_mul_f32 v[58:59], v[58:59], v[6:7]
	v_pk_mul_f32 v[60:61], v[60:61], v[8:9]
	v_pk_mul_f32 v[56:57], v[56:57], v[12:13]
	v_mul_f32_e32 v178, v23, v23
	v_mul_f32_e32 v184, v25, v25
	v_mul_f32_e32 v195, v18, v18
	v_mul_f32_e32 v196, v19, v19
	v_mul_f32_e32 v197, v20, v20
	v_mul_f32_e32 v198, v21, v21
	v_pk_fma_f32 v[140:141], v[22:23], v[22:23], v[178:179] op_sel_hi:[1,1,0]
	v_pk_fma_f32 v[142:143], v[24:25], v[24:25], v[184:185] op_sel_hi:[1,1,0]
	v_mov_b32_e32 v141, v197
	v_mov_b32_e32 v143, v198
	v_lshl_add_u64 v[94:95], v[94:95], 0, s[18:19]
	s_mov_b32 s8, s30
	s_cmp_lt_i32 s30, s24
	global_load_dwordx4 v[230:233], v[130:131], off
	s_nop 0
	global_load_dwordx4 v[234:237], v[124:125], off offset:2048
	s_waitcnt vmcnt(2) lgkmcnt(0)
	v_pk_add_f32 v[240:241], v[240:241], 1.0 op_sel_hi:[1,0]
	v_pk_add_f32 v[238:239], v[238:239], 1.0 op_sel_hi:[1,0]
	v_pk_fma_f32 v[240:241], v[76:77], v[240:241], v[244:245]
	v_pk_fma_f32 v[238:239], v[74:75], v[238:239], v[242:243]
	v_cvt_pk_bf16_f32 v238, v238, v239
	v_cvt_pk_bf16_f32 v239, v240, v241
	global_store_dwordx2 v[102:103], v[238:239], off offset:512
	global_load_dwordx4 v[238:241], v[128:129], off
	s_nop 0
	global_load_dwordx4 v[242:245], v[124:125], off offset:3072
	s_waitcnt vmcnt(3) lgkmcnt(0)
	v_pk_add_f32 v[232:233], v[232:233], 1.0 op_sel_hi:[1,0]
	v_pk_add_f32 v[230:231], v[230:231], 1.0 op_sel_hi:[1,0]
	v_pk_fma_f32 v[232:233], v[72:73], v[232:233], v[236:237]
	v_pk_fma_f32 v[230:231], v[70:71], v[230:231], v[234:235]
	v_cvt_pk_bf16_f32 v230, v230, v231
	v_cvt_pk_bf16_f32 v231, v232, v233
	global_store_dwordx2 v[102:103], v[230:231], off offset:1024
	global_load_dwordx4 v[230:233], v[126:127], off
	s_nop 0
	global_load_dwordx4 v[234:237], v[110:111], off
	s_waitcnt vmcnt(3) lgkmcnt(0)
	v_pk_add_f32 v[240:241], v[240:241], 1.0 op_sel_hi:[1,0]
	v_pk_add_f32 v[238:239], v[238:239], 1.0 op_sel_hi:[1,0]
	v_pk_fma_f32 v[240:241], v[68:69], v[240:241], v[244:245]
	v_pk_fma_f32 v[238:239], v[66:67], v[238:239], v[242:243]
	v_cvt_pk_bf16_f32 v238, v238, v239
	v_cvt_pk_bf16_f32 v239, v240, v241
	global_store_dwordx2 v[102:103], v[238:239], off offset:1536
	global_load_dwordx4 v[238:241], v[120:121], off
	s_nop 0
	global_load_dwordx4 v[242:245], v[110:111], off offset:1024
	s_waitcnt vmcnt(3) lgkmcnt(0)
	v_pk_add_f32 v[232:233], v[232:233], 1.0 op_sel_hi:[1,0]
	v_pk_add_f32 v[230:231], v[230:231], 1.0 op_sel_hi:[1,0]
	v_pk_fma_f32 v[232:233], v[64:65], v[232:233], v[236:237]
	v_pk_fma_f32 v[230:231], v[62:63], v[230:231], v[234:235]
	v_cvt_pk_bf16_f32 v230, v230, v231
	v_cvt_pk_bf16_f32 v231, v232, v233
	global_store_dwordx2 v[102:103], v[230:231], off offset:2048
	global_load_dwordx4 v[230:233], v[116:117], off
	s_nop 0
	global_load_dwordx4 v[234:237], v[110:111], off offset:2048
	s_waitcnt vmcnt(3) lgkmcnt(0)
	v_pk_add_f32 v[240:241], v[240:241], 1.0 op_sel_hi:[1,0]
	v_pk_add_f32 v[238:239], v[238:239], 1.0 op_sel_hi:[1,0]
	v_pk_fma_f32 v[240:241], v[60:61], v[240:241], v[244:245]
	v_pk_fma_f32 v[238:239], v[58:59], v[238:239], v[242:243]
	v_cvt_pk_bf16_f32 v238, v238, v239
	v_cvt_pk_bf16_f32 v239, v240, v241
	global_store_dwordx2 v[102:103], v[238:239], off offset:2560
	v_pk_add_f32 v[58:59], v[146:147], v[146:147] op_sel:[0,1] op_sel_hi:[1,0]
	v_pk_add_f32 v[60:61], v[140:141], v[142:143]
	v_mov_b32_e32 v59, v196
	global_load_dwordx4 v[238:241], v[112:113], off
	s_nop 0
	global_load_dwordx4 v[242:245], v[110:111], off offset:3072
	s_waitcnt vmcnt(3) lgkmcnt(0)
	v_pk_add_f32 v[232:233], v[232:233], 1.0 op_sel_hi:[1,0]
	v_pk_add_f32 v[230:231], v[230:231], 1.0 op_sel_hi:[1,0]
	v_pk_fma_f32 v[232:233], v[56:57], v[232:233], v[236:237]
	v_pk_fma_f32 v[230:231], v[82:83], v[230:231], v[234:235]
	v_cvt_pk_bf16_f32 v230, v230, v231
	v_cvt_pk_bf16_f32 v231, v232, v233
	global_store_dwordx2 v[102:103], v[230:231], off offset:3072
	v_pk_add_f32 v[56:57], v[144:145], v[144:145] op_sel:[0,1] op_sel_hi:[1,0]
	global_load_dwordx4 v[230:233], v[138:139], off
	s_nop 0
	global_load_dwordx4 v[234:237], v[108:109], off
	s_waitcnt vmcnt(3) lgkmcnt(0)
	v_pk_add_f32 v[240:241], v[240:241], 1.0 op_sel_hi:[1,0]
	v_pk_add_f32 v[238:239], v[238:239], 1.0 op_sel_hi:[1,0]
	v_pk_fma_f32 v[240:241], v[86:87], v[240:241], v[244:245]
	v_pk_fma_f32 v[238:239], v[84:85], v[238:239], v[242:243]
	v_cvt_pk_bf16_f32 v238, v238, v239
	v_cvt_pk_bf16_f32 v239, v240, v241
	global_store_dwordx2 v[102:103], v[238:239], off offset:3584
	v_mov_b32_e32 v57, v195
	global_load_dwordx4 v[238:241], v[136:137], off
	s_nop 0
	global_load_dwordx4 v[242:245], v[108:109], off offset:1024
	s_waitcnt vmcnt(3) lgkmcnt(0)
	v_pk_add_f32 v[232:233], v[232:233], 1.0 op_sel_hi:[1,0]
	v_pk_add_f32 v[230:231], v[230:231], 1.0 op_sel_hi:[1,0]
	v_pk_fma_f32 v[232:233], v[156:157], v[232:233], v[236:237]
	v_pk_fma_f32 v[230:231], v[88:89], v[230:231], v[234:235]
	v_bfe_u32 v51, v230, 16, 1
	v_bfe_u32 v234, v231, 16, 1
	v_add3_u32 v230, v230, v51, s26
	v_add3_u32 v231, v231, v234, s26
	v_lshrrev_b32_e32 v230, 16, v230
	v_and_or_b32 v230, v231, s27, v230
	v_cvt_pk_bf16_f32 v231, v232, v233
	global_store_dwordx2 v[104:105], v[230:231], off
	v_pk_mul_f32 v[44:45], v[44:45], v[50:51] op_sel_hi:[1,0]
	v_pk_mul_f32 v[42:43], v[42:43], v[50:51] op_sel_hi:[1,0]
	v_pk_mul_f32 v[44:45], v[44:45], v[8:9]
	v_pk_mul_f32 v[42:43], v[42:43], v[6:7]
	s_waitcnt vmcnt(1) lgkmcnt(0)
	v_pk_add_f32 v[240:241], v[240:241], 1.0 op_sel_hi:[1,0]
	v_pk_add_f32 v[238:239], v[238:239], 1.0 op_sel_hi:[1,0]
	v_pk_fma_f32 v[44:45], v[44:45], v[240:241], v[244:245]
	v_pk_fma_f32 v[42:43], v[42:43], v[238:239], v[242:243]
	v_cvt_pk_bf16_f32 v42, v42, v43
	v_cvt_pk_bf16_f32 v43, v44, v45
	global_store_dwordx2 v[104:105], v[42:43], off offset:512
	global_load_dwordx4 v[42:45], v[132:133], off
	s_nop 0
	global_load_dwordx4 v[46:49], v[108:109], off offset:2048
	v_pk_add_f32 v[52:53], v[56:57], v[58:59]
	s_waitcnt vmcnt(0) lgkmcnt(0)
	v_pk_add_f32 v[44:45], v[44:45], 1.0 op_sel_hi:[1,0]
	v_pk_add_f32 v[52:53], v[52:53], v[60:61]
	v_pk_add_f32 v[42:43], v[42:43], 1.0 op_sel_hi:[1,0]
	v_add_f32_e32 v51, v52, v53
	ds_bpermute_b32 v52, v1, v51
	s_waitcnt lgkmcnt(0)
	v_add_f32_e32 v51, v51, v52
	ds_bpermute_b32 v52, v148, v51
	s_waitcnt lgkmcnt(0)
	v_add_f32_e32 v51, v51, v52
	v_pk_mul_f32 v[40:41], v[40:41], v[50:51] op_sel_hi:[1,0]
	v_pk_mul_f32 v[38:39], v[38:39], v[50:51] op_sel_hi:[1,0]
	v_pk_mul_f32 v[40:41], v[40:41], v[12:13]
	v_pk_mul_f32 v[38:39], v[38:39], v[10:11]
	v_pk_fma_f32 v[40:41], v[40:41], v[44:45], v[48:49]
	v_pk_fma_f32 v[38:39], v[38:39], v[42:43], v[46:47]
	v_cvt_pk_bf16_f32 v38, v38, v39
	v_cvt_pk_bf16_f32 v39, v40, v41
	global_store_dwordx2 v[104:105], v[38:39], off offset:1024
	global_load_dwordx4 v[38:41], v[122:123], off
	s_nop 0
	global_load_dwordx4 v[42:45], v[108:109], off offset:3072
	v_pk_mul_f32 v[36:37], v[36:37], v[50:51] op_sel_hi:[1,0]
	v_pk_mul_f32 v[34:35], v[34:35], v[50:51] op_sel_hi:[1,0]
	v_pk_mul_f32 v[36:37], v[36:37], v[16:17]
	v_pk_mul_f32 v[34:35], v[34:35], v[14:15]
	ds_bpermute_b32 v46, v149, v51
	s_waitcnt lgkmcnt(0)
	v_add_f32_e32 v46, v51, v46
	ds_bpermute_b32 v47, v150, v46
	s_waitcnt lgkmcnt(0)
	v_add_f32_e32 v46, v46, v47
	ds_bpermute_b32 v47, v151, v46
	s_waitcnt lgkmcnt(0)
	v_add_f32_e32 v46, v46, v47
	ds_bpermute_b32 v47, v152, v46
	s_waitcnt lgkmcnt(0)
	v_add_f32_e32 v46, v46, v47
	v_fmamk_f32 v46, v46, 0x3a800000, v153
	v_mul_f32_e32 v47, 0x4f800000, v46
	v_cmp_gt_f32_e32 vcc, s25, v46
	s_waitcnt vmcnt(0)
	v_pk_add_f32 v[40:41], v[40:41], 1.0 op_sel_hi:[1,0]
	v_pk_add_f32 v[38:39], v[38:39], 1.0 op_sel_hi:[1,0]
	v_pk_fma_f32 v[36:37], v[36:37], v[40:41], v[44:45]
	v_pk_fma_f32 v[34:35], v[34:35], v[38:39], v[42:43]
	v_cvt_pk_bf16_f32 v34, v34, v35
	v_cvt_pk_bf16_f32 v35, v36, v37
	global_store_dwordx2 v[104:105], v[34:35], off offset:1536
	global_load_dwordx4 v[34:37], v[118:119], off
	s_nop 0
	global_load_dwordx4 v[38:41], v[106:107], off
	v_cndmask_b32_e32 v42, v46, v47, vcc
	v_sqrt_f32_e32 v43, v42
	s_waitcnt vmcnt(0) lgkmcnt(0)
	v_pk_add_f32 v[36:37], v[36:37], 1.0 op_sel_hi:[1,0]
	v_add_u32_e32 v44, -1, v43
	v_add_u32_e32 v45, 1, v43
	v_fma_f32 v46, -v44, v43, v42
	v_fma_f32 v47, -v45, v43, v42
	v_cmp_ge_f32_e64 s[6:7], 0, v46
	v_pk_add_f32 v[34:35], v[34:35], 1.0 op_sel_hi:[1,0]
	s_nop 0
	v_cndmask_b32_e64 v43, v43, v44, s[6:7]
	v_cmp_lt_f32_e64 s[6:7], 0, v47
	s_nop 1
	v_cndmask_b32_e64 v43, v43, v45, s[6:7]
	v_mul_f32_e32 v44, 0x37800000, v43
	v_cndmask_b32_e32 v43, v43, v44, vcc
	v_cmp_class_f32_e32 vcc, v42, v154
	s_nop 1
	v_cndmask_b32_e32 v42, v43, v42, vcc
	v_div_scale_f32 v43, s[6:7], v42, v42, 1.0
	v_rcp_f32_e32 v45, v43
	v_div_scale_f32 v44, vcc, 1.0, v42, 1.0
	v_fma_f32 v46, -v43, v45, 1.0
	v_fmac_f32_e32 v45, v46, v45
	v_mul_f32_e32 v46, v44, v45
	v_fma_f32 v47, -v43, v46, v44
	v_fmac_f32_e32 v46, v47, v45
	v_fma_f32 v43, -v43, v46, v44
	v_div_fmas_f32 v43, v43, v45, v46
	v_div_fixup_f32 v42, v43, v42, 1.0
	v_pk_mul_f32 v[32:33], v[32:33], v[42:43] op_sel_hi:[1,0]
	v_pk_mul_f32 v[30:31], v[30:31], v[42:43] op_sel_hi:[1,0]
	v_pk_mul_f32 v[32:33], v[32:33], v[4:5]
	v_pk_mul_f32 v[30:31], v[30:31], v[2:3]
	v_pk_fma_f32 v[32:33], v[32:33], v[36:37], v[40:41]
	v_pk_fma_f32 v[30:31], v[30:31], v[34:35], v[38:39]
	v_cvt_pk_bf16_f32 v30, v30, v31
	v_cvt_pk_bf16_f32 v31, v32, v33
	global_store_dwordx2 v[104:105], v[30:31], off offset:2048
	global_load_dwordx4 v[30:33], v[114:115], off
	s_nop 0
	global_load_dwordx4 v[34:37], v[106:107], off offset:1024
	v_pk_mul_f32 v[28:29], v[28:29], v[42:43] op_sel_hi:[1,0]
	v_pk_mul_f32 v[26:27], v[26:27], v[42:43] op_sel_hi:[1,0]
	v_pk_mul_f32 v[28:29], v[28:29], v[8:9]
	v_pk_mul_f32 v[26:27], v[26:27], v[6:7]
	v_lshl_add_u64 v[38:39], s[22:23], 0, v[98:99]
	v_pk_mul_f32 v[24:25], v[24:25], v[42:43] op_sel_hi:[1,0]
	v_pk_mul_f32 v[22:23], v[22:23], v[42:43] op_sel_hi:[1,0]
	v_pk_mul_f32 v[24:25], v[24:25], v[12:13]
	v_pk_mul_f32 v[22:23], v[22:23], v[10:11]
	v_pk_mul_f32 v[20:21], v[20:21], v[42:43] op_sel_hi:[1,0]
	v_pk_mul_f32 v[18:19], v[18:19], v[42:43] op_sel_hi:[1,0]
	v_pk_mul_f32 v[20:21], v[20:21], v[16:17]
	v_pk_mul_f32 v[18:19], v[18:19], v[14:15]
	s_waitcnt vmcnt(0) lgkmcnt(0)
	v_pk_add_f32 v[32:33], v[32:33], 1.0 op_sel_hi:[1,0]
	v_pk_add_f32 v[30:31], v[30:31], 1.0 op_sel_hi:[1,0]
	v_pk_fma_f32 v[28:29], v[28:29], v[32:33], v[36:37]
	v_pk_fma_f32 v[26:27], v[26:27], v[30:31], v[34:35]
	v_cvt_pk_bf16_f32 v26, v26, v27
	v_cvt_pk_bf16_f32 v27, v28, v29
	global_store_dwordx2 v[104:105], v[26:27], off offset:2560
	global_load_dwordx4 v[26:29], v[38:39], off
	s_nop 0
	global_load_dwordx4 v[30:33], v[106:107], off offset:2048
	v_lshl_add_u64 v[34:35], s[22:23], 0, v[100:101]
	s_waitcnt vmcnt(0) lgkmcnt(0)
	v_pk_add_f32 v[28:29], v[28:29], 1.0 op_sel_hi:[1,0]
	v_pk_add_f32 v[26:27], v[26:27], 1.0 op_sel_hi:[1,0]
	v_pk_fma_f32 v[24:25], v[24:25], v[28:29], v[32:33]
	v_pk_fma_f32 v[22:23], v[22:23], v[26:27], v[30:31]
	v_cvt_pk_bf16_f32 v22, v22, v23
	v_cvt_pk_bf16_f32 v23, v24, v25
	global_store_dwordx2 v[104:105], v[22:23], off offset:3072
	global_load_dwordx4 v[22:25], v[34:35], off
	s_nop 0
	global_load_dwordx4 v[26:29], v[106:107], off offset:3072
	s_waitcnt vmcnt(0) lgkmcnt(0)
	v_pk_add_f32 v[24:25], v[24:25], 1.0 op_sel_hi:[1,0]
	v_pk_add_f32 v[22:23], v[22:23], 1.0 op_sel_hi:[1,0]
	v_pk_fma_f32 v[20:21], v[20:21], v[24:25], v[28:29]
	v_pk_fma_f32 v[18:19], v[18:19], v[22:23], v[26:27]
	v_cvt_pk_bf16_f32 v18, v18, v19
	v_cvt_pk_bf16_f32 v19, v20, v21
	global_store_dwordx2 v[104:105], v[18:19], off offset:3584
	s_cbranch_scc1 .LBB0_3341

.LBB0_3449:
	v_lshl_add_u64 v[18:19], s[38:39], 0, v[94:95]
	v_lshl_add_u64 v[22:23], s[38:39], 0, v[92:93]
	v_add_co_u32_e32 v20, vcc, 0x7800000, v18
	v_add_co_u32_e64 v102, s[6:7], s30, v22
	s_nop 0
	v_addc_co_u32_e32 v21, vcc, 0, v19, vcc
	v_addc_co_u32_e64 v103, s[6:7], 0, v23, s[6:7]
	v_add_co_u32_e64 v104, s[6:7], s31, v22
	v_add_co_u32_e32 v22, vcc, 0x7801000, v18
	s_nop 0
	v_addc_co_u32_e64 v105, s[6:7], 0, v23, s[6:7]
	global_load_dwordx4 v[78:81], v[20:21], off
	global_load_dwordx4 v[74:77], v[20:21], off offset:1024
	global_load_dwordx4 v[70:73], v[20:21], off offset:2048
	global_load_dwordx4 v[66:69], v[20:21], off offset:3072
	v_addc_co_u32_e32 v23, vcc, 0, v19, vcc
	v_add_co_u32_e32 v20, vcc, 0x7802000, v18
	global_load_dwordx4 v[62:65], v[22:23], off
	global_load_dwordx4 v[58:61], v[22:23], off offset:1024
	global_load_dwordx4 v[54:57], v[22:23], off offset:2048
	global_load_dwordx4 v[50:53], v[22:23], off offset:3072
	v_addc_co_u32_e32 v21, vcc, 0, v19, vcc
	global_load_dwordx4 v[46:49], v[20:21], off
	global_load_dwordx4 v[42:45], v[20:21], off offset:1024
	global_load_dwordx4 v[38:41], v[20:21], off offset:2048
	global_load_dwordx4 v[34:37], v[20:21], off offset:3072
	v_add_co_u32_e32 v18, vcc, 0x7803000, v18
	s_ashr_i32 s8, s20, 13
	s_nop 0
	v_addc_co_u32_e32 v19, vcc, 0, v19, vcc
	global_load_dwordx4 v[30:33], v[18:19], off
	global_load_dwordx4 v[26:29], v[18:19], off offset:1024
	global_load_dwordx4 v[22:25], v[18:19], off offset:2048
	s_nop 0
	global_load_dwordx4 v[18:21], v[18:19], off offset:3072
	s_add_i32 s9, s20, 0xffffc002
	s_cmpk_lt_i32 s20, 0x4000
	s_cselect_b32 s6, s8, s9
	s_addk_i32 s6, 0x82
	s_mul_hi_i32 s7, s6, 0x9000
	s_mul_i32 s6, s6, 0x9000
	s_add_u32 s6, s26, s6
	s_addc_u32 s7, s27, s7
	s_add_u32 s10, s6, 0x1000
	s_addc_u32 s11, s7, 0
	v_lshl_add_u64 v[122:123], s[6:7], 0, v[90:91]
	v_lshl_add_u64 v[86:87], s[10:11], 0, v[90:91]
	global_load_dwordx4 v[82:85], v[122:123], off
	s_add_i32 s6, s20, 0xffffc003
	global_load_dwordx4 v[86:89], v[86:87], off
	s_cmpk_lt_i32 s20, 0x3fff
	s_cselect_b32 s6, s8, s6
	s_addk_i32 s6, 0x82
	s_mul_hi_i32 s7, s6, 0x9000
	s_mul_i32 s6, s6, 0x9000
	s_add_u32 s6, s26, s6
	s_addc_u32 s7, s27, s7
	v_lshl_add_u64 v[138:139], s[10:11], 0, v[96:97]
	v_lshl_add_u64 v[134:135], s[10:11], 0, v[98:99]
	v_lshl_add_u64 v[128:129], s[10:11], 0, v[100:101]
	s_add_u32 s10, s6, 0x1000
	v_lshl_add_u64 v[110:111], s[6:7], 0, v[90:91]
	s_addc_u32 s11, s7, 0
	s_add_i32 s6, s20, 0xffffc004
	s_cmpk_lt_i32 s20, 0x3ffe
	s_cselect_b32 s6, s8, s6
	s_addk_i32 s6, 0x82
	s_mul_hi_i32 s7, s6, 0x9000
	s_mul_i32 s6, s6, 0x9000
	v_lshl_add_u64 v[124:125], s[10:11], 0, v[90:91]
	v_lshl_add_u64 v[118:119], s[10:11], 0, v[96:97]
	v_lshl_add_u64 v[114:115], s[10:11], 0, v[98:99]
	v_lshl_add_u64 v[112:113], s[10:11], 0, v[100:101]
	s_add_u32 s10, s26, s6
	s_addc_u32 s11, s27, s7
	s_add_u32 s6, s10, 0x1000
	s_addc_u32 s7, s11, 0
	s_add_i32 s9, s20, 0xffffc005
	s_cmpk_lt_i32 s20, 0x3ffd
	v_lshl_add_u64 v[142:143], s[6:7], 0, v[90:91]
	v_lshl_add_u64 v[140:141], s[6:7], 0, v[96:97]
	v_lshl_add_u64 v[136:137], s[6:7], 0, v[98:99]
	v_lshl_add_u64 v[126:127], s[6:7], 0, v[100:101]
	s_cselect_b32 s6, s8, s9
	s_addk_i32 s6, 0x82
	s_mul_hi_i32 s7, s6, 0x9000
	s_mul_i32 s6, s6, 0x9000
	s_add_u32 s6, s26, s6
	s_addc_u32 s7, s27, s7
	s_add_u32 s44, s6, 0x1000
	v_lshl_add_u64 v[106:107], s[6:7], 0, v[90:91]
	s_addc_u32 s45, s7, 0
	v_lshl_add_u64 v[108:109], s[10:11], 0, v[90:91]
	v_lshl_add_u64 v[120:121], s[44:45], 0, v[90:91]
	v_lshl_add_u64 v[116:117], s[44:45], 0, v[96:97]
	s_add_i32 s20, s20, 32
	v_lshl_add_u64 v[92:93], v[92:93], 0, s[22:23]
	s_waitcnt vmcnt(0) lgkmcnt(0)
	v_pk_mul_f32 v[144:145], v[80:81], v[80:81]
	v_pk_mul_f32 v[146:147], v[78:79], v[78:79]
	v_pk_mul_f32 v[148:149], v[76:77], v[76:77]
	v_pk_mul_f32 v[150:151], v[74:75], v[74:75]
	v_mul_f32_e32 v160, v71, v71
	v_mul_f32_e32 v162, v73, v73
	v_pk_mov_b32 v[164:165], v[146:147], v[144:145] op_sel:[1,0]
	v_mov_b32_e32 v147, v145
	v_pk_mov_b32 v[144:145], v[150:151], v[148:149] op_sel:[1,0]
	v_mov_b32_e32 v151, v149
	v_mul_f32_e32 v173, v68, v68
	v_mul_f32_e32 v175, v69, v69
	v_pk_fma_f32 v[148:149], v[70:71], v[70:71], v[160:161] op_sel_hi:[1,1,0]
	v_pk_fma_f32 v[160:161], v[72:73], v[72:73], v[162:163] op_sel_hi:[1,1,0]
	v_pk_mul_f32 v[162:163], v[64:65], v[64:65]
	v_pk_mul_f32 v[166:167], v[62:63], v[62:63]
	v_pk_mul_f32 v[168:169], v[60:61], v[60:61]
	v_pk_mul_f32 v[170:171], v[58:59], v[58:59]
	v_mul_f32_e32 v172, v55, v55
	v_mul_f32_e32 v174, v57, v57
	v_pk_add_f32 v[146:147], v[164:165], v[146:147]
	v_pk_add_f32 v[144:145], v[144:145], v[150:151]
	v_mul_f32_e32 v159, v66, v66
	v_mul_f32_e32 v183, v67, v67
	v_mov_b32_e32 v149, v173
	v_mov_b32_e32 v161, v175
	v_pk_mov_b32 v[150:151], v[166:167], v[162:163] op_sel:[1,0]
	v_mov_b32_e32 v167, v163
	v_pk_mov_b32 v[162:163], v[170:171], v[168:169] op_sel:[1,0]
	v_mov_b32_e32 v171, v169
	v_pk_fma_f32 v[164:165], v[54:55], v[54:55], v[172:173] op_sel_hi:[1,1,0]
	v_pk_fma_f32 v[168:169], v[56:57], v[56:57], v[174:175] op_sel_hi:[1,1,0]
	v_pk_mul_f32 v[172:173], v[48:49], v[48:49]
	v_pk_mul_f32 v[174:175], v[46:47], v[46:47]
	v_pk_add_f32 v[184:185], v[146:147], v[146:147] op_sel:[0,1] op_sel_hi:[1,0]
	v_pk_add_f32 v[186:187], v[144:145], v[144:145] op_sel:[0,1] op_sel_hi:[1,0]
	v_mul_f32_e32 v181, v52, v52
	v_pk_mul_f32 v[176:177], v[44:45], v[44:45]
	v_pk_mul_f32 v[178:179], v[42:43], v[42:43]
	v_mul_f32_e32 v180, v39, v39
	v_mul_f32_e32 v182, v41, v41
	v_pk_add_f32 v[160:161], v[148:149], v[160:161]
	v_pk_add_f32 v[144:145], v[150:151], v[166:167]
	v_pk_add_f32 v[146:147], v[162:163], v[170:171]
	v_pk_mov_b32 v[148:149], v[174:175], v[172:173] op_sel:[1,0]
	v_mov_b32_e32 v175, v173
	v_mov_b32_e32 v185, v159
	v_mov_b32_e32 v187, v183
	v_mul_f32_e32 v189, v50, v50
	v_mul_f32_e32 v194, v51, v51
	v_mul_f32_e32 v188, v53, v53
	v_mul_f32_e32 v197, v36, v36
	v_mul_f32_e32 v198, v37, v37
	v_pk_mov_b32 v[150:151], v[178:179], v[176:177] op_sel:[1,0]
	v_mov_b32_e32 v179, v177
	v_pk_fma_f32 v[162:163], v[38:39], v[38:39], v[180:181] op_sel_hi:[1,1,0]
	v_pk_fma_f32 v[166:167], v[40:41], v[40:41], v[182:183] op_sel_hi:[1,1,0]
	v_pk_add_f32 v[190:191], v[144:145], v[144:145] op_sel:[0,1] op_sel_hi:[1,0]
	v_pk_add_f32 v[192:193], v[146:147], v[146:147] op_sel:[0,1] op_sel_hi:[1,0]
	v_pk_add_f32 v[148:149], v[148:149], v[174:175]
	v_pk_add_f32 v[174:175], v[184:185], v[186:187]
	v_mov_b32_e32 v165, v181
	v_mov_b32_e32 v169, v188
	v_pk_mul_f32 v[170:171], v[32:33], v[32:33]
	v_pk_mul_f32 v[172:173], v[30:31], v[30:31]
	v_pk_mul_f32 v[176:177], v[28:29], v[28:29]
	v_pk_mul_f32 v[180:181], v[26:27], v[26:27]
	v_pk_add_f32 v[150:151], v[150:151], v[178:179]
	v_mov_b32_e32 v163, v197
	v_mov_b32_e32 v167, v198
	v_mov_b32_e32 v191, v189
	v_mov_b32_e32 v193, v194
	v_pk_add_f32 v[160:161], v[174:175], v[160:161]
	v_mul_f32_e32 v195, v34, v34
	v_mul_f32_e32 v196, v35, v35
	v_pk_add_f32 v[164:165], v[164:165], v[168:169]
	v_pk_mov_b32 v[168:169], v[172:173], v[170:171] op_sel:[1,0]
	v_mov_b32_e32 v173, v171
	v_pk_mov_b32 v[170:171], v[180:181], v[176:177] op_sel:[1,0]
	v_mov_b32_e32 v181, v177
	v_pk_add_f32 v[176:177], v[148:149], v[148:149] op_sel:[0,1] op_sel_hi:[1,0]
	v_pk_add_f32 v[178:179], v[150:151], v[150:151] op_sel:[0,1] op_sel_hi:[1,0]
	v_pk_add_f32 v[162:163], v[162:163], v[166:167]
	v_pk_add_f32 v[166:167], v[190:191], v[192:193]
	v_add_f32_e32 v159, v160, v161
	v_mov_b32_e32 v177, v195
	v_mov_b32_e32 v179, v196
	v_pk_add_f32 v[160:161], v[166:167], v[164:165]
	ds_bpermute_b32 v167, v133, v159
	v_pk_add_f32 v[164:165], v[176:177], v[178:179]
	v_add_f32_e32 v166, v160, v161
	v_pk_add_f32 v[160:161], v[164:165], v[162:163]
	ds_bpermute_b32 v162, v133, v166
	v_add_f32_e32 v160, v160, v161
	ds_bpermute_b32 v161, v133, v160
	s_waitcnt lgkmcnt(2)
	v_add_f32_e32 v159, v159, v167
	ds_bpermute_b32 v163, v152, v159
	s_waitcnt lgkmcnt(2)
	v_add_f32_e32 v162, v166, v162
	ds_bpermute_b32 v164, v152, v162
	s_waitcnt lgkmcnt(2)
	v_add_f32_e32 v160, v160, v161
	ds_bpermute_b32 v161, v152, v160
	s_waitcnt lgkmcnt(2)
	v_add_f32_e32 v159, v159, v163
	ds_bpermute_b32 v163, v153, v159
	s_waitcnt lgkmcnt(2)
	v_add_f32_e32 v162, v162, v164
	ds_bpermute_b32 v164, v153, v162
	s_waitcnt lgkmcnt(2)
	v_add_f32_e32 v160, v160, v161
	ds_bpermute_b32 v161, v153, v160
	s_waitcnt lgkmcnt(2)
	v_add_f32_e32 v159, v159, v163
	ds_bpermute_b32 v163, v154, v159
	s_waitcnt lgkmcnt(2)
	v_add_f32_e32 v162, v162, v164
	ds_bpermute_b32 v164, v154, v162
	s_waitcnt lgkmcnt(2)
	v_add_f32_e32 v160, v160, v161
	ds_bpermute_b32 v161, v154, v160
	s_waitcnt lgkmcnt(2)
	v_add_f32_e32 v159, v159, v163
	ds_bpermute_b32 v163, v155, v159
	s_waitcnt lgkmcnt(2)
	v_add_f32_e32 v162, v162, v164
	ds_bpermute_b32 v164, v155, v162
	s_waitcnt lgkmcnt(2)
	v_add_f32_e32 v160, v160, v161
	ds_bpermute_b32 v161, v155, v160
	s_waitcnt lgkmcnt(2)
	v_add_f32_e32 v159, v159, v163
	ds_bpermute_b32 v163, v156, v159
	s_waitcnt lgkmcnt(2)
	v_add_f32_e32 v162, v162, v164
	ds_bpermute_b32 v164, v156, v162
	s_waitcnt lgkmcnt(2)
	v_add_f32_e32 v160, v160, v161
	ds_bpermute_b32 v161, v156, v160
	s_waitcnt lgkmcnt(2)
	v_add_f32_e32 v159, v159, v163
	v_fmamk_f32 v159, v159, 0x3a800000, v157
	s_waitcnt lgkmcnt(1)
	v_add_f32_e32 v162, v162, v164
	v_mul_f32_e32 v163, 0x4f800000, v159
	v_cmp_gt_f32_e32 vcc, s21, v159
	v_fmamk_f32 v162, v162, 0x3a800000, v157
	s_waitcnt lgkmcnt(0)
	v_add_f32_e32 v160, v160, v161
	v_cndmask_b32_e32 v159, v159, v163, vcc
	v_mul_f32_e32 v161, 0x4f800000, v162
	v_cmp_gt_f32_e64 s[6:7], s21, v162
	v_sqrt_f32_e32 v163, v159
	v_fmamk_f32 v160, v160, 0x3a800000, v157
	v_cndmask_b32_e64 v161, v162, v161, s[6:7]
	v_mul_f32_e32 v162, 0x4f800000, v160
	v_cmp_gt_f32_e64 s[8:9], s21, v160
	v_sqrt_f32_e32 v164, v161
	v_add_u32_e32 v165, -1, v163
	v_cndmask_b32_e64 v160, v160, v162, s[8:9]
	v_sqrt_f32_e32 v162, v160
	v_add_u32_e32 v166, 1, v163
	v_fma_f32 v167, -v165, v163, v159
	v_pk_add_f32 v[148:149], v[168:169], v[172:173]
	v_fma_f32 v168, -v166, v163, v159
	v_add_u32_e32 v169, -1, v164
	v_cmp_ge_f32_e64 s[10:11], 0, v167
	v_pk_add_f32 v[150:151], v[170:171], v[180:181]
	v_add_u32_e32 v170, 1, v164
	v_cndmask_b32_e64 v163, v163, v165, s[10:11]
	v_fma_f32 v165, -v169, v164, v161
	v_cmp_lt_f32_e64 s[10:11], 0, v168
	v_fma_f32 v167, -v170, v164, v161
	v_add_u32_e32 v171, -1, v162
	v_cndmask_b32_e64 v163, v163, v166, s[10:11]
	v_cmp_ge_f32_e64 s[10:11], 0, v165
	v_add_u32_e32 v172, 1, v162
	v_fma_f32 v165, -v171, v162, v160
	v_cndmask_b32_e64 v164, v164, v169, s[10:11]
	v_cmp_lt_f32_e64 s[10:11], 0, v167
	v_fma_f32 v166, -v172, v162, v160
	v_mul_f32_e32 v167, 0x37800000, v163
	v_cndmask_b32_e64 v164, v164, v170, s[10:11]
	v_cmp_ge_f32_e64 s[10:11], 0, v165
	v_cndmask_b32_e32 v163, v163, v167, vcc
	v_cmp_class_f32_e32 vcc, v159, v158
	v_cndmask_b32_e64 v162, v162, v171, s[10:11]
	v_cmp_lt_f32_e64 s[10:11], 0, v166
	v_mul_f32_e32 v165, 0x37800000, v164
	v_cndmask_b32_e32 v159, v163, v159, vcc
	v_cndmask_b32_e64 v162, v162, v172, s[10:11]
	v_cndmask_b32_e64 v163, v164, v165, s[6:7]
	v_cmp_class_f32_e32 vcc, v161, v158
	v_mul_f32_e32 v164, 0x37800000, v162
	v_div_scale_f32 v165, s[6:7], v159, v159, 1.0
	v_cndmask_b32_e32 v161, v163, v161, vcc
	v_cndmask_b32_e64 v162, v162, v164, s[8:9]
	v_cmp_class_f32_e32 vcc, v160, v158
	v_rcp_f32_e32 v163, v165
	v_div_scale_f32 v164, s[8:9], v161, v161, 1.0
	v_cndmask_b32_e32 v162, v162, v160, vcc
	v_rcp_f32_e32 v168, v164
	v_div_scale_f32 v169, s[10:11], v162, v162, 1.0
	v_rcp_f32_e32 v171, v169
	v_fma_f32 v160, -v165, v163, 1.0
	v_div_scale_f32 v166, s[6:7], 1.0, v159, 1.0
	v_fmac_f32_e32 v163, v160, v163
	v_fma_f32 v160, -v164, v168, 1.0
	v_mul_f32_e32 v172, v166, v163
	v_div_scale_f32 v167, s[8:9], 1.0, v161, 1.0
	v_fmac_f32_e32 v168, v160, v168
	v_fma_f32 v160, -v169, v171, 1.0
	v_fma_f32 v173, -v165, v172, v166
	v_div_scale_f32 v170, s[10:11], 1.0, v162, 1.0
	v_mul_f32_e32 v174, v167, v168
	v_fmac_f32_e32 v171, v160, v171
	v_fmac_f32_e32 v172, v173, v163
	v_fma_f32 v160, -v164, v174, v167
	v_mul_f32_e32 v173, v170, v171
	v_fma_f32 v165, -v165, v172, v166
	s_mov_b64 vcc, s[6:7]
	v_fmac_f32_e32 v174, v160, v168
	v_fma_f32 v160, -v169, v173, v170
	v_div_fmas_f32 v163, v165, v163, v172
	v_fma_f32 v164, -v164, v174, v167
	v_fmac_f32_e32 v173, v160, v171
	v_div_fixup_f32 v160, v163, v159, 1.0
	s_mov_b64 vcc, s[8:9]
	v_div_fmas_f32 v159, v164, v168, v174
	v_fma_f32 v163, -v169, v173, v170
	v_pk_mul_f32 v[80:81], v[80:81], v[160:161] op_sel_hi:[1,0]
	v_pk_mul_f32 v[78:79], v[78:79], v[160:161] op_sel_hi:[1,0]
	s_mov_b64 vcc, s[10:11]
	v_pk_add_f32 v[88:89], v[88:89], 1.0 op_sel_hi:[1,0]
	v_pk_add_f32 v[86:87], v[86:87], 1.0 op_sel_hi:[1,0]
	v_pk_mul_f32 v[76:77], v[76:77], v[160:161] op_sel_hi:[1,0]
	v_pk_mul_f32 v[74:75], v[74:75], v[160:161] op_sel_hi:[1,0]
	v_pk_mul_f32 v[72:73], v[72:73], v[160:161] op_sel_hi:[1,0]
	v_pk_mul_f32 v[70:71], v[70:71], v[160:161] op_sel_hi:[1,0]
	v_pk_mul_f32 v[68:69], v[68:69], v[160:161] op_sel_hi:[1,0]
	v_pk_mul_f32 v[66:67], v[66:67], v[160:161] op_sel_hi:[1,0]
	v_div_fixup_f32 v160, v159, v161, 1.0
	v_div_fmas_f32 v159, v163, v171, v173
	v_pk_mul_f32 v[78:79], v[78:79], v[2:3]
	v_pk_mul_f32 v[80:81], v[80:81], v[4:5]
	v_pk_mul_f32 v[64:65], v[64:65], v[160:161] op_sel_hi:[1,0]
	v_pk_mul_f32 v[62:63], v[62:63], v[160:161] op_sel_hi:[1,0]
	v_pk_mul_f32 v[60:61], v[60:61], v[160:161] op_sel_hi:[1,0]
	v_pk_mul_f32 v[58:59], v[58:59], v[160:161] op_sel_hi:[1,0]
	v_pk_mul_f32 v[56:57], v[56:57], v[160:161] op_sel_hi:[1,0]
	v_pk_mul_f32 v[54:55], v[54:55], v[160:161] op_sel_hi:[1,0]
	v_pk_mul_f32 v[52:53], v[52:53], v[160:161] op_sel_hi:[1,0]
	v_pk_mul_f32 v[50:51], v[50:51], v[160:161] op_sel_hi:[1,0]
	v_div_fixup_f32 v160, v159, v162, 1.0
	v_pk_fma_f32 v[80:81], v[80:81], v[88:89], v[84:85]
	v_pk_fma_f32 v[78:79], v[78:79], v[86:87], v[82:83]
	v_pk_mul_f32 v[82:83], v[50:51], v[14:15]
	v_pk_mul_f32 v[84:85], v[52:53], v[16:17]
	v_pk_mul_f32 v[48:49], v[48:49], v[160:161] op_sel_hi:[1,0]
	v_pk_mul_f32 v[46:47], v[46:47], v[160:161] op_sel_hi:[1,0]
	v_pk_mul_f32 v[86:87], v[46:47], v[2:3]
	v_pk_mul_f32 v[88:89], v[48:49], v[4:5]
	v_cvt_pk_bf16_f32 v46, v78, v79
	v_cvt_pk_bf16_f32 v47, v80, v81
	global_store_dwordx2 v[102:103], v[46:47], off
	global_load_dwordx4 v[238:241], v[138:139], off
	s_nop 0
	global_load_dwordx4 v[242:245], v[122:123], off offset:1024
	v_pk_mul_f32 v[74:75], v[74:75], v[6:7]
	v_pk_mul_f32 v[76:77], v[76:77], v[8:9]
	v_pk_mul_f32 v[70:71], v[70:71], v[10:11]
	v_pk_mul_f32 v[72:73], v[72:73], v[12:13]
	v_pk_mul_f32 v[66:67], v[66:67], v[14:15]
	v_pk_mul_f32 v[68:69], v[68:69], v[16:17]
	v_pk_mul_f32 v[62:63], v[62:63], v[2:3]
	v_pk_mul_f32 v[64:65], v[64:65], v[4:5]
	v_pk_mul_f32 v[58:59], v[58:59], v[6:7]
	v_pk_mul_f32 v[60:61], v[60:61], v[8:9]
	v_pk_mul_f32 v[54:55], v[54:55], v[10:11]
	v_pk_mul_f32 v[56:57], v[56:57], v[12:13]
	v_pk_mul_f32 v[44:45], v[44:45], v[160:161] op_sel_hi:[1,0]
	v_pk_mul_f32 v[42:43], v[42:43], v[160:161] op_sel_hi:[1,0]
	v_pk_mul_f32 v[44:45], v[44:45], v[8:9]
	v_pk_mul_f32 v[42:43], v[42:43], v[6:7]
	v_pk_mul_f32 v[40:41], v[40:41], v[160:161] op_sel_hi:[1,0]
	v_pk_mul_f32 v[38:39], v[38:39], v[160:161] op_sel_hi:[1,0]
	v_pk_mul_f32 v[40:41], v[40:41], v[12:13]
	v_pk_mul_f32 v[38:39], v[38:39], v[10:11]
	v_pk_mul_f32 v[36:37], v[36:37], v[160:161] op_sel_hi:[1,0]
	v_pk_mul_f32 v[34:35], v[34:35], v[160:161] op_sel_hi:[1,0]
	v_pk_mul_f32 v[36:37], v[36:37], v[16:17]
	v_pk_mul_f32 v[34:35], v[34:35], v[14:15]
	v_mul_f32_e32 v182, v23, v23
	v_mul_f32_e32 v188, v25, v25
	v_mul_f32_e32 v199, v18, v18
	v_mul_f32_e32 v200, v19, v19
	v_mul_f32_e32 v201, v20, v20
	v_mul_f32_e32 v202, v21, v21
	v_pk_fma_f32 v[144:145], v[22:23], v[22:23], v[182:183] op_sel_hi:[1,1,0]
	v_pk_fma_f32 v[146:147], v[24:25], v[24:25], v[188:189] op_sel_hi:[1,1,0]
	v_mov_b32_e32 v145, v201
	v_mov_b32_e32 v147, v202
	v_lshl_add_u64 v[94:95], v[94:95], 0, s[24:25]
	s_cmp_lt_i32 s20, s13
	global_load_dwordx4 v[230:233], v[134:135], off
	s_nop 0
	global_load_dwordx4 v[234:237], v[122:123], off offset:2048
	s_waitcnt vmcnt(2) lgkmcnt(0)
	v_pk_add_f32 v[240:241], v[240:241], 1.0 op_sel_hi:[1,0]
	v_pk_add_f32 v[238:239], v[238:239], 1.0 op_sel_hi:[1,0]
	v_pk_fma_f32 v[240:241], v[76:77], v[240:241], v[244:245]
	v_pk_fma_f32 v[238:239], v[74:75], v[238:239], v[242:243]
	v_cvt_pk_bf16_f32 v238, v238, v239
	v_cvt_pk_bf16_f32 v239, v240, v241
	global_store_dwordx2 v[102:103], v[238:239], off offset:512
	global_load_dwordx4 v[238:241], v[128:129], off
	s_nop 0
	global_load_dwordx4 v[242:245], v[122:123], off offset:3072
	s_waitcnt vmcnt(3) lgkmcnt(0)
	v_pk_add_f32 v[232:233], v[232:233], 1.0 op_sel_hi:[1,0]
	v_pk_add_f32 v[230:231], v[230:231], 1.0 op_sel_hi:[1,0]
	v_pk_fma_f32 v[232:233], v[72:73], v[232:233], v[236:237]
	v_pk_fma_f32 v[230:231], v[70:71], v[230:231], v[234:235]
	v_cvt_pk_bf16_f32 v230, v230, v231
	v_cvt_pk_bf16_f32 v231, v232, v233
	global_store_dwordx2 v[102:103], v[230:231], off offset:1024
	global_load_dwordx4 v[230:233], v[124:125], off
	s_nop 0
	global_load_dwordx4 v[234:237], v[110:111], off
	s_waitcnt vmcnt(3) lgkmcnt(0)
	v_pk_add_f32 v[240:241], v[240:241], 1.0 op_sel_hi:[1,0]
	v_pk_add_f32 v[238:239], v[238:239], 1.0 op_sel_hi:[1,0]
	v_pk_fma_f32 v[240:241], v[68:69], v[240:241], v[244:245]
	v_pk_fma_f32 v[238:239], v[66:67], v[238:239], v[242:243]
	v_cvt_pk_bf16_f32 v238, v238, v239
	v_cvt_pk_bf16_f32 v239, v240, v241
	global_store_dwordx2 v[102:103], v[238:239], off offset:1536
	global_load_dwordx4 v[238:241], v[118:119], off
	s_nop 0
	global_load_dwordx4 v[242:245], v[110:111], off offset:1024
	s_waitcnt vmcnt(3) lgkmcnt(0)
	v_pk_add_f32 v[232:233], v[232:233], 1.0 op_sel_hi:[1,0]
	v_pk_add_f32 v[230:231], v[230:231], 1.0 op_sel_hi:[1,0]
	v_pk_fma_f32 v[232:233], v[64:65], v[232:233], v[236:237]
	v_pk_fma_f32 v[230:231], v[62:63], v[230:231], v[234:235]
	v_cvt_pk_bf16_f32 v230, v230, v231
	v_cvt_pk_bf16_f32 v231, v232, v233
	global_store_dwordx2 v[102:103], v[230:231], off offset:2048
	global_load_dwordx4 v[230:233], v[114:115], off
	s_nop 0
	global_load_dwordx4 v[234:237], v[110:111], off offset:2048
	s_waitcnt vmcnt(3) lgkmcnt(0)
	v_pk_add_f32 v[240:241], v[240:241], 1.0 op_sel_hi:[1,0]
	v_pk_add_f32 v[238:239], v[238:239], 1.0 op_sel_hi:[1,0]
	v_pk_fma_f32 v[240:241], v[60:61], v[240:241], v[244:245]
	v_pk_fma_f32 v[238:239], v[58:59], v[238:239], v[242:243]
	v_cvt_pk_bf16_f32 v238, v238, v239
	v_cvt_pk_bf16_f32 v239, v240, v241
	global_store_dwordx2 v[102:103], v[238:239], off offset:2560
	v_pk_add_f32 v[58:59], v[144:145], v[146:147]
	global_load_dwordx4 v[238:241], v[112:113], off
	s_nop 0
	global_load_dwordx4 v[242:245], v[110:111], off offset:3072
	s_waitcnt vmcnt(3) lgkmcnt(0)
	v_pk_add_f32 v[232:233], v[232:233], 1.0 op_sel_hi:[1,0]
	v_pk_add_f32 v[230:231], v[230:231], 1.0 op_sel_hi:[1,0]
	v_pk_fma_f32 v[232:233], v[56:57], v[232:233], v[236:237]
	v_pk_fma_f32 v[230:231], v[54:55], v[230:231], v[234:235]
	v_cvt_pk_bf16_f32 v230, v230, v231
	v_cvt_pk_bf16_f32 v231, v232, v233
	global_store_dwordx2 v[102:103], v[230:231], off offset:3072
	v_pk_add_f32 v[54:55], v[148:149], v[148:149] op_sel:[0,1] op_sel_hi:[1,0]
	v_pk_add_f32 v[56:57], v[150:151], v[150:151] op_sel:[0,1] op_sel_hi:[1,0]
	v_mov_b32_e32 v55, v199
	v_mov_b32_e32 v57, v200
	global_load_dwordx4 v[230:233], v[142:143], off
	s_nop 0
	global_load_dwordx4 v[234:237], v[108:109], off
	s_waitcnt vmcnt(3) lgkmcnt(0)
	v_pk_add_f32 v[240:241], v[240:241], 1.0 op_sel_hi:[1,0]
	v_pk_add_f32 v[238:239], v[238:239], 1.0 op_sel_hi:[1,0]
	v_pk_fma_f32 v[240:241], v[84:85], v[240:241], v[244:245]
	v_pk_fma_f32 v[238:239], v[82:83], v[238:239], v[242:243]
	v_cvt_pk_bf16_f32 v238, v238, v239
	v_cvt_pk_bf16_f32 v239, v240, v241
	global_store_dwordx2 v[102:103], v[238:239], off offset:3584
	global_load_dwordx4 v[238:241], v[140:141], off
	s_nop 0
	global_load_dwordx4 v[242:245], v[108:109], off offset:1024
	s_waitcnt vmcnt(3) lgkmcnt(0)
	v_pk_add_f32 v[232:233], v[232:233], 1.0 op_sel_hi:[1,0]
	v_pk_add_f32 v[230:231], v[230:231], 1.0 op_sel_hi:[1,0]
	v_pk_fma_f32 v[232:233], v[88:89], v[232:233], v[236:237]
	v_pk_fma_f32 v[230:231], v[86:87], v[230:231], v[234:235]
	v_cvt_pk_bf16_f32 v230, v230, v231
	v_cvt_pk_bf16_f32 v231, v232, v233
	global_store_dwordx2 v[104:105], v[230:231], off
	global_load_dwordx4 v[230:233], v[136:137], off
	s_nop 0
	global_load_dwordx4 v[234:237], v[108:109], off offset:2048
	s_waitcnt vmcnt(3) lgkmcnt(0)
	v_pk_add_f32 v[240:241], v[240:241], 1.0 op_sel_hi:[1,0]
	v_pk_add_f32 v[238:239], v[238:239], 1.0 op_sel_hi:[1,0]
	v_pk_fma_f32 v[44:45], v[44:45], v[240:241], v[244:245]
	v_pk_fma_f32 v[42:43], v[42:43], v[238:239], v[242:243]
	v_cvt_pk_bf16_f32 v42, v42, v43
	v_cvt_pk_bf16_f32 v43, v44, v45
	global_store_dwordx2 v[104:105], v[42:43], off offset:512
	v_pk_add_f32 v[50:51], v[54:55], v[56:57]
	global_load_dwordx4 v[238:241], v[126:127], off
	s_nop 0
	global_load_dwordx4 v[242:245], v[108:109], off offset:3072
	s_waitcnt vmcnt(3) lgkmcnt(0)
	v_pk_add_f32 v[232:233], v[232:233], 1.0 op_sel_hi:[1,0]
	v_pk_add_f32 v[230:231], v[230:231], 1.0 op_sel_hi:[1,0]
	v_pk_fma_f32 v[40:41], v[40:41], v[232:233], v[236:237]
	v_pk_fma_f32 v[38:39], v[38:39], v[230:231], v[234:235]
	v_cvt_pk_bf16_f32 v38, v38, v39
	v_cvt_pk_bf16_f32 v39, v40, v41
	global_store_dwordx2 v[104:105], v[38:39], off offset:1024
	v_pk_add_f32 v[50:51], v[50:51], v[58:59]
	s_waitcnt vmcnt(1) lgkmcnt(0)
	v_pk_add_f32 v[240:241], v[240:241], 1.0 op_sel_hi:[1,0]
	v_pk_add_f32 v[238:239], v[238:239], 1.0 op_sel_hi:[1,0]
	v_pk_fma_f32 v[36:37], v[36:37], v[240:241], v[244:245]
	v_pk_fma_f32 v[34:35], v[34:35], v[238:239], v[242:243]
	v_cvt_pk_bf16_f32 v34, v34, v35
	v_cvt_pk_bf16_f32 v35, v36, v37
	global_store_dwordx2 v[104:105], v[34:35], off offset:1536
	global_load_dwordx4 v[34:37], v[120:121], off
	s_nop 0
	global_load_dwordx4 v[38:41], v[106:107], off
	v_add_f32_e32 v50, v50, v51
	ds_bpermute_b32 v51, v133, v50
	s_waitcnt lgkmcnt(0)
	v_add_f32_e32 v50, v50, v51
	ds_bpermute_b32 v51, v152, v50
	s_waitcnt lgkmcnt(0)
	v_add_f32_e32 v50, v50, v51
	ds_bpermute_b32 v46, v153, v50
	s_waitcnt lgkmcnt(0)
	v_add_f32_e32 v46, v50, v46
	ds_bpermute_b32 v47, v154, v46
	s_waitcnt lgkmcnt(0)
	v_add_f32_e32 v46, v46, v47
	ds_bpermute_b32 v47, v155, v46
	s_waitcnt lgkmcnt(0)
	v_add_f32_e32 v46, v46, v47
	ds_bpermute_b32 v47, v156, v46
	s_waitcnt lgkmcnt(0)
	v_add_f32_e32 v46, v46, v47
	v_fmamk_f32 v46, v46, 0x3a800000, v157
	v_mul_f32_e32 v47, 0x4f800000, v46
	v_cmp_gt_f32_e32 vcc, s21, v46
	s_waitcnt vmcnt(0)
	v_pk_add_f32 v[36:37], v[36:37], 1.0 op_sel_hi:[1,0]
	v_cndmask_b32_e32 v42, v46, v47, vcc
	v_sqrt_f32_e32 v43, v42
	v_pk_add_f32 v[34:35], v[34:35], 1.0 op_sel_hi:[1,0]
	v_add_u32_e32 v44, -1, v43
	v_add_u32_e32 v45, 1, v43
	v_fma_f32 v46, -v44, v43, v42
	v_fma_f32 v47, -v45, v43, v42
	v_cmp_ge_f32_e64 s[6:7], 0, v46
	s_nop 1
	v_cndmask_b32_e64 v43, v43, v44, s[6:7]
	v_cmp_lt_f32_e64 s[6:7], 0, v47
	s_nop 1
	v_cndmask_b32_e64 v43, v43, v45, s[6:7]
	v_mul_f32_e32 v44, 0x37800000, v43
	v_cndmask_b32_e32 v43, v43, v44, vcc
	v_cmp_class_f32_e32 vcc, v42, v158
	s_nop 1
	v_cndmask_b32_e32 v42, v43, v42, vcc
	v_div_scale_f32 v43, s[6:7], v42, v42, 1.0
	v_rcp_f32_e32 v45, v43
	v_div_scale_f32 v44, vcc, 1.0, v42, 1.0
	v_fma_f32 v46, -v43, v45, 1.0
	v_fmac_f32_e32 v45, v46, v45
	v_mul_f32_e32 v46, v44, v45
	v_fma_f32 v47, -v43, v46, v44
	v_fmac_f32_e32 v46, v47, v45
	v_fma_f32 v43, -v43, v46, v44
	v_div_fmas_f32 v43, v43, v45, v46
	v_div_fixup_f32 v42, v43, v42, 1.0
	v_pk_mul_f32 v[32:33], v[32:33], v[42:43] op_sel_hi:[1,0]
	v_pk_mul_f32 v[30:31], v[30:31], v[42:43] op_sel_hi:[1,0]
	v_pk_mul_f32 v[32:33], v[32:33], v[4:5]
	v_pk_mul_f32 v[30:31], v[30:31], v[2:3]
	v_pk_fma_f32 v[32:33], v[32:33], v[36:37], v[40:41]
	v_pk_fma_f32 v[30:31], v[30:31], v[34:35], v[38:39]
	v_cvt_pk_bf16_f32 v30, v30, v31
	v_cvt_pk_bf16_f32 v31, v32, v33
	global_store_dwordx2 v[104:105], v[30:31], off offset:2048
	global_load_dwordx4 v[30:33], v[116:117], off
	s_nop 0
	global_load_dwordx4 v[34:37], v[106:107], off offset:1024
	v_pk_mul_f32 v[28:29], v[28:29], v[42:43] op_sel_hi:[1,0]
	v_pk_mul_f32 v[26:27], v[26:27], v[42:43] op_sel_hi:[1,0]
	v_pk_mul_f32 v[28:29], v[28:29], v[8:9]
	v_pk_mul_f32 v[26:27], v[26:27], v[6:7]
	v_lshl_add_u64 v[38:39], s[44:45], 0, v[98:99]
	v_pk_mul_f32 v[24:25], v[24:25], v[42:43] op_sel_hi:[1,0]
	v_pk_mul_f32 v[22:23], v[22:23], v[42:43] op_sel_hi:[1,0]
	v_pk_mul_f32 v[24:25], v[24:25], v[12:13]
	v_pk_mul_f32 v[22:23], v[22:23], v[10:11]
	v_pk_mul_f32 v[20:21], v[20:21], v[42:43] op_sel_hi:[1,0]
	v_pk_mul_f32 v[18:19], v[18:19], v[42:43] op_sel_hi:[1,0]
	v_pk_mul_f32 v[20:21], v[20:21], v[16:17]
	v_pk_mul_f32 v[18:19], v[18:19], v[14:15]
	s_waitcnt vmcnt(0) lgkmcnt(0)
	v_pk_add_f32 v[32:33], v[32:33], 1.0 op_sel_hi:[1,0]
	v_pk_add_f32 v[30:31], v[30:31], 1.0 op_sel_hi:[1,0]
	v_pk_fma_f32 v[28:29], v[28:29], v[32:33], v[36:37]
	v_pk_fma_f32 v[26:27], v[26:27], v[30:31], v[34:35]
	v_cvt_pk_bf16_f32 v26, v26, v27
	v_cvt_pk_bf16_f32 v27, v28, v29
	global_store_dwordx2 v[104:105], v[26:27], off offset:2560
	global_load_dwordx4 v[26:29], v[38:39], off
	s_nop 0
	global_load_dwordx4 v[30:33], v[106:107], off offset:2048
	v_lshl_add_u64 v[34:35], s[44:45], 0, v[100:101]
	s_waitcnt vmcnt(0) lgkmcnt(0)
	v_pk_add_f32 v[28:29], v[28:29], 1.0 op_sel_hi:[1,0]
	v_pk_add_f32 v[26:27], v[26:27], 1.0 op_sel_hi:[1,0]
	v_pk_fma_f32 v[24:25], v[24:25], v[28:29], v[32:33]
	v_pk_fma_f32 v[22:23], v[22:23], v[26:27], v[30:31]
	v_cvt_pk_bf16_f32 v22, v22, v23
	v_cvt_pk_bf16_f32 v23, v24, v25
	global_store_dwordx2 v[104:105], v[22:23], off offset:3072
	global_load_dwordx4 v[22:25], v[34:35], off
	s_nop 0
	global_load_dwordx4 v[26:29], v[106:107], off offset:3072
	s_waitcnt vmcnt(0) lgkmcnt(0)
	v_pk_add_f32 v[24:25], v[24:25], 1.0 op_sel_hi:[1,0]
	v_pk_add_f32 v[22:23], v[22:23], 1.0 op_sel_hi:[1,0]
	v_pk_fma_f32 v[20:21], v[20:21], v[24:25], v[28:29]
	v_pk_fma_f32 v[18:19], v[18:19], v[22:23], v[26:27]
	v_cvt_pk_bf16_f32 v18, v18, v19
	v_cvt_pk_bf16_f32 v19, v20, v21
	global_store_dwordx2 v[104:105], v[18:19], off offset:3584
	s_cbranch_scc1 .LBB0_3449

.LBB0_3611:
	v_lshl_add_u64 v[18:19], s[38:39], 0, v[94:95]
	v_lshl_add_u64 v[22:23], s[38:39], 0, v[92:93]
	v_add_co_u32_e32 v20, vcc, 0x7800000, v18
	v_add_co_u32_e64 v102, s[6:7], s23, v22
	s_nop 0
	v_addc_co_u32_e32 v21, vcc, 0, v19, vcc
	v_addc_co_u32_e64 v103, s[6:7], 0, v23, s[6:7]
	v_add_co_u32_e64 v104, s[6:7], s24, v22
	v_add_co_u32_e32 v22, vcc, 0x7801000, v18
	s_nop 0
	v_addc_co_u32_e64 v105, s[6:7], 0, v23, s[6:7]
	global_load_dwordx4 v[78:81], v[20:21], off
	global_load_dwordx4 v[74:77], v[20:21], off offset:1024
	global_load_dwordx4 v[70:73], v[20:21], off offset:2048
	global_load_dwordx4 v[66:69], v[20:21], off offset:3072
	v_addc_co_u32_e32 v23, vcc, 0, v19, vcc
	v_add_co_u32_e32 v20, vcc, 0x7802000, v18
	global_load_dwordx4 v[62:65], v[22:23], off
	global_load_dwordx4 v[58:61], v[22:23], off offset:1024
	global_load_dwordx4 v[54:57], v[22:23], off offset:2048
	global_load_dwordx4 v[50:53], v[22:23], off offset:3072
	v_addc_co_u32_e32 v21, vcc, 0, v19, vcc
	v_add_co_u32_e32 v82, vcc, 0x7803000, v18
	global_load_dwordx4 v[46:49], v[20:21], off
	global_load_dwordx4 v[42:45], v[20:21], off offset:1024
	global_load_dwordx4 v[38:41], v[20:21], off offset:2048
	global_load_dwordx4 v[34:37], v[20:21], off offset:3072
	v_addc_co_u32_e32 v83, vcc, 0, v19, vcc
	global_load_dwordx4 v[30:33], v[82:83], off
	global_load_dwordx4 v[26:29], v[82:83], off offset:1024
	global_load_dwordx4 v[22:25], v[82:83], off offset:2048
	global_load_dwordx4 v[18:21], v[82:83], off offset:3072
	s_add_i32 s25, s8, 32
	s_add_i32 s10, s8, 0xffffc022
	s_ashr_i32 s9, s25, 13
	s_cmpk_lt_i32 s25, 0x4000
	s_cselect_b32 s6, s9, s10
	s_addk_i32 s6, 0x82
	s_mul_hi_i32 s7, s6, 0x9000
	s_mul_i32 s6, s6, 0x9000
	s_add_u32 s6, s2, s6
	s_addc_u32 s7, s5, s7
	s_add_u32 s10, s6, 0x1000
	s_addc_u32 s11, s7, 0
	v_lshl_add_u64 v[124:125], s[6:7], 0, v[90:91]
	v_lshl_add_u64 v[86:87], s[10:11], 0, v[90:91]
	global_load_dwordx4 v[82:85], v[124:125], off
	s_add_i32 s6, s8, 0xffffc023
	global_load_dwordx4 v[86:89], v[86:87], off
	s_cmpk_lt_i32 s25, 0x3fff
	s_cselect_b32 s6, s9, s6
	s_addk_i32 s6, 0x82
	s_mul_hi_i32 s7, s6, 0x9000
	s_mul_i32 s6, s6, 0x9000
	s_add_u32 s6, s2, s6
	s_addc_u32 s7, s5, s7
	v_lshl_add_u64 v[138:139], s[10:11], 0, v[96:97]
	v_lshl_add_u64 v[134:135], s[10:11], 0, v[98:99]
	v_lshl_add_u64 v[128:129], s[10:11], 0, v[100:101]
	s_add_u32 s10, s6, 0x1000
	v_lshl_add_u64 v[110:111], s[6:7], 0, v[90:91]
	s_addc_u32 s11, s7, 0
	s_add_i32 s6, s8, 0xffffc024
	s_cmpk_lt_i32 s25, 0x3ffe
	s_cselect_b32 s6, s9, s6
	s_addk_i32 s6, 0x82
	s_mul_hi_i32 s7, s6, 0x9000
	s_mul_i32 s6, s6, 0x9000
	v_lshl_add_u64 v[126:127], s[10:11], 0, v[90:91]
	v_lshl_add_u64 v[120:121], s[10:11], 0, v[96:97]
	v_lshl_add_u64 v[116:117], s[10:11], 0, v[98:99]
	v_lshl_add_u64 v[112:113], s[10:11], 0, v[100:101]
	s_add_u32 s10, s2, s6
	s_addc_u32 s11, s5, s7
	s_add_u32 s6, s10, 0x1000
	s_addc_u32 s7, s11, 0
	s_addk_i32 s8, 0xc025
	s_cmpk_lt_i32 s25, 0x3ffd
	v_lshl_add_u64 v[142:143], s[6:7], 0, v[90:91]
	v_lshl_add_u64 v[140:141], s[6:7], 0, v[96:97]
	v_lshl_add_u64 v[136:137], s[6:7], 0, v[98:99]
	v_lshl_add_u64 v[122:123], s[6:7], 0, v[100:101]
	s_cselect_b32 s6, s9, s8
	s_addk_i32 s6, 0x82
	s_mul_hi_i32 s7, s6, 0x9000
	s_mul_i32 s6, s6, 0x9000
	s_add_u32 s6, s2, s6
	s_addc_u32 s7, s5, s7
	s_add_u32 s20, s6, 0x1000
	v_lshl_add_u64 v[106:107], s[6:7], 0, v[90:91]
	s_addc_u32 s21, s7, 0
	v_lshl_add_u64 v[108:109], s[10:11], 0, v[90:91]
	v_lshl_add_u64 v[118:119], s[20:21], 0, v[90:91]
	v_lshl_add_u64 v[114:115], s[20:21], 0, v[96:97]
	v_lshl_add_u64 v[92:93], v[92:93], 0, s[14:15]
	s_waitcnt vmcnt(0) lgkmcnt(0)
	v_pk_mul_f32 v[144:145], v[80:81], v[80:81]
	v_pk_mul_f32 v[146:147], v[78:79], v[78:79]
	v_pk_mul_f32 v[148:149], v[76:77], v[76:77]
	v_pk_mul_f32 v[150:151], v[74:75], v[74:75]
	v_mul_f32_e32 v158, v71, v71
	v_mul_f32_e32 v160, v73, v73
	v_mul_f32_e32 v171, v68, v68
	v_mul_f32_e32 v173, v69, v69
	v_pk_mov_b32 v[162:163], v[146:147], v[144:145] op_sel:[1,0]
	v_mov_b32_e32 v147, v145
	v_pk_mov_b32 v[144:145], v[150:151], v[148:149] op_sel:[1,0]
	v_mov_b32_e32 v151, v149
	v_pk_fma_f32 v[148:149], v[70:71], v[70:71], v[158:159] op_sel_hi:[1,1,0]
	v_pk_fma_f32 v[158:159], v[72:73], v[72:73], v[160:161] op_sel_hi:[1,1,0]
	v_pk_mul_f32 v[160:161], v[64:65], v[64:65]
	v_pk_mul_f32 v[164:165], v[62:63], v[62:63]
	v_pk_mul_f32 v[166:167], v[60:61], v[60:61]
	v_pk_mul_f32 v[168:169], v[58:59], v[58:59]
	v_mul_f32_e32 v170, v55, v55
	v_mul_f32_e32 v172, v57, v57
	v_pk_add_f32 v[146:147], v[162:163], v[146:147]
	v_pk_add_f32 v[144:145], v[144:145], v[150:151]
	v_mov_b32_e32 v149, v171
	v_mov_b32_e32 v159, v173
	v_pk_mov_b32 v[150:151], v[164:165], v[160:161] op_sel:[1,0]
	v_mov_b32_e32 v165, v161
	v_pk_mov_b32 v[160:161], v[168:169], v[166:167] op_sel:[1,0]
	v_mov_b32_e32 v169, v167
	v_pk_fma_f32 v[162:163], v[54:55], v[54:55], v[170:171] op_sel_hi:[1,1,0]
	v_pk_fma_f32 v[166:167], v[56:57], v[56:57], v[172:173] op_sel_hi:[1,1,0]
	v_pk_mul_f32 v[170:171], v[48:49], v[48:49]
	v_pk_mul_f32 v[172:173], v[46:47], v[46:47]
	v_pk_mul_f32 v[174:175], v[44:45], v[44:45]
	v_pk_mul_f32 v[176:177], v[42:43], v[42:43]
	v_mul_f32_e32 v157, v66, v66
	v_mul_f32_e32 v181, v67, v67
	v_mul_f32_e32 v179, v52, v52
	v_mul_f32_e32 v186, v53, v53
	v_mul_f32_e32 v178, v39, v39
	v_mul_f32_e32 v180, v41, v41
	v_pk_add_f32 v[182:183], v[146:147], v[146:147] op_sel:[0,1] op_sel_hi:[1,0]
	v_pk_add_f32 v[184:185], v[144:145], v[144:145] op_sel:[0,1] op_sel_hi:[1,0]
	v_pk_add_f32 v[158:159], v[148:149], v[158:159]
	v_pk_add_f32 v[144:145], v[150:151], v[164:165]
	v_pk_add_f32 v[146:147], v[160:161], v[168:169]
	v_pk_mov_b32 v[148:149], v[172:173], v[170:171] op_sel:[1,0]
	v_mov_b32_e32 v173, v171
	v_pk_mov_b32 v[150:151], v[176:177], v[174:175] op_sel:[1,0]
	v_mov_b32_e32 v177, v175
	v_mul_f32_e32 v187, v50, v50
	v_mul_f32_e32 v192, v51, v51
	v_mul_f32_e32 v195, v36, v36
	v_mul_f32_e32 v196, v37, v37
	v_mov_b32_e32 v163, v179
	v_mov_b32_e32 v167, v186
	v_pk_fma_f32 v[160:161], v[38:39], v[38:39], v[178:179] op_sel_hi:[1,1,0]
	v_pk_fma_f32 v[164:165], v[40:41], v[40:41], v[180:181] op_sel_hi:[1,1,0]
	v_pk_mul_f32 v[168:169], v[32:33], v[32:33]
	v_pk_mul_f32 v[170:171], v[30:31], v[30:31]
	v_pk_mul_f32 v[174:175], v[28:29], v[28:29]
	v_pk_mul_f32 v[178:179], v[26:27], v[26:27]
	v_mov_b32_e32 v183, v157
	v_mov_b32_e32 v185, v181
	v_pk_add_f32 v[188:189], v[144:145], v[144:145] op_sel:[0,1] op_sel_hi:[1,0]
	v_pk_add_f32 v[190:191], v[146:147], v[146:147] op_sel:[0,1] op_sel_hi:[1,0]
	v_pk_add_f32 v[148:149], v[148:149], v[172:173]
	v_pk_add_f32 v[150:151], v[150:151], v[176:177]
	v_mul_f32_e32 v193, v34, v34
	v_mul_f32_e32 v194, v35, v35
	v_pk_add_f32 v[162:163], v[162:163], v[166:167]
	v_mov_b32_e32 v161, v195
	v_mov_b32_e32 v165, v196
	v_pk_mov_b32 v[166:167], v[170:171], v[168:169] op_sel:[1,0]
	v_mov_b32_e32 v171, v169
	v_pk_mov_b32 v[168:169], v[178:179], v[174:175] op_sel:[1,0]
	v_mov_b32_e32 v179, v175
	v_pk_add_f32 v[172:173], v[182:183], v[184:185]
	v_mov_b32_e32 v189, v187
	v_mov_b32_e32 v191, v192
	v_pk_add_f32 v[174:175], v[148:149], v[148:149] op_sel:[0,1] op_sel_hi:[1,0]
	v_pk_add_f32 v[176:177], v[150:151], v[150:151] op_sel:[0,1] op_sel_hi:[1,0]
	v_pk_add_f32 v[160:161], v[160:161], v[164:165]
	v_pk_add_f32 v[158:159], v[172:173], v[158:159]
	v_pk_add_f32 v[164:165], v[188:189], v[190:191]
	v_mov_b32_e32 v175, v193
	v_mov_b32_e32 v177, v194
	v_add_f32_e32 v157, v158, v159
	v_pk_add_f32 v[158:159], v[164:165], v[162:163]
	v_pk_add_f32 v[162:163], v[174:175], v[176:177]
	v_add_f32_e32 v164, v158, v159
	v_pk_add_f32 v[158:159], v[162:163], v[160:161]
	ds_bpermute_b32 v160, v1, v157
	ds_bpermute_b32 v161, v1, v164
	v_add_f32_e32 v158, v158, v159
	ds_bpermute_b32 v159, v1, v158
	v_pk_add_f32 v[148:149], v[166:167], v[170:171]
	s_waitcnt lgkmcnt(2)
	v_add_f32_e32 v157, v157, v160
	ds_bpermute_b32 v160, v131, v157
	s_waitcnt lgkmcnt(2)
	v_add_f32_e32 v161, v164, v161
	ds_bpermute_b32 v162, v131, v161
	s_waitcnt lgkmcnt(2)
	v_add_f32_e32 v158, v158, v159
	ds_bpermute_b32 v159, v131, v158
	s_waitcnt lgkmcnt(2)
	v_add_f32_e32 v157, v157, v160
	ds_bpermute_b32 v160, v133, v157
	s_waitcnt lgkmcnt(2)
	v_add_f32_e32 v161, v161, v162
	ds_bpermute_b32 v162, v133, v161
	s_waitcnt lgkmcnt(2)
	v_add_f32_e32 v158, v158, v159
	ds_bpermute_b32 v159, v133, v158
	s_waitcnt lgkmcnt(2)
	v_add_f32_e32 v157, v157, v160
	ds_bpermute_b32 v160, v152, v157
	s_waitcnt lgkmcnt(2)
	v_add_f32_e32 v161, v161, v162
	ds_bpermute_b32 v162, v152, v161
	s_waitcnt lgkmcnt(2)
	v_add_f32_e32 v158, v158, v159
	ds_bpermute_b32 v159, v152, v158
	s_waitcnt lgkmcnt(2)
	v_add_f32_e32 v157, v157, v160
	ds_bpermute_b32 v160, v153, v157
	s_waitcnt lgkmcnt(2)
	v_add_f32_e32 v161, v161, v162
	ds_bpermute_b32 v162, v153, v161
	s_waitcnt lgkmcnt(2)
	v_add_f32_e32 v158, v158, v159
	ds_bpermute_b32 v159, v153, v158
	s_waitcnt lgkmcnt(2)
	v_add_f32_e32 v157, v157, v160
	ds_bpermute_b32 v160, v154, v157
	s_waitcnt lgkmcnt(2)
	v_add_f32_e32 v161, v161, v162
	ds_bpermute_b32 v162, v154, v161
	s_waitcnt lgkmcnt(2)
	v_add_f32_e32 v158, v158, v159
	ds_bpermute_b32 v159, v154, v158
	s_waitcnt lgkmcnt(2)
	v_add_f32_e32 v157, v157, v160
	v_fmamk_f32 v157, v157, 0x3a800000, v155
	s_waitcnt lgkmcnt(1)
	v_add_f32_e32 v160, v161, v162
	v_mul_f32_e32 v161, 0x4f800000, v157
	v_cmp_gt_f32_e32 vcc, s3, v157
	v_fmamk_f32 v160, v160, 0x3a800000, v155
	s_waitcnt lgkmcnt(0)
	v_add_f32_e32 v158, v158, v159
	v_cndmask_b32_e32 v157, v157, v161, vcc
	v_mul_f32_e32 v159, 0x4f800000, v160
	v_cmp_gt_f32_e64 s[6:7], s3, v160
	v_sqrt_f32_e32 v161, v157
	v_fmamk_f32 v158, v158, 0x3a800000, v155
	v_cndmask_b32_e64 v159, v160, v159, s[6:7]
	v_mul_f32_e32 v160, 0x4f800000, v158
	v_cmp_gt_f32_e64 s[8:9], s3, v158
	v_sqrt_f32_e32 v162, v159
	v_add_u32_e32 v163, -1, v161
	v_cndmask_b32_e64 v158, v158, v160, s[8:9]
	v_sqrt_f32_e32 v160, v158
	v_add_u32_e32 v164, 1, v161
	v_fma_f32 v165, -v163, v161, v157
	v_fma_f32 v166, -v164, v161, v157
	v_add_u32_e32 v167, -1, v162
	v_cmp_ge_f32_e64 s[10:11], 0, v165
	v_pk_add_f32 v[150:151], v[168:169], v[178:179]
	v_add_u32_e32 v168, 1, v162
	v_cndmask_b32_e64 v161, v161, v163, s[10:11]
	v_fma_f32 v163, -v167, v162, v159
	v_cmp_lt_f32_e64 s[10:11], 0, v166
	v_fma_f32 v165, -v168, v162, v159
	v_add_u32_e32 v169, -1, v160
	v_cndmask_b32_e64 v161, v161, v164, s[10:11]
	v_cmp_ge_f32_e64 s[10:11], 0, v163
	v_add_u32_e32 v170, 1, v160
	v_fma_f32 v163, -v169, v160, v158
	v_cndmask_b32_e64 v162, v162, v167, s[10:11]
	v_cmp_lt_f32_e64 s[10:11], 0, v165
	v_fma_f32 v164, -v170, v160, v158
	v_mul_f32_e32 v165, 0x37800000, v161
	v_cndmask_b32_e64 v162, v162, v168, s[10:11]
	v_cmp_ge_f32_e64 s[10:11], 0, v163
	v_cndmask_b32_e32 v161, v161, v165, vcc
	v_cmp_class_f32_e32 vcc, v157, v156
	v_cndmask_b32_e64 v160, v160, v169, s[10:11]
	v_cmp_lt_f32_e64 s[10:11], 0, v164
	v_mul_f32_e32 v163, 0x37800000, v162
	v_cndmask_b32_e32 v157, v161, v157, vcc
	v_cndmask_b32_e64 v160, v160, v170, s[10:11]
	v_cndmask_b32_e64 v161, v162, v163, s[6:7]
	v_cmp_class_f32_e32 vcc, v159, v156
	v_mul_f32_e32 v162, 0x37800000, v160
	v_div_scale_f32 v163, s[6:7], v157, v157, 1.0
	v_cndmask_b32_e32 v159, v161, v159, vcc
	v_cndmask_b32_e64 v160, v160, v162, s[8:9]
	v_cmp_class_f32_e32 vcc, v158, v156
	v_rcp_f32_e32 v161, v163
	v_div_scale_f32 v162, s[8:9], v159, v159, 1.0
	v_cndmask_b32_e32 v160, v160, v158, vcc
	v_rcp_f32_e32 v166, v162
	v_div_scale_f32 v167, s[10:11], v160, v160, 1.0
	v_rcp_f32_e32 v169, v167
	v_fma_f32 v158, -v163, v161, 1.0
	v_div_scale_f32 v164, s[6:7], 1.0, v157, 1.0
	v_fmac_f32_e32 v161, v158, v161
	v_fma_f32 v158, -v162, v166, 1.0
	v_mul_f32_e32 v170, v164, v161
	v_div_scale_f32 v165, s[8:9], 1.0, v159, 1.0
	v_fmac_f32_e32 v166, v158, v166
	v_fma_f32 v158, -v167, v169, 1.0
	v_fma_f32 v171, -v163, v170, v164
	v_div_scale_f32 v168, s[10:11], 1.0, v160, 1.0
	v_mul_f32_e32 v172, v165, v166
	v_fmac_f32_e32 v169, v158, v169
	v_fmac_f32_e32 v170, v171, v161
	v_fma_f32 v158, -v162, v172, v165
	v_mul_f32_e32 v171, v168, v169
	v_fma_f32 v163, -v163, v170, v164
	s_mov_b64 vcc, s[6:7]
	v_fmac_f32_e32 v172, v158, v166
	v_fma_f32 v158, -v167, v171, v168
	v_div_fmas_f32 v161, v163, v161, v170
	v_fma_f32 v162, -v162, v172, v165
	v_fmac_f32_e32 v171, v158, v169
	v_div_fixup_f32 v158, v161, v157, 1.0
	s_mov_b64 vcc, s[8:9]
	v_div_fmas_f32 v157, v162, v166, v172
	v_fma_f32 v161, -v167, v171, v168
	v_pk_mul_f32 v[80:81], v[80:81], v[158:159] op_sel_hi:[1,0]
	v_pk_mul_f32 v[78:79], v[78:79], v[158:159] op_sel_hi:[1,0]
	s_mov_b64 vcc, s[10:11]
	v_pk_add_f32 v[88:89], v[88:89], 1.0 op_sel_hi:[1,0]
	v_pk_add_f32 v[86:87], v[86:87], 1.0 op_sel_hi:[1,0]
	v_pk_mul_f32 v[76:77], v[76:77], v[158:159] op_sel_hi:[1,0]
	v_pk_mul_f32 v[74:75], v[74:75], v[158:159] op_sel_hi:[1,0]
	v_pk_mul_f32 v[72:73], v[72:73], v[158:159] op_sel_hi:[1,0]
	v_pk_mul_f32 v[70:71], v[70:71], v[158:159] op_sel_hi:[1,0]
	v_pk_mul_f32 v[68:69], v[68:69], v[158:159] op_sel_hi:[1,0]
	v_pk_mul_f32 v[66:67], v[66:67], v[158:159] op_sel_hi:[1,0]
	v_div_fixup_f32 v158, v157, v159, 1.0
	v_div_fmas_f32 v157, v161, v169, v171
	v_pk_mul_f32 v[78:79], v[78:79], v[2:3]
	v_pk_mul_f32 v[80:81], v[80:81], v[4:5]
	v_pk_mul_f32 v[64:65], v[64:65], v[158:159] op_sel_hi:[1,0]
	v_pk_mul_f32 v[62:63], v[62:63], v[158:159] op_sel_hi:[1,0]
	v_pk_mul_f32 v[60:61], v[60:61], v[158:159] op_sel_hi:[1,0]
	v_pk_mul_f32 v[58:59], v[58:59], v[158:159] op_sel_hi:[1,0]
	v_pk_mul_f32 v[56:57], v[56:57], v[158:159] op_sel_hi:[1,0]
	v_pk_mul_f32 v[54:55], v[54:55], v[158:159] op_sel_hi:[1,0]
	v_pk_mul_f32 v[52:53], v[52:53], v[158:159] op_sel_hi:[1,0]
	v_pk_mul_f32 v[158:159], v[50:51], v[158:159] op_sel_hi:[1,0]
	v_div_fixup_f32 v50, v157, v160, 1.0
	v_pk_fma_f32 v[80:81], v[80:81], v[88:89], v[84:85]
	v_pk_fma_f32 v[78:79], v[78:79], v[86:87], v[82:83]
	v_pk_mul_f32 v[86:87], v[52:53], v[16:17]
	v_pk_mul_f32 v[48:49], v[48:49], v[50:51] op_sel_hi:[1,0]
	v_pk_mul_f32 v[46:47], v[46:47], v[50:51] op_sel_hi:[1,0]
	v_pk_mul_f32 v[82:83], v[54:55], v[10:11]
	v_pk_mul_f32 v[84:85], v[158:159], v[14:15]
	v_pk_mul_f32 v[88:89], v[46:47], v[2:3]
	v_pk_mul_f32 v[158:159], v[48:49], v[4:5]
	v_cvt_pk_bf16_f32 v46, v78, v79
	v_cvt_pk_bf16_f32 v47, v80, v81
	global_store_dwordx2 v[102:103], v[46:47], off
	global_load_dwordx4 v[238:241], v[138:139], off
	s_nop 0
	global_load_dwordx4 v[242:245], v[124:125], off offset:1024
	v_pk_mul_f32 v[74:75], v[74:75], v[6:7]
	v_pk_mul_f32 v[76:77], v[76:77], v[8:9]
	v_pk_mul_f32 v[70:71], v[70:71], v[10:11]
	v_pk_mul_f32 v[72:73], v[72:73], v[12:13]
	v_pk_mul_f32 v[66:67], v[66:67], v[14:15]
	v_pk_mul_f32 v[68:69], v[68:69], v[16:17]
	v_pk_mul_f32 v[62:63], v[62:63], v[2:3]
	v_pk_mul_f32 v[64:65], v[64:65], v[4:5]
	v_pk_mul_f32 v[58:59], v[58:59], v[6:7]
	v_pk_mul_f32 v[60:61], v[60:61], v[8:9]
	v_pk_mul_f32 v[56:57], v[56:57], v[12:13]
	v_mul_f32_e32 v180, v23, v23
	v_mul_f32_e32 v186, v25, v25
	v_mul_f32_e32 v197, v18, v18
	v_mul_f32_e32 v198, v19, v19
	v_mul_f32_e32 v199, v20, v20
	v_mul_f32_e32 v200, v21, v21
	v_pk_fma_f32 v[144:145], v[22:23], v[22:23], v[180:181] op_sel_hi:[1,1,0]
	v_pk_fma_f32 v[146:147], v[24:25], v[24:25], v[186:187] op_sel_hi:[1,1,0]
	v_mov_b32_e32 v145, v199
	v_mov_b32_e32 v147, v200
	v_lshl_add_u64 v[94:95], v[94:95], 0, s[18:19]
	s_mov_b32 s8, s25
	s_cmp_lt_i32 s25, s13
	global_load_dwordx4 v[230:233], v[134:135], off
	s_nop 0
	global_load_dwordx4 v[234:237], v[124:125], off offset:2048
	s_waitcnt vmcnt(2) lgkmcnt(0)
	v_pk_add_f32 v[240:241], v[240:241], 1.0 op_sel_hi:[1,0]
	v_pk_add_f32 v[238:239], v[238:239], 1.0 op_sel_hi:[1,0]
	v_pk_fma_f32 v[240:241], v[76:77], v[240:241], v[244:245]
	v_pk_fma_f32 v[238:239], v[74:75], v[238:239], v[242:243]
	v_cvt_pk_bf16_f32 v238, v238, v239
	v_cvt_pk_bf16_f32 v239, v240, v241
	global_store_dwordx2 v[102:103], v[238:239], off offset:512
	global_load_dwordx4 v[238:241], v[128:129], off
	s_nop 0
	global_load_dwordx4 v[242:245], v[124:125], off offset:3072
	s_waitcnt vmcnt(3) lgkmcnt(0)
	v_pk_add_f32 v[232:233], v[232:233], 1.0 op_sel_hi:[1,0]
	v_pk_add_f32 v[230:231], v[230:231], 1.0 op_sel_hi:[1,0]
	v_pk_fma_f32 v[232:233], v[72:73], v[232:233], v[236:237]
	v_pk_fma_f32 v[230:231], v[70:71], v[230:231], v[234:235]
	v_cvt_pk_bf16_f32 v230, v230, v231
	v_cvt_pk_bf16_f32 v231, v232, v233
	global_store_dwordx2 v[102:103], v[230:231], off offset:1024
	global_load_dwordx4 v[230:233], v[126:127], off
	s_nop 0
	global_load_dwordx4 v[234:237], v[110:111], off
	s_waitcnt vmcnt(3) lgkmcnt(0)
	v_pk_add_f32 v[240:241], v[240:241], 1.0 op_sel_hi:[1,0]
	v_pk_add_f32 v[238:239], v[238:239], 1.0 op_sel_hi:[1,0]
	v_pk_fma_f32 v[240:241], v[68:69], v[240:241], v[244:245]
	v_pk_fma_f32 v[238:239], v[66:67], v[238:239], v[242:243]
	v_cvt_pk_bf16_f32 v238, v238, v239
	v_cvt_pk_bf16_f32 v239, v240, v241
	global_store_dwordx2 v[102:103], v[238:239], off offset:1536
	global_load_dwordx4 v[238:241], v[120:121], off
	s_nop 0
	global_load_dwordx4 v[242:245], v[110:111], off offset:1024
	s_waitcnt vmcnt(3) lgkmcnt(0)
	v_pk_add_f32 v[232:233], v[232:233], 1.0 op_sel_hi:[1,0]
	v_pk_add_f32 v[230:231], v[230:231], 1.0 op_sel_hi:[1,0]
	v_pk_fma_f32 v[232:233], v[64:65], v[232:233], v[236:237]
	v_pk_fma_f32 v[230:231], v[62:63], v[230:231], v[234:235]
	v_cvt_pk_bf16_f32 v230, v230, v231
	v_cvt_pk_bf16_f32 v231, v232, v233
	global_store_dwordx2 v[102:103], v[230:231], off offset:2048
	global_load_dwordx4 v[230:233], v[116:117], off
	s_nop 0
	global_load_dwordx4 v[234:237], v[110:111], off offset:2048
	s_waitcnt vmcnt(3) lgkmcnt(0)
	v_pk_add_f32 v[240:241], v[240:241], 1.0 op_sel_hi:[1,0]
	v_pk_add_f32 v[238:239], v[238:239], 1.0 op_sel_hi:[1,0]
	v_pk_fma_f32 v[240:241], v[60:61], v[240:241], v[244:245]
	v_pk_fma_f32 v[238:239], v[58:59], v[238:239], v[242:243]
	v_cvt_pk_bf16_f32 v238, v238, v239
	v_cvt_pk_bf16_f32 v239, v240, v241
	global_store_dwordx2 v[102:103], v[238:239], off offset:2560
	v_pk_add_f32 v[58:59], v[150:151], v[150:151] op_sel:[0,1] op_sel_hi:[1,0]
	v_pk_add_f32 v[60:61], v[144:145], v[146:147]
	v_mov_b32_e32 v59, v198
	global_load_dwordx4 v[238:241], v[112:113], off
	s_nop 0
	global_load_dwordx4 v[242:245], v[110:111], off offset:3072
	s_waitcnt vmcnt(3) lgkmcnt(0)
	v_pk_add_f32 v[232:233], v[232:233], 1.0 op_sel_hi:[1,0]
	v_pk_add_f32 v[230:231], v[230:231], 1.0 op_sel_hi:[1,0]
	v_pk_fma_f32 v[232:233], v[56:57], v[232:233], v[236:237]
	v_pk_fma_f32 v[230:231], v[82:83], v[230:231], v[234:235]
	v_cvt_pk_bf16_f32 v230, v230, v231
	v_cvt_pk_bf16_f32 v231, v232, v233
	global_store_dwordx2 v[102:103], v[230:231], off offset:3072
	v_pk_add_f32 v[56:57], v[148:149], v[148:149] op_sel:[0,1] op_sel_hi:[1,0]
	global_load_dwordx4 v[230:233], v[142:143], off
	s_nop 0
	global_load_dwordx4 v[234:237], v[108:109], off
	s_waitcnt vmcnt(3) lgkmcnt(0)
	v_pk_add_f32 v[240:241], v[240:241], 1.0 op_sel_hi:[1,0]
	v_pk_add_f32 v[238:239], v[238:239], 1.0 op_sel_hi:[1,0]
	v_pk_fma_f32 v[240:241], v[86:87], v[240:241], v[244:245]
	v_pk_fma_f32 v[238:239], v[84:85], v[238:239], v[242:243]
	v_cvt_pk_bf16_f32 v238, v238, v239
	v_cvt_pk_bf16_f32 v239, v240, v241
	global_store_dwordx2 v[102:103], v[238:239], off offset:3584
	v_mov_b32_e32 v57, v197
	global_load_dwordx4 v[238:241], v[140:141], off
	s_nop 0
	global_load_dwordx4 v[242:245], v[108:109], off offset:1024
	s_waitcnt vmcnt(3) lgkmcnt(0)
	v_pk_add_f32 v[232:233], v[232:233], 1.0 op_sel_hi:[1,0]
	v_pk_add_f32 v[230:231], v[230:231], 1.0 op_sel_hi:[1,0]
	v_pk_fma_f32 v[232:233], v[158:159], v[232:233], v[236:237]
	v_pk_fma_f32 v[230:231], v[88:89], v[230:231], v[234:235]
	v_bfe_u32 v51, v230, 16, 1
	v_bfe_u32 v234, v231, 16, 1
	v_add3_u32 v230, v230, v51, s4
	v_add3_u32 v231, v231, v234, s4
	v_lshrrev_b32_e32 v230, 16, v230
	v_and_or_b32 v230, v231, s22, v230
	v_cvt_pk_bf16_f32 v231, v232, v233
	global_store_dwordx2 v[104:105], v[230:231], off
	v_pk_mul_f32 v[44:45], v[44:45], v[50:51] op_sel_hi:[1,0]
	v_pk_mul_f32 v[42:43], v[42:43], v[50:51] op_sel_hi:[1,0]
	v_pk_mul_f32 v[44:45], v[44:45], v[8:9]
	v_pk_mul_f32 v[42:43], v[42:43], v[6:7]
	s_waitcnt vmcnt(1) lgkmcnt(0)
	v_pk_add_f32 v[240:241], v[240:241], 1.0 op_sel_hi:[1,0]
	v_pk_add_f32 v[238:239], v[238:239], 1.0 op_sel_hi:[1,0]
	v_pk_fma_f32 v[44:45], v[44:45], v[240:241], v[244:245]
	v_pk_fma_f32 v[42:43], v[42:43], v[238:239], v[242:243]
	v_cvt_pk_bf16_f32 v42, v42, v43
	v_cvt_pk_bf16_f32 v43, v44, v45
	global_store_dwordx2 v[104:105], v[42:43], off offset:512
	global_load_dwordx4 v[42:45], v[136:137], off
	s_nop 0
	global_load_dwordx4 v[46:49], v[108:109], off offset:2048
	v_pk_add_f32 v[52:53], v[56:57], v[58:59]
	s_waitcnt vmcnt(0) lgkmcnt(0)
	v_pk_add_f32 v[44:45], v[44:45], 1.0 op_sel_hi:[1,0]
	v_pk_add_f32 v[52:53], v[52:53], v[60:61]
	v_pk_add_f32 v[42:43], v[42:43], 1.0 op_sel_hi:[1,0]
	v_add_f32_e32 v51, v52, v53
	ds_bpermute_b32 v52, v1, v51
	s_waitcnt lgkmcnt(0)
	v_add_f32_e32 v51, v51, v52
	ds_bpermute_b32 v52, v131, v51
	s_waitcnt lgkmcnt(0)
	v_add_f32_e32 v51, v51, v52
	v_pk_mul_f32 v[40:41], v[40:41], v[50:51] op_sel_hi:[1,0]
	v_pk_mul_f32 v[38:39], v[38:39], v[50:51] op_sel_hi:[1,0]
	v_pk_mul_f32 v[40:41], v[40:41], v[12:13]
	v_pk_mul_f32 v[38:39], v[38:39], v[10:11]
	v_pk_fma_f32 v[40:41], v[40:41], v[44:45], v[48:49]
	v_pk_fma_f32 v[38:39], v[38:39], v[42:43], v[46:47]
	v_cvt_pk_bf16_f32 v38, v38, v39
	v_cvt_pk_bf16_f32 v39, v40, v41
	global_store_dwordx2 v[104:105], v[38:39], off offset:1024
	global_load_dwordx4 v[38:41], v[122:123], off
	s_nop 0
	global_load_dwordx4 v[42:45], v[108:109], off offset:3072
	v_pk_mul_f32 v[36:37], v[36:37], v[50:51] op_sel_hi:[1,0]
	v_pk_mul_f32 v[34:35], v[34:35], v[50:51] op_sel_hi:[1,0]
	v_pk_mul_f32 v[36:37], v[36:37], v[16:17]
	v_pk_mul_f32 v[34:35], v[34:35], v[14:15]
	ds_bpermute_b32 v46, v133, v51
	s_waitcnt lgkmcnt(0)
	v_add_f32_e32 v46, v51, v46
	ds_bpermute_b32 v47, v152, v46
	s_waitcnt lgkmcnt(0)
	v_add_f32_e32 v46, v46, v47
	ds_bpermute_b32 v47, v153, v46
	s_waitcnt lgkmcnt(0)
	v_add_f32_e32 v46, v46, v47
	ds_bpermute_b32 v47, v154, v46
	s_waitcnt lgkmcnt(0)
	v_add_f32_e32 v46, v46, v47
	v_fmamk_f32 v46, v46, 0x3a800000, v155
	v_mul_f32_e32 v47, 0x4f800000, v46
	v_cmp_gt_f32_e32 vcc, s3, v46
	s_waitcnt vmcnt(0)
	v_pk_add_f32 v[40:41], v[40:41], 1.0 op_sel_hi:[1,0]
	v_pk_add_f32 v[38:39], v[38:39], 1.0 op_sel_hi:[1,0]
	v_pk_fma_f32 v[36:37], v[36:37], v[40:41], v[44:45]
	v_pk_fma_f32 v[34:35], v[34:35], v[38:39], v[42:43]
	v_cvt_pk_bf16_f32 v34, v34, v35
	v_cvt_pk_bf16_f32 v35, v36, v37
	global_store_dwordx2 v[104:105], v[34:35], off offset:1536
	global_load_dwordx4 v[34:37], v[118:119], off
	s_nop 0
	global_load_dwordx4 v[38:41], v[106:107], off
	v_cndmask_b32_e32 v42, v46, v47, vcc
	v_sqrt_f32_e32 v43, v42
	s_waitcnt vmcnt(0) lgkmcnt(0)
	v_pk_add_f32 v[36:37], v[36:37], 1.0 op_sel_hi:[1,0]
	v_add_u32_e32 v44, -1, v43
	v_add_u32_e32 v45, 1, v43
	v_fma_f32 v46, -v44, v43, v42
	v_fma_f32 v47, -v45, v43, v42
	v_cmp_ge_f32_e64 s[6:7], 0, v46
	v_pk_add_f32 v[34:35], v[34:35], 1.0 op_sel_hi:[1,0]
	s_nop 0
	v_cndmask_b32_e64 v43, v43, v44, s[6:7]
	v_cmp_lt_f32_e64 s[6:7], 0, v47
	s_nop 1
	v_cndmask_b32_e64 v43, v43, v45, s[6:7]
	v_mul_f32_e32 v44, 0x37800000, v43
	v_cndmask_b32_e32 v43, v43, v44, vcc
	v_cmp_class_f32_e32 vcc, v42, v156
	s_nop 1
	v_cndmask_b32_e32 v42, v43, v42, vcc
	v_div_scale_f32 v43, s[6:7], v42, v42, 1.0
	v_rcp_f32_e32 v45, v43
	v_div_scale_f32 v44, vcc, 1.0, v42, 1.0
	v_fma_f32 v46, -v43, v45, 1.0
	v_fmac_f32_e32 v45, v46, v45
	v_mul_f32_e32 v46, v44, v45
	v_fma_f32 v47, -v43, v46, v44
	v_fmac_f32_e32 v46, v47, v45
	v_fma_f32 v43, -v43, v46, v44
	v_div_fmas_f32 v43, v43, v45, v46
	v_div_fixup_f32 v42, v43, v42, 1.0
	v_pk_mul_f32 v[32:33], v[32:33], v[42:43] op_sel_hi:[1,0]
	v_pk_mul_f32 v[30:31], v[30:31], v[42:43] op_sel_hi:[1,0]
	v_pk_mul_f32 v[32:33], v[32:33], v[4:5]
	v_pk_mul_f32 v[30:31], v[30:31], v[2:3]
	v_pk_fma_f32 v[32:33], v[32:33], v[36:37], v[40:41]
	v_pk_fma_f32 v[30:31], v[30:31], v[34:35], v[38:39]
	v_cvt_pk_bf16_f32 v30, v30, v31
	v_cvt_pk_bf16_f32 v31, v32, v33
	global_store_dwordx2 v[104:105], v[30:31], off offset:2048
	global_load_dwordx4 v[30:33], v[114:115], off
	s_nop 0
	global_load_dwordx4 v[34:37], v[106:107], off offset:1024
	v_pk_mul_f32 v[28:29], v[28:29], v[42:43] op_sel_hi:[1,0]
	v_pk_mul_f32 v[26:27], v[26:27], v[42:43] op_sel_hi:[1,0]
	v_pk_mul_f32 v[28:29], v[28:29], v[8:9]
	v_pk_mul_f32 v[26:27], v[26:27], v[6:7]
	v_lshl_add_u64 v[38:39], s[20:21], 0, v[98:99]
	v_pk_mul_f32 v[24:25], v[24:25], v[42:43] op_sel_hi:[1,0]
	v_pk_mul_f32 v[22:23], v[22:23], v[42:43] op_sel_hi:[1,0]
	v_pk_mul_f32 v[24:25], v[24:25], v[12:13]
	v_pk_mul_f32 v[22:23], v[22:23], v[10:11]
	v_pk_mul_f32 v[20:21], v[20:21], v[42:43] op_sel_hi:[1,0]
	v_pk_mul_f32 v[18:19], v[18:19], v[42:43] op_sel_hi:[1,0]
	v_pk_mul_f32 v[20:21], v[20:21], v[16:17]
	v_pk_mul_f32 v[18:19], v[18:19], v[14:15]
	s_waitcnt vmcnt(0) lgkmcnt(0)
	v_pk_add_f32 v[32:33], v[32:33], 1.0 op_sel_hi:[1,0]
	v_pk_add_f32 v[30:31], v[30:31], 1.0 op_sel_hi:[1,0]
	v_pk_fma_f32 v[28:29], v[28:29], v[32:33], v[36:37]
	v_pk_fma_f32 v[26:27], v[26:27], v[30:31], v[34:35]
	v_cvt_pk_bf16_f32 v26, v26, v27
	v_cvt_pk_bf16_f32 v27, v28, v29
	global_store_dwordx2 v[104:105], v[26:27], off offset:2560
	global_load_dwordx4 v[26:29], v[38:39], off
	s_nop 0
	global_load_dwordx4 v[30:33], v[106:107], off offset:2048
	v_lshl_add_u64 v[34:35], s[20:21], 0, v[100:101]
	s_waitcnt vmcnt(0) lgkmcnt(0)
	v_pk_add_f32 v[28:29], v[28:29], 1.0 op_sel_hi:[1,0]
	v_pk_add_f32 v[26:27], v[26:27], 1.0 op_sel_hi:[1,0]
	v_pk_fma_f32 v[24:25], v[24:25], v[28:29], v[32:33]
	v_pk_fma_f32 v[22:23], v[22:23], v[26:27], v[30:31]
	v_cvt_pk_bf16_f32 v22, v22, v23
	v_cvt_pk_bf16_f32 v23, v24, v25
	global_store_dwordx2 v[104:105], v[22:23], off offset:3072
	global_load_dwordx4 v[22:25], v[34:35], off
	s_nop 0
	global_load_dwordx4 v[26:29], v[106:107], off offset:3072
	s_waitcnt vmcnt(0) lgkmcnt(0)
	v_pk_add_f32 v[24:25], v[24:25], 1.0 op_sel_hi:[1,0]
	v_pk_add_f32 v[22:23], v[22:23], 1.0 op_sel_hi:[1,0]
	v_pk_fma_f32 v[20:21], v[20:21], v[24:25], v[28:29]
	v_pk_fma_f32 v[18:19], v[18:19], v[22:23], v[26:27]
	v_cvt_pk_bf16_f32 v18, v18, v19
	v_cvt_pk_bf16_f32 v19, v20, v21
	global_store_dwordx2 v[104:105], v[18:19], off offset:3584
	s_cbranch_scc1 .LBB0_3611

.LBB0_5544:
	v_lshl_add_u64 v[18:19], s[68:69], 0, v[94:95]
	v_lshl_add_u64 v[22:23], s[68:69], 0, v[92:93]
	v_add_co_u32_e32 v20, vcc, 0x7800000, v18
	v_add_co_u32_e64 v102, s[6:7], s24, v22
	s_nop 0
	v_addc_co_u32_e32 v21, vcc, 0, v19, vcc
	v_addc_co_u32_e64 v103, s[6:7], 0, v23, s[6:7]
	v_add_co_u32_e64 v104, s[6:7], s25, v22
	v_add_co_u32_e32 v22, vcc, 0x7801000, v18
	s_nop 0
	v_addc_co_u32_e64 v105, s[6:7], 0, v23, s[6:7]
	global_load_dwordx4 v[78:81], v[20:21], off
	global_load_dwordx4 v[74:77], v[20:21], off offset:1024
	global_load_dwordx4 v[70:73], v[20:21], off offset:2048
	global_load_dwordx4 v[66:69], v[20:21], off offset:3072
	v_addc_co_u32_e32 v23, vcc, 0, v19, vcc
	v_add_co_u32_e32 v20, vcc, 0x7802000, v18
	global_load_dwordx4 v[62:65], v[22:23], off
	global_load_dwordx4 v[58:61], v[22:23], off offset:1024
	global_load_dwordx4 v[54:57], v[22:23], off offset:2048
	global_load_dwordx4 v[50:53], v[22:23], off offset:3072
	v_addc_co_u32_e32 v21, vcc, 0, v19, vcc
	v_add_co_u32_e32 v82, vcc, 0x7803000, v18
	global_load_dwordx4 v[46:49], v[20:21], off
	global_load_dwordx4 v[42:45], v[20:21], off offset:1024
	global_load_dwordx4 v[38:41], v[20:21], off offset:2048
	global_load_dwordx4 v[34:37], v[20:21], off offset:3072
	v_addc_co_u32_e32 v83, vcc, 0, v19, vcc
	global_load_dwordx4 v[30:33], v[82:83], off
	global_load_dwordx4 v[26:29], v[82:83], off offset:1024
	global_load_dwordx4 v[22:25], v[82:83], off offset:2048
	global_load_dwordx4 v[18:21], v[82:83], off offset:3072
	s_ashr_i32 s8, s12, 13
	s_add_i32 s9, s12, 0xffffc002
	s_cmpk_lt_i32 s12, 0x4000
	s_cselect_b32 s6, s8, s9
	s_addk_i32 s6, 0x82
	s_mul_hi_i32 s7, s6, 0x9000
	s_mul_i32 s6, s6, 0x9000
	s_add_u32 s9, s3, s6
	s_addc_u32 s11, s4, s7
	s_add_u32 s6, s9, 0x6000
	s_addc_u32 s7, s11, 0
	s_add_u32 s10, s9, 0x7000
	s_addc_u32 s11, s11, 0
	v_lshl_add_u64 v[82:83], s[6:7], 0, v[90:91]
	v_lshl_add_u64 v[86:87], s[10:11], 0, v[90:91]
	global_load_dwordx4 v[82:85], v[82:83], off
	v_lshl_add_u64 v[148:149], s[6:7], 0, v[96:97]
	global_load_dwordx4 v[86:89], v[86:87], off
	v_lshl_add_u64 v[142:143], s[6:7], 0, v[98:99]
	v_lshl_add_u64 v[132:133], s[6:7], 0, v[100:101]
	s_add_i32 s6, s12, 0xffffc003
	s_cmpk_lt_i32 s12, 0x3fff
	s_cselect_b32 s6, s8, s6
	s_addk_i32 s6, 0x82
	s_mul_hi_i32 s7, s6, 0x9000
	s_mul_i32 s6, s6, 0x9000
	s_add_u32 s9, s3, s6
	v_lshl_add_u64 v[152:153], s[10:11], 0, v[96:97]
	v_lshl_add_u64 v[146:147], s[10:11], 0, v[98:99]
	v_lshl_add_u64 v[140:141], s[10:11], 0, v[100:101]
	s_addc_u32 s11, s4, s7
	s_add_u32 s6, s9, 0x6000
	s_addc_u32 s7, s11, 0
	s_add_u32 s10, s9, 0x7000
	v_lshl_add_u64 v[134:135], s[6:7], 0, v[90:91]
	v_lshl_add_u64 v[126:127], s[6:7], 0, v[96:97]
	v_lshl_add_u64 v[118:119], s[6:7], 0, v[98:99]
	v_lshl_add_u64 v[114:115], s[6:7], 0, v[100:101]
	s_addc_u32 s11, s11, 0
	s_add_i32 s6, s12, 0xffffc004
	s_cmpk_lt_i32 s12, 0x3ffe
	s_cselect_b32 s6, s8, s6
	s_addk_i32 s6, 0x82
	s_mul_hi_i32 s7, s6, 0x9000
	s_mul_i32 s6, s6, 0x9000
	s_add_u32 s6, s3, s6
	s_addc_u32 s7, s4, s7
	v_lshl_add_u64 v[136:137], s[10:11], 0, v[90:91]
	v_lshl_add_u64 v[130:131], s[10:11], 0, v[96:97]
	v_lshl_add_u64 v[122:123], s[10:11], 0, v[98:99]
	v_lshl_add_u64 v[116:117], s[10:11], 0, v[100:101]
	s_add_u32 s10, s6, 0x6000
	s_addc_u32 s11, s7, 0
	s_add_u32 s6, s6, 0x7000
	s_addc_u32 s7, s7, 0
	s_add_i32 s9, s12, 0xffffc005
	s_cmpk_lt_i32 s12, 0x3ffd
	v_lshl_add_u64 v[156:157], s[6:7], 0, v[90:91]
	v_lshl_add_u64 v[154:155], s[6:7], 0, v[96:97]
	v_lshl_add_u64 v[150:151], s[6:7], 0, v[98:99]
	v_lshl_add_u64 v[138:139], s[6:7], 0, v[100:101]
	s_cselect_b32 s6, s8, s9
	s_addk_i32 s6, 0x82
	s_waitcnt vmcnt(0) lgkmcnt(0)
	v_pk_mul_f32 v[158:159], v[80:81], v[80:81]
	v_pk_mul_f32 v[160:161], v[78:79], v[78:79]
	v_pk_mul_f32 v[162:163], v[76:77], v[76:77]
	v_pk_mul_f32 v[164:165], v[74:75], v[74:75]
	v_mul_f32_e32 v174, v71, v71
	v_mul_f32_e32 v176, v73, v73
	v_mul_f32_e32 v187, v68, v68
	v_mul_f32_e32 v189, v69, v69
	v_pk_mov_b32 v[178:179], v[160:161], v[158:159] op_sel:[1,0]
	v_mov_b32_e32 v161, v159
	v_pk_mov_b32 v[158:159], v[164:165], v[162:163] op_sel:[1,0]
	v_mov_b32_e32 v165, v163
	v_pk_fma_f32 v[162:163], v[70:71], v[70:71], v[174:175] op_sel_hi:[1,1,0]
	v_pk_fma_f32 v[174:175], v[72:73], v[72:73], v[176:177] op_sel_hi:[1,1,0]
	v_pk_mul_f32 v[176:177], v[64:65], v[64:65]
	v_pk_mul_f32 v[180:181], v[62:63], v[62:63]
	v_pk_mul_f32 v[182:183], v[60:61], v[60:61]
	v_pk_mul_f32 v[184:185], v[58:59], v[58:59]
	v_mul_f32_e32 v186, v55, v55
	v_mul_f32_e32 v188, v57, v57
	v_pk_add_f32 v[160:161], v[178:179], v[160:161]
	v_pk_add_f32 v[158:159], v[158:159], v[164:165]
	v_mov_b32_e32 v163, v187
	v_mov_b32_e32 v175, v189
	v_pk_mov_b32 v[164:165], v[180:181], v[176:177] op_sel:[1,0]
	v_mov_b32_e32 v181, v177
	v_pk_mov_b32 v[176:177], v[184:185], v[182:183] op_sel:[1,0]
	v_mov_b32_e32 v185, v183
	v_pk_fma_f32 v[178:179], v[54:55], v[54:55], v[186:187] op_sel_hi:[1,1,0]
	v_pk_fma_f32 v[182:183], v[56:57], v[56:57], v[188:189] op_sel_hi:[1,1,0]
	v_pk_mul_f32 v[186:187], v[48:49], v[48:49]
	v_pk_mul_f32 v[188:189], v[46:47], v[46:47]
	v_pk_mul_f32 v[190:191], v[44:45], v[44:45]
	v_pk_mul_f32 v[192:193], v[42:43], v[42:43]
	v_mul_f32_e32 v197, v66, v66
	v_mul_f32_e32 v203, v67, v67
	v_mul_f32_e32 v195, v52, v52
	v_mul_f32_e32 v202, v53, v53
	v_mul_f32_e32 v194, v39, v39
	v_mul_f32_e32 v196, v41, v41
	v_pk_add_f32 v[198:199], v[160:161], v[160:161] op_sel:[0,1] op_sel_hi:[1,0]
	v_pk_add_f32 v[200:201], v[158:159], v[158:159] op_sel:[0,1] op_sel_hi:[1,0]
	v_pk_add_f32 v[174:175], v[162:163], v[174:175]
	v_pk_add_f32 v[158:159], v[164:165], v[180:181]
	v_pk_add_f32 v[160:161], v[176:177], v[184:185]
	v_pk_mov_b32 v[162:163], v[188:189], v[186:187] op_sel:[1,0]
	v_mov_b32_e32 v189, v187
	v_pk_mov_b32 v[164:165], v[192:193], v[190:191] op_sel:[1,0]
	v_mov_b32_e32 v193, v191
	v_mul_f32_e32 v208, v50, v50
	v_mul_f32_e32 v209, v51, v51
	v_mul_f32_e32 v212, v36, v36
	v_mul_f32_e32 v213, v37, v37
	v_mov_b32_e32 v179, v195
	v_mov_b32_e32 v183, v202
	v_pk_fma_f32 v[176:177], v[38:39], v[38:39], v[194:195] op_sel_hi:[1,1,0]
	v_pk_fma_f32 v[180:181], v[40:41], v[40:41], v[196:197] op_sel_hi:[1,1,0]
	v_pk_mul_f32 v[184:185], v[32:33], v[32:33]
	v_pk_mul_f32 v[186:187], v[30:31], v[30:31]
	v_pk_mul_f32 v[190:191], v[28:29], v[28:29]
	v_pk_mul_f32 v[194:195], v[26:27], v[26:27]
	v_mov_b32_e32 v199, v197
	v_mov_b32_e32 v201, v203
	v_pk_add_f32 v[204:205], v[158:159], v[158:159] op_sel:[0,1] op_sel_hi:[1,0]
	v_pk_add_f32 v[206:207], v[160:161], v[160:161] op_sel:[0,1] op_sel_hi:[1,0]
	v_pk_add_f32 v[162:163], v[162:163], v[188:189]
	v_pk_add_f32 v[164:165], v[164:165], v[192:193]
	v_mul_f32_e32 v210, v34, v34
	v_mul_f32_e32 v211, v35, v35
	v_pk_add_f32 v[178:179], v[178:179], v[182:183]
	v_mov_b32_e32 v177, v212
	v_mov_b32_e32 v181, v213
	v_pk_mov_b32 v[182:183], v[186:187], v[184:185] op_sel:[1,0]
	v_mov_b32_e32 v187, v185
	v_pk_mov_b32 v[184:185], v[194:195], v[190:191] op_sel:[1,0]
	v_mov_b32_e32 v195, v191
	v_pk_add_f32 v[188:189], v[198:199], v[200:201]
	v_mov_b32_e32 v205, v208
	v_mov_b32_e32 v207, v209
	v_pk_add_f32 v[190:191], v[162:163], v[162:163] op_sel:[0,1] op_sel_hi:[1,0]
	v_pk_add_f32 v[192:193], v[164:165], v[164:165] op_sel:[0,1] op_sel_hi:[1,0]
	v_pk_add_f32 v[176:177], v[176:177], v[180:181]
	v_pk_add_f32 v[174:175], v[188:189], v[174:175]
	v_pk_add_f32 v[180:181], v[204:205], v[206:207]
	v_mov_b32_e32 v191, v210
	v_mov_b32_e32 v193, v211
	v_pk_add_f32 v[162:163], v[182:183], v[186:187]
	v_add_f32_e32 v182, v174, v175
	v_pk_add_f32 v[174:175], v[180:181], v[178:179]
	v_pk_add_f32 v[178:179], v[190:191], v[192:193]
	v_add_f32_e32 v180, v174, v175
	v_pk_add_f32 v[174:175], v[178:179], v[176:177]
	ds_bpermute_b32 v176, v1, v182
	v_add_f32_e32 v174, v174, v175
	ds_bpermute_b32 v175, v1, v180
	ds_bpermute_b32 v177, v1, v174
	s_mul_hi_i32 s7, s6, 0x9000
	s_waitcnt lgkmcnt(2)
	v_add_f32_e32 v176, v182, v176
	ds_bpermute_b32 v178, v167, v176
	s_waitcnt lgkmcnt(2)
	v_add_f32_e32 v175, v180, v175
	ds_bpermute_b32 v179, v167, v175
	s_waitcnt lgkmcnt(2)
	v_add_f32_e32 v174, v174, v177
	ds_bpermute_b32 v177, v167, v174
	s_waitcnt lgkmcnt(2)
	v_add_f32_e32 v176, v176, v178
	ds_bpermute_b32 v178, v168, v176
	s_waitcnt lgkmcnt(2)
	v_add_f32_e32 v175, v175, v179
	ds_bpermute_b32 v179, v168, v175
	s_waitcnt lgkmcnt(2)
	v_add_f32_e32 v174, v174, v177
	ds_bpermute_b32 v177, v168, v174
	s_waitcnt lgkmcnt(2)
	v_add_f32_e32 v176, v176, v178
	ds_bpermute_b32 v178, v169, v176
	s_waitcnt lgkmcnt(2)
	v_add_f32_e32 v175, v175, v179
	ds_bpermute_b32 v179, v169, v175
	s_waitcnt lgkmcnt(2)
	v_add_f32_e32 v174, v174, v177
	ds_bpermute_b32 v177, v169, v174
	s_waitcnt lgkmcnt(2)
	v_add_f32_e32 v176, v176, v178
	ds_bpermute_b32 v178, v170, v176
	s_waitcnt lgkmcnt(2)
	v_add_f32_e32 v175, v175, v179
	ds_bpermute_b32 v179, v170, v175
	s_waitcnt lgkmcnt(2)
	v_add_f32_e32 v174, v174, v177
	ds_bpermute_b32 v177, v170, v174
	s_waitcnt lgkmcnt(2)
	v_add_f32_e32 v176, v176, v178
	ds_bpermute_b32 v178, v171, v176
	s_waitcnt lgkmcnt(2)
	v_add_f32_e32 v175, v175, v179
	ds_bpermute_b32 v179, v171, v175
	s_mul_i32 s6, s6, 0x9000
	s_waitcnt lgkmcnt(2)
	v_add_f32_e32 v174, v174, v177
	s_add_u32 s6, s3, s6
	ds_bpermute_b32 v177, v171, v174
	s_addc_u32 s7, s4, s7
	s_waitcnt lgkmcnt(2)
	v_add_f32_e32 v176, v176, v178
	s_add_u32 s18, s6, 0x6000
	v_fmamk_f32 v176, v176, 0x3a800000, v172
	s_addc_u32 s19, s7, 0
	s_waitcnt lgkmcnt(1)
	v_add_f32_e32 v175, v175, v179
	v_mul_f32_e32 v178, 0x4f800000, v176
	v_cmp_gt_f32_e32 vcc, s13, v176
	s_add_u32 s20, s6, 0x7000
	v_fmamk_f32 v175, v175, 0x3a800000, v172
	v_cndmask_b32_e32 v176, v176, v178, vcc
	s_addc_u32 s21, s7, 0
	s_waitcnt lgkmcnt(0)
	v_add_f32_e32 v174, v174, v177
	v_mul_f32_e32 v177, 0x4f800000, v175
	v_cmp_gt_f32_e64 s[6:7], s13, v175
	v_sqrt_f32_e32 v178, v176
	v_fmamk_f32 v174, v174, 0x3a800000, v172
	v_cndmask_b32_e64 v175, v175, v177, s[6:7]
	v_mul_f32_e32 v177, 0x4f800000, v174
	v_cmp_gt_f32_e64 s[8:9], s13, v174
	v_sqrt_f32_e32 v179, v175
	v_add_u32_e32 v180, -1, v178
	v_cndmask_b32_e64 v174, v174, v177, s[8:9]
	v_sqrt_f32_e32 v177, v174
	v_add_u32_e32 v181, 1, v178
	v_fma_f32 v182, -v180, v178, v176
	v_lshl_add_u64 v[112:113], s[10:11], 0, v[90:91]
	v_lshl_add_u64 v[106:107], s[10:11], 0, v[96:97]
	v_lshl_add_u64 v[110:111], s[10:11], 0, v[98:99]
	v_lshl_add_u64 v[108:109], s[10:11], 0, v[100:101]
	v_pk_add_f32 v[164:165], v[184:185], v[194:195]
	v_fma_f32 v183, -v181, v178, v176
	v_add_u32_e32 v184, -1, v179
	v_cmp_ge_f32_e64 s[10:11], 0, v182
	v_add_u32_e32 v185, 1, v179
	v_fma_f32 v182, -v185, v179, v175
	v_cndmask_b32_e64 v178, v178, v180, s[10:11]
	v_fma_f32 v180, -v184, v179, v175
	v_cmp_lt_f32_e64 s[10:11], 0, v183
	v_add_u32_e32 v186, -1, v177
	v_add_u32_e32 v187, 1, v177
	v_cndmask_b32_e64 v178, v178, v181, s[10:11]
	v_cmp_ge_f32_e64 s[10:11], 0, v180
	v_fma_f32 v180, -v186, v177, v174
	v_fma_f32 v181, -v187, v177, v174
	v_cndmask_b32_e64 v179, v179, v184, s[10:11]
	v_cmp_lt_f32_e64 s[10:11], 0, v182
	v_mul_f32_e32 v182, 0x37800000, v178
	v_cndmask_b32_e32 v178, v178, v182, vcc
	v_cndmask_b32_e64 v179, v179, v185, s[10:11]
	v_cmp_ge_f32_e64 s[10:11], 0, v180
	v_cmp_class_f32_e32 vcc, v176, v173
	v_mul_f32_e32 v180, 0x37800000, v179
	v_cndmask_b32_e64 v177, v177, v186, s[10:11]
	v_cmp_lt_f32_e64 s[10:11], 0, v181
	v_cndmask_b32_e32 v176, v178, v176, vcc
	v_cndmask_b32_e64 v178, v179, v180, s[6:7]
	v_cndmask_b32_e64 v177, v177, v187, s[10:11]
	v_cmp_class_f32_e32 vcc, v175, v173
	v_mul_f32_e32 v179, 0x37800000, v177
	v_div_scale_f32 v180, s[6:7], v176, v176, 1.0
	v_cndmask_b32_e32 v175, v178, v175, vcc
	v_cndmask_b32_e64 v177, v177, v179, s[8:9]
	v_cmp_class_f32_e32 vcc, v174, v173
	v_rcp_f32_e32 v178, v180
	v_div_scale_f32 v179, s[8:9], v175, v175, 1.0
	v_cndmask_b32_e32 v177, v177, v174, vcc
	v_rcp_f32_e32 v183, v179
	v_div_scale_f32 v184, s[10:11], v177, v177, 1.0
	v_rcp_f32_e32 v186, v184
	v_fma_f32 v174, -v180, v178, 1.0
	v_div_scale_f32 v181, s[6:7], 1.0, v176, 1.0
	v_fmac_f32_e32 v178, v174, v178
	v_fma_f32 v174, -v179, v183, 1.0
	v_mul_f32_e32 v187, v181, v178
	v_div_scale_f32 v182, s[8:9], 1.0, v175, 1.0
	v_fmac_f32_e32 v183, v174, v183
	v_fma_f32 v174, -v184, v186, 1.0
	v_fma_f32 v188, -v180, v187, v181
	v_div_scale_f32 v185, s[10:11], 1.0, v177, 1.0
	v_mul_f32_e32 v189, v182, v183
	v_fmac_f32_e32 v186, v174, v186
	v_fmac_f32_e32 v187, v188, v178
	v_fma_f32 v174, -v179, v189, v182
	v_mul_f32_e32 v188, v185, v186
	v_fma_f32 v180, -v180, v187, v181
	s_mov_b64 vcc, s[6:7]
	v_fmac_f32_e32 v189, v174, v183
	v_fma_f32 v174, -v184, v188, v185
	v_div_fmas_f32 v178, v180, v178, v187
	v_fma_f32 v179, -v179, v189, v182
	v_fmac_f32_e32 v188, v174, v186
	v_div_fixup_f32 v174, v178, v176, 1.0
	s_mov_b64 vcc, s[8:9]
	v_div_fmas_f32 v176, v179, v183, v189
	v_fma_f32 v178, -v184, v188, v185
	v_pk_mul_f32 v[80:81], v[80:81], v[174:175] op_sel_hi:[1,0]
	v_pk_mul_f32 v[78:79], v[78:79], v[174:175] op_sel_hi:[1,0]
	s_mov_b64 vcc, s[10:11]
	v_pk_add_f32 v[88:89], v[88:89], 1.0 op_sel_hi:[1,0]
	v_pk_add_f32 v[86:87], v[86:87], 1.0 op_sel_hi:[1,0]
	v_pk_mul_f32 v[76:77], v[76:77], v[174:175] op_sel_hi:[1,0]
	v_pk_mul_f32 v[74:75], v[74:75], v[174:175] op_sel_hi:[1,0]
	v_pk_mul_f32 v[72:73], v[72:73], v[174:175] op_sel_hi:[1,0]
	v_pk_mul_f32 v[70:71], v[70:71], v[174:175] op_sel_hi:[1,0]
	v_pk_mul_f32 v[68:69], v[68:69], v[174:175] op_sel_hi:[1,0]
	v_pk_mul_f32 v[66:67], v[66:67], v[174:175] op_sel_hi:[1,0]
	v_div_fixup_f32 v174, v176, v175, 1.0
	v_div_fmas_f32 v176, v178, v186, v188
	v_pk_mul_f32 v[78:79], v[2:3], v[78:79]
	v_pk_mul_f32 v[80:81], v[4:5], v[80:81]
	v_pk_mul_f32 v[64:65], v[64:65], v[174:175] op_sel_hi:[1,0]
	v_pk_mul_f32 v[62:63], v[62:63], v[174:175] op_sel_hi:[1,0]
	v_pk_mul_f32 v[60:61], v[60:61], v[174:175] op_sel_hi:[1,0]
	v_pk_mul_f32 v[58:59], v[58:59], v[174:175] op_sel_hi:[1,0]
	v_pk_mul_f32 v[56:57], v[56:57], v[174:175] op_sel_hi:[1,0]
	v_pk_mul_f32 v[54:55], v[54:55], v[174:175] op_sel_hi:[1,0]
	v_pk_mul_f32 v[52:53], v[52:53], v[174:175] op_sel_hi:[1,0]
	v_pk_mul_f32 v[174:175], v[50:51], v[174:175] op_sel_hi:[1,0]
	v_div_fixup_f32 v50, v176, v177, 1.0
	v_pk_fma_f32 v[80:81], v[88:89], v[80:81], v[84:85]
	v_pk_fma_f32 v[78:79], v[86:87], v[78:79], v[82:83]
	v_pk_mul_f32 v[86:87], v[16:17], v[52:53]
	v_pk_mul_f32 v[48:49], v[48:49], v[50:51] op_sel_hi:[1,0]
	v_pk_mul_f32 v[46:47], v[46:47], v[50:51] op_sel_hi:[1,0]
	v_pk_mul_f32 v[82:83], v[10:11], v[54:55]
	v_pk_mul_f32 v[84:85], v[14:15], v[174:175]
	v_pk_mul_f32 v[88:89], v[2:3], v[46:47]
	v_pk_mul_f32 v[174:175], v[4:5], v[48:49]
	v_cvt_pk_bf16_f32 v46, v78, v79
	v_cvt_pk_bf16_f32 v47, v80, v81
	global_store_dwordx2 v[102:103], v[46:47], off
	global_load_dwordx4 v[238:241], v[152:153], off
	s_nop 0
	global_load_dwordx4 v[242:245], v[148:149], off
	v_pk_mul_f32 v[74:75], v[6:7], v[74:75]
	v_pk_mul_f32 v[76:77], v[8:9], v[76:77]
	v_pk_mul_f32 v[70:71], v[10:11], v[70:71]
	v_pk_mul_f32 v[72:73], v[12:13], v[72:73]
	v_pk_mul_f32 v[66:67], v[66:67], v[14:15]
	v_pk_mul_f32 v[68:69], v[68:69], v[16:17]
	v_pk_mul_f32 v[62:63], v[2:3], v[62:63]
	v_pk_mul_f32 v[64:65], v[4:5], v[64:65]
	v_pk_mul_f32 v[58:59], v[6:7], v[58:59]
	v_pk_mul_f32 v[60:61], v[8:9], v[60:61]
	v_pk_mul_f32 v[56:57], v[12:13], v[56:57]
	v_mul_f32_e32 v196, v23, v23
	v_mul_f32_e32 v202, v25, v25
	v_mul_f32_e32 v214, v18, v18
	v_mul_f32_e32 v215, v19, v19
	v_mul_f32_e32 v216, v20, v20
	v_mul_f32_e32 v217, v21, v21
	v_pk_fma_f32 v[158:159], v[22:23], v[22:23], v[196:197] op_sel_hi:[1,1,0]
	v_pk_fma_f32 v[160:161], v[24:25], v[24:25], v[202:203] op_sel_hi:[1,1,0]
	v_mov_b32_e32 v159, v216
	v_mov_b32_e32 v161, v217
	v_lshl_add_u64 v[144:145], s[20:21], 0, v[90:91]
	v_lshl_add_u64 v[128:129], s[18:19], 0, v[90:91]
	v_lshl_add_u64 v[124:125], s[20:21], 0, v[96:97]
	v_lshl_add_u64 v[120:121], s[18:19], 0, v[96:97]
	s_add_i32 s12, s12, 32
	v_lshl_add_u64 v[92:93], v[92:93], 0, s[14:15]
	v_lshl_add_u64 v[94:95], v[94:95], 0, s[16:17]
	s_cmp_lt_i32 s12, s2
	global_load_dwordx4 v[230:233], v[146:147], off
	s_nop 0
	global_load_dwordx4 v[234:237], v[142:143], off
	s_waitcnt vmcnt(2) lgkmcnt(0)
	v_pk_add_f32 v[240:241], v[240:241], 1.0 op_sel_hi:[1,0]
	v_pk_add_f32 v[238:239], v[238:239], 1.0 op_sel_hi:[1,0]
	v_pk_fma_f32 v[240:241], v[240:241], v[76:77], v[244:245]
	v_pk_fma_f32 v[238:239], v[238:239], v[74:75], v[242:243]
	v_cvt_pk_bf16_f32 v238, v238, v239
	v_cvt_pk_bf16_f32 v239, v240, v241
	global_store_dwordx2 v[102:103], v[238:239], off offset:512
	global_load_dwordx4 v[238:241], v[140:141], off
	s_nop 0
	global_load_dwordx4 v[242:245], v[132:133], off
	s_waitcnt vmcnt(3) lgkmcnt(0)
	v_pk_add_f32 v[232:233], v[232:233], 1.0 op_sel_hi:[1,0]
	v_pk_add_f32 v[230:231], v[230:231], 1.0 op_sel_hi:[1,0]
	v_pk_fma_f32 v[232:233], v[72:73], v[232:233], v[236:237]
	v_pk_fma_f32 v[230:231], v[70:71], v[230:231], v[234:235]
	v_cvt_pk_bf16_f32 v230, v230, v231
	v_cvt_pk_bf16_f32 v231, v232, v233
	global_store_dwordx2 v[102:103], v[230:231], off offset:1024
	global_load_dwordx4 v[230:233], v[136:137], off
	s_nop 0
	global_load_dwordx4 v[234:237], v[134:135], off
	s_waitcnt vmcnt(3) lgkmcnt(0)
	v_pk_add_f32 v[240:241], v[240:241], 1.0 op_sel_hi:[1,0]
	v_pk_add_f32 v[238:239], v[238:239], 1.0 op_sel_hi:[1,0]
	v_pk_fma_f32 v[240:241], v[68:69], v[240:241], v[244:245]
	v_pk_fma_f32 v[238:239], v[66:67], v[238:239], v[242:243]
	v_cvt_pk_bf16_f32 v238, v238, v239
	v_cvt_pk_bf16_f32 v239, v240, v241
	global_store_dwordx2 v[102:103], v[238:239], off offset:1536
	global_load_dwordx4 v[238:241], v[130:131], off
	s_nop 0
	global_load_dwordx4 v[242:245], v[126:127], off
	s_waitcnt vmcnt(3) lgkmcnt(0)
	v_pk_add_f32 v[232:233], v[232:233], 1.0 op_sel_hi:[1,0]
	v_pk_add_f32 v[230:231], v[230:231], 1.0 op_sel_hi:[1,0]
	v_pk_fma_f32 v[232:233], v[232:233], v[64:65], v[236:237]
	v_pk_fma_f32 v[230:231], v[230:231], v[62:63], v[234:235]
	v_cvt_pk_bf16_f32 v230, v230, v231
	v_cvt_pk_bf16_f32 v231, v232, v233
	global_store_dwordx2 v[102:103], v[230:231], off offset:2048
	global_load_dwordx4 v[230:233], v[122:123], off
	s_nop 0
	global_load_dwordx4 v[234:237], v[118:119], off
	s_waitcnt vmcnt(3) lgkmcnt(0)
	v_pk_add_f32 v[240:241], v[240:241], 1.0 op_sel_hi:[1,0]
	v_pk_add_f32 v[238:239], v[238:239], 1.0 op_sel_hi:[1,0]
	v_pk_fma_f32 v[240:241], v[240:241], v[60:61], v[244:245]
	v_pk_fma_f32 v[238:239], v[238:239], v[58:59], v[242:243]
	v_cvt_pk_bf16_f32 v238, v238, v239
	v_cvt_pk_bf16_f32 v239, v240, v241
	global_store_dwordx2 v[102:103], v[238:239], off offset:2560
	v_pk_add_f32 v[58:59], v[164:165], v[164:165] op_sel:[0,1] op_sel_hi:[1,0]
	v_pk_add_f32 v[60:61], v[158:159], v[160:161]
	v_mov_b32_e32 v59, v215
	global_load_dwordx4 v[238:241], v[116:117], off
	s_nop 0
	global_load_dwordx4 v[242:245], v[114:115], off
	s_waitcnt vmcnt(3) lgkmcnt(0)
	v_pk_add_f32 v[232:233], v[232:233], 1.0 op_sel_hi:[1,0]
	v_pk_add_f32 v[230:231], v[230:231], 1.0 op_sel_hi:[1,0]
	v_pk_fma_f32 v[232:233], v[232:233], v[56:57], v[236:237]
	v_pk_fma_f32 v[230:231], v[230:231], v[82:83], v[234:235]
	v_cvt_pk_bf16_f32 v230, v230, v231
	v_cvt_pk_bf16_f32 v231, v232, v233
	global_store_dwordx2 v[102:103], v[230:231], off offset:3072
	v_pk_add_f32 v[56:57], v[162:163], v[162:163] op_sel:[0,1] op_sel_hi:[1,0]
	global_load_dwordx4 v[230:233], v[156:157], off
	s_nop 0
	global_load_dwordx4 v[234:237], v[112:113], off
	s_waitcnt vmcnt(3) lgkmcnt(0)
	v_pk_add_f32 v[240:241], v[240:241], 1.0 op_sel_hi:[1,0]
	v_pk_add_f32 v[238:239], v[238:239], 1.0 op_sel_hi:[1,0]
	v_pk_fma_f32 v[240:241], v[86:87], v[240:241], v[244:245]
	v_pk_fma_f32 v[238:239], v[84:85], v[238:239], v[242:243]
	v_cvt_pk_bf16_f32 v238, v238, v239
	v_cvt_pk_bf16_f32 v239, v240, v241
	global_store_dwordx2 v[102:103], v[238:239], off offset:3584
	v_mov_b32_e32 v57, v214
	global_load_dwordx4 v[238:241], v[154:155], off
	s_nop 0
	global_load_dwordx4 v[242:245], v[106:107], off
	s_waitcnt vmcnt(3) lgkmcnt(0)
	v_pk_add_f32 v[232:233], v[232:233], 1.0 op_sel_hi:[1,0]
	v_pk_add_f32 v[230:231], v[230:231], 1.0 op_sel_hi:[1,0]
	v_pk_fma_f32 v[232:233], v[232:233], v[174:175], v[236:237]
	v_pk_fma_f32 v[230:231], v[230:231], v[88:89], v[234:235]
	v_bfe_u32 v51, v230, 16, 1
	v_bfe_u32 v234, v231, 16, 1
	v_add3_u32 v230, v230, v51, s22
	v_add3_u32 v231, v231, v234, s22
	v_lshrrev_b32_e32 v230, 16, v230
	v_and_or_b32 v230, v231, s23, v230
	v_cvt_pk_bf16_f32 v231, v232, v233
	global_store_dwordx2 v[104:105], v[230:231], off
	v_pk_mul_f32 v[44:45], v[44:45], v[50:51] op_sel_hi:[1,0]
	v_pk_mul_f32 v[42:43], v[42:43], v[50:51] op_sel_hi:[1,0]
	v_pk_mul_f32 v[44:45], v[8:9], v[44:45]
	v_pk_mul_f32 v[42:43], v[6:7], v[42:43]
	s_waitcnt vmcnt(1) lgkmcnt(0)
	v_pk_add_f32 v[240:241], v[240:241], 1.0 op_sel_hi:[1,0]
	v_pk_add_f32 v[238:239], v[238:239], 1.0 op_sel_hi:[1,0]
	v_pk_fma_f32 v[44:45], v[240:241], v[44:45], v[244:245]
	v_pk_fma_f32 v[42:43], v[238:239], v[42:43], v[242:243]
	v_cvt_pk_bf16_f32 v42, v42, v43
	v_cvt_pk_bf16_f32 v43, v44, v45
	global_store_dwordx2 v[104:105], v[42:43], off offset:512
	global_load_dwordx4 v[42:45], v[150:151], off
	s_nop 0
	global_load_dwordx4 v[46:49], v[110:111], off
	v_pk_add_f32 v[52:53], v[56:57], v[58:59]
	s_waitcnt vmcnt(0) lgkmcnt(0)
	v_pk_add_f32 v[44:45], v[44:45], 1.0 op_sel_hi:[1,0]
	v_pk_add_f32 v[52:53], v[52:53], v[60:61]
	v_pk_add_f32 v[42:43], v[42:43], 1.0 op_sel_hi:[1,0]
	v_add_f32_e32 v51, v52, v53
	ds_bpermute_b32 v52, v1, v51
	s_waitcnt lgkmcnt(0)
	v_add_f32_e32 v51, v51, v52
	ds_bpermute_b32 v52, v167, v51
	s_waitcnt lgkmcnt(0)
	v_add_f32_e32 v51, v51, v52
	v_pk_mul_f32 v[40:41], v[40:41], v[50:51] op_sel_hi:[1,0]
	v_pk_mul_f32 v[38:39], v[38:39], v[50:51] op_sel_hi:[1,0]
	v_pk_mul_f32 v[40:41], v[12:13], v[40:41]
	v_pk_mul_f32 v[38:39], v[10:11], v[38:39]
	v_pk_fma_f32 v[40:41], v[44:45], v[40:41], v[48:49]
	v_pk_fma_f32 v[38:39], v[42:43], v[38:39], v[46:47]
	v_cvt_pk_bf16_f32 v38, v38, v39
	v_cvt_pk_bf16_f32 v39, v40, v41
	global_store_dwordx2 v[104:105], v[38:39], off offset:1024
	global_load_dwordx4 v[38:41], v[138:139], off
	s_nop 0
	global_load_dwordx4 v[42:45], v[108:109], off
	v_pk_mul_f32 v[36:37], v[36:37], v[50:51] op_sel_hi:[1,0]
	v_pk_mul_f32 v[34:35], v[34:35], v[50:51] op_sel_hi:[1,0]
	v_pk_mul_f32 v[36:37], v[16:17], v[36:37]
	v_pk_mul_f32 v[34:35], v[14:15], v[34:35]
	ds_bpermute_b32 v46, v168, v51
	s_waitcnt lgkmcnt(0)
	v_add_f32_e32 v46, v51, v46
	ds_bpermute_b32 v47, v169, v46
	s_waitcnt lgkmcnt(0)
	v_add_f32_e32 v46, v46, v47
	ds_bpermute_b32 v47, v170, v46
	s_waitcnt lgkmcnt(0)
	v_add_f32_e32 v46, v46, v47
	ds_bpermute_b32 v47, v171, v46
	s_waitcnt lgkmcnt(0)
	v_add_f32_e32 v46, v46, v47
	v_fmamk_f32 v46, v46, 0x3a800000, v172
	v_mul_f32_e32 v47, 0x4f800000, v46
	v_cmp_gt_f32_e32 vcc, s13, v46
	s_waitcnt vmcnt(0)
	v_pk_add_f32 v[40:41], v[40:41], 1.0 op_sel_hi:[1,0]
	v_pk_add_f32 v[38:39], v[38:39], 1.0 op_sel_hi:[1,0]
	v_pk_fma_f32 v[36:37], v[36:37], v[40:41], v[44:45]
	v_pk_fma_f32 v[34:35], v[34:35], v[38:39], v[42:43]
	v_cvt_pk_bf16_f32 v34, v34, v35
	v_cvt_pk_bf16_f32 v35, v36, v37
	global_store_dwordx2 v[104:105], v[34:35], off offset:1536
	global_load_dwordx4 v[34:37], v[144:145], off
	s_nop 0
	global_load_dwordx4 v[38:41], v[128:129], off
	v_cndmask_b32_e32 v42, v46, v47, vcc
	v_sqrt_f32_e32 v43, v42
	s_waitcnt vmcnt(0) lgkmcnt(0)
	v_pk_add_f32 v[36:37], v[36:37], 1.0 op_sel_hi:[1,0]
	v_add_u32_e32 v44, -1, v43
	v_add_u32_e32 v45, 1, v43
	v_fma_f32 v46, -v44, v43, v42
	v_fma_f32 v47, -v45, v43, v42
	v_cmp_ge_f32_e64 s[6:7], 0, v46
	v_pk_add_f32 v[34:35], v[34:35], 1.0 op_sel_hi:[1,0]
	s_nop 0
	v_cndmask_b32_e64 v43, v43, v44, s[6:7]
	v_cmp_lt_f32_e64 s[6:7], 0, v47
	s_nop 1
	v_cndmask_b32_e64 v43, v43, v45, s[6:7]
	v_mul_f32_e32 v44, 0x37800000, v43
	v_cndmask_b32_e32 v43, v43, v44, vcc
	v_cmp_class_f32_e32 vcc, v42, v173
	s_nop 1
	v_cndmask_b32_e32 v42, v43, v42, vcc
	v_div_scale_f32 v43, s[6:7], v42, v42, 1.0
	v_rcp_f32_e32 v45, v43
	v_div_scale_f32 v44, vcc, 1.0, v42, 1.0
	v_fma_f32 v46, -v43, v45, 1.0
	v_fmac_f32_e32 v45, v46, v45
	v_mul_f32_e32 v46, v44, v45
	v_fma_f32 v47, -v43, v46, v44
	v_fmac_f32_e32 v46, v47, v45
	v_fma_f32 v43, -v43, v46, v44
	v_div_fmas_f32 v43, v43, v45, v46
	v_div_fixup_f32 v42, v43, v42, 1.0
	v_pk_mul_f32 v[32:33], v[32:33], v[42:43] op_sel_hi:[1,0]
	v_pk_mul_f32 v[30:31], v[30:31], v[42:43] op_sel_hi:[1,0]
	v_pk_mul_f32 v[32:33], v[4:5], v[32:33]
	v_pk_mul_f32 v[30:31], v[2:3], v[30:31]
	v_pk_fma_f32 v[32:33], v[36:37], v[32:33], v[40:41]
	v_pk_fma_f32 v[30:31], v[34:35], v[30:31], v[38:39]
	v_cvt_pk_bf16_f32 v30, v30, v31
	v_cvt_pk_bf16_f32 v31, v32, v33
	global_store_dwordx2 v[104:105], v[30:31], off offset:2048
	global_load_dwordx4 v[30:33], v[124:125], off
	s_nop 0
	global_load_dwordx4 v[34:37], v[120:121], off
	v_pk_mul_f32 v[28:29], v[28:29], v[42:43] op_sel_hi:[1,0]
	v_pk_mul_f32 v[26:27], v[26:27], v[42:43] op_sel_hi:[1,0]
	v_pk_mul_f32 v[28:29], v[8:9], v[28:29]
	v_pk_mul_f32 v[26:27], v[6:7], v[26:27]
	v_lshl_add_u64 v[40:41], s[20:21], 0, v[98:99]
	v_lshl_add_u64 v[38:39], s[18:19], 0, v[98:99]
	v_pk_mul_f32 v[24:25], v[24:25], v[42:43] op_sel_hi:[1,0]
	v_pk_mul_f32 v[22:23], v[22:23], v[42:43] op_sel_hi:[1,0]
	v_pk_mul_f32 v[24:25], v[12:13], v[24:25]
	v_pk_mul_f32 v[22:23], v[10:11], v[22:23]
	v_pk_mul_f32 v[20:21], v[20:21], v[42:43] op_sel_hi:[1,0]
	v_pk_mul_f32 v[18:19], v[18:19], v[42:43] op_sel_hi:[1,0]
	v_pk_mul_f32 v[20:21], v[16:17], v[20:21]
	v_pk_mul_f32 v[18:19], v[14:15], v[18:19]
	s_waitcnt vmcnt(0) lgkmcnt(0)
	v_pk_add_f32 v[32:33], v[32:33], 1.0 op_sel_hi:[1,0]
	v_pk_add_f32 v[30:31], v[30:31], 1.0 op_sel_hi:[1,0]
	v_pk_fma_f32 v[28:29], v[32:33], v[28:29], v[36:37]
	v_pk_fma_f32 v[26:27], v[30:31], v[26:27], v[34:35]
	v_cvt_pk_bf16_f32 v26, v26, v27
	v_cvt_pk_bf16_f32 v27, v28, v29
	global_store_dwordx2 v[104:105], v[26:27], off offset:2560
	global_load_dwordx4 v[26:29], v[40:41], off
	s_nop 0
	global_load_dwordx4 v[30:33], v[38:39], off
	v_lshl_add_u64 v[36:37], s[20:21], 0, v[100:101]
	v_lshl_add_u64 v[34:35], s[18:19], 0, v[100:101]
	s_waitcnt vmcnt(0) lgkmcnt(0)
	v_pk_add_f32 v[28:29], v[28:29], 1.0 op_sel_hi:[1,0]
	v_pk_add_f32 v[26:27], v[26:27], 1.0 op_sel_hi:[1,0]
	v_pk_fma_f32 v[24:25], v[28:29], v[24:25], v[32:33]
	v_pk_fma_f32 v[22:23], v[26:27], v[22:23], v[30:31]
	v_cvt_pk_bf16_f32 v22, v22, v23
	v_cvt_pk_bf16_f32 v23, v24, v25
	global_store_dwordx2 v[104:105], v[22:23], off offset:3072
	global_load_dwordx4 v[22:25], v[36:37], off
	s_nop 0
	global_load_dwordx4 v[26:29], v[34:35], off
	s_waitcnt vmcnt(0) lgkmcnt(0)
	v_pk_add_f32 v[24:25], v[24:25], 1.0 op_sel_hi:[1,0]
	v_pk_add_f32 v[22:23], v[22:23], 1.0 op_sel_hi:[1,0]
	v_pk_fma_f32 v[20:21], v[20:21], v[24:25], v[28:29]
	v_pk_fma_f32 v[18:19], v[18:19], v[22:23], v[26:27]
	v_cvt_pk_bf16_f32 v18, v18, v19
	v_cvt_pk_bf16_f32 v19, v20, v21
	global_store_dwordx2 v[104:105], v[18:19], off offset:3584
	s_cbranch_scc1 .LBB0_5544

.LBB0_5693:
	v_lshl_add_u64 v[18:19], s[68:69], 0, v[94:95]
	v_lshl_add_u64 v[22:23], s[68:69], 0, v[92:93]
	v_add_co_u32_e32 v20, vcc, 0x7800000, v18
	v_add_co_u32_e64 v102, s[6:7], s22, v22
	s_nop 0
	v_addc_co_u32_e32 v21, vcc, 0, v19, vcc
	v_addc_co_u32_e64 v103, s[6:7], 0, v23, s[6:7]
	v_add_co_u32_e64 v104, s[6:7], s23, v22
	v_add_co_u32_e32 v22, vcc, 0x7801000, v18
	s_nop 0
	v_addc_co_u32_e64 v105, s[6:7], 0, v23, s[6:7]
	global_load_dwordx4 v[78:81], v[20:21], off
	global_load_dwordx4 v[74:77], v[20:21], off offset:1024
	global_load_dwordx4 v[70:73], v[20:21], off offset:2048
	global_load_dwordx4 v[66:69], v[20:21], off offset:3072
	v_addc_co_u32_e32 v23, vcc, 0, v19, vcc
	v_add_co_u32_e32 v20, vcc, 0x7802000, v18
	global_load_dwordx4 v[62:65], v[22:23], off
	global_load_dwordx4 v[58:61], v[22:23], off offset:1024
	global_load_dwordx4 v[54:57], v[22:23], off offset:2048
	global_load_dwordx4 v[50:53], v[22:23], off offset:3072
	v_addc_co_u32_e32 v21, vcc, 0, v19, vcc
	v_add_co_u32_e32 v82, vcc, 0x7803000, v18
	global_load_dwordx4 v[46:49], v[20:21], off
	global_load_dwordx4 v[42:45], v[20:21], off offset:1024
	global_load_dwordx4 v[38:41], v[20:21], off offset:2048
	global_load_dwordx4 v[34:37], v[20:21], off offset:3072
	v_addc_co_u32_e32 v83, vcc, 0, v19, vcc
	global_load_dwordx4 v[30:33], v[82:83], off
	global_load_dwordx4 v[26:29], v[82:83], off offset:1024
	global_load_dwordx4 v[22:25], v[82:83], off offset:2048
	global_load_dwordx4 v[18:21], v[82:83], off offset:3072
	s_add_i32 s24, s8, 32
	s_add_i32 s10, s8, 0xffffc022
	s_ashr_i32 s9, s24, 13
	s_cmpk_lt_i32 s24, 0x4000
	s_cselect_b32 s6, s9, s10
	s_addk_i32 s6, 0x82
	s_mul_hi_i32 s7, s6, 0x9000
	s_mul_i32 s6, s6, 0x9000
	s_add_u32 s10, s4, s6
	s_addc_u32 s11, s5, s7
	s_add_u32 s6, s10, 0x6000
	s_addc_u32 s7, s11, 0
	s_add_u32 s10, s10, 0x7000
	s_addc_u32 s11, s11, 0
	v_lshl_add_u64 v[82:83], s[6:7], 0, v[90:91]
	v_lshl_add_u64 v[86:87], s[10:11], 0, v[90:91]
	global_load_dwordx4 v[82:85], v[82:83], off
	v_lshl_add_u64 v[148:149], s[6:7], 0, v[96:97]
	global_load_dwordx4 v[86:89], v[86:87], off
	v_lshl_add_u64 v[142:143], s[6:7], 0, v[98:99]
	v_lshl_add_u64 v[132:133], s[6:7], 0, v[100:101]
	s_add_i32 s6, s8, 0xffffc023
	s_cmpk_lt_i32 s24, 0x3fff
	s_cselect_b32 s6, s9, s6
	s_addk_i32 s6, 0x82
	s_mul_hi_i32 s7, s6, 0x9000
	s_mul_i32 s6, s6, 0x9000
	v_lshl_add_u64 v[152:153], s[10:11], 0, v[96:97]
	v_lshl_add_u64 v[146:147], s[10:11], 0, v[98:99]
	v_lshl_add_u64 v[140:141], s[10:11], 0, v[100:101]
	s_add_u32 s10, s4, s6
	s_addc_u32 s11, s5, s7
	s_add_u32 s6, s10, 0x6000
	s_addc_u32 s7, s11, 0
	s_add_u32 s10, s10, 0x7000
	v_lshl_add_u64 v[134:135], s[6:7], 0, v[90:91]
	v_lshl_add_u64 v[126:127], s[6:7], 0, v[96:97]
	v_lshl_add_u64 v[118:119], s[6:7], 0, v[98:99]
	v_lshl_add_u64 v[114:115], s[6:7], 0, v[100:101]
	s_addc_u32 s11, s11, 0
	s_add_i32 s6, s8, 0xffffc024
	s_cmpk_lt_i32 s24, 0x3ffe
	s_cselect_b32 s6, s9, s6
	s_addk_i32 s6, 0x82
	s_mul_hi_i32 s7, s6, 0x9000
	s_mul_i32 s6, s6, 0x9000
	s_add_u32 s6, s4, s6
	s_addc_u32 s7, s5, s7
	v_lshl_add_u64 v[136:137], s[10:11], 0, v[90:91]
	v_lshl_add_u64 v[130:131], s[10:11], 0, v[96:97]
	v_lshl_add_u64 v[122:123], s[10:11], 0, v[98:99]
	v_lshl_add_u64 v[116:117], s[10:11], 0, v[100:101]
	s_add_u32 s10, s6, 0x6000
	s_addc_u32 s11, s7, 0
	s_add_u32 s6, s6, 0x7000
	s_addc_u32 s7, s7, 0
	s_addk_i32 s8, 0xc025
	s_cmpk_lt_i32 s24, 0x3ffd
	v_lshl_add_u64 v[156:157], s[6:7], 0, v[90:91]
	v_lshl_add_u64 v[154:155], s[6:7], 0, v[96:97]
	v_lshl_add_u64 v[150:151], s[6:7], 0, v[98:99]
	v_lshl_add_u64 v[138:139], s[6:7], 0, v[100:101]
	s_cselect_b32 s6, s9, s8
	s_waitcnt vmcnt(0) lgkmcnt(0)
	v_pk_mul_f32 v[158:159], v[80:81], v[80:81]
	v_pk_mul_f32 v[160:161], v[78:79], v[78:79]
	v_pk_mul_f32 v[162:163], v[76:77], v[76:77]
	v_pk_mul_f32 v[164:165], v[74:75], v[74:75]
	v_mul_f32_e32 v174, v71, v71
	v_mul_f32_e32 v176, v73, v73
	v_mul_f32_e32 v187, v68, v68
	v_mul_f32_e32 v189, v69, v69
	v_pk_mov_b32 v[178:179], v[160:161], v[158:159] op_sel:[1,0]
	v_mov_b32_e32 v161, v159
	v_pk_mov_b32 v[158:159], v[164:165], v[162:163] op_sel:[1,0]
	v_mov_b32_e32 v165, v163
	v_pk_fma_f32 v[162:163], v[70:71], v[70:71], v[174:175] op_sel_hi:[1,1,0]
	v_pk_fma_f32 v[174:175], v[72:73], v[72:73], v[176:177] op_sel_hi:[1,1,0]
	v_pk_mul_f32 v[176:177], v[64:65], v[64:65]
	v_pk_mul_f32 v[180:181], v[62:63], v[62:63]
	v_pk_mul_f32 v[182:183], v[60:61], v[60:61]
	v_pk_mul_f32 v[184:185], v[58:59], v[58:59]
	v_mul_f32_e32 v186, v55, v55
	v_mul_f32_e32 v188, v57, v57
	v_pk_add_f32 v[160:161], v[178:179], v[160:161]
	v_pk_add_f32 v[158:159], v[158:159], v[164:165]
	v_mov_b32_e32 v163, v187
	v_mov_b32_e32 v175, v189
	v_pk_mov_b32 v[164:165], v[180:181], v[176:177] op_sel:[1,0]
	v_mov_b32_e32 v181, v177
	v_pk_mov_b32 v[176:177], v[184:185], v[182:183] op_sel:[1,0]
	v_mov_b32_e32 v185, v183
	v_pk_fma_f32 v[178:179], v[54:55], v[54:55], v[186:187] op_sel_hi:[1,1,0]
	v_pk_fma_f32 v[182:183], v[56:57], v[56:57], v[188:189] op_sel_hi:[1,1,0]
	v_pk_mul_f32 v[186:187], v[48:49], v[48:49]
	v_pk_mul_f32 v[188:189], v[46:47], v[46:47]
	v_pk_mul_f32 v[190:191], v[44:45], v[44:45]
	v_pk_mul_f32 v[192:193], v[42:43], v[42:43]
	v_mul_f32_e32 v173, v66, v66
	v_mul_f32_e32 v197, v67, v67
	v_mul_f32_e32 v195, v52, v52
	v_mul_f32_e32 v202, v53, v53
	v_mul_f32_e32 v194, v39, v39
	v_mul_f32_e32 v196, v41, v41
	v_pk_add_f32 v[198:199], v[160:161], v[160:161] op_sel:[0,1] op_sel_hi:[1,0]
	v_pk_add_f32 v[200:201], v[158:159], v[158:159] op_sel:[0,1] op_sel_hi:[1,0]
	v_pk_add_f32 v[174:175], v[162:163], v[174:175]
	v_pk_add_f32 v[158:159], v[164:165], v[180:181]
	v_pk_add_f32 v[160:161], v[176:177], v[184:185]
	v_pk_mov_b32 v[162:163], v[188:189], v[186:187] op_sel:[1,0]
	v_mov_b32_e32 v189, v187
	v_pk_mov_b32 v[164:165], v[192:193], v[190:191] op_sel:[1,0]
	v_mov_b32_e32 v193, v191
	v_mul_f32_e32 v203, v50, v50
	v_mul_f32_e32 v208, v51, v51
	v_mul_f32_e32 v211, v36, v36
	v_mul_f32_e32 v212, v37, v37
	v_mov_b32_e32 v179, v195
	v_mov_b32_e32 v183, v202
	v_pk_fma_f32 v[176:177], v[38:39], v[38:39], v[194:195] op_sel_hi:[1,1,0]
	v_pk_fma_f32 v[180:181], v[40:41], v[40:41], v[196:197] op_sel_hi:[1,1,0]
	v_pk_mul_f32 v[184:185], v[32:33], v[32:33]
	v_pk_mul_f32 v[186:187], v[30:31], v[30:31]
	v_pk_mul_f32 v[190:191], v[28:29], v[28:29]
	v_pk_mul_f32 v[194:195], v[26:27], v[26:27]
	v_mov_b32_e32 v199, v173
	v_mov_b32_e32 v201, v197
	v_pk_add_f32 v[204:205], v[158:159], v[158:159] op_sel:[0,1] op_sel_hi:[1,0]
	v_pk_add_f32 v[206:207], v[160:161], v[160:161] op_sel:[0,1] op_sel_hi:[1,0]
	v_pk_add_f32 v[162:163], v[162:163], v[188:189]
	v_pk_add_f32 v[164:165], v[164:165], v[192:193]
	v_mul_f32_e32 v209, v34, v34
	v_mul_f32_e32 v210, v35, v35
	v_pk_add_f32 v[178:179], v[178:179], v[182:183]
	v_mov_b32_e32 v177, v211
	v_mov_b32_e32 v181, v212
	v_pk_mov_b32 v[182:183], v[186:187], v[184:185] op_sel:[1,0]
	v_mov_b32_e32 v187, v185
	v_pk_mov_b32 v[184:185], v[194:195], v[190:191] op_sel:[1,0]
	v_mov_b32_e32 v195, v191
	v_pk_add_f32 v[188:189], v[198:199], v[200:201]
	v_mov_b32_e32 v205, v203
	v_mov_b32_e32 v207, v208
	v_pk_add_f32 v[190:191], v[162:163], v[162:163] op_sel:[0,1] op_sel_hi:[1,0]
	v_pk_add_f32 v[192:193], v[164:165], v[164:165] op_sel:[0,1] op_sel_hi:[1,0]
	v_pk_add_f32 v[176:177], v[176:177], v[180:181]
	v_pk_add_f32 v[174:175], v[188:189], v[174:175]
	v_pk_add_f32 v[180:181], v[204:205], v[206:207]
	v_mov_b32_e32 v191, v209
	v_mov_b32_e32 v193, v210
	v_add_f32_e32 v173, v174, v175
	v_pk_add_f32 v[174:175], v[180:181], v[178:179]
	v_pk_add_f32 v[178:179], v[190:191], v[192:193]
	v_add_f32_e32 v180, v174, v175
	v_pk_add_f32 v[174:175], v[178:179], v[176:177]
	ds_bpermute_b32 v176, v1, v173
	v_add_f32_e32 v174, v174, v175
	ds_bpermute_b32 v175, v1, v180
	ds_bpermute_b32 v177, v1, v174
	s_addk_i32 s6, 0x82
	s_waitcnt lgkmcnt(2)
	v_add_f32_e32 v173, v173, v176
	ds_bpermute_b32 v176, v166, v173
	s_waitcnt lgkmcnt(2)
	v_add_f32_e32 v175, v180, v175
	ds_bpermute_b32 v178, v166, v175
	s_waitcnt lgkmcnt(2)
	v_add_f32_e32 v174, v174, v177
	ds_bpermute_b32 v177, v166, v174
	s_waitcnt lgkmcnt(2)
	v_add_f32_e32 v173, v173, v176
	ds_bpermute_b32 v176, v167, v173
	s_waitcnt lgkmcnt(2)
	v_add_f32_e32 v175, v175, v178
	ds_bpermute_b32 v178, v167, v175
	s_waitcnt lgkmcnt(2)
	v_add_f32_e32 v174, v174, v177
	ds_bpermute_b32 v177, v167, v174
	s_waitcnt lgkmcnt(2)
	v_add_f32_e32 v173, v173, v176
	ds_bpermute_b32 v176, v168, v173
	s_waitcnt lgkmcnt(2)
	v_add_f32_e32 v175, v175, v178
	ds_bpermute_b32 v178, v168, v175
	s_waitcnt lgkmcnt(2)
	v_add_f32_e32 v174, v174, v177
	ds_bpermute_b32 v177, v168, v174
	s_waitcnt lgkmcnt(2)
	v_add_f32_e32 v173, v173, v176
	ds_bpermute_b32 v176, v169, v173
	s_waitcnt lgkmcnt(2)
	v_add_f32_e32 v175, v175, v178
	ds_bpermute_b32 v178, v169, v175
	s_waitcnt lgkmcnt(2)
	v_add_f32_e32 v174, v174, v177
	ds_bpermute_b32 v177, v169, v174
	s_waitcnt lgkmcnt(2)
	v_add_f32_e32 v173, v173, v176
	ds_bpermute_b32 v176, v170, v173
	s_waitcnt lgkmcnt(2)
	v_add_f32_e32 v175, v175, v178
	ds_bpermute_b32 v178, v170, v175
	s_mul_hi_i32 s7, s6, 0x9000
	s_mul_i32 s6, s6, 0x9000
	s_waitcnt lgkmcnt(2)
	v_add_f32_e32 v174, v174, v177
	s_add_u32 s6, s4, s6
	ds_bpermute_b32 v177, v170, v174
	s_addc_u32 s7, s5, s7
	s_waitcnt lgkmcnt(2)
	v_add_f32_e32 v173, v173, v176
	s_add_u32 s16, s6, 0x6000
	v_fmamk_f32 v173, v173, 0x3a800000, v171
	s_addc_u32 s17, s7, 0
	s_waitcnt lgkmcnt(1)
	v_add_f32_e32 v175, v175, v178
	v_mul_f32_e32 v176, 0x4f800000, v173
	v_cmp_gt_f32_e32 vcc, s2, v173
	s_add_u32 s18, s6, 0x7000
	v_fmamk_f32 v175, v175, 0x3a800000, v171
	v_cndmask_b32_e32 v173, v173, v176, vcc
	s_addc_u32 s19, s7, 0
	s_waitcnt lgkmcnt(0)
	v_add_f32_e32 v174, v174, v177
	v_mul_f32_e32 v176, 0x4f800000, v175
	v_cmp_gt_f32_e64 s[6:7], s2, v175
	v_sqrt_f32_e32 v177, v173
	v_fmamk_f32 v174, v174, 0x3a800000, v171
	v_cndmask_b32_e64 v175, v175, v176, s[6:7]
	v_mul_f32_e32 v176, 0x4f800000, v174
	v_cmp_gt_f32_e64 s[8:9], s2, v174
	v_sqrt_f32_e32 v178, v175
	v_add_u32_e32 v179, -1, v177
	v_cndmask_b32_e64 v174, v174, v176, s[8:9]
	v_sqrt_f32_e32 v176, v174
	v_add_u32_e32 v180, 1, v177
	v_fma_f32 v181, -v179, v177, v173
	v_lshl_add_u64 v[112:113], s[10:11], 0, v[90:91]
	v_lshl_add_u64 v[106:107], s[10:11], 0, v[96:97]
	v_lshl_add_u64 v[110:111], s[10:11], 0, v[98:99]
	v_lshl_add_u64 v[108:109], s[10:11], 0, v[100:101]
	v_pk_add_f32 v[162:163], v[182:183], v[186:187]
	v_fma_f32 v182, -v180, v177, v173
	v_add_u32_e32 v183, -1, v178
	v_cmp_ge_f32_e64 s[10:11], 0, v181
	v_pk_add_f32 v[164:165], v[184:185], v[194:195]
	v_add_u32_e32 v184, 1, v178
	v_cndmask_b32_e64 v177, v177, v179, s[10:11]
	v_fma_f32 v179, -v183, v178, v175
	v_cmp_lt_f32_e64 s[10:11], 0, v182
	v_fma_f32 v181, -v184, v178, v175
	v_add_u32_e32 v185, -1, v176
	v_cndmask_b32_e64 v177, v177, v180, s[10:11]
	v_cmp_ge_f32_e64 s[10:11], 0, v179
	v_add_u32_e32 v186, 1, v176
	v_fma_f32 v179, -v185, v176, v174
	v_cndmask_b32_e64 v178, v178, v183, s[10:11]
	v_cmp_lt_f32_e64 s[10:11], 0, v181
	v_fma_f32 v180, -v186, v176, v174
	v_mul_f32_e32 v181, 0x37800000, v177
	v_cndmask_b32_e64 v178, v178, v184, s[10:11]
	v_cmp_ge_f32_e64 s[10:11], 0, v179
	v_cndmask_b32_e32 v177, v177, v181, vcc
	v_cmp_class_f32_e32 vcc, v173, v172
	v_cndmask_b32_e64 v176, v176, v185, s[10:11]
	v_cmp_lt_f32_e64 s[10:11], 0, v180
	v_mul_f32_e32 v179, 0x37800000, v178
	v_cndmask_b32_e32 v173, v177, v173, vcc
	v_cndmask_b32_e64 v176, v176, v186, s[10:11]
	v_cndmask_b32_e64 v177, v178, v179, s[6:7]
	v_cmp_class_f32_e32 vcc, v175, v172
	v_mul_f32_e32 v178, 0x37800000, v176
	v_div_scale_f32 v179, s[6:7], v173, v173, 1.0
	v_cndmask_b32_e32 v175, v177, v175, vcc
	v_cndmask_b32_e64 v176, v176, v178, s[8:9]
	v_cmp_class_f32_e32 vcc, v174, v172
	v_rcp_f32_e32 v177, v179
	v_div_scale_f32 v178, s[8:9], v175, v175, 1.0
	v_cndmask_b32_e32 v176, v176, v174, vcc
	v_rcp_f32_e32 v182, v178
	v_div_scale_f32 v183, s[10:11], v176, v176, 1.0
	v_rcp_f32_e32 v185, v183
	v_fma_f32 v174, -v179, v177, 1.0
	v_div_scale_f32 v180, s[6:7], 1.0, v173, 1.0
	v_fmac_f32_e32 v177, v174, v177
	v_fma_f32 v174, -v178, v182, 1.0
	v_mul_f32_e32 v186, v180, v177
	v_div_scale_f32 v181, s[8:9], 1.0, v175, 1.0
	v_fmac_f32_e32 v182, v174, v182
	v_fma_f32 v174, -v183, v185, 1.0
	v_fma_f32 v187, -v179, v186, v180
	v_div_scale_f32 v184, s[10:11], 1.0, v176, 1.0
	v_mul_f32_e32 v188, v181, v182
	v_fmac_f32_e32 v185, v174, v185
	v_fmac_f32_e32 v186, v187, v177
	v_fma_f32 v174, -v178, v188, v181
	v_mul_f32_e32 v187, v184, v185
	v_fma_f32 v179, -v179, v186, v180
	s_mov_b64 vcc, s[6:7]
	v_fmac_f32_e32 v188, v174, v182
	v_fma_f32 v174, -v183, v187, v184
	v_div_fmas_f32 v177, v179, v177, v186
	v_fma_f32 v178, -v178, v188, v181
	v_fmac_f32_e32 v187, v174, v185
	v_div_fixup_f32 v174, v177, v173, 1.0
	s_mov_b64 vcc, s[8:9]
	v_div_fmas_f32 v173, v178, v182, v188
	v_fma_f32 v177, -v183, v187, v184
	v_pk_mul_f32 v[80:81], v[80:81], v[174:175] op_sel_hi:[1,0]
	v_pk_mul_f32 v[78:79], v[78:79], v[174:175] op_sel_hi:[1,0]
	s_mov_b64 vcc, s[10:11]
	v_pk_add_f32 v[88:89], v[88:89], 1.0 op_sel_hi:[1,0]
	v_pk_add_f32 v[86:87], v[86:87], 1.0 op_sel_hi:[1,0]
	v_pk_mul_f32 v[76:77], v[76:77], v[174:175] op_sel_hi:[1,0]
	v_pk_mul_f32 v[74:75], v[74:75], v[174:175] op_sel_hi:[1,0]
	v_pk_mul_f32 v[72:73], v[72:73], v[174:175] op_sel_hi:[1,0]
	v_pk_mul_f32 v[70:71], v[70:71], v[174:175] op_sel_hi:[1,0]
	v_pk_mul_f32 v[68:69], v[68:69], v[174:175] op_sel_hi:[1,0]
	v_pk_mul_f32 v[66:67], v[66:67], v[174:175] op_sel_hi:[1,0]
	v_div_fixup_f32 v174, v173, v175, 1.0
	v_div_fmas_f32 v173, v177, v185, v187
	v_pk_mul_f32 v[78:79], v[2:3], v[78:79]
	v_pk_mul_f32 v[80:81], v[4:5], v[80:81]
	v_pk_mul_f32 v[64:65], v[64:65], v[174:175] op_sel_hi:[1,0]
	v_pk_mul_f32 v[62:63], v[62:63], v[174:175] op_sel_hi:[1,0]
	v_pk_mul_f32 v[60:61], v[60:61], v[174:175] op_sel_hi:[1,0]
	v_pk_mul_f32 v[58:59], v[58:59], v[174:175] op_sel_hi:[1,0]
	v_pk_mul_f32 v[56:57], v[56:57], v[174:175] op_sel_hi:[1,0]
	v_pk_mul_f32 v[54:55], v[54:55], v[174:175] op_sel_hi:[1,0]
	v_pk_mul_f32 v[52:53], v[52:53], v[174:175] op_sel_hi:[1,0]
	v_pk_mul_f32 v[174:175], v[50:51], v[174:175] op_sel_hi:[1,0]
	v_div_fixup_f32 v50, v173, v176, 1.0
	v_pk_fma_f32 v[80:81], v[88:89], v[80:81], v[84:85]
	v_pk_fma_f32 v[78:79], v[86:87], v[78:79], v[82:83]
	v_pk_mul_f32 v[86:87], v[16:17], v[52:53]
	v_pk_mul_f32 v[48:49], v[48:49], v[50:51] op_sel_hi:[1,0]
	v_pk_mul_f32 v[46:47], v[46:47], v[50:51] op_sel_hi:[1,0]
	v_pk_mul_f32 v[82:83], v[10:11], v[54:55]
	v_pk_mul_f32 v[84:85], v[14:15], v[174:175]
	v_pk_mul_f32 v[88:89], v[2:3], v[46:47]
	v_pk_mul_f32 v[174:175], v[4:5], v[48:49]
	v_cvt_pk_bf16_f32 v46, v78, v79
	v_cvt_pk_bf16_f32 v47, v80, v81
	global_store_dwordx2 v[102:103], v[46:47], off
	global_load_dwordx4 v[238:241], v[152:153], off
	s_nop 0
	global_load_dwordx4 v[242:245], v[148:149], off
	v_pk_mul_f32 v[74:75], v[6:7], v[74:75]
	v_pk_mul_f32 v[76:77], v[8:9], v[76:77]
	v_pk_mul_f32 v[70:71], v[10:11], v[70:71]
	v_pk_mul_f32 v[72:73], v[12:13], v[72:73]
	v_pk_mul_f32 v[66:67], v[66:67], v[14:15]
	v_pk_mul_f32 v[68:69], v[68:69], v[16:17]
	v_pk_mul_f32 v[62:63], v[2:3], v[62:63]
	v_pk_mul_f32 v[64:65], v[4:5], v[64:65]
	v_pk_mul_f32 v[58:59], v[6:7], v[58:59]
	v_pk_mul_f32 v[60:61], v[8:9], v[60:61]
	v_pk_mul_f32 v[56:57], v[12:13], v[56:57]
	v_mul_f32_e32 v196, v23, v23
	v_mul_f32_e32 v202, v25, v25
	v_mul_f32_e32 v213, v18, v18
	v_mul_f32_e32 v214, v19, v19
	v_mul_f32_e32 v215, v20, v20
	v_mul_f32_e32 v216, v21, v21
	v_pk_fma_f32 v[158:159], v[22:23], v[22:23], v[196:197] op_sel_hi:[1,1,0]
	v_pk_fma_f32 v[160:161], v[24:25], v[24:25], v[202:203] op_sel_hi:[1,1,0]
	v_mov_b32_e32 v159, v215
	v_mov_b32_e32 v161, v216
	v_lshl_add_u64 v[144:145], s[18:19], 0, v[90:91]
	v_lshl_add_u64 v[128:129], s[16:17], 0, v[90:91]
	v_lshl_add_u64 v[124:125], s[18:19], 0, v[96:97]
	v_lshl_add_u64 v[120:121], s[16:17], 0, v[96:97]
	v_lshl_add_u64 v[92:93], v[92:93], 0, s[12:13]
	v_lshl_add_u64 v[94:95], v[94:95], 0, s[14:15]
	s_mov_b32 s8, s24
	s_cmp_lt_i32 s24, s20
	global_load_dwordx4 v[230:233], v[146:147], off
	s_nop 0
	global_load_dwordx4 v[234:237], v[142:143], off
	s_waitcnt vmcnt(2) lgkmcnt(0)
	v_pk_add_f32 v[240:241], v[240:241], 1.0 op_sel_hi:[1,0]
	v_pk_add_f32 v[238:239], v[238:239], 1.0 op_sel_hi:[1,0]
	v_pk_fma_f32 v[240:241], v[240:241], v[76:77], v[244:245]
	v_pk_fma_f32 v[238:239], v[238:239], v[74:75], v[242:243]
	v_cvt_pk_bf16_f32 v238, v238, v239
	v_cvt_pk_bf16_f32 v239, v240, v241
	global_store_dwordx2 v[102:103], v[238:239], off offset:512
	global_load_dwordx4 v[238:241], v[140:141], off
	s_nop 0
	global_load_dwordx4 v[242:245], v[132:133], off
	s_waitcnt vmcnt(3) lgkmcnt(0)
	v_pk_add_f32 v[232:233], v[232:233], 1.0 op_sel_hi:[1,0]
	v_pk_add_f32 v[230:231], v[230:231], 1.0 op_sel_hi:[1,0]
	v_pk_fma_f32 v[232:233], v[72:73], v[232:233], v[236:237]
	v_pk_fma_f32 v[230:231], v[70:71], v[230:231], v[234:235]
	v_cvt_pk_bf16_f32 v230, v230, v231
	v_cvt_pk_bf16_f32 v231, v232, v233
	global_store_dwordx2 v[102:103], v[230:231], off offset:1024
	global_load_dwordx4 v[230:233], v[136:137], off
	s_nop 0
	global_load_dwordx4 v[234:237], v[134:135], off
	s_waitcnt vmcnt(3) lgkmcnt(0)
	v_pk_add_f32 v[240:241], v[240:241], 1.0 op_sel_hi:[1,0]
	v_pk_add_f32 v[238:239], v[238:239], 1.0 op_sel_hi:[1,0]
	v_pk_fma_f32 v[240:241], v[68:69], v[240:241], v[244:245]
	v_pk_fma_f32 v[238:239], v[66:67], v[238:239], v[242:243]
	v_cvt_pk_bf16_f32 v238, v238, v239
	v_cvt_pk_bf16_f32 v239, v240, v241
	global_store_dwordx2 v[102:103], v[238:239], off offset:1536
	global_load_dwordx4 v[238:241], v[130:131], off
	s_nop 0
	global_load_dwordx4 v[242:245], v[126:127], off
	s_waitcnt vmcnt(3) lgkmcnt(0)
	v_pk_add_f32 v[232:233], v[232:233], 1.0 op_sel_hi:[1,0]
	v_pk_add_f32 v[230:231], v[230:231], 1.0 op_sel_hi:[1,0]
	v_pk_fma_f32 v[232:233], v[232:233], v[64:65], v[236:237]
	v_pk_fma_f32 v[230:231], v[230:231], v[62:63], v[234:235]
	v_cvt_pk_bf16_f32 v230, v230, v231
	v_cvt_pk_bf16_f32 v231, v232, v233
	global_store_dwordx2 v[102:103], v[230:231], off offset:2048
	global_load_dwordx4 v[230:233], v[122:123], off
	s_nop 0
	global_load_dwordx4 v[234:237], v[118:119], off
	s_waitcnt vmcnt(3) lgkmcnt(0)
	v_pk_add_f32 v[240:241], v[240:241], 1.0 op_sel_hi:[1,0]
	v_pk_add_f32 v[238:239], v[238:239], 1.0 op_sel_hi:[1,0]
	v_pk_fma_f32 v[240:241], v[240:241], v[60:61], v[244:245]
	v_pk_fma_f32 v[238:239], v[238:239], v[58:59], v[242:243]
	v_cvt_pk_bf16_f32 v238, v238, v239
	v_cvt_pk_bf16_f32 v239, v240, v241
	global_store_dwordx2 v[102:103], v[238:239], off offset:2560
	v_pk_add_f32 v[58:59], v[164:165], v[164:165] op_sel:[0,1] op_sel_hi:[1,0]
	v_pk_add_f32 v[60:61], v[158:159], v[160:161]
	v_mov_b32_e32 v59, v214
	global_load_dwordx4 v[238:241], v[116:117], off
	s_nop 0
	global_load_dwordx4 v[242:245], v[114:115], off
	s_waitcnt vmcnt(3) lgkmcnt(0)
	v_pk_add_f32 v[232:233], v[232:233], 1.0 op_sel_hi:[1,0]
	v_pk_add_f32 v[230:231], v[230:231], 1.0 op_sel_hi:[1,0]
	v_pk_fma_f32 v[232:233], v[232:233], v[56:57], v[236:237]
	v_pk_fma_f32 v[230:231], v[230:231], v[82:83], v[234:235]
	v_cvt_pk_bf16_f32 v230, v230, v231
	v_cvt_pk_bf16_f32 v231, v232, v233
	global_store_dwordx2 v[102:103], v[230:231], off offset:3072
	v_pk_add_f32 v[56:57], v[162:163], v[162:163] op_sel:[0,1] op_sel_hi:[1,0]
	global_load_dwordx4 v[230:233], v[156:157], off
	s_nop 0
	global_load_dwordx4 v[234:237], v[112:113], off
	s_waitcnt vmcnt(3) lgkmcnt(0)
	v_pk_add_f32 v[240:241], v[240:241], 1.0 op_sel_hi:[1,0]
	v_pk_add_f32 v[238:239], v[238:239], 1.0 op_sel_hi:[1,0]
	v_pk_fma_f32 v[240:241], v[86:87], v[240:241], v[244:245]
	v_pk_fma_f32 v[238:239], v[84:85], v[238:239], v[242:243]
	v_cvt_pk_bf16_f32 v238, v238, v239
	v_cvt_pk_bf16_f32 v239, v240, v241
	global_store_dwordx2 v[102:103], v[238:239], off offset:3584
	v_mov_b32_e32 v57, v213
	global_load_dwordx4 v[238:241], v[154:155], off
	s_nop 0
	global_load_dwordx4 v[242:245], v[106:107], off
	s_waitcnt vmcnt(3) lgkmcnt(0)
	v_pk_add_f32 v[232:233], v[232:233], 1.0 op_sel_hi:[1,0]
	v_pk_add_f32 v[230:231], v[230:231], 1.0 op_sel_hi:[1,0]
	v_pk_fma_f32 v[232:233], v[232:233], v[174:175], v[236:237]
	v_pk_fma_f32 v[230:231], v[230:231], v[88:89], v[234:235]
	v_bfe_u32 v51, v230, 16, 1
	v_bfe_u32 v234, v231, 16, 1
	v_add3_u32 v230, v230, v51, s3
	v_add3_u32 v231, v231, v234, s3
	v_lshrrev_b32_e32 v230, 16, v230
	v_and_or_b32 v230, v231, s21, v230
	v_cvt_pk_bf16_f32 v231, v232, v233
	global_store_dwordx2 v[104:105], v[230:231], off
	v_pk_mul_f32 v[44:45], v[44:45], v[50:51] op_sel_hi:[1,0]
	v_pk_mul_f32 v[42:43], v[42:43], v[50:51] op_sel_hi:[1,0]
	v_pk_mul_f32 v[44:45], v[8:9], v[44:45]
	v_pk_mul_f32 v[42:43], v[6:7], v[42:43]
	s_waitcnt vmcnt(1) lgkmcnt(0)
	v_pk_add_f32 v[240:241], v[240:241], 1.0 op_sel_hi:[1,0]
	v_pk_add_f32 v[238:239], v[238:239], 1.0 op_sel_hi:[1,0]
	v_pk_fma_f32 v[44:45], v[240:241], v[44:45], v[244:245]
	v_pk_fma_f32 v[42:43], v[238:239], v[42:43], v[242:243]
	v_cvt_pk_bf16_f32 v42, v42, v43
	v_cvt_pk_bf16_f32 v43, v44, v45
	global_store_dwordx2 v[104:105], v[42:43], off offset:512
	global_load_dwordx4 v[42:45], v[150:151], off
	s_nop 0
	global_load_dwordx4 v[46:49], v[110:111], off
	v_pk_add_f32 v[52:53], v[56:57], v[58:59]
	s_waitcnt vmcnt(0) lgkmcnt(0)
	v_pk_add_f32 v[44:45], v[44:45], 1.0 op_sel_hi:[1,0]
	v_pk_add_f32 v[52:53], v[52:53], v[60:61]
	v_pk_add_f32 v[42:43], v[42:43], 1.0 op_sel_hi:[1,0]
	v_add_f32_e32 v51, v52, v53
	ds_bpermute_b32 v52, v1, v51
	s_waitcnt lgkmcnt(0)
	v_add_f32_e32 v51, v51, v52
	ds_bpermute_b32 v52, v166, v51
	s_waitcnt lgkmcnt(0)
	v_add_f32_e32 v51, v51, v52
	v_pk_mul_f32 v[40:41], v[40:41], v[50:51] op_sel_hi:[1,0]
	v_pk_mul_f32 v[38:39], v[38:39], v[50:51] op_sel_hi:[1,0]
	v_pk_mul_f32 v[40:41], v[12:13], v[40:41]
	v_pk_mul_f32 v[38:39], v[10:11], v[38:39]
	v_pk_fma_f32 v[40:41], v[44:45], v[40:41], v[48:49]
	v_pk_fma_f32 v[38:39], v[42:43], v[38:39], v[46:47]
	v_cvt_pk_bf16_f32 v38, v38, v39
	v_cvt_pk_bf16_f32 v39, v40, v41
	global_store_dwordx2 v[104:105], v[38:39], off offset:1024
	global_load_dwordx4 v[38:41], v[138:139], off
	s_nop 0
	global_load_dwordx4 v[42:45], v[108:109], off
	v_pk_mul_f32 v[36:37], v[36:37], v[50:51] op_sel_hi:[1,0]
	v_pk_mul_f32 v[34:35], v[34:35], v[50:51] op_sel_hi:[1,0]
	v_pk_mul_f32 v[36:37], v[16:17], v[36:37]
	v_pk_mul_f32 v[34:35], v[14:15], v[34:35]
	ds_bpermute_b32 v46, v167, v51
	s_waitcnt lgkmcnt(0)
	v_add_f32_e32 v46, v51, v46
	ds_bpermute_b32 v47, v168, v46
	s_waitcnt lgkmcnt(0)
	v_add_f32_e32 v46, v46, v47
	ds_bpermute_b32 v47, v169, v46
	s_waitcnt lgkmcnt(0)
	v_add_f32_e32 v46, v46, v47
	ds_bpermute_b32 v47, v170, v46
	s_waitcnt lgkmcnt(0)
	v_add_f32_e32 v46, v46, v47
	v_fmamk_f32 v46, v46, 0x3a800000, v171
	v_mul_f32_e32 v47, 0x4f800000, v46
	v_cmp_gt_f32_e32 vcc, s2, v46
	s_waitcnt vmcnt(0)
	v_pk_add_f32 v[40:41], v[40:41], 1.0 op_sel_hi:[1,0]
	v_pk_add_f32 v[38:39], v[38:39], 1.0 op_sel_hi:[1,0]
	v_pk_fma_f32 v[36:37], v[36:37], v[40:41], v[44:45]
	v_pk_fma_f32 v[34:35], v[34:35], v[38:39], v[42:43]
	v_cvt_pk_bf16_f32 v34, v34, v35
	v_cvt_pk_bf16_f32 v35, v36, v37
	global_store_dwordx2 v[104:105], v[34:35], off offset:1536
	global_load_dwordx4 v[34:37], v[144:145], off
	s_nop 0
	global_load_dwordx4 v[38:41], v[128:129], off
	v_cndmask_b32_e32 v42, v46, v47, vcc
	v_sqrt_f32_e32 v43, v42
	s_waitcnt vmcnt(0) lgkmcnt(0)
	v_pk_add_f32 v[36:37], v[36:37], 1.0 op_sel_hi:[1,0]
	v_add_u32_e32 v44, -1, v43
	v_add_u32_e32 v45, 1, v43
	v_fma_f32 v46, -v44, v43, v42
	v_fma_f32 v47, -v45, v43, v42
	v_cmp_ge_f32_e64 s[6:7], 0, v46
	v_pk_add_f32 v[34:35], v[34:35], 1.0 op_sel_hi:[1,0]
	s_nop 0
	v_cndmask_b32_e64 v43, v43, v44, s[6:7]
	v_cmp_lt_f32_e64 s[6:7], 0, v47
	s_nop 1
	v_cndmask_b32_e64 v43, v43, v45, s[6:7]
	v_mul_f32_e32 v44, 0x37800000, v43
	v_cndmask_b32_e32 v43, v43, v44, vcc
	v_cmp_class_f32_e32 vcc, v42, v172
	s_nop 1
	v_cndmask_b32_e32 v42, v43, v42, vcc
	v_div_scale_f32 v43, s[6:7], v42, v42, 1.0
	v_rcp_f32_e32 v45, v43
	v_div_scale_f32 v44, vcc, 1.0, v42, 1.0
	v_fma_f32 v46, -v43, v45, 1.0
	v_fmac_f32_e32 v45, v46, v45
	v_mul_f32_e32 v46, v44, v45
	v_fma_f32 v47, -v43, v46, v44
	v_fmac_f32_e32 v46, v47, v45
	v_fma_f32 v43, -v43, v46, v44
	v_div_fmas_f32 v43, v43, v45, v46
	v_div_fixup_f32 v42, v43, v42, 1.0
	v_pk_mul_f32 v[32:33], v[32:33], v[42:43] op_sel_hi:[1,0]
	v_pk_mul_f32 v[30:31], v[30:31], v[42:43] op_sel_hi:[1,0]
	v_pk_mul_f32 v[32:33], v[4:5], v[32:33]
	v_pk_mul_f32 v[30:31], v[2:3], v[30:31]
	v_pk_fma_f32 v[32:33], v[36:37], v[32:33], v[40:41]
	v_pk_fma_f32 v[30:31], v[34:35], v[30:31], v[38:39]
	v_cvt_pk_bf16_f32 v30, v30, v31
	v_cvt_pk_bf16_f32 v31, v32, v33
	global_store_dwordx2 v[104:105], v[30:31], off offset:2048
	global_load_dwordx4 v[30:33], v[124:125], off
	s_nop 0
	global_load_dwordx4 v[34:37], v[120:121], off
	v_pk_mul_f32 v[28:29], v[28:29], v[42:43] op_sel_hi:[1,0]
	v_pk_mul_f32 v[26:27], v[26:27], v[42:43] op_sel_hi:[1,0]
	v_pk_mul_f32 v[28:29], v[8:9], v[28:29]
	v_pk_mul_f32 v[26:27], v[6:7], v[26:27]
	v_lshl_add_u64 v[40:41], s[18:19], 0, v[98:99]
	v_lshl_add_u64 v[38:39], s[16:17], 0, v[98:99]
	v_pk_mul_f32 v[24:25], v[24:25], v[42:43] op_sel_hi:[1,0]
	v_pk_mul_f32 v[22:23], v[22:23], v[42:43] op_sel_hi:[1,0]
	v_pk_mul_f32 v[24:25], v[12:13], v[24:25]
	v_pk_mul_f32 v[22:23], v[10:11], v[22:23]
	v_pk_mul_f32 v[20:21], v[20:21], v[42:43] op_sel_hi:[1,0]
	v_pk_mul_f32 v[18:19], v[18:19], v[42:43] op_sel_hi:[1,0]
	v_pk_mul_f32 v[20:21], v[16:17], v[20:21]
	v_pk_mul_f32 v[18:19], v[14:15], v[18:19]
	s_waitcnt vmcnt(0) lgkmcnt(0)
	v_pk_add_f32 v[32:33], v[32:33], 1.0 op_sel_hi:[1,0]
	v_pk_add_f32 v[30:31], v[30:31], 1.0 op_sel_hi:[1,0]
	v_pk_fma_f32 v[28:29], v[32:33], v[28:29], v[36:37]
	v_pk_fma_f32 v[26:27], v[30:31], v[26:27], v[34:35]
	v_cvt_pk_bf16_f32 v26, v26, v27
	v_cvt_pk_bf16_f32 v27, v28, v29
	global_store_dwordx2 v[104:105], v[26:27], off offset:2560
	global_load_dwordx4 v[26:29], v[40:41], off
	s_nop 0
	global_load_dwordx4 v[30:33], v[38:39], off
	v_lshl_add_u64 v[36:37], s[18:19], 0, v[100:101]
	v_lshl_add_u64 v[34:35], s[16:17], 0, v[100:101]
	s_waitcnt vmcnt(0) lgkmcnt(0)
	v_pk_add_f32 v[28:29], v[28:29], 1.0 op_sel_hi:[1,0]
	v_pk_add_f32 v[26:27], v[26:27], 1.0 op_sel_hi:[1,0]
	v_pk_fma_f32 v[24:25], v[28:29], v[24:25], v[32:33]
	v_pk_fma_f32 v[22:23], v[26:27], v[22:23], v[30:31]
	v_cvt_pk_bf16_f32 v22, v22, v23
	v_cvt_pk_bf16_f32 v23, v24, v25
	global_store_dwordx2 v[104:105], v[22:23], off offset:3072
	global_load_dwordx4 v[22:25], v[36:37], off
	s_nop 0
	global_load_dwordx4 v[26:29], v[34:35], off
	s_waitcnt vmcnt(0) lgkmcnt(0)
	v_pk_add_f32 v[24:25], v[24:25], 1.0 op_sel_hi:[1,0]
	v_pk_add_f32 v[22:23], v[22:23], 1.0 op_sel_hi:[1,0]
	v_pk_fma_f32 v[20:21], v[20:21], v[24:25], v[28:29]
	v_pk_fma_f32 v[18:19], v[18:19], v[22:23], v[26:27]
	v_cvt_pk_bf16_f32 v18, v18, v19
	v_cvt_pk_bf16_f32 v19, v20, v21
	global_store_dwordx2 v[104:105], v[18:19], off offset:3584
	s_cbranch_scc1 .LBB0_5693
